# GEMM phases: wait after the last epilogue counted (vmcnt 16: LDS-DMA only), store drain overlaps the sample-group GEMM
# speedup vs baseline: 1.0183x; 1.0034x over previous
.LBB0_155:
	ds_read_b128 v[154:157], v150
	ds_read_b128 v[158:161], v150 offset:1024
	ds_read_b128 v[162:165], v150 offset:2048
	ds_read_b128 v[166:169], v150 offset:3072
	s_add_u32 s26, s20, 0xfffc0080
	s_addc_u32 s27, s21, -1
	s_cmp_eq_u32 s86, 12
	s_cselect_b32 s29, s15, s27
	s_cselect_b32 s28, s82, s26
	s_cselect_b32 s27, s13, s85
	s_cselect_b32 s26, s83, s84
	v_lshl_add_u64 v[202:203], s[20:21], 0, v[138:139]
	s_add_i32 m0, s11, 0xc000
	ds_read_b128 v[170:173], v151
	ds_read_b128 v[174:177], v151 offset:1024
	ds_read_b128 v[178:181], v151 offset:2048
	ds_read_b128 v[182:185], v151 offset:3072
	ds_read_b128 v[186:189], v151 offset:4096
	ds_read_b128 v[190:193], v151 offset:5120
	ds_read_b128 v[194:197], v151 offset:6144
	ds_read_b128 v[198:201], v151 offset:7168
	global_load_lds_dwordx4 v[202:203], off
	v_lshl_add_u64 v[202:203], s[20:21], 0, v[140:141]
	s_add_i32 m0, s11, 0xe000
	s_nop 0
	global_load_lds_dwordx4 v[202:203], off
	s_waitcnt lgkmcnt(8)
	s_barrier
	s_waitcnt lgkmcnt(0)
	s_waitcnt lgkmcnt(0)
	v_mfma_f32_16x16x32_bf16 v[124:127], v[154:157], v[170:173], v[124:127]
	v_mfma_f32_16x16x32_bf16 v[120:123], v[162:165], v[170:173], v[120:123]
	v_mfma_f32_16x16x32_bf16 v[116:119], v[154:157], v[178:181], v[116:119]
	v_mfma_f32_16x16x32_bf16 v[112:115], v[162:165], v[178:181], v[112:115]
	v_mfma_f32_16x16x32_bf16 v[100:103], v[154:157], v[186:189], v[100:103]
	v_mfma_f32_16x16x32_bf16 v[96:99], v[162:165], v[186:189], v[96:99]
	v_mfma_f32_16x16x32_bf16 v[84:87], v[154:157], v[194:197], v[84:87]
	v_mfma_f32_16x16x32_bf16 v[80:83], v[162:165], v[194:197], v[80:83]
	v_mfma_f32_16x16x32_bf16 v[124:127], v[158:161], v[174:177], v[124:127]
	v_mfma_f32_16x16x32_bf16 v[120:123], v[166:169], v[174:177], v[120:123]
	v_mfma_f32_16x16x32_bf16 v[116:119], v[158:161], v[182:185], v[116:119]
	v_mfma_f32_16x16x32_bf16 v[112:115], v[166:169], v[182:185], v[112:115]
	v_mfma_f32_16x16x32_bf16 v[100:103], v[158:161], v[190:193], v[100:103]
	v_mfma_f32_16x16x32_bf16 v[96:99], v[166:169], v[190:193], v[96:99]
	v_mfma_f32_16x16x32_bf16 v[84:87], v[158:161], v[198:201], v[84:87]
	v_mfma_f32_16x16x32_bf16 v[80:83], v[166:169], v[198:201], v[80:83]
	s_barrier
	s_add_i32 s87, s72, s34
	v_lshl_add_u64 v[218:219], s[26:27], 0, v[134:135]
	s_mov_b32 m0, s87
	ds_read_b128 v[202:205], v152
	ds_read_b128 v[206:209], v152 offset:1024
	ds_read_b128 v[210:213], v152 offset:2048
	ds_read_b128 v[214:217], v152 offset:3072
	global_load_lds_dwordx4 v[218:219], off
	v_lshl_add_u64 v[220:221], s[26:27], 0, v[130:131]
	s_add_i32 m0, s87, 0x2000
	s_nop 0
	global_load_lds_dwordx4 v[220:221], off
	s_barrier
	s_waitcnt lgkmcnt(0)
	s_waitcnt lgkmcnt(0)
	v_mfma_f32_16x16x32_bf16 v[108:111], v[202:205], v[170:173], v[108:111]
	v_mfma_f32_16x16x32_bf16 v[104:107], v[210:213], v[170:173], v[104:107]
	v_mfma_f32_16x16x32_bf16 v[92:95], v[202:205], v[178:181], v[92:95]
	v_mfma_f32_16x16x32_bf16 v[88:91], v[210:213], v[178:181], v[88:91]
	v_mfma_f32_16x16x32_bf16 v[76:79], v[202:205], v[186:189], v[76:79]
	v_mfma_f32_16x16x32_bf16 v[72:75], v[210:213], v[186:189], v[72:75]
	v_mfma_f32_16x16x32_bf16 v[68:71], v[202:205], v[194:197], v[68:71]
	v_mfma_f32_16x16x32_bf16 v[64:67], v[210:213], v[194:197], v[64:67]
	v_mfma_f32_16x16x32_bf16 v[108:111], v[206:209], v[174:177], v[108:111]
	v_mfma_f32_16x16x32_bf16 v[104:107], v[214:217], v[174:177], v[104:107]
	v_mfma_f32_16x16x32_bf16 v[92:95], v[206:209], v[182:185], v[92:95]
	v_mfma_f32_16x16x32_bf16 v[88:91], v[214:217], v[182:185], v[88:91]
	v_mfma_f32_16x16x32_bf16 v[76:79], v[206:209], v[190:193], v[76:79]
	v_mfma_f32_16x16x32_bf16 v[72:75], v[214:217], v[190:193], v[72:75]
	v_mfma_f32_16x16x32_bf16 v[68:71], v[206:209], v[198:201], v[68:71]
	v_mfma_f32_16x16x32_bf16 v[64:67], v[214:217], v[198:201], v[64:67]
	s_mov_b32 m0, s11
	v_lshl_add_u64 v[222:223], s[28:29], 0, v[136:137]
	s_barrier
	ds_read_b128 v[170:173], v151 offset:16384
	ds_read_b128 v[174:177], v151 offset:17408
	ds_read_b128 v[178:181], v151 offset:18432
	ds_read_b128 v[182:185], v151 offset:19456
	ds_read_b128 v[186:189], v151 offset:20480
	ds_read_b128 v[190:193], v151 offset:21504
	ds_read_b128 v[194:197], v151 offset:22528
	ds_read_b128 v[198:201], v151 offset:23552
	global_load_lds_dwordx4 v[222:223], off
	v_lshl_add_u64 v[224:225], s[28:29], 0, v[132:133]
	s_mov_b32 m0, s35
	s_nop 0
	global_load_lds_dwordx4 v[224:225], off
	s_barrier
	s_waitcnt lgkmcnt(0)
	s_waitcnt lgkmcnt(0)
	v_mfma_f32_16x16x32_bf16 v[60:63], v[154:157], v[170:173], v[60:63]
	v_mfma_f32_16x16x32_bf16 v[56:59], v[162:165], v[170:173], v[56:59]
	v_mfma_f32_16x16x32_bf16 v[52:55], v[154:157], v[178:181], v[52:55]
	v_mfma_f32_16x16x32_bf16 v[48:51], v[162:165], v[178:181], v[48:51]
	v_mfma_f32_16x16x32_bf16 v[36:39], v[154:157], v[186:189], v[36:39]
	v_mfma_f32_16x16x32_bf16 v[32:35], v[162:165], v[186:189], v[32:35]
	v_mfma_f32_16x16x32_bf16 v[20:23], v[154:157], v[194:197], v[20:23]
	v_mfma_f32_16x16x32_bf16 v[16:19], v[162:165], v[194:197], v[16:19]
	v_mfma_f32_16x16x32_bf16 v[60:63], v[158:161], v[174:177], v[60:63]
	v_mfma_f32_16x16x32_bf16 v[56:59], v[166:169], v[174:177], v[56:59]
	v_mfma_f32_16x16x32_bf16 v[52:55], v[158:161], v[182:185], v[52:55]
	v_mfma_f32_16x16x32_bf16 v[48:51], v[166:169], v[182:185], v[48:51]
	v_mfma_f32_16x16x32_bf16 v[36:39], v[158:161], v[190:193], v[36:39]
	v_mfma_f32_16x16x32_bf16 v[32:35], v[166:169], v[190:193], v[32:35]
	v_mfma_f32_16x16x32_bf16 v[20:23], v[158:161], v[198:201], v[20:23]
	v_mfma_f32_16x16x32_bf16 v[16:19], v[166:169], v[198:201], v[16:19]
	s_barrier
	s_add_u32 s88, s26, 0x40000
	s_addc_u32 s89, s27, 0
	s_add_i32 s87, s73, s34
	v_lshl_add_u64 v[154:155], s[88:89], 0, v[134:135]
	s_mov_b32 m0, s87
	s_nop 0
	global_load_lds_dwordx4 v[154:155], off
	v_lshl_add_u64 v[154:155], s[88:89], 0, v[130:131]
	s_add_i32 m0, s87, 0x2000
	s_nop 0
	global_load_lds_dwordx4 v[154:155], off
	s_waitcnt vmcnt(6)
	s_barrier
	v_mfma_f32_16x16x32_bf16 v[44:47], v[202:205], v[170:173], v[44:47]
	v_mfma_f32_16x16x32_bf16 v[40:43], v[210:213], v[170:173], v[40:43]
	v_mfma_f32_16x16x32_bf16 v[28:31], v[202:205], v[178:181], v[28:31]
	v_mfma_f32_16x16x32_bf16 v[24:27], v[210:213], v[178:181], v[24:27]
	v_mfma_f32_16x16x32_bf16 v[12:15], v[202:205], v[186:189], v[12:15]
	v_mfma_f32_16x16x32_bf16 v[8:11], v[210:213], v[186:189], v[8:11]
	v_mfma_f32_16x16x32_bf16 v[4:7], v[202:205], v[194:197], v[4:7]
	v_mfma_f32_16x16x32_bf16 v[0:3], v[210:213], v[194:197], v[0:3]
	v_mfma_f32_16x16x32_bf16 v[44:47], v[206:209], v[174:177], v[44:47]
	v_mfma_f32_16x16x32_bf16 v[40:43], v[214:217], v[174:177], v[40:43]
	v_mfma_f32_16x16x32_bf16 v[28:31], v[206:209], v[182:185], v[28:31]
	v_mfma_f32_16x16x32_bf16 v[24:27], v[214:217], v[182:185], v[24:27]
	v_mfma_f32_16x16x32_bf16 v[12:15], v[206:209], v[190:193], v[12:15]
	v_mfma_f32_16x16x32_bf16 v[8:11], v[214:217], v[190:193], v[8:11]
	v_mfma_f32_16x16x32_bf16 v[4:7], v[206:209], v[198:201], v[4:7]
	v_mfma_f32_16x16x32_bf16 v[0:3], v[214:217], v[198:201], v[0:3]
	s_add_i32 s87, 0, 0x18000
	v_add_u32_e32 v153, s87, v148
	s_barrier
	ds_read_b128 v[154:157], v153
	ds_read_b128 v[158:161], v153 offset:1024
	ds_read_b128 v[162:165], v153 offset:2048
	ds_read_b128 v[166:169], v153 offset:3072
	s_add_u32 s28, s28, 0x40000
	s_addc_u32 s29, s29, 0
	s_mov_b32 m0, s54
	v_lshl_add_u64 v[202:203], s[28:29], 0, v[136:137]
	ds_read_b128 v[170:173], v151 offset:32768
	ds_read_b128 v[174:177], v151 offset:33792
	ds_read_b128 v[178:181], v151 offset:34816
	ds_read_b128 v[182:185], v151 offset:35840
	ds_read_b128 v[186:189], v151 offset:36864
	ds_read_b128 v[190:193], v151 offset:37888
	ds_read_b128 v[194:197], v151 offset:38912
	ds_read_b128 v[198:201], v151 offset:39936
	global_load_lds_dwordx4 v[202:203], off
	v_lshl_add_u64 v[202:203], s[28:29], 0, v[132:133]
	s_mov_b32 m0, s55
	s_nop 0
	global_load_lds_dwordx4 v[202:203], off
	s_waitcnt lgkmcnt(8)
	s_barrier
	s_waitcnt lgkmcnt(0)
	s_waitcnt lgkmcnt(0)
	v_mfma_f32_16x16x32_bf16 v[124:127], v[154:157], v[170:173], v[124:127]
	v_mfma_f32_16x16x32_bf16 v[120:123], v[162:165], v[170:173], v[120:123]
	v_mfma_f32_16x16x32_bf16 v[116:119], v[154:157], v[178:181], v[116:119]
	v_mfma_f32_16x16x32_bf16 v[112:115], v[162:165], v[178:181], v[112:115]
	v_mfma_f32_16x16x32_bf16 v[100:103], v[154:157], v[186:189], v[100:103]
	v_mfma_f32_16x16x32_bf16 v[96:99], v[162:165], v[186:189], v[96:99]
	v_mfma_f32_16x16x32_bf16 v[84:87], v[154:157], v[194:197], v[84:87]
	v_mfma_f32_16x16x32_bf16 v[80:83], v[162:165], v[194:197], v[80:83]
	v_mfma_f32_16x16x32_bf16 v[124:127], v[158:161], v[174:177], v[124:127]
	v_mfma_f32_16x16x32_bf16 v[120:123], v[166:169], v[174:177], v[120:123]
	v_mfma_f32_16x16x32_bf16 v[116:119], v[158:161], v[182:185], v[116:119]
	v_mfma_f32_16x16x32_bf16 v[112:115], v[166:169], v[182:185], v[112:115]
	v_mfma_f32_16x16x32_bf16 v[100:103], v[158:161], v[190:193], v[100:103]
	v_mfma_f32_16x16x32_bf16 v[96:99], v[166:169], v[190:193], v[96:99]
	v_mfma_f32_16x16x32_bf16 v[84:87], v[158:161], v[198:201], v[84:87]
	v_mfma_f32_16x16x32_bf16 v[80:83], v[166:169], v[198:201], v[80:83]
	s_barrier
	s_add_i32 s28, 0, 0x1c000
	s_add_i32 s29, s87, s34
	v_add_u32_e32 v153, s28, v148
	v_lshl_add_u64 v[218:219], v[218:219], 0, s[8:9]
	s_mov_b32 m0, s29
	ds_read_b128 v[202:205], v153
	ds_read_b128 v[206:209], v153 offset:1024
	ds_read_b128 v[210:213], v153 offset:2048
	ds_read_b128 v[214:217], v153 offset:3072
	global_load_lds_dwordx4 v[218:219], off
	v_lshl_add_u64 v[218:219], v[220:221], 0, s[8:9]
	s_add_i32 m0, s29, 0x2000
	s_nop 0
	global_load_lds_dwordx4 v[218:219], off
	s_barrier
	s_waitcnt lgkmcnt(0)
	s_waitcnt lgkmcnt(0)
	v_mfma_f32_16x16x32_bf16 v[108:111], v[202:205], v[170:173], v[108:111]
	v_mfma_f32_16x16x32_bf16 v[104:107], v[210:213], v[170:173], v[104:107]
	v_mfma_f32_16x16x32_bf16 v[92:95], v[202:205], v[178:181], v[92:95]
	v_mfma_f32_16x16x32_bf16 v[88:91], v[210:213], v[178:181], v[88:91]
	v_mfma_f32_16x16x32_bf16 v[76:79], v[202:205], v[186:189], v[76:79]
	v_mfma_f32_16x16x32_bf16 v[72:75], v[210:213], v[186:189], v[72:75]
	v_mfma_f32_16x16x32_bf16 v[68:71], v[202:205], v[194:197], v[68:71]
	v_mfma_f32_16x16x32_bf16 v[64:67], v[210:213], v[194:197], v[64:67]
	v_mfma_f32_16x16x32_bf16 v[108:111], v[206:209], v[174:177], v[108:111]
	v_mfma_f32_16x16x32_bf16 v[104:107], v[214:217], v[174:177], v[104:107]
	v_mfma_f32_16x16x32_bf16 v[92:95], v[206:209], v[182:185], v[92:95]
	v_mfma_f32_16x16x32_bf16 v[88:91], v[214:217], v[182:185], v[88:91]
	v_mfma_f32_16x16x32_bf16 v[76:79], v[206:209], v[190:193], v[76:79]
	v_mfma_f32_16x16x32_bf16 v[72:75], v[214:217], v[190:193], v[72:75]
	v_mfma_f32_16x16x32_bf16 v[68:71], v[206:209], v[198:201], v[68:71]
	v_mfma_f32_16x16x32_bf16 v[64:67], v[214:217], v[198:201], v[64:67]
	s_mov_b32 m0, s57
	v_lshl_add_u64 v[218:219], v[222:223], 0, s[8:9]
	s_barrier
	ds_read_b128 v[170:173], v151 offset:49152
	ds_read_b128 v[174:177], v151 offset:50176
	ds_read_b128 v[178:181], v151 offset:51200
	ds_read_b128 v[182:185], v151 offset:52224
	ds_read_b128 v[186:189], v151 offset:53248
	ds_read_b128 v[190:193], v151 offset:54272
	ds_read_b128 v[194:197], v151 offset:55296
	ds_read_b128 v[198:201], v151 offset:56320
	global_load_lds_dwordx4 v[218:219], off
	v_lshl_add_u64 v[218:219], v[224:225], 0, s[8:9]
	s_mov_b32 m0, s70
	s_nop 0
	global_load_lds_dwordx4 v[218:219], off
	s_barrier
	s_waitcnt lgkmcnt(0)
	s_waitcnt lgkmcnt(0)
	v_mfma_f32_16x16x32_bf16 v[60:63], v[154:157], v[170:173], v[60:63]
	v_mfma_f32_16x16x32_bf16 v[56:59], v[162:165], v[170:173], v[56:59]
	v_mfma_f32_16x16x32_bf16 v[52:55], v[154:157], v[178:181], v[52:55]
	v_mfma_f32_16x16x32_bf16 v[48:51], v[162:165], v[178:181], v[48:51]
	v_mfma_f32_16x16x32_bf16 v[36:39], v[154:157], v[186:189], v[36:39]
	v_mfma_f32_16x16x32_bf16 v[32:35], v[162:165], v[186:189], v[32:35]
	v_mfma_f32_16x16x32_bf16 v[20:23], v[154:157], v[194:197], v[20:23]
	v_mfma_f32_16x16x32_bf16 v[16:19], v[162:165], v[194:197], v[16:19]
	v_mfma_f32_16x16x32_bf16 v[60:63], v[158:161], v[174:177], v[60:63]
	v_mfma_f32_16x16x32_bf16 v[56:59], v[166:169], v[174:177], v[56:59]
	v_mfma_f32_16x16x32_bf16 v[52:55], v[158:161], v[182:185], v[52:55]
	v_mfma_f32_16x16x32_bf16 v[48:51], v[166:169], v[182:185], v[48:51]
	v_mfma_f32_16x16x32_bf16 v[36:39], v[158:161], v[190:193], v[36:39]
	v_mfma_f32_16x16x32_bf16 v[32:35], v[166:169], v[190:193], v[32:35]
	v_mfma_f32_16x16x32_bf16 v[20:23], v[158:161], v[198:201], v[20:23]
	v_mfma_f32_16x16x32_bf16 v[16:19], v[166:169], v[198:201], v[16:19]
	s_barrier
	s_add_u32 s26, s26, 0x40080
	s_addc_u32 s27, s27, 0
	s_add_i32 s28, s28, s34
	v_lshl_add_u64 v[154:155], s[26:27], 0, v[134:135]
	s_mov_b32 m0, s28
	s_nop 0
	global_load_lds_dwordx4 v[154:155], off
	v_lshl_add_u64 v[154:155], s[26:27], 0, v[130:131]
	s_add_i32 m0, s28, 0x2000
	s_nop 0
	global_load_lds_dwordx4 v[154:155], off
	s_waitcnt vmcnt(6)
	s_barrier
	v_mfma_f32_16x16x32_bf16 v[44:47], v[202:205], v[170:173], v[44:47]
	v_mfma_f32_16x16x32_bf16 v[40:43], v[210:213], v[170:173], v[40:43]
	v_mfma_f32_16x16x32_bf16 v[28:31], v[202:205], v[178:181], v[28:31]
	v_mfma_f32_16x16x32_bf16 v[24:27], v[210:213], v[178:181], v[24:27]
	v_mfma_f32_16x16x32_bf16 v[12:15], v[202:205], v[186:189], v[12:15]
	v_mfma_f32_16x16x32_bf16 v[8:11], v[210:213], v[186:189], v[8:11]
	v_mfma_f32_16x16x32_bf16 v[4:7], v[202:205], v[194:197], v[4:7]
	v_mfma_f32_16x16x32_bf16 v[0:3], v[210:213], v[194:197], v[0:3]
	v_mfma_f32_16x16x32_bf16 v[44:47], v[206:209], v[174:177], v[44:47]
	v_mfma_f32_16x16x32_bf16 v[40:43], v[214:217], v[174:177], v[40:43]
	v_mfma_f32_16x16x32_bf16 v[28:31], v[206:209], v[182:185], v[28:31]
	v_mfma_f32_16x16x32_bf16 v[24:27], v[214:217], v[182:185], v[24:27]
	v_mfma_f32_16x16x32_bf16 v[12:15], v[206:209], v[190:193], v[12:15]
	v_mfma_f32_16x16x32_bf16 v[8:11], v[214:217], v[190:193], v[8:11]
	v_mfma_f32_16x16x32_bf16 v[4:7], v[206:209], v[198:201], v[4:7]
	v_mfma_f32_16x16x32_bf16 v[0:3], v[214:217], v[198:201], v[0:3]
	s_add_i32 s86, s86, 2
	s_add_u32 s20, s20, 0x100
	s_addc_u32 s21, s21, 0
	s_add_u32 s84, s84, 0x100
	s_addc_u32 s85, s85, 0
	s_cmp_gt_u32 s86, 13
	s_barrier
	s_cbranch_scc0 .LBB0_155
	v_lshl_add_u32 v153, s10, 8, v147
	v_lshl_or_b32 v154, s75, 8, v149
	v_mov_b64_e32 v[156:157], s[46:47]
	v_ashrrev_i32_e32 v155, 31, v154
	v_cvt_pk_bf16_f32 v68, v68, v69
	v_cvt_pk_bf16_f32 v69, v70, v71
	v_cvt_pk_bf16_f32 v70, v64, v65
	v_add_u32_e32 v64, 0x80, v153
	v_mad_i64_i32 v[158:159], s[20:21], v153, s74, v[156:157]
	v_cvt_pk_bf16_f32 v124, v124, v125
	v_cvt_pk_bf16_f32 v125, v126, v127
	v_cvt_pk_bf16_f32 v126, v120, v121
	v_lshlrev_b64 v[120:121], 1, v[154:155]
	v_mad_i64_i32 v[64:65], s[20:21], v64, s74, v[156:157]
	v_cvt_pk_bf16_f32 v127, v122, v123
	v_lshl_add_u64 v[122:123], v[158:159], 0, v[120:121]
	v_cvt_pk_bf16_f32 v108, v108, v109
	v_cvt_pk_bf16_f32 v109, v110, v111
	v_cvt_pk_bf16_f32 v110, v104, v105
	v_cvt_pk_bf16_f32 v111, v106, v107
	v_or_b32_e32 v104, 16, v153
	v_cvt_pk_bf16_f32 v60, v60, v61
	v_cvt_pk_bf16_f32 v61, v62, v63
	v_cvt_pk_bf16_f32 v62, v56, v57
	v_lshl_add_u64 v[56:57], v[64:65], 0, v[120:121]
	v_cvt_pk_bf16_f32 v44, v44, v45
	v_cvt_pk_bf16_f32 v45, v46, v47
	v_cvt_pk_bf16_f32 v46, v40, v41
	v_cvt_pk_bf16_f32 v47, v42, v43
	v_add_u32_e32 v40, 0x90, v153
	global_store_dwordx4 v[122:123], v[108:111], off offset:256
	global_store_dwordx4 v[56:57], v[44:47], off offset:256
	v_cvt_pk_bf16_f32 v92, v92, v93
	v_mad_i64_i32 v[108:109], s[20:21], v104, s74, v[156:157]
	v_mad_i64_i32 v[44:45], s[20:21], v40, s74, v[156:157]
	v_lshl_add_u64 v[108:109], v[108:109], 0, v[120:121]
	v_cvt_pk_bf16_f32 v93, v94, v95
	v_cvt_pk_bf16_f32 v94, v88, v89
	v_cvt_pk_bf16_f32 v95, v90, v91
	v_or_b32_e32 v88, 32, v153
	v_lshl_add_u64 v[44:45], v[44:45], 0, v[120:121]
	v_cvt_pk_bf16_f32 v28, v28, v29
	v_cvt_pk_bf16_f32 v29, v30, v31
	v_cvt_pk_bf16_f32 v30, v24, v25
	v_cvt_pk_bf16_f32 v31, v26, v27
	v_add_u32_e32 v24, 0xa0, v153
	global_store_dwordx4 v[108:109], v[92:95], off offset:256
	global_store_dwordx4 v[44:45], v[28:31], off offset:256
	v_cvt_pk_bf16_f32 v76, v76, v77
	v_mad_i64_i32 v[92:93], s[20:21], v88, s74, v[156:157]
	v_mad_i64_i32 v[28:29], s[20:21], v24, s74, v[156:157]
	v_lshl_add_u64 v[92:93], v[92:93], 0, v[120:121]
	v_cvt_pk_bf16_f32 v77, v78, v79
	v_cvt_pk_bf16_f32 v78, v72, v73
	v_cvt_pk_bf16_f32 v79, v74, v75
	v_or_b32_e32 v72, 48, v153
	v_lshl_add_u64 v[28:29], v[28:29], 0, v[120:121]
	v_cvt_pk_bf16_f32 v12, v12, v13
	v_cvt_pk_bf16_f32 v13, v14, v15
	v_cvt_pk_bf16_f32 v14, v8, v9
	v_cvt_pk_bf16_f32 v15, v10, v11
	v_add_u32_e32 v8, 0xb0, v153
	global_store_dwordx4 v[92:93], v[76:79], off offset:256
	global_store_dwordx4 v[28:29], v[12:15], off offset:256
	v_cvt_pk_bf16_f32 v104, v116, v117
	v_mad_i64_i32 v[76:77], s[20:21], v72, s74, v[156:157]
	v_mad_i64_i32 v[12:13], s[20:21], v8, s74, v[156:157]
	v_cvt_pk_bf16_f32 v105, v118, v119
	v_cvt_pk_bf16_f32 v106, v112, v113
	v_cvt_pk_bf16_f32 v107, v114, v115
	v_cvt_pk_bf16_f32 v88, v100, v101
	v_cvt_pk_bf16_f32 v89, v102, v103
	v_cvt_pk_bf16_f32 v90, v96, v97
	v_cvt_pk_bf16_f32 v91, v98, v99
	v_cvt_pk_bf16_f32 v72, v84, v85
	v_cvt_pk_bf16_f32 v73, v86, v87
	v_cvt_pk_bf16_f32 v74, v80, v81
	v_cvt_pk_bf16_f32 v75, v82, v83
	v_lshl_add_u64 v[76:77], v[76:77], 0, v[120:121]
	v_cvt_pk_bf16_f32 v71, v66, v67
	v_cvt_pk_bf16_f32 v63, v58, v59
	v_cvt_pk_bf16_f32 v40, v52, v53
	v_cvt_pk_bf16_f32 v41, v54, v55
	v_cvt_pk_bf16_f32 v42, v48, v49
	v_cvt_pk_bf16_f32 v43, v50, v51
	v_cvt_pk_bf16_f32 v24, v36, v37
	v_cvt_pk_bf16_f32 v25, v38, v39
	v_cvt_pk_bf16_f32 v26, v32, v33
	v_cvt_pk_bf16_f32 v27, v34, v35
	v_cvt_pk_bf16_f32 v8, v20, v21
	v_cvt_pk_bf16_f32 v9, v22, v23
	v_cvt_pk_bf16_f32 v10, v16, v17
	v_cvt_pk_bf16_f32 v11, v18, v19
	v_lshl_add_u64 v[12:13], v[12:13], 0, v[120:121]
	v_cvt_pk_bf16_f32 v4, v4, v5
	v_cvt_pk_bf16_f32 v5, v6, v7
	v_cvt_pk_bf16_f32 v6, v0, v1
	v_cvt_pk_bf16_f32 v7, v2, v3
	s_and_b64 vcc, exec, s[4:5]
	s_mov_b32 s75, s12
	s_mov_b32 s10, s14
	s_mov_b64 s[26:27], s[18:19]
	s_mov_b64 s[20:21], s[16:17]
	global_store_dwordx4 v[122:123], v[124:127], off
	global_store_dwordx4 v[108:109], v[104:107], off
	global_store_dwordx4 v[92:93], v[88:91], off
	global_store_dwordx4 v[76:77], v[72:75], off
	global_store_dwordx4 v[76:77], v[68:71], off offset:256
	global_store_dwordx4 v[56:57], v[60:63], off
	global_store_dwordx4 v[44:45], v[40:43], off
	global_store_dwordx4 v[28:29], v[24:27], off
	global_store_dwordx4 v[12:13], v[8:11], off
	global_store_dwordx4 v[12:13], v[4:7], off offset:256
	s_cbranch_vccz .LBB0_152
	s_waitcnt vmcnt(16)
	s_cmpk_gt_u32 s30, 0xff
	s_cbranch_scc1 .LBB0_159
	s_barrier

.LBB0_486:
	ds_read_b128 v[154:157], v151
	ds_read_b128 v[158:161], v151 offset:1024
	ds_read_b128 v[162:165], v151 offset:2048
	ds_read_b128 v[166:169], v151 offset:3072
	s_add_u32 s30, s28, 0xfffc0080
	s_addc_u32 s31, s29, -1
	s_cmp_eq_u32 s84, 12
	s_cselect_b32 s35, s19, s31
	s_cselect_b32 s34, s80, s30
	s_cselect_b32 s31, s17, s83
	s_cselect_b32 s30, s81, s82
	v_lshl_add_u64 v[202:203], s[28:29], 0, v[138:139]
	s_add_i32 m0, s15, 0xc000
	ds_read_b128 v[170:173], v152
	ds_read_b128 v[174:177], v152 offset:1024
	ds_read_b128 v[178:181], v152 offset:2048
	ds_read_b128 v[182:185], v152 offset:3072
	ds_read_b128 v[186:189], v152 offset:4096
	ds_read_b128 v[190:193], v152 offset:5120
	ds_read_b128 v[194:197], v152 offset:6144
	ds_read_b128 v[198:201], v152 offset:7168
	global_load_lds_dwordx4 v[202:203], off
	v_lshl_add_u64 v[202:203], s[28:29], 0, v[140:141]
	s_add_i32 m0, s15, 0xe000
	s_nop 0
	global_load_lds_dwordx4 v[202:203], off
	s_waitcnt lgkmcnt(8)
	s_barrier
	s_waitcnt lgkmcnt(0)
	s_waitcnt lgkmcnt(0)
	v_mfma_f32_16x16x32_bf16 v[124:127], v[154:157], v[170:173], v[124:127]
	v_mfma_f32_16x16x32_bf16 v[120:123], v[162:165], v[170:173], v[120:123]
	v_mfma_f32_16x16x32_bf16 v[116:119], v[154:157], v[178:181], v[116:119]
	v_mfma_f32_16x16x32_bf16 v[112:115], v[162:165], v[178:181], v[112:115]
	v_mfma_f32_16x16x32_bf16 v[100:103], v[154:157], v[186:189], v[100:103]
	v_mfma_f32_16x16x32_bf16 v[96:99], v[162:165], v[186:189], v[96:99]
	v_mfma_f32_16x16x32_bf16 v[84:87], v[154:157], v[194:197], v[84:87]
	v_mfma_f32_16x16x32_bf16 v[80:83], v[162:165], v[194:197], v[80:83]
	v_mfma_f32_16x16x32_bf16 v[124:127], v[158:161], v[174:177], v[124:127]
	v_mfma_f32_16x16x32_bf16 v[120:123], v[166:169], v[174:177], v[120:123]
	v_mfma_f32_16x16x32_bf16 v[116:119], v[158:161], v[182:185], v[116:119]
	v_mfma_f32_16x16x32_bf16 v[112:115], v[166:169], v[182:185], v[112:115]
	v_mfma_f32_16x16x32_bf16 v[100:103], v[158:161], v[190:193], v[100:103]
	v_mfma_f32_16x16x32_bf16 v[96:99], v[166:169], v[190:193], v[96:99]
	v_mfma_f32_16x16x32_bf16 v[84:87], v[158:161], v[198:201], v[84:87]
	v_mfma_f32_16x16x32_bf16 v[80:83], v[166:169], v[198:201], v[80:83]
	s_barrier
	s_add_i32 s85, s74, s55
	v_lshl_add_u64 v[218:219], s[30:31], 0, v[134:135]
	s_mov_b32 m0, s85
	ds_read_b128 v[202:205], v153
	ds_read_b128 v[206:209], v153 offset:1024
	ds_read_b128 v[210:213], v153 offset:2048
	ds_read_b128 v[214:217], v153 offset:3072
	global_load_lds_dwordx4 v[218:219], off
	v_lshl_add_u64 v[220:221], s[30:31], 0, v[130:131]
	s_add_i32 m0, s85, 0x2000
	s_nop 0
	global_load_lds_dwordx4 v[220:221], off
	s_barrier
	s_waitcnt lgkmcnt(0)
	s_waitcnt lgkmcnt(0)
	v_mfma_f32_16x16x32_bf16 v[108:111], v[202:205], v[170:173], v[108:111]
	v_mfma_f32_16x16x32_bf16 v[104:107], v[210:213], v[170:173], v[104:107]
	v_mfma_f32_16x16x32_bf16 v[92:95], v[202:205], v[178:181], v[92:95]
	v_mfma_f32_16x16x32_bf16 v[88:91], v[210:213], v[178:181], v[88:91]
	v_mfma_f32_16x16x32_bf16 v[76:79], v[202:205], v[186:189], v[76:79]
	v_mfma_f32_16x16x32_bf16 v[72:75], v[210:213], v[186:189], v[72:75]
	v_mfma_f32_16x16x32_bf16 v[68:71], v[202:205], v[194:197], v[68:71]
	v_mfma_f32_16x16x32_bf16 v[64:67], v[210:213], v[194:197], v[64:67]
	v_mfma_f32_16x16x32_bf16 v[108:111], v[206:209], v[174:177], v[108:111]
	v_mfma_f32_16x16x32_bf16 v[104:107], v[214:217], v[174:177], v[104:107]
	v_mfma_f32_16x16x32_bf16 v[92:95], v[206:209], v[182:185], v[92:95]
	v_mfma_f32_16x16x32_bf16 v[88:91], v[214:217], v[182:185], v[88:91]
	v_mfma_f32_16x16x32_bf16 v[76:79], v[206:209], v[190:193], v[76:79]
	v_mfma_f32_16x16x32_bf16 v[72:75], v[214:217], v[190:193], v[72:75]
	v_mfma_f32_16x16x32_bf16 v[68:71], v[206:209], v[198:201], v[68:71]
	v_mfma_f32_16x16x32_bf16 v[64:67], v[214:217], v[198:201], v[64:67]
	s_mov_b32 m0, s15
	v_lshl_add_u64 v[222:223], s[34:35], 0, v[136:137]
	s_barrier
	ds_read_b128 v[170:173], v152 offset:16384
	ds_read_b128 v[174:177], v152 offset:17408
	ds_read_b128 v[178:181], v152 offset:18432
	ds_read_b128 v[182:185], v152 offset:19456
	ds_read_b128 v[186:189], v152 offset:20480
	ds_read_b128 v[190:193], v152 offset:21504
	ds_read_b128 v[194:197], v152 offset:22528
	ds_read_b128 v[198:201], v152 offset:23552
	global_load_lds_dwordx4 v[222:223], off
	v_lshl_add_u64 v[224:225], s[34:35], 0, v[132:133]
	s_mov_b32 m0, s57
	s_nop 0
	global_load_lds_dwordx4 v[224:225], off
	s_barrier
	s_waitcnt lgkmcnt(0)
	s_waitcnt lgkmcnt(0)
	v_mfma_f32_16x16x32_bf16 v[60:63], v[154:157], v[170:173], v[60:63]
	v_mfma_f32_16x16x32_bf16 v[56:59], v[162:165], v[170:173], v[56:59]
	v_mfma_f32_16x16x32_bf16 v[52:55], v[154:157], v[178:181], v[52:55]
	v_mfma_f32_16x16x32_bf16 v[48:51], v[162:165], v[178:181], v[48:51]
	v_mfma_f32_16x16x32_bf16 v[36:39], v[154:157], v[186:189], v[36:39]
	v_mfma_f32_16x16x32_bf16 v[32:35], v[162:165], v[186:189], v[32:35]
	v_mfma_f32_16x16x32_bf16 v[20:23], v[154:157], v[194:197], v[20:23]
	v_mfma_f32_16x16x32_bf16 v[16:19], v[162:165], v[194:197], v[16:19]
	v_mfma_f32_16x16x32_bf16 v[60:63], v[158:161], v[174:177], v[60:63]
	v_mfma_f32_16x16x32_bf16 v[56:59], v[166:169], v[174:177], v[56:59]
	v_mfma_f32_16x16x32_bf16 v[52:55], v[158:161], v[182:185], v[52:55]
	v_mfma_f32_16x16x32_bf16 v[48:51], v[166:169], v[182:185], v[48:51]
	v_mfma_f32_16x16x32_bf16 v[36:39], v[158:161], v[190:193], v[36:39]
	v_mfma_f32_16x16x32_bf16 v[32:35], v[166:169], v[190:193], v[32:35]
	v_mfma_f32_16x16x32_bf16 v[20:23], v[158:161], v[198:201], v[20:23]
	v_mfma_f32_16x16x32_bf16 v[16:19], v[166:169], v[198:201], v[16:19]
	s_barrier
	s_add_u32 s86, s30, 0x40000
	s_addc_u32 s87, s31, 0
	s_add_i32 s85, s75, s55
	v_lshl_add_u64 v[154:155], s[86:87], 0, v[134:135]
	s_mov_b32 m0, s85
	s_nop 0
	global_load_lds_dwordx4 v[154:155], off
	v_lshl_add_u64 v[154:155], s[86:87], 0, v[130:131]
	s_add_i32 m0, s85, 0x2000
	s_nop 0
	global_load_lds_dwordx4 v[154:155], off
	s_waitcnt vmcnt(6)
	s_barrier
	v_mfma_f32_16x16x32_bf16 v[44:47], v[202:205], v[170:173], v[44:47]
	v_mfma_f32_16x16x32_bf16 v[40:43], v[210:213], v[170:173], v[40:43]
	v_mfma_f32_16x16x32_bf16 v[28:31], v[202:205], v[178:181], v[28:31]
	v_mfma_f32_16x16x32_bf16 v[24:27], v[210:213], v[178:181], v[24:27]
	v_mfma_f32_16x16x32_bf16 v[12:15], v[202:205], v[186:189], v[12:15]
	v_mfma_f32_16x16x32_bf16 v[8:11], v[210:213], v[186:189], v[8:11]
	v_mfma_f32_16x16x32_bf16 v[4:7], v[202:205], v[194:197], v[4:7]
	v_mfma_f32_16x16x32_bf16 v[0:3], v[210:213], v[194:197], v[0:3]
	v_mfma_f32_16x16x32_bf16 v[44:47], v[206:209], v[174:177], v[44:47]
	v_mfma_f32_16x16x32_bf16 v[40:43], v[214:217], v[174:177], v[40:43]
	v_mfma_f32_16x16x32_bf16 v[28:31], v[206:209], v[182:185], v[28:31]
	v_mfma_f32_16x16x32_bf16 v[24:27], v[214:217], v[182:185], v[24:27]
	v_mfma_f32_16x16x32_bf16 v[12:15], v[206:209], v[190:193], v[12:15]
	v_mfma_f32_16x16x32_bf16 v[8:11], v[214:217], v[190:193], v[8:11]
	v_mfma_f32_16x16x32_bf16 v[4:7], v[206:209], v[198:201], v[4:7]
	v_mfma_f32_16x16x32_bf16 v[0:3], v[214:217], v[198:201], v[0:3]
	s_add_i32 s85, 0, 0x18000
	v_add_u32_e32 v166, s85, v149
	s_barrier
	ds_read_b128 v[154:157], v166
	ds_read_b128 v[158:161], v166 offset:1024
	ds_read_b128 v[162:165], v166 offset:2048
	ds_read_b128 v[166:169], v166 offset:3072
	s_add_u32 s34, s34, 0x40000
	s_addc_u32 s35, s35, 0
	s_mov_b32 m0, s60
	v_lshl_add_u64 v[202:203], s[34:35], 0, v[136:137]
	ds_read_b128 v[170:173], v152 offset:32768
	ds_read_b128 v[174:177], v152 offset:33792
	ds_read_b128 v[178:181], v152 offset:34816
	ds_read_b128 v[182:185], v152 offset:35840
	ds_read_b128 v[186:189], v152 offset:36864
	ds_read_b128 v[190:193], v152 offset:37888
	ds_read_b128 v[194:197], v152 offset:38912
	ds_read_b128 v[198:201], v152 offset:39936
	global_load_lds_dwordx4 v[202:203], off
	v_lshl_add_u64 v[202:203], s[34:35], 0, v[132:133]
	s_mov_b32 m0, s61
	s_nop 0
	global_load_lds_dwordx4 v[202:203], off
	s_waitcnt lgkmcnt(8)
	s_barrier
	s_waitcnt lgkmcnt(0)
	s_waitcnt lgkmcnt(0)
	v_mfma_f32_16x16x32_bf16 v[124:127], v[154:157], v[170:173], v[124:127]
	v_mfma_f32_16x16x32_bf16 v[120:123], v[162:165], v[170:173], v[120:123]
	v_mfma_f32_16x16x32_bf16 v[116:119], v[154:157], v[178:181], v[116:119]
	v_mfma_f32_16x16x32_bf16 v[112:115], v[162:165], v[178:181], v[112:115]
	v_mfma_f32_16x16x32_bf16 v[100:103], v[154:157], v[186:189], v[100:103]
	v_mfma_f32_16x16x32_bf16 v[96:99], v[162:165], v[186:189], v[96:99]
	v_mfma_f32_16x16x32_bf16 v[84:87], v[154:157], v[194:197], v[84:87]
	v_mfma_f32_16x16x32_bf16 v[80:83], v[162:165], v[194:197], v[80:83]
	v_mfma_f32_16x16x32_bf16 v[124:127], v[158:161], v[174:177], v[124:127]
	v_mfma_f32_16x16x32_bf16 v[120:123], v[166:169], v[174:177], v[120:123]
	v_mfma_f32_16x16x32_bf16 v[116:119], v[158:161], v[182:185], v[116:119]
	v_mfma_f32_16x16x32_bf16 v[112:115], v[166:169], v[182:185], v[112:115]
	v_mfma_f32_16x16x32_bf16 v[100:103], v[158:161], v[190:193], v[100:103]
	v_mfma_f32_16x16x32_bf16 v[96:99], v[166:169], v[190:193], v[96:99]
	v_mfma_f32_16x16x32_bf16 v[84:87], v[158:161], v[198:201], v[84:87]
	v_mfma_f32_16x16x32_bf16 v[80:83], v[166:169], v[198:201], v[80:83]
	s_barrier
	s_add_i32 s34, 0, 0x1c000
	s_add_i32 s35, s85, s55
	v_add_u32_e32 v214, s34, v149
	v_lshl_add_u64 v[218:219], v[218:219], 0, s[8:9]
	s_mov_b32 m0, s35
	ds_read_b128 v[202:205], v214
	ds_read_b128 v[206:209], v214 offset:1024
	ds_read_b128 v[210:213], v214 offset:2048
	ds_read_b128 v[214:217], v214 offset:3072
	global_load_lds_dwordx4 v[218:219], off
	v_lshl_add_u64 v[218:219], v[220:221], 0, s[8:9]
	s_add_i32 m0, s35, 0x2000
	s_nop 0
	global_load_lds_dwordx4 v[218:219], off
	s_barrier
	s_waitcnt lgkmcnt(0)
	s_waitcnt lgkmcnt(0)
	v_mfma_f32_16x16x32_bf16 v[108:111], v[202:205], v[170:173], v[108:111]
	v_mfma_f32_16x16x32_bf16 v[104:107], v[210:213], v[170:173], v[104:107]
	v_mfma_f32_16x16x32_bf16 v[92:95], v[202:205], v[178:181], v[92:95]
	v_mfma_f32_16x16x32_bf16 v[88:91], v[210:213], v[178:181], v[88:91]
	v_mfma_f32_16x16x32_bf16 v[76:79], v[202:205], v[186:189], v[76:79]
	v_mfma_f32_16x16x32_bf16 v[72:75], v[210:213], v[186:189], v[72:75]
	v_mfma_f32_16x16x32_bf16 v[68:71], v[202:205], v[194:197], v[68:71]
	v_mfma_f32_16x16x32_bf16 v[64:67], v[210:213], v[194:197], v[64:67]
	v_mfma_f32_16x16x32_bf16 v[108:111], v[206:209], v[174:177], v[108:111]
	v_mfma_f32_16x16x32_bf16 v[104:107], v[214:217], v[174:177], v[104:107]
	v_mfma_f32_16x16x32_bf16 v[92:95], v[206:209], v[182:185], v[92:95]
	v_mfma_f32_16x16x32_bf16 v[88:91], v[214:217], v[182:185], v[88:91]
	v_mfma_f32_16x16x32_bf16 v[76:79], v[206:209], v[190:193], v[76:79]
	v_mfma_f32_16x16x32_bf16 v[72:75], v[214:217], v[190:193], v[72:75]
	v_mfma_f32_16x16x32_bf16 v[68:71], v[206:209], v[198:201], v[68:71]
	v_mfma_f32_16x16x32_bf16 v[64:67], v[214:217], v[198:201], v[64:67]
	s_mov_b32 m0, s71
	v_lshl_add_u64 v[218:219], v[222:223], 0, s[8:9]
	s_barrier
	ds_read_b128 v[170:173], v152 offset:49152
	ds_read_b128 v[174:177], v152 offset:50176
	ds_read_b128 v[178:181], v152 offset:51200
	ds_read_b128 v[182:185], v152 offset:52224
	ds_read_b128 v[186:189], v152 offset:53248
	ds_read_b128 v[190:193], v152 offset:54272
	ds_read_b128 v[194:197], v152 offset:55296
	ds_read_b128 v[198:201], v152 offset:56320
	global_load_lds_dwordx4 v[218:219], off
	v_lshl_add_u64 v[218:219], v[224:225], 0, s[8:9]
	s_mov_b32 m0, s72
	s_nop 0
	global_load_lds_dwordx4 v[218:219], off
	s_barrier
	s_waitcnt lgkmcnt(0)
	s_waitcnt lgkmcnt(0)
	v_mfma_f32_16x16x32_bf16 v[60:63], v[154:157], v[170:173], v[60:63]
	v_mfma_f32_16x16x32_bf16 v[56:59], v[162:165], v[170:173], v[56:59]
	v_mfma_f32_16x16x32_bf16 v[52:55], v[154:157], v[178:181], v[52:55]
	v_mfma_f32_16x16x32_bf16 v[48:51], v[162:165], v[178:181], v[48:51]
	v_mfma_f32_16x16x32_bf16 v[36:39], v[154:157], v[186:189], v[36:39]
	v_mfma_f32_16x16x32_bf16 v[32:35], v[162:165], v[186:189], v[32:35]
	v_mfma_f32_16x16x32_bf16 v[20:23], v[154:157], v[194:197], v[20:23]
	v_mfma_f32_16x16x32_bf16 v[16:19], v[162:165], v[194:197], v[16:19]
	v_mfma_f32_16x16x32_bf16 v[60:63], v[158:161], v[174:177], v[60:63]
	v_mfma_f32_16x16x32_bf16 v[56:59], v[166:169], v[174:177], v[56:59]
	v_mfma_f32_16x16x32_bf16 v[52:55], v[158:161], v[182:185], v[52:55]
	v_mfma_f32_16x16x32_bf16 v[48:51], v[166:169], v[182:185], v[48:51]
	v_mfma_f32_16x16x32_bf16 v[36:39], v[158:161], v[190:193], v[36:39]
	v_mfma_f32_16x16x32_bf16 v[32:35], v[166:169], v[190:193], v[32:35]
	v_mfma_f32_16x16x32_bf16 v[20:23], v[158:161], v[198:201], v[20:23]
	v_mfma_f32_16x16x32_bf16 v[16:19], v[166:169], v[198:201], v[16:19]
	s_barrier
	s_add_u32 s30, s30, 0x40080
	s_addc_u32 s31, s31, 0
	s_add_i32 s34, s34, s55
	v_lshl_add_u64 v[154:155], s[30:31], 0, v[134:135]
	s_mov_b32 m0, s34
	s_nop 0
	global_load_lds_dwordx4 v[154:155], off
	v_lshl_add_u64 v[154:155], s[30:31], 0, v[130:131]
	s_add_i32 m0, s34, 0x2000
	s_nop 0
	global_load_lds_dwordx4 v[154:155], off
	s_waitcnt vmcnt(6)
	s_barrier
	v_mfma_f32_16x16x32_bf16 v[44:47], v[202:205], v[170:173], v[44:47]
	v_mfma_f32_16x16x32_bf16 v[40:43], v[210:213], v[170:173], v[40:43]
	v_mfma_f32_16x16x32_bf16 v[28:31], v[202:205], v[178:181], v[28:31]
	v_mfma_f32_16x16x32_bf16 v[24:27], v[210:213], v[178:181], v[24:27]
	v_mfma_f32_16x16x32_bf16 v[12:15], v[202:205], v[186:189], v[12:15]
	v_mfma_f32_16x16x32_bf16 v[8:11], v[210:213], v[186:189], v[8:11]
	v_mfma_f32_16x16x32_bf16 v[4:7], v[202:205], v[194:197], v[4:7]
	v_mfma_f32_16x16x32_bf16 v[0:3], v[210:213], v[194:197], v[0:3]
	v_mfma_f32_16x16x32_bf16 v[44:47], v[206:209], v[174:177], v[44:47]
	v_mfma_f32_16x16x32_bf16 v[40:43], v[214:217], v[174:177], v[40:43]
	v_mfma_f32_16x16x32_bf16 v[28:31], v[206:209], v[182:185], v[28:31]
	v_mfma_f32_16x16x32_bf16 v[24:27], v[214:217], v[182:185], v[24:27]
	v_mfma_f32_16x16x32_bf16 v[12:15], v[206:209], v[190:193], v[12:15]
	v_mfma_f32_16x16x32_bf16 v[8:11], v[214:217], v[190:193], v[8:11]
	v_mfma_f32_16x16x32_bf16 v[4:7], v[206:209], v[198:201], v[4:7]
	v_mfma_f32_16x16x32_bf16 v[0:3], v[214:217], v[198:201], v[0:3]
	s_add_i32 s84, s84, 2
	s_add_u32 s28, s28, 0x100
	s_addc_u32 s29, s29, 0
	s_add_u32 s82, s82, 0x100
	s_addc_u32 s83, s83, 0
	s_cmp_gt_u32 s84, 13
	s_barrier
	s_cbranch_scc0 .LBB0_486
	v_lshl_add_u32 v154, s14, 8, v148
	v_lshl_or_b32 v156, s79, 8, v150
	v_ashrrev_i32_e32 v155, 31, v154
	v_lshlrev_b64 v[158:159], 11, v[154:155]
	v_ashrrev_i32_e32 v157, 31, v156
	v_lshl_add_u64 v[158:159], s[46:47], 0, v[158:159]
	v_cvt_pk_bf16_f32 v124, v124, v125
	v_cvt_pk_bf16_f32 v125, v126, v127
	v_cvt_pk_bf16_f32 v126, v120, v121
	v_lshlrev_b64 v[120:121], 1, v[156:157]
	v_cvt_pk_bf16_f32 v127, v122, v123
	v_lshl_add_u64 v[122:123], v[158:159], 0, v[120:121]
	s_mov_b32 s14, 0x40000
	v_cvt_pk_bf16_f32 v108, v108, v109
	v_cvt_pk_bf16_f32 v109, v110, v111
	v_cvt_pk_bf16_f32 v110, v104, v105
	v_or_b32_e32 v104, 16, v154
	v_cvt_pk_bf16_f32 v60, v60, v61
	v_cvt_pk_bf16_f32 v61, v62, v63
	v_cvt_pk_bf16_f32 v63, v58, v59
	s_mov_b64 s[28:29], 0x40000
	v_add_co_u32_e32 v58, vcc, s14, v122
	v_ashrrev_i32_e32 v105, 31, v104
	v_cvt_pk_bf16_f32 v62, v56, v57
	v_lshl_add_u64 v[56:57], v[122:123], 0, s[28:29]
	v_addc_co_u32_e32 v59, vcc, 0, v123, vcc
	v_cvt_pk_bf16_f32 v44, v44, v45
	v_cvt_pk_bf16_f32 v45, v46, v47
	v_cvt_pk_bf16_f32 v46, v40, v41
	v_cvt_pk_bf16_f32 v47, v42, v43
	v_cvt_pk_bf16_f32 v111, v106, v107
	v_lshlrev_b64 v[104:105], 11, v[104:105]
	v_cvt_pk_bf16_f32 v92, v92, v93
	v_cvt_pk_bf16_f32 v93, v94, v95
	v_cvt_pk_bf16_f32 v94, v88, v89
	v_or_b32_e32 v88, 32, v154
	global_store_dwordx4 v[56:57], v[44:47], off offset:256
	s_mov_b64 s[28:29], 0x48000
	global_store_dwordx4 v[122:123], v[108:111], off offset:256
	v_add_co_u32_e32 v46, vcc, s76, v122
	s_nop 0
	v_lshl_add_u64 v[108:109], s[46:47], 0, v[104:105]
	v_ashrrev_i32_e32 v89, 31, v88
	v_lshl_add_u64 v[44:45], v[122:123], 0, s[28:29]
	v_addc_co_u32_e32 v47, vcc, 0, v123, vcc
	v_cvt_pk_bf16_f32 v28, v28, v29
	v_cvt_pk_bf16_f32 v29, v30, v31
	v_cvt_pk_bf16_f32 v30, v24, v25
	v_cvt_pk_bf16_f32 v31, v26, v27
	v_lshl_add_u64 v[108:109], v[108:109], 0, v[120:121]
	v_cvt_pk_bf16_f32 v95, v90, v91
	v_lshlrev_b64 v[88:89], 11, v[88:89]
	v_cvt_pk_bf16_f32 v76, v76, v77
	v_cvt_pk_bf16_f32 v77, v78, v79
	v_cvt_pk_bf16_f32 v78, v72, v73
	v_or_b32_e32 v72, 48, v154
	global_store_dwordx4 v[44:45], v[28:31], off offset:256
	global_store_dwordx4 v[108:109], v[92:95], off offset:256
	v_ashrrev_i32_e32 v73, 31, v72
	v_add_co_u32_e32 v30, vcc, s77, v122
	v_lshl_add_u64 v[92:93], s[46:47], 0, v[88:89]
	v_lshl_add_u64 v[28:29], v[122:123], 0, s[10:11]
	v_addc_co_u32_e32 v31, vcc, 0, v123, vcc
	v_cvt_pk_bf16_f32 v12, v12, v13
	v_cvt_pk_bf16_f32 v13, v14, v15
	v_cvt_pk_bf16_f32 v14, v8, v9
	v_cvt_pk_bf16_f32 v15, v10, v11
	v_lshl_add_u64 v[92:93], v[92:93], 0, v[120:121]
	v_cvt_pk_bf16_f32 v79, v74, v75
	v_lshlrev_b64 v[72:73], 11, v[72:73]
	global_store_dwordx4 v[28:29], v[12:15], off offset:256
	global_store_dwordx4 v[92:93], v[76:79], off offset:256
	v_cvt_pk_bf16_f32 v104, v116, v117
	v_add_co_u32_e32 v14, vcc, s78, v122
	v_lshl_add_u64 v[76:77], s[46:47], 0, v[72:73]
	s_nop 0
	v_addc_co_u32_e32 v15, vcc, 0, v123, vcc
	v_cvt_pk_bf16_f32 v105, v118, v119
	v_cvt_pk_bf16_f32 v106, v112, v113
	v_cvt_pk_bf16_f32 v107, v114, v115
	v_cvt_pk_bf16_f32 v88, v100, v101
	v_cvt_pk_bf16_f32 v89, v102, v103
	v_cvt_pk_bf16_f32 v90, v96, v97
	v_cvt_pk_bf16_f32 v91, v98, v99
	v_cvt_pk_bf16_f32 v72, v84, v85
	v_cvt_pk_bf16_f32 v73, v86, v87
	v_cvt_pk_bf16_f32 v74, v80, v81
	v_cvt_pk_bf16_f32 v75, v82, v83
	v_lshl_add_u64 v[76:77], v[76:77], 0, v[120:121]
	v_cvt_pk_bf16_f32 v68, v68, v69
	v_cvt_pk_bf16_f32 v69, v70, v71
	v_cvt_pk_bf16_f32 v70, v64, v65
	v_cvt_pk_bf16_f32 v71, v66, v67
	v_cvt_pk_bf16_f32 v40, v52, v53
	v_cvt_pk_bf16_f32 v41, v54, v55
	v_cvt_pk_bf16_f32 v42, v48, v49
	v_cvt_pk_bf16_f32 v43, v50, v51
	v_cvt_pk_bf16_f32 v24, v36, v37
	v_cvt_pk_bf16_f32 v25, v38, v39
	v_cvt_pk_bf16_f32 v26, v32, v33
	v_cvt_pk_bf16_f32 v27, v34, v35
	v_cvt_pk_bf16_f32 v8, v20, v21
	v_cvt_pk_bf16_f32 v9, v22, v23
	v_cvt_pk_bf16_f32 v10, v16, v17
	v_cvt_pk_bf16_f32 v11, v18, v19
	v_lshl_add_u64 v[12:13], v[122:123], 0, s[12:13]
	v_cvt_pk_bf16_f32 v4, v4, v5
	v_cvt_pk_bf16_f32 v5, v6, v7
	v_cvt_pk_bf16_f32 v6, v0, v1
	v_cvt_pk_bf16_f32 v7, v2, v3
	s_and_b64 vcc, exec, s[4:5]
	s_mov_b32 s79, s16
	s_mov_b32 s14, s18
	s_mov_b64 s[30:31], s[26:27]
	s_mov_b64 s[28:29], s[20:21]
	global_store_dwordx4 v[122:123], v[124:127], off
	global_store_dwordx4 v[108:109], v[104:107], off
	global_store_dwordx4 v[92:93], v[88:91], off
	global_store_dwordx4 v[76:77], v[72:75], off
	global_store_dwordx4 v[76:77], v[68:71], off offset:256
	global_store_dwordx4 v[58:59], v[60:63], off
	global_store_dwordx4 v[46:47], v[40:43], off
	global_store_dwordx4 v[30:31], v[24:27], off
	global_store_dwordx4 v[14:15], v[8:11], off
	global_store_dwordx4 v[12:13], v[4:7], off offset:256
	s_cbranch_vccz .LBB0_483
	s_waitcnt vmcnt(16)
	s_cmpk_gt_u32 s54, 0xff
	s_cbranch_scc1 .LBB0_490
	s_barrier

.LBB0_683:
	ds_read_b128 v[154:157], v151
	ds_read_b128 v[158:161], v151 offset:1024
	ds_read_b128 v[162:165], v151 offset:2048
	ds_read_b128 v[166:169], v151 offset:3072
	s_add_u32 s34, s30, 0xfffc0080
	s_addc_u32 s35, s31, -1
	s_cmp_eq_u32 s85, 12
	s_cselect_b32 s55, s19, s35
	s_cselect_b32 s54, s81, s34
	s_cselect_b32 s35, s17, s84
	s_cselect_b32 s34, s82, s83
	v_lshl_add_u64 v[202:203], s[30:31], 0, v[138:139]
	s_add_i32 m0, s29, 0xc000
	ds_read_b128 v[170:173], v152
	ds_read_b128 v[174:177], v152 offset:1024
	ds_read_b128 v[178:181], v152 offset:2048
	ds_read_b128 v[182:185], v152 offset:3072
	ds_read_b128 v[186:189], v152 offset:4096
	ds_read_b128 v[190:193], v152 offset:5120
	ds_read_b128 v[194:197], v152 offset:6144
	ds_read_b128 v[198:201], v152 offset:7168
	global_load_lds_dwordx4 v[202:203], off
	v_lshl_add_u64 v[202:203], s[30:31], 0, v[140:141]
	s_add_i32 m0, s29, 0xe000
	s_nop 0
	global_load_lds_dwordx4 v[202:203], off
	s_waitcnt lgkmcnt(8)
	s_barrier
	s_waitcnt lgkmcnt(0)
	s_waitcnt lgkmcnt(0)
	v_mfma_f32_16x16x32_bf16 v[124:127], v[154:157], v[170:173], v[124:127]
	v_mfma_f32_16x16x32_bf16 v[120:123], v[162:165], v[170:173], v[120:123]
	v_mfma_f32_16x16x32_bf16 v[108:111], v[154:157], v[178:181], v[108:111]
	v_mfma_f32_16x16x32_bf16 v[104:107], v[162:165], v[178:181], v[104:107]
	v_mfma_f32_16x16x32_bf16 v[92:95], v[154:157], v[186:189], v[92:95]
	v_mfma_f32_16x16x32_bf16 v[88:91], v[162:165], v[186:189], v[88:91]
	v_mfma_f32_16x16x32_bf16 v[76:79], v[154:157], v[194:197], v[76:79]
	v_mfma_f32_16x16x32_bf16 v[72:75], v[162:165], v[194:197], v[72:75]
	v_mfma_f32_16x16x32_bf16 v[124:127], v[158:161], v[174:177], v[124:127]
	v_mfma_f32_16x16x32_bf16 v[120:123], v[166:169], v[174:177], v[120:123]
	v_mfma_f32_16x16x32_bf16 v[108:111], v[158:161], v[182:185], v[108:111]
	v_mfma_f32_16x16x32_bf16 v[104:107], v[166:169], v[182:185], v[104:107]
	v_mfma_f32_16x16x32_bf16 v[92:95], v[158:161], v[190:193], v[92:95]
	v_mfma_f32_16x16x32_bf16 v[88:91], v[166:169], v[190:193], v[88:91]
	v_mfma_f32_16x16x32_bf16 v[76:79], v[158:161], v[198:201], v[76:79]
	v_mfma_f32_16x16x32_bf16 v[72:75], v[166:169], v[198:201], v[72:75]
	s_barrier
	s_add_i32 s86, s74, s60
	v_lshl_add_u64 v[218:219], s[34:35], 0, v[132:133]
	s_mov_b32 m0, s86
	ds_read_b128 v[202:205], v153
	ds_read_b128 v[206:209], v153 offset:1024
	ds_read_b128 v[210:213], v153 offset:2048
	ds_read_b128 v[214:217], v153 offset:3072
	global_load_lds_dwordx4 v[218:219], off
	v_lshl_add_u64 v[220:221], s[34:35], 0, v[136:137]
	s_add_i32 m0, s86, 0x2000
	s_nop 0
	global_load_lds_dwordx4 v[220:221], off
	s_barrier
	s_waitcnt lgkmcnt(0)
	s_waitcnt lgkmcnt(0)
	v_mfma_f32_16x16x32_bf16 v[116:119], v[202:205], v[170:173], v[116:119]
	v_mfma_f32_16x16x32_bf16 v[112:115], v[210:213], v[170:173], v[112:115]
	v_mfma_f32_16x16x32_bf16 v[100:103], v[202:205], v[178:181], v[100:103]
	v_mfma_f32_16x16x32_bf16 v[96:99], v[210:213], v[178:181], v[96:99]
	v_mfma_f32_16x16x32_bf16 v[84:87], v[202:205], v[186:189], v[84:87]
	v_mfma_f32_16x16x32_bf16 v[80:83], v[210:213], v[186:189], v[80:83]
	v_mfma_f32_16x16x32_bf16 v[68:71], v[202:205], v[194:197], v[68:71]
	v_mfma_f32_16x16x32_bf16 v[64:67], v[210:213], v[194:197], v[64:67]
	v_mfma_f32_16x16x32_bf16 v[116:119], v[206:209], v[174:177], v[116:119]
	v_mfma_f32_16x16x32_bf16 v[112:115], v[214:217], v[174:177], v[112:115]
	v_mfma_f32_16x16x32_bf16 v[100:103], v[206:209], v[182:185], v[100:103]
	v_mfma_f32_16x16x32_bf16 v[96:99], v[214:217], v[182:185], v[96:99]
	v_mfma_f32_16x16x32_bf16 v[84:87], v[206:209], v[190:193], v[84:87]
	v_mfma_f32_16x16x32_bf16 v[80:83], v[214:217], v[190:193], v[80:83]
	v_mfma_f32_16x16x32_bf16 v[68:71], v[206:209], v[198:201], v[68:71]
	v_mfma_f32_16x16x32_bf16 v[64:67], v[214:217], v[198:201], v[64:67]
	s_mov_b32 m0, s29
	v_lshl_add_u64 v[222:223], s[54:55], 0, v[130:131]
	s_barrier
	ds_read_b128 v[170:173], v152 offset:16384
	ds_read_b128 v[174:177], v152 offset:17408
	ds_read_b128 v[178:181], v152 offset:18432
	ds_read_b128 v[182:185], v152 offset:19456
	ds_read_b128 v[186:189], v152 offset:20480
	ds_read_b128 v[190:193], v152 offset:21504
	ds_read_b128 v[194:197], v152 offset:22528
	ds_read_b128 v[198:201], v152 offset:23552
	global_load_lds_dwordx4 v[222:223], off
	v_lshl_add_u64 v[224:225], s[54:55], 0, v[134:135]
	s_mov_b32 m0, s61
	s_nop 0
	global_load_lds_dwordx4 v[224:225], off
	s_barrier
	s_waitcnt lgkmcnt(0)
	s_waitcnt lgkmcnt(0)
	v_mfma_f32_16x16x32_bf16 v[60:63], v[154:157], v[170:173], v[60:63]
	v_mfma_f32_16x16x32_bf16 v[56:59], v[162:165], v[170:173], v[56:59]
	v_mfma_f32_16x16x32_bf16 v[44:47], v[154:157], v[178:181], v[44:47]
	v_mfma_f32_16x16x32_bf16 v[40:43], v[162:165], v[178:181], v[40:43]
	v_mfma_f32_16x16x32_bf16 v[28:31], v[154:157], v[186:189], v[28:31]
	v_mfma_f32_16x16x32_bf16 v[24:27], v[162:165], v[186:189], v[24:27]
	v_mfma_f32_16x16x32_bf16 v[12:15], v[154:157], v[194:197], v[12:15]
	v_mfma_f32_16x16x32_bf16 v[8:11], v[162:165], v[194:197], v[8:11]
	v_mfma_f32_16x16x32_bf16 v[60:63], v[158:161], v[174:177], v[60:63]
	v_mfma_f32_16x16x32_bf16 v[56:59], v[166:169], v[174:177], v[56:59]
	v_mfma_f32_16x16x32_bf16 v[44:47], v[158:161], v[182:185], v[44:47]
	v_mfma_f32_16x16x32_bf16 v[40:43], v[166:169], v[182:185], v[40:43]
	v_mfma_f32_16x16x32_bf16 v[28:31], v[158:161], v[190:193], v[28:31]
	v_mfma_f32_16x16x32_bf16 v[24:27], v[166:169], v[190:193], v[24:27]
	v_mfma_f32_16x16x32_bf16 v[12:15], v[158:161], v[198:201], v[12:15]
	v_mfma_f32_16x16x32_bf16 v[8:11], v[166:169], v[198:201], v[8:11]
	s_barrier
	s_add_u32 s86, s34, 0x40000
	s_addc_u32 s87, s35, 0
	s_add_i32 s88, s75, s60
	v_lshl_add_u64 v[154:155], s[86:87], 0, v[132:133]
	s_mov_b32 m0, s88
	s_nop 0
	global_load_lds_dwordx4 v[154:155], off
	v_lshl_add_u64 v[154:155], s[86:87], 0, v[136:137]
	s_add_i32 m0, s88, 0x2000
	s_nop 0
	global_load_lds_dwordx4 v[154:155], off
	s_waitcnt vmcnt(6)
	s_barrier
	v_mfma_f32_16x16x32_bf16 v[52:55], v[202:205], v[170:173], v[52:55]
	v_mfma_f32_16x16x32_bf16 v[48:51], v[210:213], v[170:173], v[48:51]
	v_mfma_f32_16x16x32_bf16 v[36:39], v[202:205], v[178:181], v[36:39]
	v_mfma_f32_16x16x32_bf16 v[32:35], v[210:213], v[178:181], v[32:35]
	v_mfma_f32_16x16x32_bf16 v[20:23], v[202:205], v[186:189], v[20:23]
	v_mfma_f32_16x16x32_bf16 v[16:19], v[210:213], v[186:189], v[16:19]
	v_mfma_f32_16x16x32_bf16 v[4:7], v[202:205], v[194:197], v[4:7]
	v_mfma_f32_16x16x32_bf16 v[0:3], v[210:213], v[194:197], v[0:3]
	v_mfma_f32_16x16x32_bf16 v[52:55], v[206:209], v[174:177], v[52:55]
	v_mfma_f32_16x16x32_bf16 v[48:51], v[214:217], v[174:177], v[48:51]
	v_mfma_f32_16x16x32_bf16 v[36:39], v[206:209], v[182:185], v[36:39]
	v_mfma_f32_16x16x32_bf16 v[32:35], v[214:217], v[182:185], v[32:35]
	v_mfma_f32_16x16x32_bf16 v[20:23], v[206:209], v[190:193], v[20:23]
	v_mfma_f32_16x16x32_bf16 v[16:19], v[214:217], v[190:193], v[16:19]
	v_mfma_f32_16x16x32_bf16 v[4:7], v[206:209], v[198:201], v[4:7]
	v_mfma_f32_16x16x32_bf16 v[0:3], v[214:217], v[198:201], v[0:3]
	s_add_i32 s86, 0, 0x18000
	v_add_u32_e32 v166, s86, v149
	s_barrier
	ds_read_b128 v[154:157], v166
	ds_read_b128 v[158:161], v166 offset:1024
	ds_read_b128 v[162:165], v166 offset:2048
	ds_read_b128 v[166:169], v166 offset:3072
	s_add_u32 s54, s54, 0x40000
	s_addc_u32 s55, s55, 0
	s_mov_b32 m0, s62
	v_lshl_add_u64 v[202:203], s[54:55], 0, v[130:131]
	ds_read_b128 v[170:173], v152 offset:32768
	ds_read_b128 v[174:177], v152 offset:33792
	ds_read_b128 v[178:181], v152 offset:34816
	ds_read_b128 v[182:185], v152 offset:35840
	ds_read_b128 v[186:189], v152 offset:36864
	ds_read_b128 v[190:193], v152 offset:37888
	ds_read_b128 v[194:197], v152 offset:38912
	ds_read_b128 v[198:201], v152 offset:39936
	global_load_lds_dwordx4 v[202:203], off
	v_lshl_add_u64 v[202:203], s[54:55], 0, v[134:135]
	s_mov_b32 m0, s63
	s_nop 0
	global_load_lds_dwordx4 v[202:203], off
	s_waitcnt lgkmcnt(8)
	s_barrier
	s_waitcnt lgkmcnt(0)
	s_waitcnt lgkmcnt(0)
	v_mfma_f32_16x16x32_bf16 v[124:127], v[154:157], v[170:173], v[124:127]
	v_mfma_f32_16x16x32_bf16 v[120:123], v[162:165], v[170:173], v[120:123]
	v_mfma_f32_16x16x32_bf16 v[108:111], v[154:157], v[178:181], v[108:111]
	v_mfma_f32_16x16x32_bf16 v[104:107], v[162:165], v[178:181], v[104:107]
	v_mfma_f32_16x16x32_bf16 v[92:95], v[154:157], v[186:189], v[92:95]
	v_mfma_f32_16x16x32_bf16 v[88:91], v[162:165], v[186:189], v[88:91]
	v_mfma_f32_16x16x32_bf16 v[76:79], v[154:157], v[194:197], v[76:79]
	v_mfma_f32_16x16x32_bf16 v[72:75], v[162:165], v[194:197], v[72:75]
	v_mfma_f32_16x16x32_bf16 v[124:127], v[158:161], v[174:177], v[124:127]
	v_mfma_f32_16x16x32_bf16 v[120:123], v[166:169], v[174:177], v[120:123]
	v_mfma_f32_16x16x32_bf16 v[108:111], v[158:161], v[182:185], v[108:111]
	v_mfma_f32_16x16x32_bf16 v[104:107], v[166:169], v[182:185], v[104:107]
	v_mfma_f32_16x16x32_bf16 v[92:95], v[158:161], v[190:193], v[92:95]
	v_mfma_f32_16x16x32_bf16 v[88:91], v[166:169], v[190:193], v[88:91]
	v_mfma_f32_16x16x32_bf16 v[76:79], v[158:161], v[198:201], v[76:79]
	v_mfma_f32_16x16x32_bf16 v[72:75], v[166:169], v[198:201], v[72:75]
	s_barrier
	s_add_i32 s54, 0, 0x1c000
	s_add_i32 s55, s86, s60
	v_add_u32_e32 v214, s54, v149
	v_lshl_add_u64 v[218:219], v[218:219], 0, s[8:9]
	s_mov_b32 m0, s55
	ds_read_b128 v[202:205], v214
	ds_read_b128 v[206:209], v214 offset:1024
	ds_read_b128 v[210:213], v214 offset:2048
	ds_read_b128 v[214:217], v214 offset:3072
	global_load_lds_dwordx4 v[218:219], off
	v_lshl_add_u64 v[218:219], v[220:221], 0, s[8:9]
	s_add_i32 m0, s55, 0x2000
	s_nop 0
	global_load_lds_dwordx4 v[218:219], off
	s_barrier
	s_waitcnt lgkmcnt(0)
	s_waitcnt lgkmcnt(0)
	v_mfma_f32_16x16x32_bf16 v[116:119], v[202:205], v[170:173], v[116:119]
	v_mfma_f32_16x16x32_bf16 v[112:115], v[210:213], v[170:173], v[112:115]
	v_mfma_f32_16x16x32_bf16 v[100:103], v[202:205], v[178:181], v[100:103]
	v_mfma_f32_16x16x32_bf16 v[96:99], v[210:213], v[178:181], v[96:99]
	v_mfma_f32_16x16x32_bf16 v[84:87], v[202:205], v[186:189], v[84:87]
	v_mfma_f32_16x16x32_bf16 v[80:83], v[210:213], v[186:189], v[80:83]
	v_mfma_f32_16x16x32_bf16 v[68:71], v[202:205], v[194:197], v[68:71]
	v_mfma_f32_16x16x32_bf16 v[64:67], v[210:213], v[194:197], v[64:67]
	v_mfma_f32_16x16x32_bf16 v[116:119], v[206:209], v[174:177], v[116:119]
	v_mfma_f32_16x16x32_bf16 v[112:115], v[214:217], v[174:177], v[112:115]
	v_mfma_f32_16x16x32_bf16 v[100:103], v[206:209], v[182:185], v[100:103]
	v_mfma_f32_16x16x32_bf16 v[96:99], v[214:217], v[182:185], v[96:99]
	v_mfma_f32_16x16x32_bf16 v[84:87], v[206:209], v[190:193], v[84:87]
	v_mfma_f32_16x16x32_bf16 v[80:83], v[214:217], v[190:193], v[80:83]
	v_mfma_f32_16x16x32_bf16 v[68:71], v[206:209], v[198:201], v[68:71]
	v_mfma_f32_16x16x32_bf16 v[64:67], v[214:217], v[198:201], v[64:67]
	s_mov_b32 m0, s71
	v_lshl_add_u64 v[218:219], v[222:223], 0, s[8:9]
	s_barrier
	ds_read_b128 v[170:173], v152 offset:49152
	ds_read_b128 v[174:177], v152 offset:50176
	ds_read_b128 v[178:181], v152 offset:51200
	ds_read_b128 v[182:185], v152 offset:52224
	ds_read_b128 v[186:189], v152 offset:53248
	ds_read_b128 v[190:193], v152 offset:54272
	ds_read_b128 v[194:197], v152 offset:55296
	ds_read_b128 v[198:201], v152 offset:56320
	global_load_lds_dwordx4 v[218:219], off
	v_lshl_add_u64 v[218:219], v[224:225], 0, s[8:9]
	s_mov_b32 m0, s72
	s_nop 0
	global_load_lds_dwordx4 v[218:219], off
	s_barrier
	s_waitcnt lgkmcnt(0)
	s_waitcnt lgkmcnt(0)
	v_mfma_f32_16x16x32_bf16 v[60:63], v[154:157], v[170:173], v[60:63]
	v_mfma_f32_16x16x32_bf16 v[56:59], v[162:165], v[170:173], v[56:59]
	v_mfma_f32_16x16x32_bf16 v[44:47], v[154:157], v[178:181], v[44:47]
	v_mfma_f32_16x16x32_bf16 v[40:43], v[162:165], v[178:181], v[40:43]
	v_mfma_f32_16x16x32_bf16 v[28:31], v[154:157], v[186:189], v[28:31]
	v_mfma_f32_16x16x32_bf16 v[24:27], v[162:165], v[186:189], v[24:27]
	v_mfma_f32_16x16x32_bf16 v[12:15], v[154:157], v[194:197], v[12:15]
	v_mfma_f32_16x16x32_bf16 v[8:11], v[162:165], v[194:197], v[8:11]
	v_mfma_f32_16x16x32_bf16 v[60:63], v[158:161], v[174:177], v[60:63]
	v_mfma_f32_16x16x32_bf16 v[56:59], v[166:169], v[174:177], v[56:59]
	v_mfma_f32_16x16x32_bf16 v[44:47], v[158:161], v[182:185], v[44:47]
	v_mfma_f32_16x16x32_bf16 v[40:43], v[166:169], v[182:185], v[40:43]
	v_mfma_f32_16x16x32_bf16 v[28:31], v[158:161], v[190:193], v[28:31]
	v_mfma_f32_16x16x32_bf16 v[24:27], v[166:169], v[190:193], v[24:27]
	v_mfma_f32_16x16x32_bf16 v[12:15], v[158:161], v[198:201], v[12:15]
	v_mfma_f32_16x16x32_bf16 v[8:11], v[166:169], v[198:201], v[8:11]
	s_barrier
	s_add_u32 s34, s34, 0x40080
	s_addc_u32 s35, s35, 0
	s_add_i32 s54, s54, s60
	v_lshl_add_u64 v[154:155], s[34:35], 0, v[132:133]
	s_mov_b32 m0, s54
	s_nop 0
	global_load_lds_dwordx4 v[154:155], off
	v_lshl_add_u64 v[154:155], s[34:35], 0, v[136:137]
	s_add_i32 m0, s54, 0x2000
	s_nop 0
	global_load_lds_dwordx4 v[154:155], off
	s_waitcnt vmcnt(6)
	s_barrier
	v_mfma_f32_16x16x32_bf16 v[52:55], v[202:205], v[170:173], v[52:55]
	v_mfma_f32_16x16x32_bf16 v[48:51], v[210:213], v[170:173], v[48:51]
	v_mfma_f32_16x16x32_bf16 v[36:39], v[202:205], v[178:181], v[36:39]
	v_mfma_f32_16x16x32_bf16 v[32:35], v[210:213], v[178:181], v[32:35]
	v_mfma_f32_16x16x32_bf16 v[20:23], v[202:205], v[186:189], v[20:23]
	v_mfma_f32_16x16x32_bf16 v[16:19], v[210:213], v[186:189], v[16:19]
	v_mfma_f32_16x16x32_bf16 v[4:7], v[202:205], v[194:197], v[4:7]
	v_mfma_f32_16x16x32_bf16 v[0:3], v[210:213], v[194:197], v[0:3]
	v_mfma_f32_16x16x32_bf16 v[52:55], v[206:209], v[174:177], v[52:55]
	v_mfma_f32_16x16x32_bf16 v[48:51], v[214:217], v[174:177], v[48:51]
	v_mfma_f32_16x16x32_bf16 v[36:39], v[206:209], v[182:185], v[36:39]
	v_mfma_f32_16x16x32_bf16 v[32:35], v[214:217], v[182:185], v[32:35]
	v_mfma_f32_16x16x32_bf16 v[20:23], v[206:209], v[190:193], v[20:23]
	v_mfma_f32_16x16x32_bf16 v[16:19], v[214:217], v[190:193], v[16:19]
	v_mfma_f32_16x16x32_bf16 v[4:7], v[206:209], v[198:201], v[4:7]
	v_mfma_f32_16x16x32_bf16 v[0:3], v[214:217], v[198:201], v[0:3]
	s_add_i32 s85, s85, 2
	s_add_u32 s30, s30, 0x100
	s_addc_u32 s31, s31, 0
	s_add_u32 s83, s83, 0x100
	s_addc_u32 s84, s84, 0
	s_cmp_gt_u32 s85, 13
	s_barrier
	s_cbranch_scc0 .LBB0_683
	v_lshl_add_u32 v154, s28, 8, v148
	v_max_f32_e32 v126, v126, v126
	v_max_f32_e32 v127, v127, v127
	v_lshl_or_b32 v156, s80, 8, v150
	v_ashrrev_i32_e32 v155, 31, v154
	v_max_f32_e32 v124, v124, v124
	v_max_f32_e32 v120, v120, v120
	v_max_f32_e32 v125, v125, v125
	v_max_f32_e32 v121, v121, v121
	v_max_f32_e32 v126, 0, v126
	v_max_f32_e32 v122, v122, v122
	v_max_f32_e32 v127, 0, v127
	v_max_f32_e32 v123, v123, v123
	v_lshlrev_b64 v[158:159], 13, v[154:155]
	v_max_f32_e32 v124, 0, v124
	v_max_f32_e32 v120, 0, v120
	v_max_f32_e32 v125, 0, v125
	v_max_f32_e32 v121, 0, v121
	v_max_f32_e32 v122, 0, v122
	v_max_f32_e32 v123, 0, v123
	v_pk_mul_f32 v[126:127], v[126:127], v[126:127]
	v_ashrrev_i32_e32 v157, 31, v156
	v_lshl_add_u64 v[158:159], s[46:47], 0, v[158:159]
	v_pk_mul_f32 v[124:125], v[124:125], v[124:125]
	v_pk_mul_f32 v[120:121], v[120:121], v[120:121]
	v_pk_mul_f32 v[160:161], v[122:123], v[122:123]
	v_cvt_pk_bf16_f32 v123, v126, v127
	v_lshlrev_b64 v[126:127], 1, v[156:157]
	v_max_f32_e32 v112, v112, v112
	v_max_f32_e32 v113, v113, v113
	v_cvt_pk_bf16_f32 v122, v124, v125
	v_cvt_pk_bf16_f32 v124, v120, v121
	v_cvt_pk_bf16_f32 v125, v160, v161
	v_lshl_add_u64 v[120:121], v[158:159], 0, v[126:127]
	v_max_f32_e32 v112, 0, v112
	v_max_f32_e32 v113, 0, v113
	global_store_dwordx4 v[120:121], v[122:125], off
	v_max_f32_e32 v116, v116, v116
	v_max_f32_e32 v117, v117, v117
	v_pk_mul_f32 v[122:123], v[112:113], v[112:113]
	v_max_f32_e32 v113, v114, v114
	v_max_f32_e32 v112, v118, v118
	v_max_f32_e32 v114, 0, v113
	v_max_f32_e32 v113, v119, v119
	v_max_f32_e32 v115, v115, v115
	v_max_f32_e32 v116, 0, v116
	v_max_f32_e32 v117, 0, v117
	v_max_f32_e32 v112, 0, v112
	v_max_f32_e32 v113, 0, v113
	v_max_f32_e32 v115, 0, v115
	v_pk_mul_f32 v[116:117], v[116:117], v[116:117]
	v_pk_mul_f32 v[118:119], v[112:113], v[112:113]
	v_pk_mul_f32 v[124:125], v[114:115], v[114:115]
	v_max_f32_e32 v104, v104, v104
	v_max_f32_e32 v105, v105, v105
	v_cvt_pk_bf16_f32 v112, v116, v117
	v_cvt_pk_bf16_f32 v113, v118, v119
	v_cvt_pk_bf16_f32 v114, v122, v123
	v_cvt_pk_bf16_f32 v115, v124, v125
	v_max_f32_e32 v104, 0, v104
	v_max_f32_e32 v105, 0, v105
	global_store_dwordx4 v[120:121], v[112:115], off offset:256
	v_max_f32_e32 v108, v108, v108
	v_max_f32_e32 v109, v109, v109
	v_or_b32_e32 v112, 16, v154
	v_pk_mul_f32 v[114:115], v[104:105], v[104:105]
	v_max_f32_e32 v105, v106, v106
	v_ashrrev_i32_e32 v113, 31, v112
	v_max_f32_e32 v104, v110, v110
	v_max_f32_e32 v106, 0, v105
	v_max_f32_e32 v105, v111, v111
	v_max_f32_e32 v107, v107, v107
	v_lshlrev_b64 v[112:113], 13, v[112:113]
	v_max_f32_e32 v108, 0, v108
	v_max_f32_e32 v109, 0, v109
	v_max_f32_e32 v104, 0, v104
	v_max_f32_e32 v105, 0, v105
	v_max_f32_e32 v107, 0, v107
	v_lshl_add_u64 v[112:113], s[46:47], 0, v[112:113]
	v_pk_mul_f32 v[108:109], v[108:109], v[108:109]
	v_pk_mul_f32 v[110:111], v[104:105], v[104:105]
	v_pk_mul_f32 v[116:117], v[106:107], v[106:107]
	v_max_f32_e32 v96, v96, v96
	v_max_f32_e32 v97, v97, v97
	v_cvt_pk_bf16_f32 v104, v108, v109
	v_cvt_pk_bf16_f32 v105, v110, v111
	v_cvt_pk_bf16_f32 v106, v114, v115
	v_cvt_pk_bf16_f32 v107, v116, v117
	v_lshl_add_u64 v[108:109], v[112:113], 0, v[126:127]
	v_max_f32_e32 v96, 0, v96
	v_max_f32_e32 v97, 0, v97
	global_store_dwordx4 v[108:109], v[104:107], off
	v_max_f32_e32 v100, v100, v100
	v_max_f32_e32 v101, v101, v101
	v_pk_mul_f32 v[104:105], v[96:97], v[96:97]
	v_max_f32_e32 v97, v98, v98
	v_max_f32_e32 v96, v102, v102
	v_max_f32_e32 v98, 0, v97
	v_max_f32_e32 v97, v103, v103
	v_max_f32_e32 v99, v99, v99
	v_max_f32_e32 v100, 0, v100
	v_max_f32_e32 v101, 0, v101
	v_max_f32_e32 v96, 0, v96
	v_max_f32_e32 v97, 0, v97
	v_max_f32_e32 v99, 0, v99
	v_pk_mul_f32 v[100:101], v[100:101], v[100:101]
	v_pk_mul_f32 v[102:103], v[96:97], v[96:97]
	v_pk_mul_f32 v[106:107], v[98:99], v[98:99]
	v_max_f32_e32 v88, v88, v88
	v_max_f32_e32 v89, v89, v89
	v_cvt_pk_bf16_f32 v96, v100, v101
	v_cvt_pk_bf16_f32 v97, v102, v103
	v_cvt_pk_bf16_f32 v98, v104, v105
	v_cvt_pk_bf16_f32 v99, v106, v107
	v_max_f32_e32 v88, 0, v88
	v_max_f32_e32 v89, 0, v89
	global_store_dwordx4 v[108:109], v[96:99], off offset:256
	v_max_f32_e32 v92, v92, v92
	v_max_f32_e32 v93, v93, v93
	v_or_b32_e32 v96, 32, v154
	v_pk_mul_f32 v[98:99], v[88:89], v[88:89]
	v_max_f32_e32 v89, v90, v90
	v_ashrrev_i32_e32 v97, 31, v96
	v_max_f32_e32 v88, v94, v94
	v_max_f32_e32 v90, 0, v89
	v_max_f32_e32 v89, v95, v95
	v_max_f32_e32 v91, v91, v91
	v_lshlrev_b64 v[96:97], 13, v[96:97]
	v_max_f32_e32 v92, 0, v92
	v_max_f32_e32 v93, 0, v93
	v_max_f32_e32 v88, 0, v88
	v_max_f32_e32 v89, 0, v89
	v_max_f32_e32 v91, 0, v91
	v_lshl_add_u64 v[96:97], s[46:47], 0, v[96:97]
	v_pk_mul_f32 v[92:93], v[92:93], v[92:93]
	v_pk_mul_f32 v[94:95], v[88:89], v[88:89]
	v_pk_mul_f32 v[100:101], v[90:91], v[90:91]
	v_max_f32_e32 v80, v80, v80
	v_max_f32_e32 v81, v81, v81
	v_cvt_pk_bf16_f32 v88, v92, v93
	v_cvt_pk_bf16_f32 v89, v94, v95
	v_cvt_pk_bf16_f32 v90, v98, v99
	v_cvt_pk_bf16_f32 v91, v100, v101
	v_lshl_add_u64 v[92:93], v[96:97], 0, v[126:127]
	v_max_f32_e32 v80, 0, v80
	v_max_f32_e32 v81, 0, v81
	global_store_dwordx4 v[92:93], v[88:91], off
	v_max_f32_e32 v84, v84, v84
	v_max_f32_e32 v85, v85, v85
	v_pk_mul_f32 v[88:89], v[80:81], v[80:81]
	v_max_f32_e32 v81, v82, v82
	v_max_f32_e32 v80, v86, v86
	v_max_f32_e32 v82, 0, v81
	v_max_f32_e32 v81, v87, v87
	v_max_f32_e32 v83, v83, v83
	v_max_f32_e32 v84, 0, v84
	v_max_f32_e32 v85, 0, v85
	v_max_f32_e32 v80, 0, v80
	v_max_f32_e32 v81, 0, v81
	v_max_f32_e32 v83, 0, v83
	v_pk_mul_f32 v[84:85], v[84:85], v[84:85]
	v_pk_mul_f32 v[86:87], v[80:81], v[80:81]
	v_pk_mul_f32 v[90:91], v[82:83], v[82:83]
	v_max_f32_e32 v72, v72, v72
	v_max_f32_e32 v73, v73, v73
	v_cvt_pk_bf16_f32 v80, v84, v85
	v_cvt_pk_bf16_f32 v81, v86, v87
	v_cvt_pk_bf16_f32 v82, v88, v89
	v_cvt_pk_bf16_f32 v83, v90, v91
	v_max_f32_e32 v72, 0, v72
	v_max_f32_e32 v73, 0, v73
	global_store_dwordx4 v[92:93], v[80:83], off offset:256
	v_max_f32_e32 v76, v76, v76
	v_max_f32_e32 v77, v77, v77
	v_or_b32_e32 v80, 48, v154
	v_pk_mul_f32 v[82:83], v[72:73], v[72:73]
	v_max_f32_e32 v73, v74, v74
	v_ashrrev_i32_e32 v81, 31, v80
	v_max_f32_e32 v72, v78, v78
	v_max_f32_e32 v74, 0, v73
	v_max_f32_e32 v73, v79, v79
	v_max_f32_e32 v75, v75, v75
	v_lshlrev_b64 v[80:81], 13, v[80:81]
	v_max_f32_e32 v76, 0, v76
	v_max_f32_e32 v77, 0, v77
	v_max_f32_e32 v72, 0, v72
	v_max_f32_e32 v73, 0, v73
	v_max_f32_e32 v75, 0, v75
	v_lshl_add_u64 v[80:81], s[46:47], 0, v[80:81]
	v_pk_mul_f32 v[76:77], v[76:77], v[76:77]
	v_pk_mul_f32 v[78:79], v[72:73], v[72:73]
	v_pk_mul_f32 v[84:85], v[74:75], v[74:75]
	v_max_f32_e32 v64, v64, v64
	v_max_f32_e32 v65, v65, v65
	v_cvt_pk_bf16_f32 v72, v76, v77
	v_cvt_pk_bf16_f32 v73, v78, v79
	v_cvt_pk_bf16_f32 v74, v82, v83
	v_cvt_pk_bf16_f32 v75, v84, v85
	v_lshl_add_u64 v[76:77], v[80:81], 0, v[126:127]
	v_max_f32_e32 v64, 0, v64
	v_max_f32_e32 v65, 0, v65
	global_store_dwordx4 v[76:77], v[72:75], off
	v_max_f32_e32 v68, v68, v68
	v_max_f32_e32 v69, v69, v69
	v_pk_mul_f32 v[72:73], v[64:65], v[64:65]
	v_max_f32_e32 v65, v66, v66
	v_max_f32_e32 v64, v70, v70
	v_max_f32_e32 v66, 0, v65
	v_max_f32_e32 v65, v71, v71
	v_max_f32_e32 v67, v67, v67
	v_max_f32_e32 v68, 0, v68
	v_max_f32_e32 v69, 0, v69
	v_max_f32_e32 v64, 0, v64
	v_max_f32_e32 v65, 0, v65
	v_max_f32_e32 v67, 0, v67
	v_pk_mul_f32 v[68:69], v[68:69], v[68:69]
	v_pk_mul_f32 v[70:71], v[64:65], v[64:65]
	v_pk_mul_f32 v[74:75], v[66:67], v[66:67]
	v_max_f32_e32 v56, v56, v56
	v_max_f32_e32 v57, v57, v57
	v_cvt_pk_bf16_f32 v64, v68, v69
	v_cvt_pk_bf16_f32 v65, v70, v71
	v_cvt_pk_bf16_f32 v66, v72, v73
	v_cvt_pk_bf16_f32 v67, v74, v75
	v_max_f32_e32 v56, 0, v56
	v_max_f32_e32 v57, 0, v57
	global_store_dwordx4 v[76:77], v[64:67], off offset:256
	v_max_f32_e32 v60, v60, v60
	v_max_f32_e32 v61, v61, v61
	v_pk_mul_f32 v[64:65], v[56:57], v[56:57]
	v_max_f32_e32 v57, v58, v58
	v_max_f32_e32 v56, v62, v62
	v_max_f32_e32 v58, 0, v57
	v_max_f32_e32 v57, v63, v63
	v_max_f32_e32 v56, 0, v56
	v_max_f32_e32 v57, 0, v57
	v_max_f32_e32 v59, v59, v59
	v_max_f32_e32 v60, 0, v60
	v_max_f32_e32 v61, 0, v61
	v_max_f32_e32 v59, 0, v59
	v_pk_mul_f32 v[62:63], v[56:57], v[56:57]
	v_pk_mul_f32 v[60:61], v[60:61], v[60:61]
	v_pk_mul_f32 v[66:67], v[58:59], v[58:59]
	v_cvt_pk_bf16_f32 v57, v62, v63
	v_add_co_u32_e32 v62, vcc, s76, v120
	v_max_f32_e32 v48, v48, v48
	v_max_f32_e32 v49, v49, v49
	v_cvt_pk_bf16_f32 v56, v60, v61
	v_cvt_pk_bf16_f32 v58, v64, v65
	v_cvt_pk_bf16_f32 v59, v66, v67
	v_addc_co_u32_e32 v63, vcc, 0, v121, vcc
	v_max_f32_e32 v48, 0, v48
	v_max_f32_e32 v49, 0, v49
	global_store_dwordx4 v[62:63], v[56:59], off
	v_max_f32_e32 v52, v52, v52
	v_max_f32_e32 v53, v53, v53
	v_pk_mul_f32 v[56:57], v[48:49], v[48:49]
	v_max_f32_e32 v49, v50, v50
	v_max_f32_e32 v48, v54, v54
	v_max_f32_e32 v50, 0, v49
	v_max_f32_e32 v49, v55, v55
	v_max_f32_e32 v51, v51, v51
	v_max_f32_e32 v52, 0, v52
	v_max_f32_e32 v53, 0, v53
	v_max_f32_e32 v48, 0, v48
	v_max_f32_e32 v49, 0, v49
	v_max_f32_e32 v51, 0, v51
	s_mov_b64 s[30:31], 0x100000
	v_pk_mul_f32 v[52:53], v[52:53], v[52:53]
	v_pk_mul_f32 v[54:55], v[48:49], v[48:49]
	v_pk_mul_f32 v[58:59], v[50:51], v[50:51]
	v_max_f32_e32 v40, v40, v40
	v_max_f32_e32 v41, v41, v41
	v_lshl_add_u64 v[60:61], v[120:121], 0, s[30:31]
	v_cvt_pk_bf16_f32 v48, v52, v53
	v_cvt_pk_bf16_f32 v49, v54, v55
	v_cvt_pk_bf16_f32 v50, v56, v57
	v_cvt_pk_bf16_f32 v51, v58, v59
	v_max_f32_e32 v40, 0, v40
	v_max_f32_e32 v41, 0, v41
	global_store_dwordx4 v[60:61], v[48:51], off offset:256
	v_max_f32_e32 v44, v44, v44
	v_max_f32_e32 v45, v45, v45
	v_pk_mul_f32 v[48:49], v[40:41], v[40:41]
	v_max_f32_e32 v41, v42, v42
	v_max_f32_e32 v40, v46, v46
	v_max_f32_e32 v42, 0, v41
	v_max_f32_e32 v41, v47, v47
	v_max_f32_e32 v40, 0, v40
	v_max_f32_e32 v41, 0, v41
	v_max_f32_e32 v43, v43, v43
	v_max_f32_e32 v44, 0, v44
	v_max_f32_e32 v45, 0, v45
	v_max_f32_e32 v43, 0, v43
	v_pk_mul_f32 v[46:47], v[40:41], v[40:41]
	v_pk_mul_f32 v[44:45], v[44:45], v[44:45]
	v_pk_mul_f32 v[50:51], v[42:43], v[42:43]
	v_cvt_pk_bf16_f32 v41, v46, v47
	v_add_co_u32_e32 v46, vcc, s77, v120
	v_max_f32_e32 v32, v32, v32
	v_max_f32_e32 v33, v33, v33
	v_cvt_pk_bf16_f32 v40, v44, v45
	v_cvt_pk_bf16_f32 v42, v48, v49
	v_cvt_pk_bf16_f32 v43, v50, v51
	v_addc_co_u32_e32 v47, vcc, 0, v121, vcc
	v_max_f32_e32 v32, 0, v32
	v_max_f32_e32 v33, 0, v33
	global_store_dwordx4 v[46:47], v[40:43], off
	v_max_f32_e32 v36, v36, v36
	v_max_f32_e32 v37, v37, v37
	v_pk_mul_f32 v[40:41], v[32:33], v[32:33]
	v_max_f32_e32 v33, v34, v34
	v_max_f32_e32 v32, v38, v38
	v_max_f32_e32 v34, 0, v33
	v_max_f32_e32 v33, v39, v39
	v_max_f32_e32 v35, v35, v35
	v_max_f32_e32 v36, 0, v36
	v_max_f32_e32 v37, 0, v37
	v_max_f32_e32 v32, 0, v32
	v_max_f32_e32 v33, 0, v33
	v_max_f32_e32 v35, 0, v35
	v_pk_mul_f32 v[36:37], v[36:37], v[36:37]
	v_pk_mul_f32 v[38:39], v[32:33], v[32:33]
	v_pk_mul_f32 v[42:43], v[34:35], v[34:35]
	v_max_f32_e32 v24, v24, v24
	v_max_f32_e32 v25, v25, v25
	v_lshl_add_u64 v[44:45], v[120:121], 0, s[10:11]
	v_cvt_pk_bf16_f32 v32, v36, v37
	v_cvt_pk_bf16_f32 v33, v38, v39
	v_cvt_pk_bf16_f32 v34, v40, v41
	v_cvt_pk_bf16_f32 v35, v42, v43
	v_max_f32_e32 v24, 0, v24
	v_max_f32_e32 v25, 0, v25
	global_store_dwordx4 v[44:45], v[32:35], off offset:256
	v_max_f32_e32 v28, v28, v28
	v_max_f32_e32 v29, v29, v29
	v_pk_mul_f32 v[32:33], v[24:25], v[24:25]
	v_max_f32_e32 v25, v26, v26
	v_max_f32_e32 v24, v30, v30
	v_max_f32_e32 v26, 0, v25
	v_max_f32_e32 v25, v31, v31
	v_max_f32_e32 v24, 0, v24
	v_max_f32_e32 v25, 0, v25
	v_max_f32_e32 v27, v27, v27
	v_max_f32_e32 v28, 0, v28
	v_max_f32_e32 v29, 0, v29
	v_max_f32_e32 v27, 0, v27
	v_pk_mul_f32 v[30:31], v[24:25], v[24:25]
	v_pk_mul_f32 v[28:29], v[28:29], v[28:29]
	v_pk_mul_f32 v[34:35], v[26:27], v[26:27]
	v_cvt_pk_bf16_f32 v25, v30, v31
	v_add_co_u32_e32 v30, vcc, s78, v120
	v_max_f32_e32 v16, v16, v16
	v_max_f32_e32 v17, v17, v17
	v_cvt_pk_bf16_f32 v24, v28, v29
	v_cvt_pk_bf16_f32 v26, v32, v33
	v_cvt_pk_bf16_f32 v27, v34, v35
	v_addc_co_u32_e32 v31, vcc, 0, v121, vcc
	v_max_f32_e32 v16, 0, v16
	v_max_f32_e32 v17, 0, v17
	global_store_dwordx4 v[30:31], v[24:27], off
	v_max_f32_e32 v20, v20, v20
	v_max_f32_e32 v21, v21, v21
	v_pk_mul_f32 v[24:25], v[16:17], v[16:17]
	v_max_f32_e32 v17, v18, v18
	v_max_f32_e32 v16, v22, v22
	v_max_f32_e32 v18, 0, v17
	v_max_f32_e32 v17, v23, v23
	v_max_f32_e32 v19, v19, v19
	v_max_f32_e32 v20, 0, v20
	v_max_f32_e32 v21, 0, v21
	v_max_f32_e32 v16, 0, v16
	v_max_f32_e32 v17, 0, v17
	v_max_f32_e32 v19, 0, v19
	v_pk_mul_f32 v[20:21], v[20:21], v[20:21]
	v_pk_mul_f32 v[22:23], v[16:17], v[16:17]
	v_pk_mul_f32 v[26:27], v[18:19], v[18:19]
	v_max_f32_e32 v8, v8, v8
	v_max_f32_e32 v9, v9, v9
	v_lshl_add_u64 v[28:29], v[120:121], 0, s[12:13]
	v_cvt_pk_bf16_f32 v16, v20, v21
	v_cvt_pk_bf16_f32 v17, v22, v23
	v_cvt_pk_bf16_f32 v18, v24, v25
	v_cvt_pk_bf16_f32 v19, v26, v27
	v_max_f32_e32 v8, 0, v8
	v_max_f32_e32 v9, 0, v9
	global_store_dwordx4 v[28:29], v[16:19], off offset:256
	v_max_f32_e32 v12, v12, v12
	v_max_f32_e32 v13, v13, v13
	v_pk_mul_f32 v[16:17], v[8:9], v[8:9]
	v_max_f32_e32 v9, v10, v10
	v_max_f32_e32 v8, v14, v14
	v_max_f32_e32 v10, 0, v9
	v_max_f32_e32 v9, v15, v15
	v_max_f32_e32 v8, 0, v8
	v_max_f32_e32 v9, 0, v9
	v_max_f32_e32 v11, v11, v11
	v_max_f32_e32 v12, 0, v12
	v_max_f32_e32 v13, 0, v13
	v_max_f32_e32 v11, 0, v11
	v_pk_mul_f32 v[14:15], v[8:9], v[8:9]
	v_pk_mul_f32 v[12:13], v[12:13], v[12:13]
	v_pk_mul_f32 v[18:19], v[10:11], v[10:11]
	v_cvt_pk_bf16_f32 v9, v14, v15
	v_add_co_u32_e32 v14, vcc, s79, v120
	v_max_f32_e32 v0, v0, v0
	v_max_f32_e32 v1, v1, v1
	v_cvt_pk_bf16_f32 v8, v12, v13
	v_cvt_pk_bf16_f32 v10, v16, v17
	v_cvt_pk_bf16_f32 v11, v18, v19
	v_addc_co_u32_e32 v15, vcc, 0, v121, vcc
	v_max_f32_e32 v0, 0, v0
	v_max_f32_e32 v1, 0, v1
	global_store_dwordx4 v[14:15], v[8:11], off
	v_max_f32_e32 v4, v4, v4
	v_max_f32_e32 v5, v5, v5
	v_pk_mul_f32 v[8:9], v[0:1], v[0:1]
	v_max_f32_e32 v1, v2, v2
	v_max_f32_e32 v0, v6, v6
	v_max_f32_e32 v2, 0, v1
	v_max_f32_e32 v1, v7, v7
	v_max_f32_e32 v3, v3, v3
	v_max_f32_e32 v4, 0, v4
	v_max_f32_e32 v5, 0, v5
	v_max_f32_e32 v0, 0, v0
	v_max_f32_e32 v1, 0, v1
	v_max_f32_e32 v3, 0, v3
	v_pk_mul_f32 v[4:5], v[4:5], v[4:5]
	v_pk_mul_f32 v[6:7], v[0:1], v[0:1]
	v_pk_mul_f32 v[10:11], v[2:3], v[2:3]
	v_lshl_add_u64 v[12:13], v[120:121], 0, s[14:15]
	v_cvt_pk_bf16_f32 v0, v4, v5
	v_cvt_pk_bf16_f32 v1, v6, v7
	v_cvt_pk_bf16_f32 v2, v8, v9
	v_cvt_pk_bf16_f32 v3, v10, v11
	s_and_b64 vcc, exec, s[4:5]
	s_mov_b32 s80, s16
	s_mov_b32 s28, s18
	s_mov_b64 s[34:35], s[26:27]
	s_mov_b64 s[30:31], s[20:21]
	global_store_dwordx4 v[12:13], v[0:3], off offset:256
	s_cbranch_vccz .LBB0_676
	s_waitcnt vmcnt(16)
	s_cmpk_gt_u32 s56, 0xff
	s_cbranch_scc1 .LBB0_687
	s_barrier

.LBB0_776:
	ds_read_b128 v[156:159], v152
	ds_read_b128 v[160:163], v152 offset:1024
	ds_read_b128 v[164:167], v152 offset:2048
	ds_read_b128 v[168:171], v152 offset:3072
	s_add_u32 s34, s30, 0xfff00080
	s_addc_u32 s35, s31, -1
	s_cmp_eq_u32 s85, 60
	s_cselect_b32 s55, s21, s35
	s_cselect_b32 s54, s81, s34
	s_cselect_b32 s35, s19, s84
	s_cselect_b32 s34, s82, s83
	v_lshl_add_u64 v[204:205], s[30:31], 0, v[138:139]
	s_add_i32 m0, s17, 0xc000
	ds_read_b128 v[172:175], v153
	ds_read_b128 v[176:179], v153 offset:1024
	ds_read_b128 v[180:183], v153 offset:2048
	ds_read_b128 v[184:187], v153 offset:3072
	ds_read_b128 v[188:191], v153 offset:4096
	ds_read_b128 v[192:195], v153 offset:5120
	ds_read_b128 v[196:199], v153 offset:6144
	ds_read_b128 v[200:203], v153 offset:7168
	global_load_lds_dwordx4 v[204:205], off
	v_lshl_add_u64 v[204:205], s[30:31], 0, v[140:141]
	s_add_i32 m0, s17, 0xe000
	s_nop 0
	global_load_lds_dwordx4 v[204:205], off
	s_waitcnt lgkmcnt(8)
	s_barrier
	s_waitcnt lgkmcnt(0)
	s_waitcnt lgkmcnt(0)
	v_mfma_f32_16x16x32_bf16 v[124:127], v[156:159], v[172:175], v[124:127]
	v_mfma_f32_16x16x32_bf16 v[120:123], v[164:167], v[172:175], v[120:123]
	v_mfma_f32_16x16x32_bf16 v[116:119], v[156:159], v[180:183], v[116:119]
	v_mfma_f32_16x16x32_bf16 v[112:115], v[164:167], v[180:183], v[112:115]
	v_mfma_f32_16x16x32_bf16 v[100:103], v[156:159], v[188:191], v[100:103]
	v_mfma_f32_16x16x32_bf16 v[96:99], v[164:167], v[188:191], v[96:99]
	v_mfma_f32_16x16x32_bf16 v[84:87], v[156:159], v[196:199], v[84:87]
	v_mfma_f32_16x16x32_bf16 v[80:83], v[164:167], v[196:199], v[80:83]
	v_mfma_f32_16x16x32_bf16 v[124:127], v[160:163], v[176:179], v[124:127]
	v_mfma_f32_16x16x32_bf16 v[120:123], v[168:171], v[176:179], v[120:123]
	v_mfma_f32_16x16x32_bf16 v[116:119], v[160:163], v[184:187], v[116:119]
	v_mfma_f32_16x16x32_bf16 v[112:115], v[168:171], v[184:187], v[112:115]
	v_mfma_f32_16x16x32_bf16 v[100:103], v[160:163], v[192:195], v[100:103]
	v_mfma_f32_16x16x32_bf16 v[96:99], v[168:171], v[192:195], v[96:99]
	v_mfma_f32_16x16x32_bf16 v[84:87], v[160:163], v[200:203], v[84:87]
	v_mfma_f32_16x16x32_bf16 v[80:83], v[168:171], v[200:203], v[80:83]
	s_barrier
	s_add_i32 s86, s74, s57
	v_lshl_add_u64 v[220:221], s[34:35], 0, v[134:135]
	s_mov_b32 m0, s86
	ds_read_b128 v[204:207], v154
	ds_read_b128 v[208:211], v154 offset:1024
	ds_read_b128 v[212:215], v154 offset:2048
	ds_read_b128 v[216:219], v154 offset:3072
	global_load_lds_dwordx4 v[220:221], off
	v_lshl_add_u64 v[222:223], s[34:35], 0, v[130:131]
	s_add_i32 m0, s86, 0x2000
	s_nop 0
	global_load_lds_dwordx4 v[222:223], off
	s_barrier
	s_waitcnt lgkmcnt(0)
	s_waitcnt lgkmcnt(0)
	v_mfma_f32_16x16x32_bf16 v[108:111], v[204:207], v[172:175], v[108:111]
	v_mfma_f32_16x16x32_bf16 v[104:107], v[212:215], v[172:175], v[104:107]
	v_mfma_f32_16x16x32_bf16 v[92:95], v[204:207], v[180:183], v[92:95]
	v_mfma_f32_16x16x32_bf16 v[88:91], v[212:215], v[180:183], v[88:91]
	v_mfma_f32_16x16x32_bf16 v[76:79], v[204:207], v[188:191], v[76:79]
	v_mfma_f32_16x16x32_bf16 v[72:75], v[212:215], v[188:191], v[72:75]
	v_mfma_f32_16x16x32_bf16 v[68:71], v[204:207], v[196:199], v[68:71]
	v_mfma_f32_16x16x32_bf16 v[64:67], v[212:215], v[196:199], v[64:67]
	v_mfma_f32_16x16x32_bf16 v[108:111], v[208:211], v[176:179], v[108:111]
	v_mfma_f32_16x16x32_bf16 v[104:107], v[216:219], v[176:179], v[104:107]
	v_mfma_f32_16x16x32_bf16 v[92:95], v[208:211], v[184:187], v[92:95]
	v_mfma_f32_16x16x32_bf16 v[88:91], v[216:219], v[184:187], v[88:91]
	v_mfma_f32_16x16x32_bf16 v[76:79], v[208:211], v[192:195], v[76:79]
	v_mfma_f32_16x16x32_bf16 v[72:75], v[216:219], v[192:195], v[72:75]
	v_mfma_f32_16x16x32_bf16 v[68:71], v[208:211], v[200:203], v[68:71]
	v_mfma_f32_16x16x32_bf16 v[64:67], v[216:219], v[200:203], v[64:67]
	s_mov_b32 m0, s17
	v_lshl_add_u64 v[224:225], s[54:55], 0, v[136:137]
	s_barrier
	ds_read_b128 v[172:175], v153 offset:16384
	ds_read_b128 v[176:179], v153 offset:17408
	ds_read_b128 v[180:183], v153 offset:18432
	ds_read_b128 v[184:187], v153 offset:19456
	ds_read_b128 v[188:191], v153 offset:20480
	ds_read_b128 v[192:195], v153 offset:21504
	ds_read_b128 v[196:199], v153 offset:22528
	ds_read_b128 v[200:203], v153 offset:23552
	global_load_lds_dwordx4 v[224:225], off
	v_lshl_add_u64 v[226:227], s[54:55], 0, v[132:133]
	s_mov_b32 m0, s61
	s_nop 0
	global_load_lds_dwordx4 v[226:227], off
	s_barrier
	s_waitcnt lgkmcnt(0)
	s_waitcnt lgkmcnt(0)
	v_mfma_f32_16x16x32_bf16 v[60:63], v[156:159], v[172:175], v[60:63]
	v_mfma_f32_16x16x32_bf16 v[56:59], v[164:167], v[172:175], v[56:59]
	v_mfma_f32_16x16x32_bf16 v[52:55], v[156:159], v[180:183], v[52:55]
	v_mfma_f32_16x16x32_bf16 v[48:51], v[164:167], v[180:183], v[48:51]
	v_mfma_f32_16x16x32_bf16 v[36:39], v[156:159], v[188:191], v[36:39]
	v_mfma_f32_16x16x32_bf16 v[32:35], v[164:167], v[188:191], v[32:35]
	v_mfma_f32_16x16x32_bf16 v[20:23], v[156:159], v[196:199], v[20:23]
	v_mfma_f32_16x16x32_bf16 v[16:19], v[164:167], v[196:199], v[16:19]
	v_mfma_f32_16x16x32_bf16 v[60:63], v[160:163], v[176:179], v[60:63]
	v_mfma_f32_16x16x32_bf16 v[56:59], v[168:171], v[176:179], v[56:59]
	v_mfma_f32_16x16x32_bf16 v[52:55], v[160:163], v[184:187], v[52:55]
	v_mfma_f32_16x16x32_bf16 v[48:51], v[168:171], v[184:187], v[48:51]
	v_mfma_f32_16x16x32_bf16 v[36:39], v[160:163], v[192:195], v[36:39]
	v_mfma_f32_16x16x32_bf16 v[32:35], v[168:171], v[192:195], v[32:35]
	v_mfma_f32_16x16x32_bf16 v[20:23], v[160:163], v[200:203], v[20:23]
	v_mfma_f32_16x16x32_bf16 v[16:19], v[168:171], v[200:203], v[16:19]
	s_barrier
	s_add_u32 s86, s34, 0x100000
	s_addc_u32 s87, s35, 0
	s_add_i32 s88, s75, s57
	v_lshl_add_u64 v[156:157], s[86:87], 0, v[134:135]
	s_mov_b32 m0, s88
	s_nop 0
	global_load_lds_dwordx4 v[156:157], off
	v_lshl_add_u64 v[156:157], s[86:87], 0, v[130:131]
	s_add_i32 m0, s88, 0x2000
	s_nop 0
	global_load_lds_dwordx4 v[156:157], off
	s_waitcnt vmcnt(6)
	s_barrier
	v_mfma_f32_16x16x32_bf16 v[44:47], v[204:207], v[172:175], v[44:47]
	v_mfma_f32_16x16x32_bf16 v[40:43], v[212:215], v[172:175], v[40:43]
	v_mfma_f32_16x16x32_bf16 v[28:31], v[204:207], v[180:183], v[28:31]
	v_mfma_f32_16x16x32_bf16 v[24:27], v[212:215], v[180:183], v[24:27]
	v_mfma_f32_16x16x32_bf16 v[12:15], v[204:207], v[188:191], v[12:15]
	v_mfma_f32_16x16x32_bf16 v[8:11], v[212:215], v[188:191], v[8:11]
	v_mfma_f32_16x16x32_bf16 v[4:7], v[204:207], v[196:199], v[4:7]
	v_mfma_f32_16x16x32_bf16 v[0:3], v[212:215], v[196:199], v[0:3]
	v_mfma_f32_16x16x32_bf16 v[44:47], v[208:211], v[176:179], v[44:47]
	v_mfma_f32_16x16x32_bf16 v[40:43], v[216:219], v[176:179], v[40:43]
	v_mfma_f32_16x16x32_bf16 v[28:31], v[208:211], v[184:187], v[28:31]
	v_mfma_f32_16x16x32_bf16 v[24:27], v[216:219], v[184:187], v[24:27]
	v_mfma_f32_16x16x32_bf16 v[12:15], v[208:211], v[192:195], v[12:15]
	v_mfma_f32_16x16x32_bf16 v[8:11], v[216:219], v[192:195], v[8:11]
	v_mfma_f32_16x16x32_bf16 v[4:7], v[208:211], v[200:203], v[4:7]
	v_mfma_f32_16x16x32_bf16 v[0:3], v[216:219], v[200:203], v[0:3]
	s_add_i32 s86, 0, 0x18000
	v_add_u32_e32 v155, s86, v150
	s_barrier
	ds_read_b128 v[156:159], v155
	ds_read_b128 v[160:163], v155 offset:1024
	ds_read_b128 v[164:167], v155 offset:2048
	ds_read_b128 v[168:171], v155 offset:3072
	s_add_u32 s54, s54, 0x100000
	s_addc_u32 s55, s55, 0
	s_mov_b32 m0, s62
	v_lshl_add_u64 v[204:205], s[54:55], 0, v[136:137]
	ds_read_b128 v[172:175], v153 offset:32768
	ds_read_b128 v[176:179], v153 offset:33792
	ds_read_b128 v[180:183], v153 offset:34816
	ds_read_b128 v[184:187], v153 offset:35840
	ds_read_b128 v[188:191], v153 offset:36864
	ds_read_b128 v[192:195], v153 offset:37888
	ds_read_b128 v[196:199], v153 offset:38912
	ds_read_b128 v[200:203], v153 offset:39936
	global_load_lds_dwordx4 v[204:205], off
	v_lshl_add_u64 v[204:205], s[54:55], 0, v[132:133]
	s_mov_b32 m0, s63
	s_nop 0
	global_load_lds_dwordx4 v[204:205], off
	s_waitcnt lgkmcnt(8)
	s_barrier
	s_waitcnt lgkmcnt(0)
	s_waitcnt lgkmcnt(0)
	v_mfma_f32_16x16x32_bf16 v[124:127], v[156:159], v[172:175], v[124:127]
	v_mfma_f32_16x16x32_bf16 v[120:123], v[164:167], v[172:175], v[120:123]
	v_mfma_f32_16x16x32_bf16 v[116:119], v[156:159], v[180:183], v[116:119]
	v_mfma_f32_16x16x32_bf16 v[112:115], v[164:167], v[180:183], v[112:115]
	v_mfma_f32_16x16x32_bf16 v[100:103], v[156:159], v[188:191], v[100:103]
	v_mfma_f32_16x16x32_bf16 v[96:99], v[164:167], v[188:191], v[96:99]
	v_mfma_f32_16x16x32_bf16 v[84:87], v[156:159], v[196:199], v[84:87]
	v_mfma_f32_16x16x32_bf16 v[80:83], v[164:167], v[196:199], v[80:83]
	v_mfma_f32_16x16x32_bf16 v[124:127], v[160:163], v[176:179], v[124:127]
	v_mfma_f32_16x16x32_bf16 v[120:123], v[168:171], v[176:179], v[120:123]
	v_mfma_f32_16x16x32_bf16 v[116:119], v[160:163], v[184:187], v[116:119]
	v_mfma_f32_16x16x32_bf16 v[112:115], v[168:171], v[184:187], v[112:115]
	v_mfma_f32_16x16x32_bf16 v[100:103], v[160:163], v[192:195], v[100:103]
	v_mfma_f32_16x16x32_bf16 v[96:99], v[168:171], v[192:195], v[96:99]
	v_mfma_f32_16x16x32_bf16 v[84:87], v[160:163], v[200:203], v[84:87]
	v_mfma_f32_16x16x32_bf16 v[80:83], v[168:171], v[200:203], v[80:83]
	s_barrier
	s_add_i32 s54, 0, 0x1c000
	s_add_i32 s55, s86, s57
	v_add_u32_e32 v155, s54, v150
	v_lshl_add_u64 v[220:221], v[220:221], 0, s[8:9]
	s_mov_b32 m0, s55
	ds_read_b128 v[204:207], v155
	ds_read_b128 v[208:211], v155 offset:1024
	ds_read_b128 v[212:215], v155 offset:2048
	ds_read_b128 v[216:219], v155 offset:3072
	global_load_lds_dwordx4 v[220:221], off
	v_lshl_add_u64 v[220:221], v[222:223], 0, s[8:9]
	s_add_i32 m0, s55, 0x2000
	s_nop 0
	global_load_lds_dwordx4 v[220:221], off
	s_barrier
	s_waitcnt lgkmcnt(0)
	s_waitcnt lgkmcnt(0)
	v_mfma_f32_16x16x32_bf16 v[108:111], v[204:207], v[172:175], v[108:111]
	v_mfma_f32_16x16x32_bf16 v[104:107], v[212:215], v[172:175], v[104:107]
	v_mfma_f32_16x16x32_bf16 v[92:95], v[204:207], v[180:183], v[92:95]
	v_mfma_f32_16x16x32_bf16 v[88:91], v[212:215], v[180:183], v[88:91]
	v_mfma_f32_16x16x32_bf16 v[76:79], v[204:207], v[188:191], v[76:79]
	v_mfma_f32_16x16x32_bf16 v[72:75], v[212:215], v[188:191], v[72:75]
	v_mfma_f32_16x16x32_bf16 v[68:71], v[204:207], v[196:199], v[68:71]
	v_mfma_f32_16x16x32_bf16 v[64:67], v[212:215], v[196:199], v[64:67]
	v_mfma_f32_16x16x32_bf16 v[108:111], v[208:211], v[176:179], v[108:111]
	v_mfma_f32_16x16x32_bf16 v[104:107], v[216:219], v[176:179], v[104:107]
	v_mfma_f32_16x16x32_bf16 v[92:95], v[208:211], v[184:187], v[92:95]
	v_mfma_f32_16x16x32_bf16 v[88:91], v[216:219], v[184:187], v[88:91]
	v_mfma_f32_16x16x32_bf16 v[76:79], v[208:211], v[192:195], v[76:79]
	v_mfma_f32_16x16x32_bf16 v[72:75], v[216:219], v[192:195], v[72:75]
	v_mfma_f32_16x16x32_bf16 v[68:71], v[208:211], v[200:203], v[68:71]
	v_mfma_f32_16x16x32_bf16 v[64:67], v[216:219], v[200:203], v[64:67]
	s_mov_b32 m0, s71
	v_lshl_add_u64 v[220:221], v[224:225], 0, s[8:9]
	s_barrier
	ds_read_b128 v[172:175], v153 offset:49152
	ds_read_b128 v[176:179], v153 offset:50176
	ds_read_b128 v[180:183], v153 offset:51200
	ds_read_b128 v[184:187], v153 offset:52224
	ds_read_b128 v[188:191], v153 offset:53248
	ds_read_b128 v[192:195], v153 offset:54272
	ds_read_b128 v[196:199], v153 offset:55296
	ds_read_b128 v[200:203], v153 offset:56320
	global_load_lds_dwordx4 v[220:221], off
	v_lshl_add_u64 v[220:221], v[226:227], 0, s[8:9]
	s_mov_b32 m0, s72
	s_nop 0
	global_load_lds_dwordx4 v[220:221], off
	s_barrier
	s_waitcnt lgkmcnt(0)
	s_waitcnt lgkmcnt(0)
	v_mfma_f32_16x16x32_bf16 v[60:63], v[156:159], v[172:175], v[60:63]
	v_mfma_f32_16x16x32_bf16 v[56:59], v[164:167], v[172:175], v[56:59]
	v_mfma_f32_16x16x32_bf16 v[52:55], v[156:159], v[180:183], v[52:55]
	v_mfma_f32_16x16x32_bf16 v[48:51], v[164:167], v[180:183], v[48:51]
	v_mfma_f32_16x16x32_bf16 v[36:39], v[156:159], v[188:191], v[36:39]
	v_mfma_f32_16x16x32_bf16 v[32:35], v[164:167], v[188:191], v[32:35]
	v_mfma_f32_16x16x32_bf16 v[20:23], v[156:159], v[196:199], v[20:23]
	v_mfma_f32_16x16x32_bf16 v[16:19], v[164:167], v[196:199], v[16:19]
	v_mfma_f32_16x16x32_bf16 v[60:63], v[160:163], v[176:179], v[60:63]
	v_mfma_f32_16x16x32_bf16 v[56:59], v[168:171], v[176:179], v[56:59]
	v_mfma_f32_16x16x32_bf16 v[52:55], v[160:163], v[184:187], v[52:55]
	v_mfma_f32_16x16x32_bf16 v[48:51], v[168:171], v[184:187], v[48:51]
	v_mfma_f32_16x16x32_bf16 v[36:39], v[160:163], v[192:195], v[36:39]
	v_mfma_f32_16x16x32_bf16 v[32:35], v[168:171], v[192:195], v[32:35]
	v_mfma_f32_16x16x32_bf16 v[20:23], v[160:163], v[200:203], v[20:23]
	v_mfma_f32_16x16x32_bf16 v[16:19], v[168:171], v[200:203], v[16:19]
	s_barrier
	s_add_u32 s34, s34, 0x100080
	s_addc_u32 s35, s35, 0
	s_add_i32 s54, s54, s57
	v_lshl_add_u64 v[156:157], s[34:35], 0, v[134:135]
	s_mov_b32 m0, s54
	s_nop 0
	global_load_lds_dwordx4 v[156:157], off
	v_lshl_add_u64 v[156:157], s[34:35], 0, v[130:131]
	s_add_i32 m0, s54, 0x2000
	s_nop 0
	global_load_lds_dwordx4 v[156:157], off
	s_waitcnt vmcnt(6)
	s_barrier
	v_mfma_f32_16x16x32_bf16 v[44:47], v[204:207], v[172:175], v[44:47]
	v_mfma_f32_16x16x32_bf16 v[40:43], v[212:215], v[172:175], v[40:43]
	v_mfma_f32_16x16x32_bf16 v[28:31], v[204:207], v[180:183], v[28:31]
	v_mfma_f32_16x16x32_bf16 v[24:27], v[212:215], v[180:183], v[24:27]
	v_mfma_f32_16x16x32_bf16 v[12:15], v[204:207], v[188:191], v[12:15]
	v_mfma_f32_16x16x32_bf16 v[8:11], v[212:215], v[188:191], v[8:11]
	v_mfma_f32_16x16x32_bf16 v[4:7], v[204:207], v[196:199], v[4:7]
	v_mfma_f32_16x16x32_bf16 v[0:3], v[212:215], v[196:199], v[0:3]
	v_mfma_f32_16x16x32_bf16 v[44:47], v[208:211], v[176:179], v[44:47]
	v_mfma_f32_16x16x32_bf16 v[40:43], v[216:219], v[176:179], v[40:43]
	v_mfma_f32_16x16x32_bf16 v[28:31], v[208:211], v[184:187], v[28:31]
	v_mfma_f32_16x16x32_bf16 v[24:27], v[216:219], v[184:187], v[24:27]
	v_mfma_f32_16x16x32_bf16 v[12:15], v[208:211], v[192:195], v[12:15]
	v_mfma_f32_16x16x32_bf16 v[8:11], v[216:219], v[192:195], v[8:11]
	v_mfma_f32_16x16x32_bf16 v[4:7], v[208:211], v[200:203], v[4:7]
	v_mfma_f32_16x16x32_bf16 v[0:3], v[216:219], v[200:203], v[0:3]
	s_add_i32 s85, s85, 2
	s_add_u32 s30, s30, 0x100
	s_addc_u32 s31, s31, 0
	s_add_u32 s83, s83, 0x100
	s_addc_u32 s84, s84, 0
	s_cmp_gt_u32 s85, 61
	s_barrier
	s_cbranch_scc0 .LBB0_776
	v_lshl_add_u32 v156, s16, 8, v149
	v_lshl_or_b32 v158, s80, 8, v151
	v_ashrrev_i32_e32 v157, 31, v156
	v_lshlrev_b64 v[160:161], 11, v[156:157]
	v_ashrrev_i32_e32 v159, 31, v158
	v_lshl_add_u64 v[160:161], s[44:45], 0, v[160:161]
	v_cvt_pk_bf16_f32 v124, v124, v125
	v_cvt_pk_bf16_f32 v125, v126, v127
	v_cvt_pk_bf16_f32 v126, v120, v121
	v_lshlrev_b64 v[120:121], 1, v[158:159]
	v_cvt_pk_bf16_f32 v127, v122, v123
	v_lshl_add_u64 v[122:123], v[160:161], 0, v[120:121]
	v_cvt_pk_bf16_f32 v108, v108, v109
	v_cvt_pk_bf16_f32 v109, v110, v111
	v_cvt_pk_bf16_f32 v110, v104, v105
	v_or_b32_e32 v104, 16, v156
	v_cvt_pk_bf16_f32 v60, v60, v61
	v_cvt_pk_bf16_f32 v61, v62, v63
	v_cvt_pk_bf16_f32 v63, v58, v59
	s_mov_b64 s[30:31], 0x40000
	v_add_co_u32_e32 v58, vcc, s76, v122
	v_ashrrev_i32_e32 v105, 31, v104
	v_cvt_pk_bf16_f32 v62, v56, v57
	v_lshl_add_u64 v[56:57], v[122:123], 0, s[30:31]
	v_addc_co_u32_e32 v59, vcc, 0, v123, vcc
	v_cvt_pk_bf16_f32 v44, v44, v45
	v_cvt_pk_bf16_f32 v45, v46, v47
	v_cvt_pk_bf16_f32 v46, v40, v41
	v_cvt_pk_bf16_f32 v47, v42, v43
	v_cvt_pk_bf16_f32 v111, v106, v107
	v_lshlrev_b64 v[104:105], 11, v[104:105]
	v_cvt_pk_bf16_f32 v92, v92, v93
	v_cvt_pk_bf16_f32 v93, v94, v95
	v_cvt_pk_bf16_f32 v94, v88, v89
	v_or_b32_e32 v88, 32, v156
	global_store_dwordx4 v[56:57], v[44:47], off offset:256
	global_store_dwordx4 v[122:123], v[108:111], off offset:256
	v_ashrrev_i32_e32 v89, 31, v88
	v_add_co_u32_e32 v46, vcc, s77, v122
	v_lshl_add_u64 v[108:109], s[44:45], 0, v[104:105]
	v_lshl_add_u64 v[44:45], v[122:123], 0, s[10:11]
	v_addc_co_u32_e32 v47, vcc, 0, v123, vcc
	v_cvt_pk_bf16_f32 v28, v28, v29
	v_cvt_pk_bf16_f32 v29, v30, v31
	v_cvt_pk_bf16_f32 v30, v24, v25
	v_cvt_pk_bf16_f32 v31, v26, v27
	v_lshl_add_u64 v[108:109], v[108:109], 0, v[120:121]
	v_cvt_pk_bf16_f32 v95, v90, v91
	v_lshlrev_b64 v[88:89], 11, v[88:89]
	v_cvt_pk_bf16_f32 v76, v76, v77
	v_cvt_pk_bf16_f32 v77, v78, v79
	v_cvt_pk_bf16_f32 v78, v72, v73
	v_or_b32_e32 v72, 48, v156
	global_store_dwordx4 v[44:45], v[28:31], off offset:256
	global_store_dwordx4 v[108:109], v[92:95], off offset:256
	v_ashrrev_i32_e32 v73, 31, v72
	v_add_co_u32_e32 v30, vcc, s78, v122
	v_lshl_add_u64 v[92:93], s[44:45], 0, v[88:89]
	v_lshl_add_u64 v[28:29], v[122:123], 0, s[12:13]
	v_addc_co_u32_e32 v31, vcc, 0, v123, vcc
	v_cvt_pk_bf16_f32 v12, v12, v13
	v_cvt_pk_bf16_f32 v13, v14, v15
	v_cvt_pk_bf16_f32 v14, v8, v9
	v_cvt_pk_bf16_f32 v15, v10, v11
	v_lshl_add_u64 v[92:93], v[92:93], 0, v[120:121]
	v_cvt_pk_bf16_f32 v79, v74, v75
	v_lshlrev_b64 v[72:73], 11, v[72:73]
	global_store_dwordx4 v[28:29], v[12:15], off offset:256
	global_store_dwordx4 v[92:93], v[76:79], off offset:256
	v_cvt_pk_bf16_f32 v104, v116, v117
	v_add_co_u32_e32 v14, vcc, s79, v122
	v_lshl_add_u64 v[76:77], s[44:45], 0, v[72:73]
	s_nop 0
	v_addc_co_u32_e32 v15, vcc, 0, v123, vcc
	v_cvt_pk_bf16_f32 v105, v118, v119
	v_cvt_pk_bf16_f32 v106, v112, v113
	v_cvt_pk_bf16_f32 v107, v114, v115
	v_cvt_pk_bf16_f32 v88, v100, v101
	v_cvt_pk_bf16_f32 v89, v102, v103
	v_cvt_pk_bf16_f32 v90, v96, v97
	v_cvt_pk_bf16_f32 v91, v98, v99
	v_cvt_pk_bf16_f32 v72, v84, v85
	v_cvt_pk_bf16_f32 v73, v86, v87
	v_cvt_pk_bf16_f32 v74, v80, v81
	v_cvt_pk_bf16_f32 v75, v82, v83
	v_lshl_add_u64 v[76:77], v[76:77], 0, v[120:121]
	v_cvt_pk_bf16_f32 v68, v68, v69
	v_cvt_pk_bf16_f32 v69, v70, v71
	v_cvt_pk_bf16_f32 v70, v64, v65
	v_cvt_pk_bf16_f32 v71, v66, v67
	v_cvt_pk_bf16_f32 v40, v52, v53
	v_cvt_pk_bf16_f32 v41, v54, v55
	v_cvt_pk_bf16_f32 v42, v48, v49
	v_cvt_pk_bf16_f32 v43, v50, v51
	v_cvt_pk_bf16_f32 v24, v36, v37
	v_cvt_pk_bf16_f32 v25, v38, v39
	v_cvt_pk_bf16_f32 v26, v32, v33
	v_cvt_pk_bf16_f32 v27, v34, v35
	v_cvt_pk_bf16_f32 v8, v20, v21
	v_cvt_pk_bf16_f32 v9, v22, v23
	v_cvt_pk_bf16_f32 v10, v16, v17
	v_cvt_pk_bf16_f32 v11, v18, v19
	v_lshl_add_u64 v[12:13], v[122:123], 0, s[14:15]
	v_cvt_pk_bf16_f32 v4, v4, v5
	v_cvt_pk_bf16_f32 v5, v6, v7
	v_cvt_pk_bf16_f32 v6, v0, v1
	v_cvt_pk_bf16_f32 v7, v2, v3
	s_and_b64 vcc, exec, s[4:5]
	s_mov_b32 s80, s18
	s_mov_b32 s16, s20
	s_mov_b64 s[34:35], s[28:29]
	s_mov_b64 s[30:31], s[26:27]
	global_store_dwordx4 v[122:123], v[124:127], off
	global_store_dwordx4 v[108:109], v[104:107], off
	global_store_dwordx4 v[92:93], v[88:91], off
	global_store_dwordx4 v[76:77], v[72:75], off
	global_store_dwordx4 v[76:77], v[68:71], off offset:256
	global_store_dwordx4 v[58:59], v[60:63], off
	global_store_dwordx4 v[46:47], v[40:43], off
	global_store_dwordx4 v[30:31], v[24:27], off
	global_store_dwordx4 v[14:15], v[8:11], off
	global_store_dwordx4 v[12:13], v[4:7], off offset:256
	s_cbranch_vccz .LBB0_773
	s_waitcnt vmcnt(16)
	s_cmpk_gt_u32 s56, 0xff
	s_cbranch_scc1 .LBB0_780
	s_barrier

.LBB0_912:
	ds_read_b128 v[156:159], v152
	ds_read_b128 v[160:163], v152 offset:1024
	ds_read_b128 v[164:167], v152 offset:2048
	ds_read_b128 v[168:171], v152 offset:3072
	s_add_u32 s54, s34, 0xfffc0080
	s_addc_u32 s55, s35, -1
	s_cmp_eq_u32 s87, 12
	s_cselect_b32 s57, s27, s55
	s_cselect_b32 s56, s83, s54
	s_cselect_b32 s55, s21, s86
	s_cselect_b32 s54, s84, s85
	v_lshl_add_u64 v[204:205], s[34:35], 0, v[138:139]
	s_add_i32 m0, s19, 0xc000
	ds_read_b128 v[172:175], v153
	ds_read_b128 v[176:179], v153 offset:1024
	ds_read_b128 v[180:183], v153 offset:2048
	ds_read_b128 v[184:187], v153 offset:3072
	ds_read_b128 v[188:191], v153 offset:4096
	ds_read_b128 v[192:195], v153 offset:5120
	ds_read_b128 v[196:199], v153 offset:6144
	ds_read_b128 v[200:203], v153 offset:7168
	global_load_lds_dwordx4 v[204:205], off
	v_lshl_add_u64 v[204:205], s[34:35], 0, v[140:141]
	s_add_i32 m0, s19, 0xe000
	s_nop 0
	global_load_lds_dwordx4 v[204:205], off
	s_waitcnt lgkmcnt(8)
	s_barrier
	s_waitcnt lgkmcnt(0)
	s_waitcnt lgkmcnt(0)
	v_mfma_f32_16x16x32_bf16 v[124:127], v[156:159], v[172:175], v[124:127]
	v_mfma_f32_16x16x32_bf16 v[120:123], v[164:167], v[172:175], v[120:123]
	v_mfma_f32_16x16x32_bf16 v[116:119], v[156:159], v[180:183], v[116:119]
	v_mfma_f32_16x16x32_bf16 v[112:115], v[164:167], v[180:183], v[112:115]
	v_mfma_f32_16x16x32_bf16 v[100:103], v[156:159], v[188:191], v[100:103]
	v_mfma_f32_16x16x32_bf16 v[96:99], v[164:167], v[188:191], v[96:99]
	v_mfma_f32_16x16x32_bf16 v[84:87], v[156:159], v[196:199], v[84:87]
	v_mfma_f32_16x16x32_bf16 v[80:83], v[164:167], v[196:199], v[80:83]
	v_mfma_f32_16x16x32_bf16 v[124:127], v[160:163], v[176:179], v[124:127]
	v_mfma_f32_16x16x32_bf16 v[120:123], v[168:171], v[176:179], v[120:123]
	v_mfma_f32_16x16x32_bf16 v[116:119], v[160:163], v[184:187], v[116:119]
	v_mfma_f32_16x16x32_bf16 v[112:115], v[168:171], v[184:187], v[112:115]
	v_mfma_f32_16x16x32_bf16 v[100:103], v[160:163], v[192:195], v[100:103]
	v_mfma_f32_16x16x32_bf16 v[96:99], v[168:171], v[192:195], v[96:99]
	v_mfma_f32_16x16x32_bf16 v[84:87], v[160:163], v[200:203], v[84:87]
	v_mfma_f32_16x16x32_bf16 v[80:83], v[168:171], v[200:203], v[80:83]
	s_barrier
	s_add_i32 s88, s76, s61
	v_lshl_add_u64 v[220:221], s[54:55], 0, v[134:135]
	s_mov_b32 m0, s88
	ds_read_b128 v[204:207], v154
	ds_read_b128 v[208:211], v154 offset:1024
	ds_read_b128 v[212:215], v154 offset:2048
	ds_read_b128 v[216:219], v154 offset:3072
	global_load_lds_dwordx4 v[220:221], off
	v_lshl_add_u64 v[222:223], s[54:55], 0, v[130:131]
	s_add_i32 m0, s88, 0x2000
	s_nop 0
	global_load_lds_dwordx4 v[222:223], off
	s_barrier
	s_waitcnt lgkmcnt(0)
	s_waitcnt lgkmcnt(0)
	v_mfma_f32_16x16x32_bf16 v[108:111], v[204:207], v[172:175], v[108:111]
	v_mfma_f32_16x16x32_bf16 v[104:107], v[212:215], v[172:175], v[104:107]
	v_mfma_f32_16x16x32_bf16 v[92:95], v[204:207], v[180:183], v[92:95]
	v_mfma_f32_16x16x32_bf16 v[88:91], v[212:215], v[180:183], v[88:91]
	v_mfma_f32_16x16x32_bf16 v[76:79], v[204:207], v[188:191], v[76:79]
	v_mfma_f32_16x16x32_bf16 v[72:75], v[212:215], v[188:191], v[72:75]
	v_mfma_f32_16x16x32_bf16 v[68:71], v[204:207], v[196:199], v[68:71]
	v_mfma_f32_16x16x32_bf16 v[64:67], v[212:215], v[196:199], v[64:67]
	v_mfma_f32_16x16x32_bf16 v[108:111], v[208:211], v[176:179], v[108:111]
	v_mfma_f32_16x16x32_bf16 v[104:107], v[216:219], v[176:179], v[104:107]
	v_mfma_f32_16x16x32_bf16 v[92:95], v[208:211], v[184:187], v[92:95]
	v_mfma_f32_16x16x32_bf16 v[88:91], v[216:219], v[184:187], v[88:91]
	v_mfma_f32_16x16x32_bf16 v[76:79], v[208:211], v[192:195], v[76:79]
	v_mfma_f32_16x16x32_bf16 v[72:75], v[216:219], v[192:195], v[72:75]
	v_mfma_f32_16x16x32_bf16 v[68:71], v[208:211], v[200:203], v[68:71]
	v_mfma_f32_16x16x32_bf16 v[64:67], v[216:219], v[200:203], v[64:67]
	s_mov_b32 m0, s19
	v_lshl_add_u64 v[224:225], s[56:57], 0, v[136:137]
	s_barrier
	ds_read_b128 v[172:175], v153 offset:16384
	ds_read_b128 v[176:179], v153 offset:17408
	ds_read_b128 v[180:183], v153 offset:18432
	ds_read_b128 v[184:187], v153 offset:19456
	ds_read_b128 v[188:191], v153 offset:20480
	ds_read_b128 v[192:195], v153 offset:21504
	ds_read_b128 v[196:199], v153 offset:22528
	ds_read_b128 v[200:203], v153 offset:23552
	global_load_lds_dwordx4 v[224:225], off
	v_lshl_add_u64 v[226:227], s[56:57], 0, v[132:133]
	s_mov_b32 m0, s63
	s_nop 0
	global_load_lds_dwordx4 v[226:227], off
	s_barrier
	s_waitcnt lgkmcnt(0)
	s_waitcnt lgkmcnt(0)
	v_mfma_f32_16x16x32_bf16 v[60:63], v[156:159], v[172:175], v[60:63]
	v_mfma_f32_16x16x32_bf16 v[56:59], v[164:167], v[172:175], v[56:59]
	v_mfma_f32_16x16x32_bf16 v[52:55], v[156:159], v[180:183], v[52:55]
	v_mfma_f32_16x16x32_bf16 v[48:51], v[164:167], v[180:183], v[48:51]
	v_mfma_f32_16x16x32_bf16 v[36:39], v[156:159], v[188:191], v[36:39]
	v_mfma_f32_16x16x32_bf16 v[32:35], v[164:167], v[188:191], v[32:35]
	v_mfma_f32_16x16x32_bf16 v[20:23], v[156:159], v[196:199], v[20:23]
	v_mfma_f32_16x16x32_bf16 v[16:19], v[164:167], v[196:199], v[16:19]
	v_mfma_f32_16x16x32_bf16 v[60:63], v[160:163], v[176:179], v[60:63]
	v_mfma_f32_16x16x32_bf16 v[56:59], v[168:171], v[176:179], v[56:59]
	v_mfma_f32_16x16x32_bf16 v[52:55], v[160:163], v[184:187], v[52:55]
	v_mfma_f32_16x16x32_bf16 v[48:51], v[168:171], v[184:187], v[48:51]
	v_mfma_f32_16x16x32_bf16 v[36:39], v[160:163], v[192:195], v[36:39]
	v_mfma_f32_16x16x32_bf16 v[32:35], v[168:171], v[192:195], v[32:35]
	v_mfma_f32_16x16x32_bf16 v[20:23], v[160:163], v[200:203], v[20:23]
	v_mfma_f32_16x16x32_bf16 v[16:19], v[168:171], v[200:203], v[16:19]
	s_barrier
	s_add_u32 s88, s54, 0x40000
	s_addc_u32 s89, s55, 0
	s_add_i32 s90, s77, s61
	v_lshl_add_u64 v[156:157], s[88:89], 0, v[134:135]
	s_mov_b32 m0, s90
	s_nop 0
	global_load_lds_dwordx4 v[156:157], off
	v_lshl_add_u64 v[156:157], s[88:89], 0, v[130:131]
	s_add_i32 m0, s90, 0x2000
	s_nop 0
	global_load_lds_dwordx4 v[156:157], off
	s_waitcnt vmcnt(6)
	s_barrier
	v_mfma_f32_16x16x32_bf16 v[44:47], v[204:207], v[172:175], v[44:47]
	v_mfma_f32_16x16x32_bf16 v[40:43], v[212:215], v[172:175], v[40:43]
	v_mfma_f32_16x16x32_bf16 v[28:31], v[204:207], v[180:183], v[28:31]
	v_mfma_f32_16x16x32_bf16 v[24:27], v[212:215], v[180:183], v[24:27]
	v_mfma_f32_16x16x32_bf16 v[12:15], v[204:207], v[188:191], v[12:15]
	v_mfma_f32_16x16x32_bf16 v[8:11], v[212:215], v[188:191], v[8:11]
	v_mfma_f32_16x16x32_bf16 v[4:7], v[204:207], v[196:199], v[4:7]
	v_mfma_f32_16x16x32_bf16 v[0:3], v[212:215], v[196:199], v[0:3]
	v_mfma_f32_16x16x32_bf16 v[44:47], v[208:211], v[176:179], v[44:47]
	v_mfma_f32_16x16x32_bf16 v[40:43], v[216:219], v[176:179], v[40:43]
	v_mfma_f32_16x16x32_bf16 v[28:31], v[208:211], v[184:187], v[28:31]
	v_mfma_f32_16x16x32_bf16 v[24:27], v[216:219], v[184:187], v[24:27]
	v_mfma_f32_16x16x32_bf16 v[12:15], v[208:211], v[192:195], v[12:15]
	v_mfma_f32_16x16x32_bf16 v[8:11], v[216:219], v[192:195], v[8:11]
	v_mfma_f32_16x16x32_bf16 v[4:7], v[208:211], v[200:203], v[4:7]
	v_mfma_f32_16x16x32_bf16 v[0:3], v[216:219], v[200:203], v[0:3]
	s_add_i32 s88, 0, 0x18000
	v_add_u32_e32 v155, s88, v150
	s_barrier
	ds_read_b128 v[156:159], v155
	ds_read_b128 v[160:163], v155 offset:1024
	ds_read_b128 v[164:167], v155 offset:2048
	ds_read_b128 v[168:171], v155 offset:3072
	s_add_u32 s56, s56, 0x40000
	s_addc_u32 s57, s57, 0
	s_mov_b32 m0, s70
	v_lshl_add_u64 v[204:205], s[56:57], 0, v[136:137]
	ds_read_b128 v[172:175], v153 offset:32768
	ds_read_b128 v[176:179], v153 offset:33792
	ds_read_b128 v[180:183], v153 offset:34816
	ds_read_b128 v[184:187], v153 offset:35840
	ds_read_b128 v[188:191], v153 offset:36864
	ds_read_b128 v[192:195], v153 offset:37888
	ds_read_b128 v[196:199], v153 offset:38912
	ds_read_b128 v[200:203], v153 offset:39936
	global_load_lds_dwordx4 v[204:205], off
	v_lshl_add_u64 v[204:205], s[56:57], 0, v[132:133]
	s_mov_b32 m0, s71
	s_nop 0
	global_load_lds_dwordx4 v[204:205], off
	s_waitcnt lgkmcnt(8)
	s_barrier
	s_waitcnt lgkmcnt(0)
	s_waitcnt lgkmcnt(0)
	v_mfma_f32_16x16x32_bf16 v[124:127], v[156:159], v[172:175], v[124:127]
	v_mfma_f32_16x16x32_bf16 v[120:123], v[164:167], v[172:175], v[120:123]
	v_mfma_f32_16x16x32_bf16 v[116:119], v[156:159], v[180:183], v[116:119]
	v_mfma_f32_16x16x32_bf16 v[112:115], v[164:167], v[180:183], v[112:115]
	v_mfma_f32_16x16x32_bf16 v[100:103], v[156:159], v[188:191], v[100:103]
	v_mfma_f32_16x16x32_bf16 v[96:99], v[164:167], v[188:191], v[96:99]
	v_mfma_f32_16x16x32_bf16 v[84:87], v[156:159], v[196:199], v[84:87]
	v_mfma_f32_16x16x32_bf16 v[80:83], v[164:167], v[196:199], v[80:83]
	v_mfma_f32_16x16x32_bf16 v[124:127], v[160:163], v[176:179], v[124:127]
	v_mfma_f32_16x16x32_bf16 v[120:123], v[168:171], v[176:179], v[120:123]
	v_mfma_f32_16x16x32_bf16 v[116:119], v[160:163], v[184:187], v[116:119]
	v_mfma_f32_16x16x32_bf16 v[112:115], v[168:171], v[184:187], v[112:115]
	v_mfma_f32_16x16x32_bf16 v[100:103], v[160:163], v[192:195], v[100:103]
	v_mfma_f32_16x16x32_bf16 v[96:99], v[168:171], v[192:195], v[96:99]
	v_mfma_f32_16x16x32_bf16 v[84:87], v[160:163], v[200:203], v[84:87]
	v_mfma_f32_16x16x32_bf16 v[80:83], v[168:171], v[200:203], v[80:83]
	s_barrier
	s_add_i32 s56, 0, 0x1c000
	s_add_i32 s57, s88, s61
	v_add_u32_e32 v155, s56, v150
	v_lshl_add_u64 v[220:221], v[220:221], 0, s[10:11]
	s_mov_b32 m0, s57
	ds_read_b128 v[204:207], v155
	ds_read_b128 v[208:211], v155 offset:1024
	ds_read_b128 v[212:215], v155 offset:2048
	ds_read_b128 v[216:219], v155 offset:3072
	global_load_lds_dwordx4 v[220:221], off
	v_lshl_add_u64 v[220:221], v[222:223], 0, s[10:11]
	s_add_i32 m0, s57, 0x2000
	s_nop 0
	global_load_lds_dwordx4 v[220:221], off
	s_barrier
	s_waitcnt lgkmcnt(0)
	s_waitcnt lgkmcnt(0)
	v_mfma_f32_16x16x32_bf16 v[108:111], v[204:207], v[172:175], v[108:111]
	v_mfma_f32_16x16x32_bf16 v[104:107], v[212:215], v[172:175], v[104:107]
	v_mfma_f32_16x16x32_bf16 v[92:95], v[204:207], v[180:183], v[92:95]
	v_mfma_f32_16x16x32_bf16 v[88:91], v[212:215], v[180:183], v[88:91]
	v_mfma_f32_16x16x32_bf16 v[76:79], v[204:207], v[188:191], v[76:79]
	v_mfma_f32_16x16x32_bf16 v[72:75], v[212:215], v[188:191], v[72:75]
	v_mfma_f32_16x16x32_bf16 v[68:71], v[204:207], v[196:199], v[68:71]
	v_mfma_f32_16x16x32_bf16 v[64:67], v[212:215], v[196:199], v[64:67]
	v_mfma_f32_16x16x32_bf16 v[108:111], v[208:211], v[176:179], v[108:111]
	v_mfma_f32_16x16x32_bf16 v[104:107], v[216:219], v[176:179], v[104:107]
	v_mfma_f32_16x16x32_bf16 v[92:95], v[208:211], v[184:187], v[92:95]
	v_mfma_f32_16x16x32_bf16 v[88:91], v[216:219], v[184:187], v[88:91]
	v_mfma_f32_16x16x32_bf16 v[76:79], v[208:211], v[192:195], v[76:79]
	v_mfma_f32_16x16x32_bf16 v[72:75], v[216:219], v[192:195], v[72:75]
	v_mfma_f32_16x16x32_bf16 v[68:71], v[208:211], v[200:203], v[68:71]
	v_mfma_f32_16x16x32_bf16 v[64:67], v[216:219], v[200:203], v[64:67]
	s_mov_b32 m0, s73
	v_lshl_add_u64 v[220:221], v[224:225], 0, s[10:11]
	s_barrier
	ds_read_b128 v[172:175], v153 offset:49152
	ds_read_b128 v[176:179], v153 offset:50176
	ds_read_b128 v[180:183], v153 offset:51200
	ds_read_b128 v[184:187], v153 offset:52224
	ds_read_b128 v[188:191], v153 offset:53248
	ds_read_b128 v[192:195], v153 offset:54272
	ds_read_b128 v[196:199], v153 offset:55296
	ds_read_b128 v[200:203], v153 offset:56320
	global_load_lds_dwordx4 v[220:221], off
	v_lshl_add_u64 v[220:221], v[226:227], 0, s[10:11]
	s_mov_b32 m0, s74
	s_nop 0
	global_load_lds_dwordx4 v[220:221], off
	s_barrier
	s_waitcnt lgkmcnt(0)
	s_waitcnt lgkmcnt(0)
	v_mfma_f32_16x16x32_bf16 v[60:63], v[156:159], v[172:175], v[60:63]
	v_mfma_f32_16x16x32_bf16 v[56:59], v[164:167], v[172:175], v[56:59]
	v_mfma_f32_16x16x32_bf16 v[52:55], v[156:159], v[180:183], v[52:55]
	v_mfma_f32_16x16x32_bf16 v[48:51], v[164:167], v[180:183], v[48:51]
	v_mfma_f32_16x16x32_bf16 v[36:39], v[156:159], v[188:191], v[36:39]
	v_mfma_f32_16x16x32_bf16 v[32:35], v[164:167], v[188:191], v[32:35]
	v_mfma_f32_16x16x32_bf16 v[20:23], v[156:159], v[196:199], v[20:23]
	v_mfma_f32_16x16x32_bf16 v[16:19], v[164:167], v[196:199], v[16:19]
	v_mfma_f32_16x16x32_bf16 v[60:63], v[160:163], v[176:179], v[60:63]
	v_mfma_f32_16x16x32_bf16 v[56:59], v[168:171], v[176:179], v[56:59]
	v_mfma_f32_16x16x32_bf16 v[52:55], v[160:163], v[184:187], v[52:55]
	v_mfma_f32_16x16x32_bf16 v[48:51], v[168:171], v[184:187], v[48:51]
	v_mfma_f32_16x16x32_bf16 v[36:39], v[160:163], v[192:195], v[36:39]
	v_mfma_f32_16x16x32_bf16 v[32:35], v[168:171], v[192:195], v[32:35]
	v_mfma_f32_16x16x32_bf16 v[20:23], v[160:163], v[200:203], v[20:23]
	v_mfma_f32_16x16x32_bf16 v[16:19], v[168:171], v[200:203], v[16:19]
	s_barrier
	s_add_u32 s54, s54, 0x40080
	s_addc_u32 s55, s55, 0
	s_add_i32 s56, s56, s61
	v_lshl_add_u64 v[156:157], s[54:55], 0, v[134:135]
	s_mov_b32 m0, s56
	s_nop 0
	global_load_lds_dwordx4 v[156:157], off
	v_lshl_add_u64 v[156:157], s[54:55], 0, v[130:131]
	s_add_i32 m0, s56, 0x2000
	s_nop 0
	global_load_lds_dwordx4 v[156:157], off
	s_waitcnt vmcnt(6)
	s_barrier
	v_mfma_f32_16x16x32_bf16 v[44:47], v[204:207], v[172:175], v[44:47]
	v_mfma_f32_16x16x32_bf16 v[40:43], v[212:215], v[172:175], v[40:43]
	v_mfma_f32_16x16x32_bf16 v[28:31], v[204:207], v[180:183], v[28:31]
	v_mfma_f32_16x16x32_bf16 v[24:27], v[212:215], v[180:183], v[24:27]
	v_mfma_f32_16x16x32_bf16 v[12:15], v[204:207], v[188:191], v[12:15]
	v_mfma_f32_16x16x32_bf16 v[8:11], v[212:215], v[188:191], v[8:11]
	v_mfma_f32_16x16x32_bf16 v[4:7], v[204:207], v[196:199], v[4:7]
	v_mfma_f32_16x16x32_bf16 v[0:3], v[212:215], v[196:199], v[0:3]
	v_mfma_f32_16x16x32_bf16 v[44:47], v[208:211], v[176:179], v[44:47]
	v_mfma_f32_16x16x32_bf16 v[40:43], v[216:219], v[176:179], v[40:43]
	v_mfma_f32_16x16x32_bf16 v[28:31], v[208:211], v[184:187], v[28:31]
	v_mfma_f32_16x16x32_bf16 v[24:27], v[216:219], v[184:187], v[24:27]
	v_mfma_f32_16x16x32_bf16 v[12:15], v[208:211], v[192:195], v[12:15]
	v_mfma_f32_16x16x32_bf16 v[8:11], v[216:219], v[192:195], v[8:11]
	v_mfma_f32_16x16x32_bf16 v[4:7], v[208:211], v[200:203], v[4:7]
	v_mfma_f32_16x16x32_bf16 v[0:3], v[216:219], v[200:203], v[0:3]
	s_add_i32 s87, s87, 2
	s_add_u32 s34, s34, 0x100
	s_addc_u32 s35, s35, 0
	s_add_u32 s85, s85, 0x100
	s_addc_u32 s86, s86, 0
	s_cmp_gt_u32 s87, 13
	s_barrier
	s_cbranch_scc0 .LBB0_912
	v_lshl_add_u32 v156, s18, 8, v149
	v_lshl_or_b32 v158, s82, 8, v151
	v_ashrrev_i32_e32 v157, 31, v156
	v_lshlrev_b64 v[160:161], 11, v[156:157]
	v_ashrrev_i32_e32 v159, 31, v158
	v_lshl_add_u64 v[160:161], s[46:47], 0, v[160:161]
	v_cvt_pk_bf16_f32 v124, v124, v125
	v_cvt_pk_bf16_f32 v125, v126, v127
	v_cvt_pk_bf16_f32 v126, v120, v121
	v_lshlrev_b64 v[120:121], 1, v[158:159]
	v_cvt_pk_bf16_f32 v127, v122, v123
	v_lshl_add_u64 v[122:123], v[160:161], 0, v[120:121]
	v_cvt_pk_bf16_f32 v108, v108, v109
	v_cvt_pk_bf16_f32 v109, v110, v111
	v_cvt_pk_bf16_f32 v110, v104, v105
	v_or_b32_e32 v104, 16, v156
	v_cvt_pk_bf16_f32 v60, v60, v61
	v_cvt_pk_bf16_f32 v61, v62, v63
	v_cvt_pk_bf16_f32 v63, v58, v59
	v_add_co_u32_e32 v58, vcc, s78, v122
	v_ashrrev_i32_e32 v105, 31, v104
	v_cvt_pk_bf16_f32 v62, v56, v57
	v_lshl_add_u64 v[56:57], v[122:123], 0, s[8:9]
	v_addc_co_u32_e32 v59, vcc, 0, v123, vcc
	v_cvt_pk_bf16_f32 v44, v44, v45
	v_cvt_pk_bf16_f32 v45, v46, v47
	v_cvt_pk_bf16_f32 v46, v40, v41
	v_cvt_pk_bf16_f32 v47, v42, v43
	v_cvt_pk_bf16_f32 v111, v106, v107
	v_lshlrev_b64 v[104:105], 11, v[104:105]
	v_cvt_pk_bf16_f32 v92, v92, v93
	v_cvt_pk_bf16_f32 v93, v94, v95
	v_cvt_pk_bf16_f32 v94, v88, v89
	v_or_b32_e32 v88, 32, v156
	global_store_dwordx4 v[56:57], v[44:47], off offset:256
	global_store_dwordx4 v[122:123], v[108:111], off offset:256
	v_ashrrev_i32_e32 v89, 31, v88
	v_add_co_u32_e32 v46, vcc, s79, v122
	v_lshl_add_u64 v[108:109], s[46:47], 0, v[104:105]
	v_lshl_add_u64 v[44:45], v[122:123], 0, s[12:13]
	v_addc_co_u32_e32 v47, vcc, 0, v123, vcc
	v_cvt_pk_bf16_f32 v28, v28, v29
	v_cvt_pk_bf16_f32 v29, v30, v31
	v_cvt_pk_bf16_f32 v30, v24, v25
	v_cvt_pk_bf16_f32 v31, v26, v27
	v_lshl_add_u64 v[108:109], v[108:109], 0, v[120:121]
	v_cvt_pk_bf16_f32 v95, v90, v91
	v_lshlrev_b64 v[88:89], 11, v[88:89]
	v_cvt_pk_bf16_f32 v76, v76, v77
	v_cvt_pk_bf16_f32 v77, v78, v79
	v_cvt_pk_bf16_f32 v78, v72, v73
	v_or_b32_e32 v72, 48, v156
	global_store_dwordx4 v[44:45], v[28:31], off offset:256
	global_store_dwordx4 v[108:109], v[92:95], off offset:256
	v_ashrrev_i32_e32 v73, 31, v72
	v_add_co_u32_e32 v30, vcc, s80, v122
	v_lshl_add_u64 v[92:93], s[46:47], 0, v[88:89]
	v_lshl_add_u64 v[28:29], v[122:123], 0, s[14:15]
	v_addc_co_u32_e32 v31, vcc, 0, v123, vcc
	v_cvt_pk_bf16_f32 v12, v12, v13
	v_cvt_pk_bf16_f32 v13, v14, v15
	v_cvt_pk_bf16_f32 v14, v8, v9
	v_cvt_pk_bf16_f32 v15, v10, v11
	v_lshl_add_u64 v[92:93], v[92:93], 0, v[120:121]
	v_cvt_pk_bf16_f32 v79, v74, v75
	v_lshlrev_b64 v[72:73], 11, v[72:73]
	global_store_dwordx4 v[28:29], v[12:15], off offset:256
	global_store_dwordx4 v[92:93], v[76:79], off offset:256
	v_cvt_pk_bf16_f32 v104, v116, v117
	v_add_co_u32_e32 v14, vcc, s81, v122
	v_lshl_add_u64 v[76:77], s[46:47], 0, v[72:73]
	s_nop 0
	v_addc_co_u32_e32 v15, vcc, 0, v123, vcc
	v_cvt_pk_bf16_f32 v105, v118, v119
	v_cvt_pk_bf16_f32 v106, v112, v113
	v_cvt_pk_bf16_f32 v107, v114, v115
	v_cvt_pk_bf16_f32 v88, v100, v101
	v_cvt_pk_bf16_f32 v89, v102, v103
	v_cvt_pk_bf16_f32 v90, v96, v97
	v_cvt_pk_bf16_f32 v91, v98, v99
	v_cvt_pk_bf16_f32 v72, v84, v85
	v_cvt_pk_bf16_f32 v73, v86, v87
	v_cvt_pk_bf16_f32 v74, v80, v81
	v_cvt_pk_bf16_f32 v75, v82, v83
	v_lshl_add_u64 v[76:77], v[76:77], 0, v[120:121]
	v_cvt_pk_bf16_f32 v68, v68, v69
	v_cvt_pk_bf16_f32 v69, v70, v71
	v_cvt_pk_bf16_f32 v70, v64, v65
	v_cvt_pk_bf16_f32 v71, v66, v67
	v_cvt_pk_bf16_f32 v40, v52, v53
	v_cvt_pk_bf16_f32 v41, v54, v55
	v_cvt_pk_bf16_f32 v42, v48, v49
	v_cvt_pk_bf16_f32 v43, v50, v51
	v_cvt_pk_bf16_f32 v24, v36, v37
	v_cvt_pk_bf16_f32 v25, v38, v39
	v_cvt_pk_bf16_f32 v26, v32, v33
	v_cvt_pk_bf16_f32 v27, v34, v35
	v_cvt_pk_bf16_f32 v8, v20, v21
	v_cvt_pk_bf16_f32 v9, v22, v23
	v_cvt_pk_bf16_f32 v10, v16, v17
	v_cvt_pk_bf16_f32 v11, v18, v19
	v_lshl_add_u64 v[12:13], v[122:123], 0, s[16:17]
	v_cvt_pk_bf16_f32 v4, v4, v5
	v_cvt_pk_bf16_f32 v5, v6, v7
	v_cvt_pk_bf16_f32 v6, v0, v1
	v_cvt_pk_bf16_f32 v7, v2, v3
	s_and_b64 vcc, exec, s[4:5]
	s_mov_b32 s82, s20
	s_mov_b32 s18, s26
	s_mov_b64 s[54:55], s[30:31]
	s_mov_b64 s[34:35], s[28:29]
	global_store_dwordx4 v[122:123], v[124:127], off
	global_store_dwordx4 v[108:109], v[104:107], off
	global_store_dwordx4 v[92:93], v[88:91], off
	global_store_dwordx4 v[76:77], v[72:75], off
	global_store_dwordx4 v[76:77], v[68:71], off offset:256
	global_store_dwordx4 v[58:59], v[60:63], off
	global_store_dwordx4 v[46:47], v[40:43], off
	global_store_dwordx4 v[30:31], v[24:27], off
	global_store_dwordx4 v[14:15], v[8:11], off
	global_store_dwordx4 v[12:13], v[4:7], off offset:256
	s_cbranch_vccz .LBB0_909
	s_waitcnt vmcnt(16)
	s_cmpk_gt_u32 s60, 0xff
	s_cbranch_scc1 .LBB0_916
	s_barrier

.LBB0_1116:
	ds_read_b128 v[154:157], v150
	ds_read_b128 v[158:161], v150 offset:1024
	ds_read_b128 v[162:165], v150 offset:2048
	ds_read_b128 v[166:169], v150 offset:3072
	s_add_u32 s34, s30, 0xfffc0080
	s_addc_u32 s35, s31, -1
	s_cmp_eq_u32 s77, 12
	s_cselect_b32 s37, s19, s35
	s_cselect_b32 s36, s73, s34
	s_cselect_b32 s35, s17, s76
	s_cselect_b32 s34, s74, s75
	v_lshl_add_u64 v[202:203], s[30:31], 0, v[134:135]
	s_add_i32 m0, s29, 0xc000
	ds_read_b128 v[170:173], v151
	ds_read_b128 v[174:177], v151 offset:1024
	ds_read_b128 v[178:181], v151 offset:2048
	ds_read_b128 v[182:185], v151 offset:3072
	ds_read_b128 v[186:189], v151 offset:4096
	ds_read_b128 v[190:193], v151 offset:5120
	ds_read_b128 v[194:197], v151 offset:6144
	ds_read_b128 v[198:201], v151 offset:7168
	global_load_lds_dwordx4 v[202:203], off
	v_lshl_add_u64 v[202:203], s[30:31], 0, v[136:137]
	s_add_i32 m0, s29, 0xe000
	s_nop 0
	global_load_lds_dwordx4 v[202:203], off
	s_waitcnt lgkmcnt(8)
	s_barrier
	s_waitcnt lgkmcnt(0)
	s_waitcnt lgkmcnt(0)
	v_mfma_f32_16x16x32_bf16 v[120:123], v[154:157], v[170:173], v[120:123]
	v_mfma_f32_16x16x32_bf16 v[124:127], v[162:165], v[170:173], v[124:127]
	v_mfma_f32_16x16x32_bf16 v[104:107], v[154:157], v[178:181], v[104:107]
	v_mfma_f32_16x16x32_bf16 v[108:111], v[162:165], v[178:181], v[108:111]
	v_mfma_f32_16x16x32_bf16 v[88:91], v[154:157], v[186:189], v[88:91]
	v_mfma_f32_16x16x32_bf16 v[92:95], v[162:165], v[186:189], v[92:95]
	v_mfma_f32_16x16x32_bf16 v[72:75], v[154:157], v[194:197], v[72:75]
	v_mfma_f32_16x16x32_bf16 v[76:79], v[162:165], v[194:197], v[76:79]
	v_mfma_f32_16x16x32_bf16 v[120:123], v[158:161], v[174:177], v[120:123]
	v_mfma_f32_16x16x32_bf16 v[124:127], v[166:169], v[174:177], v[124:127]
	v_mfma_f32_16x16x32_bf16 v[104:107], v[158:161], v[182:185], v[104:107]
	v_mfma_f32_16x16x32_bf16 v[108:111], v[166:169], v[182:185], v[108:111]
	v_mfma_f32_16x16x32_bf16 v[88:91], v[158:161], v[190:193], v[88:91]
	v_mfma_f32_16x16x32_bf16 v[92:95], v[166:169], v[190:193], v[92:95]
	v_mfma_f32_16x16x32_bf16 v[72:75], v[158:161], v[198:201], v[72:75]
	v_mfma_f32_16x16x32_bf16 v[76:79], v[166:169], v[198:201], v[76:79]
	s_barrier
	s_add_i32 s78, s60, s42
	v_lshl_add_u64 v[218:219], s[34:35], 0, v[130:131]
	s_mov_b32 m0, s78
	ds_read_b128 v[202:205], v152
	ds_read_b128 v[206:209], v152 offset:1024
	ds_read_b128 v[210:213], v152 offset:2048
	ds_read_b128 v[214:217], v152 offset:3072
	global_load_lds_dwordx4 v[218:219], off
	v_lshl_add_u64 v[220:221], s[34:35], 0, v[132:133]
	s_add_i32 m0, s78, 0x2000
	s_nop 0
	global_load_lds_dwordx4 v[220:221], off
	s_barrier
	s_waitcnt lgkmcnt(0)
	s_waitcnt lgkmcnt(0)
	v_mfma_f32_16x16x32_bf16 v[112:115], v[202:205], v[170:173], v[112:115]
	v_mfma_f32_16x16x32_bf16 v[116:119], v[210:213], v[170:173], v[116:119]
	v_mfma_f32_16x16x32_bf16 v[96:99], v[202:205], v[178:181], v[96:99]
	v_mfma_f32_16x16x32_bf16 v[100:103], v[210:213], v[178:181], v[100:103]
	v_mfma_f32_16x16x32_bf16 v[80:83], v[202:205], v[186:189], v[80:83]
	v_mfma_f32_16x16x32_bf16 v[84:87], v[210:213], v[186:189], v[84:87]
	v_mfma_f32_16x16x32_bf16 v[64:67], v[202:205], v[194:197], v[64:67]
	v_mfma_f32_16x16x32_bf16 v[68:71], v[210:213], v[194:197], v[68:71]
	v_mfma_f32_16x16x32_bf16 v[112:115], v[206:209], v[174:177], v[112:115]
	v_mfma_f32_16x16x32_bf16 v[116:119], v[214:217], v[174:177], v[116:119]
	v_mfma_f32_16x16x32_bf16 v[96:99], v[206:209], v[182:185], v[96:99]
	v_mfma_f32_16x16x32_bf16 v[100:103], v[214:217], v[182:185], v[100:103]
	v_mfma_f32_16x16x32_bf16 v[80:83], v[206:209], v[190:193], v[80:83]
	v_mfma_f32_16x16x32_bf16 v[84:87], v[214:217], v[190:193], v[84:87]
	v_mfma_f32_16x16x32_bf16 v[64:67], v[206:209], v[198:201], v[64:67]
	v_mfma_f32_16x16x32_bf16 v[68:71], v[214:217], v[198:201], v[68:71]
	s_mov_b32 m0, s29
	v_lshl_add_u64 v[222:223], s[36:37], 0, v[130:131]
	s_barrier
	ds_read_b128 v[170:173], v151 offset:16384
	ds_read_b128 v[174:177], v151 offset:17408
	ds_read_b128 v[178:181], v151 offset:18432
	ds_read_b128 v[182:185], v151 offset:19456
	ds_read_b128 v[186:189], v151 offset:20480
	ds_read_b128 v[190:193], v151 offset:21504
	ds_read_b128 v[194:197], v151 offset:22528
	ds_read_b128 v[198:201], v151 offset:23552
	global_load_lds_dwordx4 v[222:223], off
	v_lshl_add_u64 v[224:225], s[36:37], 0, v[132:133]
	s_mov_b32 m0, s43
	s_nop 0
	global_load_lds_dwordx4 v[224:225], off
	s_barrier
	s_waitcnt lgkmcnt(0)
	s_waitcnt lgkmcnt(0)
	v_mfma_f32_16x16x32_bf16 v[56:59], v[154:157], v[170:173], v[56:59]
	v_mfma_f32_16x16x32_bf16 v[60:63], v[162:165], v[170:173], v[60:63]
	v_mfma_f32_16x16x32_bf16 v[40:43], v[154:157], v[178:181], v[40:43]
	v_mfma_f32_16x16x32_bf16 v[44:47], v[162:165], v[178:181], v[44:47]
	v_mfma_f32_16x16x32_bf16 v[24:27], v[154:157], v[186:189], v[24:27]
	v_mfma_f32_16x16x32_bf16 v[28:31], v[162:165], v[186:189], v[28:31]
	v_mfma_f32_16x16x32_bf16 v[8:11], v[154:157], v[194:197], v[8:11]
	v_mfma_f32_16x16x32_bf16 v[12:15], v[162:165], v[194:197], v[12:15]
	v_mfma_f32_16x16x32_bf16 v[56:59], v[158:161], v[174:177], v[56:59]
	v_mfma_f32_16x16x32_bf16 v[60:63], v[166:169], v[174:177], v[60:63]
	v_mfma_f32_16x16x32_bf16 v[40:43], v[158:161], v[182:185], v[40:43]
	v_mfma_f32_16x16x32_bf16 v[44:47], v[166:169], v[182:185], v[44:47]
	v_mfma_f32_16x16x32_bf16 v[24:27], v[158:161], v[190:193], v[24:27]
	v_mfma_f32_16x16x32_bf16 v[28:31], v[166:169], v[190:193], v[28:31]
	v_mfma_f32_16x16x32_bf16 v[8:11], v[158:161], v[198:201], v[8:11]
	v_mfma_f32_16x16x32_bf16 v[12:15], v[166:169], v[198:201], v[12:15]
	s_barrier
	s_add_u32 s78, s34, 0x40000
	s_addc_u32 s79, s35, 0
	s_add_i32 s80, s61, s42
	v_lshl_add_u64 v[154:155], s[78:79], 0, v[130:131]
	s_mov_b32 m0, s80
	s_nop 0
	global_load_lds_dwordx4 v[154:155], off
	v_lshl_add_u64 v[154:155], s[78:79], 0, v[132:133]
	s_add_i32 m0, s80, 0x2000
	s_nop 0
	global_load_lds_dwordx4 v[154:155], off
	s_waitcnt vmcnt(6)
	s_barrier
	v_mfma_f32_16x16x32_bf16 v[48:51], v[202:205], v[170:173], v[48:51]
	v_mfma_f32_16x16x32_bf16 v[52:55], v[210:213], v[170:173], v[52:55]
	v_mfma_f32_16x16x32_bf16 v[32:35], v[202:205], v[178:181], v[32:35]
	v_mfma_f32_16x16x32_bf16 v[36:39], v[210:213], v[178:181], v[36:39]
	v_mfma_f32_16x16x32_bf16 v[16:19], v[202:205], v[186:189], v[16:19]
	v_mfma_f32_16x16x32_bf16 v[20:23], v[210:213], v[186:189], v[20:23]
	v_mfma_f32_16x16x32_bf16 v[0:3], v[202:205], v[194:197], v[0:3]
	v_mfma_f32_16x16x32_bf16 v[4:7], v[210:213], v[194:197], v[4:7]
	v_mfma_f32_16x16x32_bf16 v[48:51], v[206:209], v[174:177], v[48:51]
	v_mfma_f32_16x16x32_bf16 v[52:55], v[214:217], v[174:177], v[52:55]
	v_mfma_f32_16x16x32_bf16 v[32:35], v[206:209], v[182:185], v[32:35]
	v_mfma_f32_16x16x32_bf16 v[36:39], v[214:217], v[182:185], v[36:39]
	v_mfma_f32_16x16x32_bf16 v[16:19], v[206:209], v[190:193], v[16:19]
	v_mfma_f32_16x16x32_bf16 v[20:23], v[214:217], v[190:193], v[20:23]
	v_mfma_f32_16x16x32_bf16 v[0:3], v[206:209], v[198:201], v[0:3]
	v_mfma_f32_16x16x32_bf16 v[4:7], v[214:217], v[198:201], v[4:7]
	s_add_i32 s78, 0, 0x18000
	v_add_u32_e32 v153, s78, v148
	s_barrier
	ds_read_b128 v[154:157], v153
	ds_read_b128 v[158:161], v153 offset:1024
	ds_read_b128 v[162:165], v153 offset:2048
	ds_read_b128 v[166:169], v153 offset:3072
	s_add_u32 s36, s36, 0x40000
	s_addc_u32 s37, s37, 0
	s_mov_b32 m0, s52
	v_lshl_add_u64 v[202:203], s[36:37], 0, v[130:131]
	ds_read_b128 v[170:173], v151 offset:32768
	ds_read_b128 v[174:177], v151 offset:33792
	ds_read_b128 v[178:181], v151 offset:34816
	ds_read_b128 v[182:185], v151 offset:35840
	ds_read_b128 v[186:189], v151 offset:36864
	ds_read_b128 v[190:193], v151 offset:37888
	ds_read_b128 v[194:197], v151 offset:38912
	ds_read_b128 v[198:201], v151 offset:39936
	global_load_lds_dwordx4 v[202:203], off
	v_lshl_add_u64 v[202:203], s[36:37], 0, v[132:133]
	s_mov_b32 m0, s53
	s_nop 0
	global_load_lds_dwordx4 v[202:203], off
	s_waitcnt lgkmcnt(8)
	s_barrier
	s_waitcnt lgkmcnt(0)
	s_waitcnt lgkmcnt(0)
	v_mfma_f32_16x16x32_bf16 v[120:123], v[154:157], v[170:173], v[120:123]
	v_mfma_f32_16x16x32_bf16 v[124:127], v[162:165], v[170:173], v[124:127]
	v_mfma_f32_16x16x32_bf16 v[104:107], v[154:157], v[178:181], v[104:107]
	v_mfma_f32_16x16x32_bf16 v[108:111], v[162:165], v[178:181], v[108:111]
	v_mfma_f32_16x16x32_bf16 v[88:91], v[154:157], v[186:189], v[88:91]
	v_mfma_f32_16x16x32_bf16 v[92:95], v[162:165], v[186:189], v[92:95]
	v_mfma_f32_16x16x32_bf16 v[72:75], v[154:157], v[194:197], v[72:75]
	v_mfma_f32_16x16x32_bf16 v[76:79], v[162:165], v[194:197], v[76:79]
	v_mfma_f32_16x16x32_bf16 v[120:123], v[158:161], v[174:177], v[120:123]
	v_mfma_f32_16x16x32_bf16 v[124:127], v[166:169], v[174:177], v[124:127]
	v_mfma_f32_16x16x32_bf16 v[104:107], v[158:161], v[182:185], v[104:107]
	v_mfma_f32_16x16x32_bf16 v[108:111], v[166:169], v[182:185], v[108:111]
	v_mfma_f32_16x16x32_bf16 v[88:91], v[158:161], v[190:193], v[88:91]
	v_mfma_f32_16x16x32_bf16 v[92:95], v[166:169], v[190:193], v[92:95]
	v_mfma_f32_16x16x32_bf16 v[72:75], v[158:161], v[198:201], v[72:75]
	v_mfma_f32_16x16x32_bf16 v[76:79], v[166:169], v[198:201], v[76:79]
	s_barrier
	s_add_i32 s36, 0, 0x1c000
	s_add_i32 s37, s78, s42
	v_add_u32_e32 v153, s36, v148
	v_lshl_add_u64 v[218:219], v[218:219], 0, s[8:9]
	s_mov_b32 m0, s37
	ds_read_b128 v[202:205], v153
	ds_read_b128 v[206:209], v153 offset:1024
	ds_read_b128 v[210:213], v153 offset:2048
	ds_read_b128 v[214:217], v153 offset:3072
	global_load_lds_dwordx4 v[218:219], off
	v_lshl_add_u64 v[218:219], v[220:221], 0, s[8:9]
	s_add_i32 m0, s37, 0x2000
	s_nop 0
	global_load_lds_dwordx4 v[218:219], off
	s_barrier
	s_waitcnt lgkmcnt(0)
	s_waitcnt lgkmcnt(0)
	v_mfma_f32_16x16x32_bf16 v[112:115], v[202:205], v[170:173], v[112:115]
	v_mfma_f32_16x16x32_bf16 v[116:119], v[210:213], v[170:173], v[116:119]
	v_mfma_f32_16x16x32_bf16 v[96:99], v[202:205], v[178:181], v[96:99]
	v_mfma_f32_16x16x32_bf16 v[100:103], v[210:213], v[178:181], v[100:103]
	v_mfma_f32_16x16x32_bf16 v[80:83], v[202:205], v[186:189], v[80:83]
	v_mfma_f32_16x16x32_bf16 v[84:87], v[210:213], v[186:189], v[84:87]
	v_mfma_f32_16x16x32_bf16 v[64:67], v[202:205], v[194:197], v[64:67]
	v_mfma_f32_16x16x32_bf16 v[68:71], v[210:213], v[194:197], v[68:71]
	v_mfma_f32_16x16x32_bf16 v[112:115], v[206:209], v[174:177], v[112:115]
	v_mfma_f32_16x16x32_bf16 v[116:119], v[214:217], v[174:177], v[116:119]
	v_mfma_f32_16x16x32_bf16 v[96:99], v[206:209], v[182:185], v[96:99]
	v_mfma_f32_16x16x32_bf16 v[100:103], v[214:217], v[182:185], v[100:103]
	v_mfma_f32_16x16x32_bf16 v[80:83], v[206:209], v[190:193], v[80:83]
	v_mfma_f32_16x16x32_bf16 v[84:87], v[214:217], v[190:193], v[84:87]
	v_mfma_f32_16x16x32_bf16 v[64:67], v[206:209], v[198:201], v[64:67]
	v_mfma_f32_16x16x32_bf16 v[68:71], v[214:217], v[198:201], v[68:71]
	s_mov_b32 m0, s55
	v_lshl_add_u64 v[218:219], v[222:223], 0, s[8:9]
	s_barrier
	ds_read_b128 v[170:173], v151 offset:49152
	ds_read_b128 v[174:177], v151 offset:50176
	ds_read_b128 v[178:181], v151 offset:51200
	ds_read_b128 v[182:185], v151 offset:52224
	ds_read_b128 v[186:189], v151 offset:53248
	ds_read_b128 v[190:193], v151 offset:54272
	ds_read_b128 v[194:197], v151 offset:55296
	ds_read_b128 v[198:201], v151 offset:56320
	global_load_lds_dwordx4 v[218:219], off
	v_lshl_add_u64 v[218:219], v[224:225], 0, s[8:9]
	s_mov_b32 m0, s56
	s_nop 0
	global_load_lds_dwordx4 v[218:219], off
	s_barrier
	s_waitcnt lgkmcnt(0)
	s_waitcnt lgkmcnt(0)
	v_mfma_f32_16x16x32_bf16 v[56:59], v[154:157], v[170:173], v[56:59]
	v_mfma_f32_16x16x32_bf16 v[60:63], v[162:165], v[170:173], v[60:63]
	v_mfma_f32_16x16x32_bf16 v[40:43], v[154:157], v[178:181], v[40:43]
	v_mfma_f32_16x16x32_bf16 v[44:47], v[162:165], v[178:181], v[44:47]
	v_mfma_f32_16x16x32_bf16 v[24:27], v[154:157], v[186:189], v[24:27]
	v_mfma_f32_16x16x32_bf16 v[28:31], v[162:165], v[186:189], v[28:31]
	v_mfma_f32_16x16x32_bf16 v[8:11], v[154:157], v[194:197], v[8:11]
	v_mfma_f32_16x16x32_bf16 v[12:15], v[162:165], v[194:197], v[12:15]
	v_mfma_f32_16x16x32_bf16 v[56:59], v[158:161], v[174:177], v[56:59]
	v_mfma_f32_16x16x32_bf16 v[60:63], v[166:169], v[174:177], v[60:63]
	v_mfma_f32_16x16x32_bf16 v[40:43], v[158:161], v[182:185], v[40:43]
	v_mfma_f32_16x16x32_bf16 v[44:47], v[166:169], v[182:185], v[44:47]
	v_mfma_f32_16x16x32_bf16 v[24:27], v[158:161], v[190:193], v[24:27]
	v_mfma_f32_16x16x32_bf16 v[28:31], v[166:169], v[190:193], v[28:31]
	v_mfma_f32_16x16x32_bf16 v[8:11], v[158:161], v[198:201], v[8:11]
	v_mfma_f32_16x16x32_bf16 v[12:15], v[166:169], v[198:201], v[12:15]
	s_barrier
	s_add_u32 s34, s34, 0x40080
	s_addc_u32 s35, s35, 0
	s_add_i32 s36, s36, s42
	v_lshl_add_u64 v[154:155], s[34:35], 0, v[130:131]
	s_mov_b32 m0, s36
	s_nop 0
	global_load_lds_dwordx4 v[154:155], off
	v_lshl_add_u64 v[154:155], s[34:35], 0, v[132:133]
	s_add_i32 m0, s36, 0x2000
	s_nop 0
	global_load_lds_dwordx4 v[154:155], off
	s_waitcnt vmcnt(6)
	s_barrier
	v_mfma_f32_16x16x32_bf16 v[48:51], v[202:205], v[170:173], v[48:51]
	v_mfma_f32_16x16x32_bf16 v[52:55], v[210:213], v[170:173], v[52:55]
	v_mfma_f32_16x16x32_bf16 v[32:35], v[202:205], v[178:181], v[32:35]
	v_mfma_f32_16x16x32_bf16 v[36:39], v[210:213], v[178:181], v[36:39]
	v_mfma_f32_16x16x32_bf16 v[16:19], v[202:205], v[186:189], v[16:19]
	v_mfma_f32_16x16x32_bf16 v[20:23], v[210:213], v[186:189], v[20:23]
	v_mfma_f32_16x16x32_bf16 v[0:3], v[202:205], v[194:197], v[0:3]
	v_mfma_f32_16x16x32_bf16 v[4:7], v[210:213], v[194:197], v[4:7]
	v_mfma_f32_16x16x32_bf16 v[48:51], v[206:209], v[174:177], v[48:51]
	v_mfma_f32_16x16x32_bf16 v[52:55], v[214:217], v[174:177], v[52:55]
	v_mfma_f32_16x16x32_bf16 v[32:35], v[206:209], v[182:185], v[32:35]
	v_mfma_f32_16x16x32_bf16 v[36:39], v[214:217], v[182:185], v[36:39]
	v_mfma_f32_16x16x32_bf16 v[16:19], v[206:209], v[190:193], v[16:19]
	v_mfma_f32_16x16x32_bf16 v[20:23], v[214:217], v[190:193], v[20:23]
	v_mfma_f32_16x16x32_bf16 v[0:3], v[206:209], v[198:201], v[0:3]
	v_mfma_f32_16x16x32_bf16 v[4:7], v[214:217], v[198:201], v[4:7]
	s_add_i32 s77, s77, 2
	s_add_u32 s30, s30, 0x100
	s_addc_u32 s31, s31, 0
	s_add_u32 s75, s75, 0x100
	s_addc_u32 s76, s76, 0
	s_cmp_gt_u32 s77, 13
	s_barrier
	s_cbranch_scc0 .LBB0_1116
	v_mul_f32_e32 v124, 0xbfb8aa3b, v124
	v_exp_f32_e32 v154, v124
	v_mul_f32_e32 v124, 0xbfb8aa3b, v125
	v_exp_f32_e32 v155, v124
	v_lshl_add_u32 v124, s28, 8, v145
	v_ashrrev_i32_e32 v125, 31, v124
	v_lshlrev_b64 v[158:159], 11, v[124:125]
	v_pk_add_f32 v[154:155], v[154:155], 1.0 op_sel_hi:[1,0]
	v_mul_f32_e32 v126, 0xbfb8aa3b, v126
	v_div_scale_f32 v153, s[30:31], v155, v155, v121
	v_rcp_f32_e32 v157, v153
	v_mul_f32_e32 v127, 0xbfb8aa3b, v127
	v_exp_f32_e32 v126, v126
	v_exp_f32_e32 v127, v127
	v_fma_f32 v125, -v153, v157, 1.0
	v_fmac_f32_e32 v157, v125, v157
	v_div_scale_f32 v125, vcc, v121, v155, v121
	v_mul_f32_e32 v160, v125, v157
	v_fma_f32 v161, -v153, v160, v125
	v_fmac_f32_e32 v160, v161, v157
	v_fma_f32 v125, -v153, v160, v125
	v_div_scale_f32 v153, s[30:31], v154, v154, v120
	v_rcp_f32_e32 v161, v153
	v_div_fmas_f32 v125, v125, v157, v160
	v_div_fixup_f32 v121, v125, v155, v121
	v_pk_add_f32 v[126:127], v[126:127], 1.0 op_sel_hi:[1,0]
	v_fma_f32 v125, -v153, v161, 1.0
	v_fmac_f32_e32 v161, v125, v161
	v_div_scale_f32 v125, vcc, v120, v154, v120
	v_mul_f32_e32 v155, v125, v161
	v_fma_f32 v157, -v153, v155, v125
	v_fmac_f32_e32 v155, v157, v161
	v_fma_f32 v125, -v153, v155, v125
	v_div_scale_f32 v153, s[30:31], v127, v127, v123
	v_rcp_f32_e32 v157, v153
	v_div_fmas_f32 v125, v125, v161, v155
	v_div_fixup_f32 v120, v125, v154, v120
	v_mul_f32_e32 v116, 0xbfb8aa3b, v116
	v_fma_f32 v125, -v153, v157, 1.0
	v_fmac_f32_e32 v157, v125, v157
	v_div_scale_f32 v125, vcc, v123, v127, v123
	v_mul_f32_e32 v154, v125, v157
	v_fma_f32 v155, -v153, v154, v125
	v_fmac_f32_e32 v154, v155, v157
	v_fma_f32 v125, -v153, v154, v125
	v_div_scale_f32 v153, s[30:31], v126, v126, v122
	v_rcp_f32_e32 v155, v153
	v_div_fmas_f32 v125, v125, v157, v154
	v_div_fixup_f32 v123, v125, v127, v123
	v_mul_f32_e32 v117, 0xbfb8aa3b, v117
	v_fma_f32 v125, -v153, v155, 1.0
	v_fmac_f32_e32 v155, v125, v155
	v_div_scale_f32 v125, vcc, v122, v126, v122
	v_mul_f32_e32 v127, v125, v155
	v_fma_f32 v154, -v153, v127, v125
	v_exp_f32_e32 v116, v116
	v_exp_f32_e32 v117, v117
	v_fmac_f32_e32 v127, v154, v155
	v_fma_f32 v125, -v153, v127, v125
	v_div_fmas_f32 v125, v125, v155, v127
	v_div_fixup_f32 v125, v125, v126, v122
	v_pk_add_f32 v[126:127], v[116:117], 1.0 op_sel_hi:[1,0]
	v_cvt_pk_bf16_f32 v123, v125, v123
	v_div_scale_f32 v125, s[30:31], v127, v127, v113
	v_lshl_or_b32 v156, s72, 7, v149
	v_rcp_f32_e32 v153, v125
	v_ashrrev_i32_e32 v157, 31, v156
	v_lshl_add_u64 v[158:159], s[46:47], 0, v[158:159]
	v_cvt_pk_bf16_f32 v122, v120, v121
	v_lshlrev_b64 v[120:121], 1, v[156:157]
	v_lshl_add_u64 v[116:117], v[158:159], 0, v[120:121]
	global_store_dwordx2 v[116:117], v[122:123], off
	v_fma_f32 v122, -v125, v153, 1.0
	v_fmac_f32_e32 v153, v122, v153
	v_div_scale_f32 v122, vcc, v113, v127, v113
	v_mul_f32_e32 v123, v122, v153
	v_fma_f32 v154, -v125, v123, v122
	v_fmac_f32_e32 v123, v154, v153
	v_fma_f32 v122, -v125, v123, v122
	v_div_scale_f32 v125, s[30:31], v126, v126, v112
	v_rcp_f32_e32 v154, v125
	v_div_fmas_f32 v122, v122, v153, v123
	v_mul_f32_e32 v118, 0xbfb8aa3b, v118
	v_mul_f32_e32 v119, 0xbfb8aa3b, v119
	v_div_fixup_f32 v113, v122, v127, v113
	v_fma_f32 v122, -v125, v154, 1.0
	v_exp_f32_e32 v118, v118
	v_exp_f32_e32 v119, v119
	v_fmac_f32_e32 v154, v122, v154
	v_div_scale_f32 v122, vcc, v112, v126, v112
	v_mul_f32_e32 v123, v122, v154
	v_fma_f32 v127, -v125, v123, v122
	v_fmac_f32_e32 v123, v127, v154
	v_pk_add_f32 v[118:119], v[118:119], 1.0 op_sel_hi:[1,0]
	v_fma_f32 v122, -v125, v123, v122
	v_div_scale_f32 v125, s[30:31], v119, v119, v115
	v_rcp_f32_e32 v127, v125
	v_div_fmas_f32 v122, v122, v154, v123
	v_div_fixup_f32 v112, v122, v126, v112
	v_mul_f32_e32 v108, 0xbfb8aa3b, v108
	v_fma_f32 v122, -v125, v127, 1.0
	v_fmac_f32_e32 v127, v122, v127
	v_div_scale_f32 v122, vcc, v115, v119, v115
	v_mul_f32_e32 v123, v122, v127
	v_fma_f32 v126, -v125, v123, v122
	v_fmac_f32_e32 v123, v126, v127
	v_fma_f32 v122, -v125, v123, v122
	v_div_scale_f32 v125, s[30:31], v118, v118, v114
	v_rcp_f32_e32 v126, v125
	v_div_fmas_f32 v122, v122, v127, v123
	v_div_fixup_f32 v115, v122, v119, v115
	v_mul_f32_e32 v109, 0xbfb8aa3b, v109
	v_fma_f32 v119, -v125, v126, 1.0
	v_fmac_f32_e32 v126, v119, v126
	v_div_scale_f32 v119, vcc, v114, v118, v114
	v_mul_f32_e32 v122, v119, v126
	v_fma_f32 v123, -v125, v122, v119
	v_exp_f32_e32 v108, v108
	v_exp_f32_e32 v109, v109
	v_fmac_f32_e32 v122, v123, v126
	v_fma_f32 v119, -v125, v122, v119
	v_div_fmas_f32 v119, v119, v126, v122
	v_div_fixup_f32 v114, v119, v118, v114
	v_pk_add_f32 v[108:109], v[108:109], 1.0 op_sel_hi:[1,0]
	v_cvt_pk_bf16_f32 v112, v112, v113
	v_cvt_pk_bf16_f32 v113, v114, v115
	v_div_scale_f32 v114, s[30:31], v109, v109, v105
	v_rcp_f32_e32 v115, v114
	v_mul_f32_e32 v110, 0xbfb8aa3b, v110
	v_mul_f32_e32 v111, 0xbfb8aa3b, v111
	v_exp_f32_e32 v110, v110
	v_fma_f32 v118, -v114, v115, 1.0
	v_fmac_f32_e32 v115, v118, v115
	v_div_scale_f32 v118, vcc, v105, v109, v105
	v_mul_f32_e32 v119, v118, v115
	v_fma_f32 v122, -v114, v119, v118
	v_fmac_f32_e32 v119, v122, v115
	v_fma_f32 v114, -v114, v119, v118
	v_div_scale_f32 v118, s[30:31], v108, v108, v104
	v_rcp_f32_e32 v122, v118
	v_div_fmas_f32 v114, v114, v115, v119
	v_exp_f32_e32 v111, v111
	v_div_fixup_f32 v105, v114, v109, v105
	v_fma_f32 v109, -v118, v122, 1.0
	v_fmac_f32_e32 v122, v109, v122
	v_div_scale_f32 v109, vcc, v104, v108, v104
	v_mul_f32_e32 v114, v109, v122
	v_fma_f32 v115, -v118, v114, v109
	v_pk_add_f32 v[110:111], v[110:111], 1.0 op_sel_hi:[1,0]
	v_fmac_f32_e32 v114, v115, v122
	v_div_scale_f32 v115, s[30:31], v111, v111, v107
	v_fma_f32 v109, -v118, v114, v109
	v_rcp_f32_e32 v118, v115
	v_div_fmas_f32 v109, v109, v122, v114
	v_div_fixup_f32 v104, v109, v108, v104
	v_mul_f32_e32 v100, 0xbfb8aa3b, v100
	v_fma_f32 v108, -v115, v118, 1.0
	v_fmac_f32_e32 v118, v108, v118
	v_div_scale_f32 v108, vcc, v107, v111, v107
	v_mul_f32_e32 v109, v108, v118
	v_fma_f32 v114, -v115, v109, v108
	v_fmac_f32_e32 v109, v114, v118
	v_div_scale_f32 v114, s[30:31], v110, v110, v106
	v_fma_f32 v108, -v115, v109, v108
	v_rcp_f32_e32 v115, v114
	v_div_fmas_f32 v108, v108, v118, v109
	v_div_fixup_f32 v107, v108, v111, v107
	v_mul_f32_e32 v101, 0xbfb8aa3b, v101
	v_fma_f32 v108, -v114, v115, 1.0
	v_fmac_f32_e32 v115, v108, v115
	v_div_scale_f32 v108, vcc, v106, v110, v106
	v_mul_f32_e32 v109, v108, v115
	v_exp_f32_e32 v100, v100
	v_exp_f32_e32 v101, v101
	v_fma_f32 v111, -v114, v109, v108
	v_fmac_f32_e32 v109, v111, v115
	v_fma_f32 v108, -v114, v109, v108
	v_div_fmas_f32 v108, v108, v115, v109
	v_pk_add_f32 v[100:101], v[100:101], 1.0 op_sel_hi:[1,0]
	global_store_dwordx2 v[116:117], v[112:113], off offset:128
	v_or_b32_e32 v112, 16, v124
	v_div_fixup_f32 v106, v108, v110, v106
	v_div_scale_f32 v108, s[30:31], v101, v101, v97
	v_ashrrev_i32_e32 v113, 31, v112
	v_rcp_f32_e32 v109, v108
	v_lshlrev_b64 v[112:113], 11, v[112:113]
	v_lshl_add_u64 v[112:113], s[46:47], 0, v[112:113]
	v_cvt_pk_bf16_f32 v104, v104, v105
	v_cvt_pk_bf16_f32 v105, v106, v107
	v_lshl_add_u64 v[106:107], v[112:113], 0, v[120:121]
	global_store_dwordx2 v[106:107], v[104:105], off
	v_fma_f32 v104, -v108, v109, 1.0
	v_fmac_f32_e32 v109, v104, v109
	v_div_scale_f32 v104, vcc, v97, v101, v97
	v_mul_f32_e32 v105, v104, v109
	v_fma_f32 v110, -v108, v105, v104
	v_fmac_f32_e32 v105, v110, v109
	v_fma_f32 v104, -v108, v105, v104
	v_div_scale_f32 v108, s[30:31], v100, v100, v96
	v_rcp_f32_e32 v110, v108
	v_mul_f32_e32 v102, 0xbfb8aa3b, v102
	v_mul_f32_e32 v103, 0xbfb8aa3b, v103
	v_div_fmas_f32 v104, v104, v109, v105
	v_exp_f32_e32 v102, v102
	v_exp_f32_e32 v103, v103
	v_div_fixup_f32 v97, v104, v101, v97
	v_fma_f32 v101, -v108, v110, 1.0
	v_fmac_f32_e32 v110, v101, v110
	v_div_scale_f32 v101, vcc, v96, v100, v96
	v_mul_f32_e32 v104, v101, v110
	v_fma_f32 v105, -v108, v104, v101
	v_pk_add_f32 v[102:103], v[102:103], 1.0 op_sel_hi:[1,0]
	v_fmac_f32_e32 v104, v105, v110
	v_div_scale_f32 v105, s[30:31], v103, v103, v99
	v_fma_f32 v101, -v108, v104, v101
	v_rcp_f32_e32 v108, v105
	v_div_fmas_f32 v101, v101, v110, v104
	v_div_fixup_f32 v96, v101, v100, v96
	v_mul_f32_e32 v92, 0xbfb8aa3b, v92
	v_fma_f32 v100, -v105, v108, 1.0
	v_fmac_f32_e32 v108, v100, v108
	v_div_scale_f32 v100, vcc, v99, v103, v99
	v_mul_f32_e32 v101, v100, v108
	v_fma_f32 v104, -v105, v101, v100
	v_fmac_f32_e32 v101, v104, v108
	v_div_scale_f32 v104, s[30:31], v102, v102, v98
	v_fma_f32 v100, -v105, v101, v100
	v_rcp_f32_e32 v105, v104
	v_div_fmas_f32 v100, v100, v108, v101
	v_div_fixup_f32 v99, v100, v103, v99
	v_mul_f32_e32 v93, 0xbfb8aa3b, v93
	v_fma_f32 v100, -v104, v105, 1.0
	v_fmac_f32_e32 v105, v100, v105
	v_div_scale_f32 v100, vcc, v98, v102, v98
	v_mul_f32_e32 v101, v100, v105
	v_fma_f32 v103, -v104, v101, v100
	v_exp_f32_e32 v92, v92
	v_exp_f32_e32 v93, v93
	v_fmac_f32_e32 v101, v103, v105
	v_fma_f32 v100, -v104, v101, v100
	v_div_fmas_f32 v100, v100, v105, v101
	v_div_fixup_f32 v98, v100, v102, v98
	v_pk_add_f32 v[92:93], v[92:93], 1.0 op_sel_hi:[1,0]
	v_cvt_pk_bf16_f32 v96, v96, v97
	v_cvt_pk_bf16_f32 v97, v98, v99
	v_div_scale_f32 v98, s[30:31], v93, v93, v89
	v_rcp_f32_e32 v99, v98
	v_mul_f32_e32 v94, 0xbfb8aa3b, v94
	v_mul_f32_e32 v95, 0xbfb8aa3b, v95
	v_exp_f32_e32 v94, v94
	v_fma_f32 v100, -v98, v99, 1.0
	v_fmac_f32_e32 v99, v100, v99
	v_div_scale_f32 v100, vcc, v89, v93, v89
	v_mul_f32_e32 v101, v100, v99
	v_fma_f32 v102, -v98, v101, v100
	v_fmac_f32_e32 v101, v102, v99
	v_fma_f32 v98, -v98, v101, v100
	v_div_scale_f32 v100, s[30:31], v92, v92, v88
	v_rcp_f32_e32 v102, v100
	v_div_fmas_f32 v98, v98, v99, v101
	v_exp_f32_e32 v95, v95
	v_div_fixup_f32 v89, v98, v93, v89
	v_fma_f32 v93, -v100, v102, 1.0
	v_fmac_f32_e32 v102, v93, v102
	v_div_scale_f32 v93, vcc, v88, v92, v88
	v_mul_f32_e32 v98, v93, v102
	v_fma_f32 v99, -v100, v98, v93
	v_pk_add_f32 v[94:95], v[94:95], 1.0 op_sel_hi:[1,0]
	v_fmac_f32_e32 v98, v99, v102
	v_div_scale_f32 v99, s[30:31], v95, v95, v91
	v_fma_f32 v93, -v100, v98, v93
	v_rcp_f32_e32 v100, v99
	v_div_fmas_f32 v93, v93, v102, v98
	v_div_fixup_f32 v88, v93, v92, v88
	v_mul_f32_e32 v84, 0xbfb8aa3b, v84
	v_fma_f32 v92, -v99, v100, 1.0
	v_fmac_f32_e32 v100, v92, v100
	v_div_scale_f32 v92, vcc, v91, v95, v91
	v_mul_f32_e32 v93, v92, v100
	v_fma_f32 v98, -v99, v93, v92
	v_fmac_f32_e32 v93, v98, v100
	v_div_scale_f32 v98, s[30:31], v94, v94, v90
	v_fma_f32 v92, -v99, v93, v92
	v_rcp_f32_e32 v99, v98
	v_div_fmas_f32 v92, v92, v100, v93
	v_div_fixup_f32 v91, v92, v95, v91
	v_mul_f32_e32 v85, 0xbfb8aa3b, v85
	v_fma_f32 v92, -v98, v99, 1.0
	v_fmac_f32_e32 v99, v92, v99
	v_div_scale_f32 v92, vcc, v90, v94, v90
	v_mul_f32_e32 v93, v92, v99
	v_exp_f32_e32 v84, v84
	v_exp_f32_e32 v85, v85
	v_fma_f32 v95, -v98, v93, v92
	v_fmac_f32_e32 v93, v95, v99
	v_fma_f32 v92, -v98, v93, v92
	v_div_fmas_f32 v92, v92, v99, v93
	v_pk_add_f32 v[84:85], v[84:85], 1.0 op_sel_hi:[1,0]
	global_store_dwordx2 v[106:107], v[96:97], off offset:128
	v_or_b32_e32 v96, 32, v124
	v_div_fixup_f32 v90, v92, v94, v90
	v_div_scale_f32 v92, s[30:31], v85, v85, v81
	v_ashrrev_i32_e32 v97, 31, v96
	v_rcp_f32_e32 v93, v92
	v_lshlrev_b64 v[96:97], 11, v[96:97]
	v_lshl_add_u64 v[96:97], s[46:47], 0, v[96:97]
	v_cvt_pk_bf16_f32 v88, v88, v89
	v_cvt_pk_bf16_f32 v89, v90, v91
	v_lshl_add_u64 v[90:91], v[96:97], 0, v[120:121]
	global_store_dwordx2 v[90:91], v[88:89], off
	v_fma_f32 v88, -v92, v93, 1.0
	v_fmac_f32_e32 v93, v88, v93
	v_div_scale_f32 v88, vcc, v81, v85, v81
	v_mul_f32_e32 v89, v88, v93
	v_fma_f32 v94, -v92, v89, v88
	v_fmac_f32_e32 v89, v94, v93
	v_fma_f32 v88, -v92, v89, v88
	v_div_scale_f32 v92, s[30:31], v84, v84, v80
	v_rcp_f32_e32 v94, v92
	v_mul_f32_e32 v86, 0xbfb8aa3b, v86
	v_mul_f32_e32 v87, 0xbfb8aa3b, v87
	v_div_fmas_f32 v88, v88, v93, v89
	v_exp_f32_e32 v86, v86
	v_exp_f32_e32 v87, v87
	v_div_fixup_f32 v81, v88, v85, v81
	v_fma_f32 v85, -v92, v94, 1.0
	v_fmac_f32_e32 v94, v85, v94
	v_div_scale_f32 v85, vcc, v80, v84, v80
	v_mul_f32_e32 v88, v85, v94
	v_fma_f32 v89, -v92, v88, v85
	v_pk_add_f32 v[86:87], v[86:87], 1.0 op_sel_hi:[1,0]
	v_fmac_f32_e32 v88, v89, v94
	v_div_scale_f32 v89, s[30:31], v87, v87, v83
	v_fma_f32 v85, -v92, v88, v85
	v_rcp_f32_e32 v92, v89
	v_div_fmas_f32 v85, v85, v94, v88
	v_div_fixup_f32 v80, v85, v84, v80
	v_mul_f32_e32 v76, 0xbfb8aa3b, v76
	v_fma_f32 v84, -v89, v92, 1.0
	v_fmac_f32_e32 v92, v84, v92
	v_div_scale_f32 v84, vcc, v83, v87, v83
	v_mul_f32_e32 v85, v84, v92
	v_fma_f32 v88, -v89, v85, v84
	v_fmac_f32_e32 v85, v88, v92
	v_div_scale_f32 v88, s[30:31], v86, v86, v82
	v_fma_f32 v84, -v89, v85, v84
	v_rcp_f32_e32 v89, v88
	v_div_fmas_f32 v84, v84, v92, v85
	v_div_fixup_f32 v83, v84, v87, v83
	v_mul_f32_e32 v77, 0xbfb8aa3b, v77
	v_fma_f32 v84, -v88, v89, 1.0
	v_fmac_f32_e32 v89, v84, v89
	v_div_scale_f32 v84, vcc, v82, v86, v82
	v_mul_f32_e32 v85, v84, v89
	v_fma_f32 v87, -v88, v85, v84
	v_exp_f32_e32 v76, v76
	v_exp_f32_e32 v77, v77
	v_fmac_f32_e32 v85, v87, v89
	v_fma_f32 v84, -v88, v85, v84
	v_div_fmas_f32 v84, v84, v89, v85
	v_div_fixup_f32 v82, v84, v86, v82
	v_pk_add_f32 v[76:77], v[76:77], 1.0 op_sel_hi:[1,0]
	v_cvt_pk_bf16_f32 v80, v80, v81
	v_cvt_pk_bf16_f32 v81, v82, v83
	v_div_scale_f32 v82, s[30:31], v77, v77, v73
	v_rcp_f32_e32 v83, v82
	v_mul_f32_e32 v78, 0xbfb8aa3b, v78
	v_mul_f32_e32 v79, 0xbfb8aa3b, v79
	v_exp_f32_e32 v78, v78
	v_fma_f32 v84, -v82, v83, 1.0
	v_fmac_f32_e32 v83, v84, v83
	v_div_scale_f32 v84, vcc, v73, v77, v73
	v_mul_f32_e32 v85, v84, v83
	v_fma_f32 v86, -v82, v85, v84
	v_fmac_f32_e32 v85, v86, v83
	v_fma_f32 v82, -v82, v85, v84
	v_div_scale_f32 v84, s[30:31], v76, v76, v72
	v_rcp_f32_e32 v86, v84
	v_div_fmas_f32 v82, v82, v83, v85
	v_exp_f32_e32 v79, v79
	v_div_fixup_f32 v73, v82, v77, v73
	v_fma_f32 v77, -v84, v86, 1.0
	v_fmac_f32_e32 v86, v77, v86
	v_div_scale_f32 v77, vcc, v72, v76, v72
	v_mul_f32_e32 v82, v77, v86
	v_fma_f32 v83, -v84, v82, v77
	v_pk_add_f32 v[78:79], v[78:79], 1.0 op_sel_hi:[1,0]
	v_fmac_f32_e32 v82, v83, v86
	v_div_scale_f32 v83, s[30:31], v79, v79, v75
	v_fma_f32 v77, -v84, v82, v77
	v_rcp_f32_e32 v84, v83
	v_div_fmas_f32 v77, v77, v86, v82
	v_div_fixup_f32 v72, v77, v76, v72
	v_mul_f32_e32 v68, 0xbfb8aa3b, v68
	v_fma_f32 v76, -v83, v84, 1.0
	v_fmac_f32_e32 v84, v76, v84
	v_div_scale_f32 v76, vcc, v75, v79, v75
	v_mul_f32_e32 v77, v76, v84
	v_fma_f32 v82, -v83, v77, v76
	v_fmac_f32_e32 v77, v82, v84
	v_div_scale_f32 v82, s[30:31], v78, v78, v74
	v_fma_f32 v76, -v83, v77, v76
	v_rcp_f32_e32 v83, v82
	v_div_fmas_f32 v76, v76, v84, v77
	v_div_fixup_f32 v75, v76, v79, v75
	v_mul_f32_e32 v69, 0xbfb8aa3b, v69
	v_fma_f32 v76, -v82, v83, 1.0
	v_fmac_f32_e32 v83, v76, v83
	v_div_scale_f32 v76, vcc, v74, v78, v74
	v_mul_f32_e32 v77, v76, v83
	v_exp_f32_e32 v68, v68
	v_exp_f32_e32 v69, v69
	v_fma_f32 v79, -v82, v77, v76
	v_fmac_f32_e32 v77, v79, v83
	v_fma_f32 v76, -v82, v77, v76
	v_div_fmas_f32 v76, v76, v83, v77
	v_pk_add_f32 v[68:69], v[68:69], 1.0 op_sel_hi:[1,0]
	global_store_dwordx2 v[90:91], v[80:81], off offset:128
	v_or_b32_e32 v80, 48, v124
	v_div_fixup_f32 v74, v76, v78, v74
	v_div_scale_f32 v76, s[30:31], v69, v69, v65
	v_ashrrev_i32_e32 v81, 31, v80
	v_rcp_f32_e32 v77, v76
	v_lshlrev_b64 v[80:81], 11, v[80:81]
	v_lshl_add_u64 v[80:81], s[46:47], 0, v[80:81]
	v_cvt_pk_bf16_f32 v72, v72, v73
	v_cvt_pk_bf16_f32 v73, v74, v75
	v_lshl_add_u64 v[74:75], v[80:81], 0, v[120:121]
	global_store_dwordx2 v[74:75], v[72:73], off
	v_fma_f32 v72, -v76, v77, 1.0
	v_fmac_f32_e32 v77, v72, v77
	v_div_scale_f32 v72, vcc, v65, v69, v65
	v_mul_f32_e32 v73, v72, v77
	v_fma_f32 v78, -v76, v73, v72
	v_fmac_f32_e32 v73, v78, v77
	v_fma_f32 v72, -v76, v73, v72
	v_div_scale_f32 v76, s[30:31], v68, v68, v64
	v_rcp_f32_e32 v78, v76
	v_mul_f32_e32 v70, 0xbfb8aa3b, v70
	v_mul_f32_e32 v71, 0xbfb8aa3b, v71
	v_div_fmas_f32 v72, v72, v77, v73
	v_exp_f32_e32 v70, v70
	v_exp_f32_e32 v71, v71
	v_div_fixup_f32 v65, v72, v69, v65
	v_fma_f32 v69, -v76, v78, 1.0
	v_fmac_f32_e32 v78, v69, v78
	v_div_scale_f32 v69, vcc, v64, v68, v64
	v_mul_f32_e32 v72, v69, v78
	v_fma_f32 v73, -v76, v72, v69
	v_pk_add_f32 v[70:71], v[70:71], 1.0 op_sel_hi:[1,0]
	v_fmac_f32_e32 v72, v73, v78
	v_div_scale_f32 v73, s[30:31], v71, v71, v67
	v_fma_f32 v69, -v76, v72, v69
	v_rcp_f32_e32 v76, v73
	v_div_fmas_f32 v69, v69, v78, v72
	v_div_fixup_f32 v64, v69, v68, v64
	v_mul_f32_e32 v60, 0xbfb8aa3b, v60
	v_fma_f32 v68, -v73, v76, 1.0
	v_fmac_f32_e32 v76, v68, v76
	v_div_scale_f32 v68, vcc, v67, v71, v67
	v_mul_f32_e32 v69, v68, v76
	v_fma_f32 v72, -v73, v69, v68
	v_fmac_f32_e32 v69, v72, v76
	v_div_scale_f32 v72, s[30:31], v70, v70, v66
	v_fma_f32 v68, -v73, v69, v68
	v_rcp_f32_e32 v73, v72
	v_div_fmas_f32 v68, v68, v76, v69
	v_div_fixup_f32 v67, v68, v71, v67
	v_mul_f32_e32 v61, 0xbfb8aa3b, v61
	v_fma_f32 v68, -v72, v73, 1.0
	v_fmac_f32_e32 v73, v68, v73
	v_div_scale_f32 v68, vcc, v66, v70, v66
	v_mul_f32_e32 v69, v68, v73
	v_exp_f32_e32 v60, v60
	v_exp_f32_e32 v61, v61
	v_fma_f32 v71, -v72, v69, v68
	v_fmac_f32_e32 v69, v71, v73
	v_fma_f32 v68, -v72, v69, v68
	v_div_fmas_f32 v68, v68, v73, v69
	v_pk_add_f32 v[60:61], v[60:61], 1.0 op_sel_hi:[1,0]
	v_div_fixup_f32 v66, v68, v70, v66
	v_div_scale_f32 v68, s[30:31], v61, v61, v57
	v_rcp_f32_e32 v69, v68
	v_cvt_pk_bf16_f32 v64, v64, v65
	v_cvt_pk_bf16_f32 v65, v66, v67
	global_store_dwordx2 v[74:75], v[64:65], off offset:128
	v_fma_f32 v64, -v68, v69, 1.0
	v_fmac_f32_e32 v69, v64, v69
	v_div_scale_f32 v64, vcc, v57, v61, v57
	v_mul_f32_e32 v65, v64, v69
	v_fma_f32 v66, -v68, v65, v64
	v_fmac_f32_e32 v65, v66, v69
	v_div_scale_f32 v66, s[30:31], v60, v60, v56
	v_rcp_f32_e32 v67, v66
	v_fma_f32 v64, -v68, v65, v64
	v_mul_f32_e32 v62, 0xbfb8aa3b, v62
	v_mul_f32_e32 v63, 0xbfb8aa3b, v63
	v_div_fmas_f32 v64, v64, v69, v65
	v_exp_f32_e32 v62, v62
	v_exp_f32_e32 v63, v63
	v_div_fixup_f32 v57, v64, v61, v57
	v_fma_f32 v61, -v66, v67, 1.0
	v_fmac_f32_e32 v67, v61, v67
	v_div_scale_f32 v61, vcc, v56, v60, v56
	v_mul_f32_e32 v64, v61, v67
	v_fma_f32 v65, -v66, v64, v61
	v_pk_add_f32 v[62:63], v[62:63], 1.0 op_sel_hi:[1,0]
	v_fmac_f32_e32 v64, v65, v67
	v_div_scale_f32 v65, s[30:31], v63, v63, v59
	v_fma_f32 v61, -v66, v64, v61
	v_rcp_f32_e32 v66, v65
	v_div_fmas_f32 v61, v61, v67, v64
	v_div_fixup_f32 v56, v61, v60, v56
	v_mul_f32_e32 v52, 0xbfb8aa3b, v52
	v_fma_f32 v60, -v65, v66, 1.0
	v_fmac_f32_e32 v66, v60, v66
	v_div_scale_f32 v60, vcc, v59, v63, v59
	v_mul_f32_e32 v61, v60, v66
	v_fma_f32 v64, -v65, v61, v60
	v_fmac_f32_e32 v61, v64, v66
	v_div_scale_f32 v64, s[30:31], v62, v62, v58
	v_fma_f32 v60, -v65, v61, v60
	v_rcp_f32_e32 v65, v64
	v_div_fmas_f32 v60, v60, v66, v61
	v_div_fixup_f32 v59, v60, v63, v59
	v_mul_f32_e32 v53, 0xbfb8aa3b, v53
	v_fma_f32 v60, -v64, v65, 1.0
	v_fmac_f32_e32 v65, v60, v65
	v_div_scale_f32 v60, vcc, v58, v62, v58
	v_mul_f32_e32 v61, v60, v65
	v_exp_f32_e32 v52, v52
	v_exp_f32_e32 v53, v53
	v_fma_f32 v63, -v64, v61, v60
	v_fmac_f32_e32 v61, v63, v65
	v_fma_f32 v60, -v64, v61, v60
	v_div_fmas_f32 v60, v60, v65, v61
	v_pk_add_f32 v[52:53], v[52:53], 1.0 op_sel_hi:[1,0]
	v_div_fixup_f32 v58, v60, v62, v58
	v_div_scale_f32 v62, s[30:31], v53, v53, v49
	v_rcp_f32_e32 v63, v62
	v_add_co_u32_e32 v60, vcc, s62, v116
	v_cvt_pk_bf16_f32 v56, v56, v57
	v_cvt_pk_bf16_f32 v57, v58, v59
	v_addc_co_u32_e32 v61, vcc, 0, v117, vcc
	global_store_dwordx2 v[60:61], v[56:57], off
	v_fma_f32 v56, -v62, v63, 1.0
	v_fmac_f32_e32 v63, v56, v63
	v_div_scale_f32 v56, vcc, v49, v53, v49
	v_mul_f32_e32 v57, v56, v63
	v_fma_f32 v60, -v62, v57, v56
	v_fmac_f32_e32 v57, v60, v63
	v_div_scale_f32 v60, s[30:31], v52, v52, v48
	v_rcp_f32_e32 v61, v60
	v_fma_f32 v56, -v62, v57, v56
	v_mul_f32_e32 v54, 0xbfb8aa3b, v54
	v_mul_f32_e32 v55, 0xbfb8aa3b, v55
	v_div_fmas_f32 v56, v56, v63, v57
	v_exp_f32_e32 v54, v54
	v_exp_f32_e32 v55, v55
	v_div_fixup_f32 v49, v56, v53, v49
	v_fma_f32 v53, -v60, v61, 1.0
	v_fmac_f32_e32 v61, v53, v61
	v_div_scale_f32 v53, vcc, v48, v52, v48
	v_mul_f32_e32 v56, v53, v61
	v_fma_f32 v57, -v60, v56, v53
	v_pk_add_f32 v[54:55], v[54:55], 1.0 op_sel_hi:[1,0]
	v_fmac_f32_e32 v56, v57, v61
	v_div_scale_f32 v57, s[30:31], v55, v55, v51
	v_fma_f32 v53, -v60, v56, v53
	v_rcp_f32_e32 v60, v57
	v_div_fmas_f32 v53, v53, v61, v56
	v_div_fixup_f32 v48, v53, v52, v48
	v_mul_f32_e32 v44, 0xbfb8aa3b, v44
	v_fma_f32 v52, -v57, v60, 1.0
	v_fmac_f32_e32 v60, v52, v60
	v_div_scale_f32 v52, vcc, v51, v55, v51
	v_mul_f32_e32 v53, v52, v60
	v_fma_f32 v56, -v57, v53, v52
	v_fmac_f32_e32 v53, v56, v60
	v_div_scale_f32 v56, s[30:31], v54, v54, v50
	v_fma_f32 v52, -v57, v53, v52
	v_rcp_f32_e32 v57, v56
	v_div_fmas_f32 v52, v52, v60, v53
	v_div_fixup_f32 v51, v52, v55, v51
	v_mul_f32_e32 v45, 0xbfb8aa3b, v45
	v_fma_f32 v52, -v56, v57, 1.0
	v_fmac_f32_e32 v57, v52, v57
	v_div_scale_f32 v52, vcc, v50, v54, v50
	v_mul_f32_e32 v53, v52, v57
	v_exp_f32_e32 v44, v44
	v_exp_f32_e32 v45, v45
	v_fma_f32 v55, -v56, v53, v52
	v_fmac_f32_e32 v53, v55, v57
	v_fma_f32 v52, -v56, v53, v52
	v_div_fmas_f32 v52, v52, v57, v53
	v_pk_add_f32 v[44:45], v[44:45], 1.0 op_sel_hi:[1,0]
	v_div_fixup_f32 v50, v52, v54, v50
	v_div_scale_f32 v52, s[30:31], v45, v45, v41
	v_rcp_f32_e32 v53, v52
	v_lshl_add_u64 v[58:59], v[116:117], 0, s[6:7]
	v_cvt_pk_bf16_f32 v48, v48, v49
	v_cvt_pk_bf16_f32 v49, v50, v51
	global_store_dwordx2 v[58:59], v[48:49], off offset:128
	v_fma_f32 v48, -v52, v53, 1.0
	v_fmac_f32_e32 v53, v48, v53
	v_div_scale_f32 v48, vcc, v41, v45, v41
	v_mul_f32_e32 v49, v48, v53
	v_fma_f32 v50, -v52, v49, v48
	v_fmac_f32_e32 v49, v50, v53
	v_div_scale_f32 v50, s[30:31], v44, v44, v40
	v_rcp_f32_e32 v51, v50
	v_fma_f32 v48, -v52, v49, v48
	v_mul_f32_e32 v46, 0xbfb8aa3b, v46
	v_mul_f32_e32 v47, 0xbfb8aa3b, v47
	v_div_fmas_f32 v48, v48, v53, v49
	v_exp_f32_e32 v46, v46
	v_exp_f32_e32 v47, v47
	v_div_fixup_f32 v41, v48, v45, v41
	v_fma_f32 v45, -v50, v51, 1.0
	v_fmac_f32_e32 v51, v45, v51
	v_div_scale_f32 v45, vcc, v40, v44, v40
	v_mul_f32_e32 v48, v45, v51
	v_fma_f32 v49, -v50, v48, v45
	v_pk_add_f32 v[46:47], v[46:47], 1.0 op_sel_hi:[1,0]
	v_fmac_f32_e32 v48, v49, v51
	v_div_scale_f32 v49, s[30:31], v47, v47, v43
	v_fma_f32 v45, -v50, v48, v45
	v_rcp_f32_e32 v50, v49
	v_div_fmas_f32 v45, v45, v51, v48
	v_div_fixup_f32 v40, v45, v44, v40
	v_mul_f32_e32 v36, 0xbfb8aa3b, v36
	v_fma_f32 v44, -v49, v50, 1.0
	v_fmac_f32_e32 v50, v44, v50
	v_div_scale_f32 v44, vcc, v43, v47, v43
	v_mul_f32_e32 v45, v44, v50
	v_fma_f32 v48, -v49, v45, v44
	v_fmac_f32_e32 v45, v48, v50
	v_div_scale_f32 v48, s[30:31], v46, v46, v42
	v_fma_f32 v44, -v49, v45, v44
	v_rcp_f32_e32 v49, v48
	v_div_fmas_f32 v44, v44, v50, v45
	v_div_fixup_f32 v43, v44, v47, v43
	v_mul_f32_e32 v37, 0xbfb8aa3b, v37
	v_fma_f32 v44, -v48, v49, 1.0
	v_fmac_f32_e32 v49, v44, v49
	v_div_scale_f32 v44, vcc, v42, v46, v42
	v_mul_f32_e32 v45, v44, v49
	v_exp_f32_e32 v36, v36
	v_exp_f32_e32 v37, v37
	v_fma_f32 v47, -v48, v45, v44
	v_fmac_f32_e32 v45, v47, v49
	v_fma_f32 v44, -v48, v45, v44
	v_div_fmas_f32 v44, v44, v49, v45
	v_pk_add_f32 v[36:37], v[36:37], 1.0 op_sel_hi:[1,0]
	v_div_fixup_f32 v42, v44, v46, v42
	v_div_scale_f32 v46, s[30:31], v37, v37, v33
	v_rcp_f32_e32 v47, v46
	v_add_co_u32_e32 v44, vcc, s63, v116
	v_cvt_pk_bf16_f32 v40, v40, v41
	v_cvt_pk_bf16_f32 v41, v42, v43
	v_addc_co_u32_e32 v45, vcc, 0, v117, vcc
	global_store_dwordx2 v[44:45], v[40:41], off
	v_fma_f32 v40, -v46, v47, 1.0
	v_fmac_f32_e32 v47, v40, v47
	v_div_scale_f32 v40, vcc, v33, v37, v33
	v_mul_f32_e32 v41, v40, v47
	v_fma_f32 v44, -v46, v41, v40
	v_fmac_f32_e32 v41, v44, v47
	v_div_scale_f32 v44, s[30:31], v36, v36, v32
	v_rcp_f32_e32 v45, v44
	v_fma_f32 v40, -v46, v41, v40
	v_mul_f32_e32 v38, 0xbfb8aa3b, v38
	v_mul_f32_e32 v39, 0xbfb8aa3b, v39
	v_div_fmas_f32 v40, v40, v47, v41
	v_exp_f32_e32 v38, v38
	v_exp_f32_e32 v39, v39
	v_div_fixup_f32 v33, v40, v37, v33
	v_fma_f32 v37, -v44, v45, 1.0
	v_fmac_f32_e32 v45, v37, v45
	v_div_scale_f32 v37, vcc, v32, v36, v32
	v_mul_f32_e32 v40, v37, v45
	v_fma_f32 v41, -v44, v40, v37
	v_pk_add_f32 v[38:39], v[38:39], 1.0 op_sel_hi:[1,0]
	v_fmac_f32_e32 v40, v41, v45
	v_div_scale_f32 v41, s[30:31], v39, v39, v35
	v_fma_f32 v37, -v44, v40, v37
	v_rcp_f32_e32 v44, v41
	v_div_fmas_f32 v37, v37, v45, v40
	v_div_fixup_f32 v32, v37, v36, v32
	v_mul_f32_e32 v28, 0xbfb8aa3b, v28
	v_fma_f32 v36, -v41, v44, 1.0
	v_fmac_f32_e32 v44, v36, v44
	v_div_scale_f32 v36, vcc, v35, v39, v35
	v_mul_f32_e32 v37, v36, v44
	v_fma_f32 v40, -v41, v37, v36
	v_fmac_f32_e32 v37, v40, v44
	v_div_scale_f32 v40, s[30:31], v38, v38, v34
	v_fma_f32 v36, -v41, v37, v36
	v_rcp_f32_e32 v41, v40
	v_div_fmas_f32 v36, v36, v44, v37
	v_div_fixup_f32 v35, v36, v39, v35
	v_mul_f32_e32 v29, 0xbfb8aa3b, v29
	v_fma_f32 v36, -v40, v41, 1.0
	v_fmac_f32_e32 v41, v36, v41
	v_div_scale_f32 v36, vcc, v34, v38, v34
	v_mul_f32_e32 v37, v36, v41
	v_exp_f32_e32 v28, v28
	v_exp_f32_e32 v29, v29
	v_fma_f32 v39, -v40, v37, v36
	v_fmac_f32_e32 v37, v39, v41
	v_fma_f32 v36, -v40, v37, v36
	v_div_fmas_f32 v36, v36, v41, v37
	v_pk_add_f32 v[28:29], v[28:29], 1.0 op_sel_hi:[1,0]
	v_div_fixup_f32 v34, v36, v38, v34
	v_div_scale_f32 v36, s[30:31], v29, v29, v25
	v_rcp_f32_e32 v37, v36
	v_lshl_add_u64 v[42:43], v[116:117], 0, s[10:11]
	v_cvt_pk_bf16_f32 v32, v32, v33
	v_cvt_pk_bf16_f32 v33, v34, v35
	global_store_dwordx2 v[42:43], v[32:33], off offset:128
	v_fma_f32 v32, -v36, v37, 1.0
	v_fmac_f32_e32 v37, v32, v37
	v_div_scale_f32 v32, vcc, v25, v29, v25
	v_mul_f32_e32 v33, v32, v37
	v_fma_f32 v34, -v36, v33, v32
	v_fmac_f32_e32 v33, v34, v37
	v_div_scale_f32 v34, s[30:31], v28, v28, v24
	v_rcp_f32_e32 v35, v34
	v_fma_f32 v32, -v36, v33, v32
	v_mul_f32_e32 v30, 0xbfb8aa3b, v30
	v_mul_f32_e32 v31, 0xbfb8aa3b, v31
	v_div_fmas_f32 v32, v32, v37, v33
	v_exp_f32_e32 v30, v30
	v_exp_f32_e32 v31, v31
	v_div_fixup_f32 v25, v32, v29, v25
	v_fma_f32 v29, -v34, v35, 1.0
	v_fmac_f32_e32 v35, v29, v35
	v_div_scale_f32 v29, vcc, v24, v28, v24
	v_mul_f32_e32 v32, v29, v35
	v_fma_f32 v33, -v34, v32, v29
	v_pk_add_f32 v[30:31], v[30:31], 1.0 op_sel_hi:[1,0]
	v_fmac_f32_e32 v32, v33, v35
	v_div_scale_f32 v33, s[30:31], v31, v31, v27
	v_fma_f32 v29, -v34, v32, v29
	v_rcp_f32_e32 v34, v33
	v_div_fmas_f32 v29, v29, v35, v32
	v_div_fixup_f32 v24, v29, v28, v24
	v_mul_f32_e32 v20, 0xbfb8aa3b, v20
	v_fma_f32 v28, -v33, v34, 1.0
	v_fmac_f32_e32 v34, v28, v34
	v_div_scale_f32 v28, vcc, v27, v31, v27
	v_mul_f32_e32 v29, v28, v34
	v_fma_f32 v32, -v33, v29, v28
	v_fmac_f32_e32 v29, v32, v34
	v_div_scale_f32 v32, s[30:31], v30, v30, v26
	v_fma_f32 v28, -v33, v29, v28
	v_rcp_f32_e32 v33, v32
	v_div_fmas_f32 v28, v28, v34, v29
	v_div_fixup_f32 v27, v28, v31, v27
	v_mul_f32_e32 v21, 0xbfb8aa3b, v21
	v_fma_f32 v28, -v32, v33, 1.0
	v_fmac_f32_e32 v33, v28, v33
	v_div_scale_f32 v28, vcc, v26, v30, v26
	v_mul_f32_e32 v29, v28, v33
	v_exp_f32_e32 v20, v20
	v_exp_f32_e32 v21, v21
	v_fma_f32 v31, -v32, v29, v28
	v_fmac_f32_e32 v29, v31, v33
	v_fma_f32 v28, -v32, v29, v28
	v_div_fmas_f32 v28, v28, v33, v29
	v_pk_add_f32 v[20:21], v[20:21], 1.0 op_sel_hi:[1,0]
	v_div_fixup_f32 v26, v28, v30, v26
	v_div_scale_f32 v30, s[30:31], v21, v21, v17
	v_rcp_f32_e32 v31, v30
	v_add_co_u32_e32 v28, vcc, s70, v116
	v_cvt_pk_bf16_f32 v24, v24, v25
	v_cvt_pk_bf16_f32 v25, v26, v27
	v_addc_co_u32_e32 v29, vcc, 0, v117, vcc
	global_store_dwordx2 v[28:29], v[24:25], off
	v_fma_f32 v24, -v30, v31, 1.0
	v_fmac_f32_e32 v31, v24, v31
	v_div_scale_f32 v24, vcc, v17, v21, v17
	v_mul_f32_e32 v25, v24, v31
	v_fma_f32 v28, -v30, v25, v24
	v_fmac_f32_e32 v25, v28, v31
	v_div_scale_f32 v28, s[30:31], v20, v20, v16
	v_rcp_f32_e32 v29, v28
	v_fma_f32 v24, -v30, v25, v24
	v_mul_f32_e32 v22, 0xbfb8aa3b, v22
	v_mul_f32_e32 v23, 0xbfb8aa3b, v23
	v_div_fmas_f32 v24, v24, v31, v25
	v_exp_f32_e32 v22, v22
	v_exp_f32_e32 v23, v23
	v_div_fixup_f32 v17, v24, v21, v17
	v_fma_f32 v21, -v28, v29, 1.0
	v_fmac_f32_e32 v29, v21, v29
	v_div_scale_f32 v21, vcc, v16, v20, v16
	v_mul_f32_e32 v24, v21, v29
	v_fma_f32 v25, -v28, v24, v21
	v_pk_add_f32 v[22:23], v[22:23], 1.0 op_sel_hi:[1,0]
	v_fmac_f32_e32 v24, v25, v29
	v_div_scale_f32 v25, s[30:31], v23, v23, v19
	v_fma_f32 v21, -v28, v24, v21
	v_rcp_f32_e32 v28, v25
	v_div_fmas_f32 v21, v21, v29, v24
	v_div_fixup_f32 v16, v21, v20, v16
	v_mul_f32_e32 v12, 0xbfb8aa3b, v12
	v_fma_f32 v20, -v25, v28, 1.0
	v_fmac_f32_e32 v28, v20, v28
	v_div_scale_f32 v20, vcc, v19, v23, v19
	v_mul_f32_e32 v21, v20, v28
	v_fma_f32 v24, -v25, v21, v20
	v_fmac_f32_e32 v21, v24, v28
	v_div_scale_f32 v24, s[30:31], v22, v22, v18
	v_fma_f32 v20, -v25, v21, v20
	v_rcp_f32_e32 v25, v24
	v_div_fmas_f32 v20, v20, v28, v21
	v_div_fixup_f32 v19, v20, v23, v19
	v_mul_f32_e32 v13, 0xbfb8aa3b, v13
	v_fma_f32 v20, -v24, v25, 1.0
	v_fmac_f32_e32 v25, v20, v25
	v_div_scale_f32 v20, vcc, v18, v22, v18
	v_mul_f32_e32 v21, v20, v25
	v_exp_f32_e32 v12, v12
	v_exp_f32_e32 v13, v13
	v_fma_f32 v23, -v24, v21, v20
	v_fmac_f32_e32 v21, v23, v25
	v_fma_f32 v20, -v24, v21, v20
	v_div_fmas_f32 v20, v20, v25, v21
	v_pk_add_f32 v[12:13], v[12:13], 1.0 op_sel_hi:[1,0]
	v_div_fixup_f32 v18, v20, v22, v18
	v_div_scale_f32 v20, s[30:31], v13, v13, v9
	v_rcp_f32_e32 v21, v20
	v_lshl_add_u64 v[26:27], v[116:117], 0, s[12:13]
	v_cvt_pk_bf16_f32 v16, v16, v17
	v_cvt_pk_bf16_f32 v17, v18, v19
	global_store_dwordx2 v[26:27], v[16:17], off offset:128
	v_fma_f32 v16, -v20, v21, 1.0
	v_fmac_f32_e32 v21, v16, v21
	v_div_scale_f32 v16, vcc, v9, v13, v9
	v_mul_f32_e32 v17, v16, v21
	v_fma_f32 v18, -v20, v17, v16
	v_fmac_f32_e32 v17, v18, v21
	v_div_scale_f32 v18, s[30:31], v12, v12, v8
	v_rcp_f32_e32 v19, v18
	v_fma_f32 v16, -v20, v17, v16
	v_mul_f32_e32 v14, 0xbfb8aa3b, v14
	v_mul_f32_e32 v15, 0xbfb8aa3b, v15
	v_div_fmas_f32 v16, v16, v21, v17
	v_exp_f32_e32 v14, v14
	v_exp_f32_e32 v15, v15
	v_div_fixup_f32 v9, v16, v13, v9
	v_fma_f32 v13, -v18, v19, 1.0
	v_fmac_f32_e32 v19, v13, v19
	v_div_scale_f32 v13, vcc, v8, v12, v8
	v_mul_f32_e32 v16, v13, v19
	v_fma_f32 v17, -v18, v16, v13
	v_pk_add_f32 v[14:15], v[14:15], 1.0 op_sel_hi:[1,0]
	v_fmac_f32_e32 v16, v17, v19
	v_div_scale_f32 v17, s[30:31], v15, v15, v11
	v_fma_f32 v13, -v18, v16, v13
	v_rcp_f32_e32 v18, v17
	v_div_fmas_f32 v13, v13, v19, v16
	v_div_fixup_f32 v8, v13, v12, v8
	v_mul_f32_e32 v4, 0xbfb8aa3b, v4
	v_fma_f32 v12, -v17, v18, 1.0
	v_fmac_f32_e32 v18, v12, v18
	v_div_scale_f32 v12, vcc, v11, v15, v11
	v_mul_f32_e32 v13, v12, v18
	v_fma_f32 v16, -v17, v13, v12
	v_fmac_f32_e32 v13, v16, v18
	v_div_scale_f32 v16, s[30:31], v14, v14, v10
	v_fma_f32 v12, -v17, v13, v12
	v_rcp_f32_e32 v17, v16
	v_div_fmas_f32 v12, v12, v18, v13
	v_div_fixup_f32 v11, v12, v15, v11
	v_mul_f32_e32 v5, 0xbfb8aa3b, v5
	v_fma_f32 v12, -v16, v17, 1.0
	v_fmac_f32_e32 v17, v12, v17
	v_div_scale_f32 v12, vcc, v10, v14, v10
	v_mul_f32_e32 v13, v12, v17
	v_exp_f32_e32 v4, v4
	v_exp_f32_e32 v5, v5
	v_fma_f32 v15, -v16, v13, v12
	v_fmac_f32_e32 v13, v15, v17
	v_fma_f32 v12, -v16, v13, v12
	v_div_fmas_f32 v12, v12, v17, v13
	v_pk_add_f32 v[4:5], v[4:5], 1.0 op_sel_hi:[1,0]
	v_div_fixup_f32 v10, v12, v14, v10
	v_div_scale_f32 v14, s[30:31], v5, v5, v1
	v_rcp_f32_e32 v15, v14
	v_add_co_u32_e32 v12, vcc, s71, v116
	v_cvt_pk_bf16_f32 v8, v8, v9
	v_cvt_pk_bf16_f32 v9, v10, v11
	v_addc_co_u32_e32 v13, vcc, 0, v117, vcc
	global_store_dwordx2 v[12:13], v[8:9], off
	v_fma_f32 v8, -v14, v15, 1.0
	v_fmac_f32_e32 v15, v8, v15
	v_div_scale_f32 v8, vcc, v1, v5, v1
	v_mul_f32_e32 v9, v8, v15
	v_fma_f32 v12, -v14, v9, v8
	v_fmac_f32_e32 v9, v12, v15
	v_div_scale_f32 v12, s[30:31], v4, v4, v0
	v_rcp_f32_e32 v13, v12
	v_fma_f32 v8, -v14, v9, v8
	v_mul_f32_e32 v6, 0xbfb8aa3b, v6
	v_mul_f32_e32 v7, 0xbfb8aa3b, v7
	v_div_fmas_f32 v8, v8, v15, v9
	v_exp_f32_e32 v6, v6
	v_exp_f32_e32 v7, v7
	v_div_fixup_f32 v1, v8, v5, v1
	v_fma_f32 v5, -v12, v13, 1.0
	v_fmac_f32_e32 v13, v5, v13
	v_div_scale_f32 v5, vcc, v0, v4, v0
	v_mul_f32_e32 v8, v5, v13
	v_fma_f32 v9, -v12, v8, v5
	v_pk_add_f32 v[6:7], v[6:7], 1.0 op_sel_hi:[1,0]
	v_fmac_f32_e32 v8, v9, v13
	v_div_scale_f32 v9, s[30:31], v7, v7, v3
	v_fma_f32 v5, -v12, v8, v5
	v_rcp_f32_e32 v12, v9
	v_div_fmas_f32 v5, v5, v13, v8
	v_div_fixup_f32 v0, v5, v4, v0
	v_lshl_add_u64 v[10:11], v[116:117], 0, s[14:15]
	v_fma_f32 v4, -v9, v12, 1.0
	v_fmac_f32_e32 v12, v4, v12
	v_div_scale_f32 v4, vcc, v3, v7, v3
	v_mul_f32_e32 v5, v4, v12
	v_fma_f32 v8, -v9, v5, v4
	v_fmac_f32_e32 v5, v8, v12
	v_div_scale_f32 v8, s[30:31], v6, v6, v2
	v_fma_f32 v4, -v9, v5, v4
	v_rcp_f32_e32 v9, v8
	v_div_fmas_f32 v4, v4, v12, v5
	v_div_fixup_f32 v3, v4, v7, v3
	v_cvt_pk_bf16_f32 v0, v0, v1
	v_fma_f32 v4, -v8, v9, 1.0
	v_fmac_f32_e32 v9, v4, v9
	v_div_scale_f32 v4, vcc, v2, v6, v2
	v_mul_f32_e32 v5, v4, v9
	v_fma_f32 v7, -v8, v5, v4
	v_fmac_f32_e32 v5, v7, v9
	v_fma_f32 v4, -v8, v5, v4
	v_div_fmas_f32 v4, v4, v9, v5
	v_div_fixup_f32 v2, v4, v6, v2
	v_cvt_pk_bf16_f32 v1, v2, v3
	s_and_b64 vcc, exec, s[4:5]
	s_mov_b32 s72, s16
	s_mov_b32 s28, s18
	s_mov_b64 s[34:35], s[26:27]
	s_mov_b64 s[30:31], s[20:21]
	global_store_dwordx2 v[10:11], v[0:1], off offset:128
	s_cbranch_vccz .LBB0_1109
	s_waitcnt vmcnt(16)
	s_cmpk_gt_u32 s40, 0xff
	s_cbranch_scc1 .LBB0_1120
	s_barrier

.LBB0_1141:
	ds_read_b128 v[150:153], v145
	ds_read_b128 v[154:157], v145 offset:1024
	ds_read_b128 v[158:161], v145 offset:2048
	ds_read_b128 v[162:165], v145 offset:3072
	s_add_u32 s34, s30, 0xfffc0080
	s_addc_u32 s35, s31, -1
	s_cmp_eq_u32 s77, 12
	s_cselect_b32 s37, s19, s35
	s_cselect_b32 s36, s73, s34
	s_cselect_b32 s35, s17, s76
	s_cselect_b32 s34, s74, s75
	v_lshl_add_u64 v[198:199], s[30:31], 0, v[134:135]
	s_add_i32 m0, s29, 0xc000
	ds_read_b128 v[166:169], v148
	ds_read_b128 v[170:173], v148 offset:1024
	ds_read_b128 v[174:177], v148 offset:2048
	ds_read_b128 v[178:181], v148 offset:3072
	ds_read_b128 v[182:185], v148 offset:4096
	ds_read_b128 v[186:189], v148 offset:5120
	ds_read_b128 v[190:193], v148 offset:6144
	ds_read_b128 v[194:197], v148 offset:7168
	global_load_lds_dwordx4 v[198:199], off
	v_lshl_add_u64 v[198:199], s[30:31], 0, v[136:137]
	s_add_i32 m0, s29, 0xe000
	s_nop 0
	global_load_lds_dwordx4 v[198:199], off
	s_waitcnt lgkmcnt(8)
	s_barrier
	s_waitcnt lgkmcnt(0)
	s_waitcnt lgkmcnt(0)
	v_mfma_f32_16x16x32_bf16 v[120:123], v[150:153], v[166:169], v[120:123]
	v_mfma_f32_16x16x32_bf16 v[124:127], v[158:161], v[166:169], v[124:127]
	v_mfma_f32_16x16x32_bf16 v[104:107], v[150:153], v[174:177], v[104:107]
	v_mfma_f32_16x16x32_bf16 v[108:111], v[158:161], v[174:177], v[108:111]
	v_mfma_f32_16x16x32_bf16 v[88:91], v[150:153], v[182:185], v[88:91]
	v_mfma_f32_16x16x32_bf16 v[92:95], v[158:161], v[182:185], v[92:95]
	v_mfma_f32_16x16x32_bf16 v[72:75], v[150:153], v[190:193], v[72:75]
	v_mfma_f32_16x16x32_bf16 v[76:79], v[158:161], v[190:193], v[76:79]
	v_mfma_f32_16x16x32_bf16 v[120:123], v[154:157], v[170:173], v[120:123]
	v_mfma_f32_16x16x32_bf16 v[124:127], v[162:165], v[170:173], v[124:127]
	v_mfma_f32_16x16x32_bf16 v[104:107], v[154:157], v[178:181], v[104:107]
	v_mfma_f32_16x16x32_bf16 v[108:111], v[162:165], v[178:181], v[108:111]
	v_mfma_f32_16x16x32_bf16 v[88:91], v[154:157], v[186:189], v[88:91]
	v_mfma_f32_16x16x32_bf16 v[92:95], v[162:165], v[186:189], v[92:95]
	v_mfma_f32_16x16x32_bf16 v[72:75], v[154:157], v[194:197], v[72:75]
	v_mfma_f32_16x16x32_bf16 v[76:79], v[162:165], v[194:197], v[76:79]
	s_barrier
	s_add_i32 s78, s60, s42
	v_lshl_add_u64 v[214:215], s[34:35], 0, v[130:131]
	s_mov_b32 m0, s78
	ds_read_b128 v[198:201], v149
	ds_read_b128 v[202:205], v149 offset:1024
	ds_read_b128 v[206:209], v149 offset:2048
	ds_read_b128 v[210:213], v149 offset:3072
	global_load_lds_dwordx4 v[214:215], off
	v_lshl_add_u64 v[216:217], s[34:35], 0, v[132:133]
	s_add_i32 m0, s78, 0x2000
	s_nop 0
	global_load_lds_dwordx4 v[216:217], off
	s_barrier
	s_waitcnt lgkmcnt(0)
	s_waitcnt lgkmcnt(0)
	v_mfma_f32_16x16x32_bf16 v[112:115], v[198:201], v[166:169], v[112:115]
	v_mfma_f32_16x16x32_bf16 v[116:119], v[206:209], v[166:169], v[116:119]
	v_mfma_f32_16x16x32_bf16 v[96:99], v[198:201], v[174:177], v[96:99]
	v_mfma_f32_16x16x32_bf16 v[100:103], v[206:209], v[174:177], v[100:103]
	v_mfma_f32_16x16x32_bf16 v[80:83], v[198:201], v[182:185], v[80:83]
	v_mfma_f32_16x16x32_bf16 v[84:87], v[206:209], v[182:185], v[84:87]
	v_mfma_f32_16x16x32_bf16 v[64:67], v[198:201], v[190:193], v[64:67]
	v_mfma_f32_16x16x32_bf16 v[68:71], v[206:209], v[190:193], v[68:71]
	v_mfma_f32_16x16x32_bf16 v[112:115], v[202:205], v[170:173], v[112:115]
	v_mfma_f32_16x16x32_bf16 v[116:119], v[210:213], v[170:173], v[116:119]
	v_mfma_f32_16x16x32_bf16 v[96:99], v[202:205], v[178:181], v[96:99]
	v_mfma_f32_16x16x32_bf16 v[100:103], v[210:213], v[178:181], v[100:103]
	v_mfma_f32_16x16x32_bf16 v[80:83], v[202:205], v[186:189], v[80:83]
	v_mfma_f32_16x16x32_bf16 v[84:87], v[210:213], v[186:189], v[84:87]
	v_mfma_f32_16x16x32_bf16 v[64:67], v[202:205], v[194:197], v[64:67]
	v_mfma_f32_16x16x32_bf16 v[68:71], v[210:213], v[194:197], v[68:71]
	s_mov_b32 m0, s29
	v_lshl_add_u64 v[218:219], s[36:37], 0, v[130:131]
	s_barrier
	ds_read_b128 v[166:169], v148 offset:16384
	ds_read_b128 v[170:173], v148 offset:17408
	ds_read_b128 v[174:177], v148 offset:18432
	ds_read_b128 v[178:181], v148 offset:19456
	ds_read_b128 v[182:185], v148 offset:20480
	ds_read_b128 v[186:189], v148 offset:21504
	ds_read_b128 v[190:193], v148 offset:22528
	ds_read_b128 v[194:197], v148 offset:23552
	global_load_lds_dwordx4 v[218:219], off
	v_lshl_add_u64 v[220:221], s[36:37], 0, v[132:133]
	s_mov_b32 m0, s43
	s_nop 0
	global_load_lds_dwordx4 v[220:221], off
	s_barrier
	s_waitcnt lgkmcnt(0)
	s_waitcnt lgkmcnt(0)
	v_mfma_f32_16x16x32_bf16 v[56:59], v[150:153], v[166:169], v[56:59]
	v_mfma_f32_16x16x32_bf16 v[60:63], v[158:161], v[166:169], v[60:63]
	v_mfma_f32_16x16x32_bf16 v[40:43], v[150:153], v[174:177], v[40:43]
	v_mfma_f32_16x16x32_bf16 v[44:47], v[158:161], v[174:177], v[44:47]
	v_mfma_f32_16x16x32_bf16 v[24:27], v[150:153], v[182:185], v[24:27]
	v_mfma_f32_16x16x32_bf16 v[28:31], v[158:161], v[182:185], v[28:31]
	v_mfma_f32_16x16x32_bf16 v[8:11], v[150:153], v[190:193], v[8:11]
	v_mfma_f32_16x16x32_bf16 v[12:15], v[158:161], v[190:193], v[12:15]
	v_mfma_f32_16x16x32_bf16 v[56:59], v[154:157], v[170:173], v[56:59]
	v_mfma_f32_16x16x32_bf16 v[60:63], v[162:165], v[170:173], v[60:63]
	v_mfma_f32_16x16x32_bf16 v[40:43], v[154:157], v[178:181], v[40:43]
	v_mfma_f32_16x16x32_bf16 v[44:47], v[162:165], v[178:181], v[44:47]
	v_mfma_f32_16x16x32_bf16 v[24:27], v[154:157], v[186:189], v[24:27]
	v_mfma_f32_16x16x32_bf16 v[28:31], v[162:165], v[186:189], v[28:31]
	v_mfma_f32_16x16x32_bf16 v[8:11], v[154:157], v[194:197], v[8:11]
	v_mfma_f32_16x16x32_bf16 v[12:15], v[162:165], v[194:197], v[12:15]
	s_barrier
	s_add_u32 s78, s34, 0x40000
	s_addc_u32 s79, s35, 0
	s_add_i32 s80, s61, s42
	v_lshl_add_u64 v[150:151], s[78:79], 0, v[130:131]
	s_mov_b32 m0, s80
	s_nop 0
	global_load_lds_dwordx4 v[150:151], off
	v_lshl_add_u64 v[150:151], s[78:79], 0, v[132:133]
	s_add_i32 m0, s80, 0x2000
	s_nop 0
	global_load_lds_dwordx4 v[150:151], off
	s_waitcnt vmcnt(6)
	s_barrier
	v_mfma_f32_16x16x32_bf16 v[48:51], v[198:201], v[166:169], v[48:51]
	v_mfma_f32_16x16x32_bf16 v[52:55], v[206:209], v[166:169], v[52:55]
	v_mfma_f32_16x16x32_bf16 v[32:35], v[198:201], v[174:177], v[32:35]
	v_mfma_f32_16x16x32_bf16 v[36:39], v[206:209], v[174:177], v[36:39]
	v_mfma_f32_16x16x32_bf16 v[16:19], v[198:201], v[182:185], v[16:19]
	v_mfma_f32_16x16x32_bf16 v[20:23], v[206:209], v[182:185], v[20:23]
	v_mfma_f32_16x16x32_bf16 v[0:3], v[198:201], v[190:193], v[0:3]
	v_mfma_f32_16x16x32_bf16 v[4:7], v[206:209], v[190:193], v[4:7]
	v_mfma_f32_16x16x32_bf16 v[48:51], v[202:205], v[170:173], v[48:51]
	v_mfma_f32_16x16x32_bf16 v[52:55], v[210:213], v[170:173], v[52:55]
	v_mfma_f32_16x16x32_bf16 v[32:35], v[202:205], v[178:181], v[32:35]
	v_mfma_f32_16x16x32_bf16 v[36:39], v[210:213], v[178:181], v[36:39]
	v_mfma_f32_16x16x32_bf16 v[16:19], v[202:205], v[186:189], v[16:19]
	v_mfma_f32_16x16x32_bf16 v[20:23], v[210:213], v[186:189], v[20:23]
	v_mfma_f32_16x16x32_bf16 v[0:3], v[202:205], v[194:197], v[0:3]
	v_mfma_f32_16x16x32_bf16 v[4:7], v[210:213], v[194:197], v[4:7]
	s_add_i32 s78, 0, 0x18000
	v_add_u32_e32 v162, s78, v143
	s_barrier
	ds_read_b128 v[150:153], v162
	ds_read_b128 v[154:157], v162 offset:1024
	ds_read_b128 v[158:161], v162 offset:2048
	ds_read_b128 v[162:165], v162 offset:3072
	s_add_u32 s36, s36, 0x40000
	s_addc_u32 s37, s37, 0
	s_mov_b32 m0, s52
	v_lshl_add_u64 v[198:199], s[36:37], 0, v[130:131]
	ds_read_b128 v[166:169], v148 offset:32768
	ds_read_b128 v[170:173], v148 offset:33792
	ds_read_b128 v[174:177], v148 offset:34816
	ds_read_b128 v[178:181], v148 offset:35840
	ds_read_b128 v[182:185], v148 offset:36864
	ds_read_b128 v[186:189], v148 offset:37888
	ds_read_b128 v[190:193], v148 offset:38912
	ds_read_b128 v[194:197], v148 offset:39936
	global_load_lds_dwordx4 v[198:199], off
	v_lshl_add_u64 v[198:199], s[36:37], 0, v[132:133]
	s_mov_b32 m0, s53
	s_nop 0
	global_load_lds_dwordx4 v[198:199], off
	s_waitcnt lgkmcnt(8)
	s_barrier
	s_waitcnt lgkmcnt(0)
	s_waitcnt lgkmcnt(0)
	v_mfma_f32_16x16x32_bf16 v[120:123], v[150:153], v[166:169], v[120:123]
	v_mfma_f32_16x16x32_bf16 v[124:127], v[158:161], v[166:169], v[124:127]
	v_mfma_f32_16x16x32_bf16 v[104:107], v[150:153], v[174:177], v[104:107]
	v_mfma_f32_16x16x32_bf16 v[108:111], v[158:161], v[174:177], v[108:111]
	v_mfma_f32_16x16x32_bf16 v[88:91], v[150:153], v[182:185], v[88:91]
	v_mfma_f32_16x16x32_bf16 v[92:95], v[158:161], v[182:185], v[92:95]
	v_mfma_f32_16x16x32_bf16 v[72:75], v[150:153], v[190:193], v[72:75]
	v_mfma_f32_16x16x32_bf16 v[76:79], v[158:161], v[190:193], v[76:79]
	v_mfma_f32_16x16x32_bf16 v[120:123], v[154:157], v[170:173], v[120:123]
	v_mfma_f32_16x16x32_bf16 v[124:127], v[162:165], v[170:173], v[124:127]
	v_mfma_f32_16x16x32_bf16 v[104:107], v[154:157], v[178:181], v[104:107]
	v_mfma_f32_16x16x32_bf16 v[108:111], v[162:165], v[178:181], v[108:111]
	v_mfma_f32_16x16x32_bf16 v[88:91], v[154:157], v[186:189], v[88:91]
	v_mfma_f32_16x16x32_bf16 v[92:95], v[162:165], v[186:189], v[92:95]
	v_mfma_f32_16x16x32_bf16 v[72:75], v[154:157], v[194:197], v[72:75]
	v_mfma_f32_16x16x32_bf16 v[76:79], v[162:165], v[194:197], v[76:79]
	s_barrier
	s_add_i32 s36, 0, 0x1c000
	s_add_i32 s37, s78, s42
	v_add_u32_e32 v210, s36, v143
	v_lshl_add_u64 v[214:215], v[214:215], 0, s[8:9]
	s_mov_b32 m0, s37
	ds_read_b128 v[198:201], v210
	ds_read_b128 v[202:205], v210 offset:1024
	ds_read_b128 v[206:209], v210 offset:2048
	ds_read_b128 v[210:213], v210 offset:3072
	global_load_lds_dwordx4 v[214:215], off
	v_lshl_add_u64 v[214:215], v[216:217], 0, s[8:9]
	s_add_i32 m0, s37, 0x2000
	s_nop 0
	global_load_lds_dwordx4 v[214:215], off
	s_barrier
	s_waitcnt lgkmcnt(0)
	s_waitcnt lgkmcnt(0)
	v_mfma_f32_16x16x32_bf16 v[112:115], v[198:201], v[166:169], v[112:115]
	v_mfma_f32_16x16x32_bf16 v[116:119], v[206:209], v[166:169], v[116:119]
	v_mfma_f32_16x16x32_bf16 v[96:99], v[198:201], v[174:177], v[96:99]
	v_mfma_f32_16x16x32_bf16 v[100:103], v[206:209], v[174:177], v[100:103]
	v_mfma_f32_16x16x32_bf16 v[80:83], v[198:201], v[182:185], v[80:83]
	v_mfma_f32_16x16x32_bf16 v[84:87], v[206:209], v[182:185], v[84:87]
	v_mfma_f32_16x16x32_bf16 v[64:67], v[198:201], v[190:193], v[64:67]
	v_mfma_f32_16x16x32_bf16 v[68:71], v[206:209], v[190:193], v[68:71]
	v_mfma_f32_16x16x32_bf16 v[112:115], v[202:205], v[170:173], v[112:115]
	v_mfma_f32_16x16x32_bf16 v[116:119], v[210:213], v[170:173], v[116:119]
	v_mfma_f32_16x16x32_bf16 v[96:99], v[202:205], v[178:181], v[96:99]
	v_mfma_f32_16x16x32_bf16 v[100:103], v[210:213], v[178:181], v[100:103]
	v_mfma_f32_16x16x32_bf16 v[80:83], v[202:205], v[186:189], v[80:83]
	v_mfma_f32_16x16x32_bf16 v[84:87], v[210:213], v[186:189], v[84:87]
	v_mfma_f32_16x16x32_bf16 v[64:67], v[202:205], v[194:197], v[64:67]
	v_mfma_f32_16x16x32_bf16 v[68:71], v[210:213], v[194:197], v[68:71]
	s_mov_b32 m0, s55
	v_lshl_add_u64 v[214:215], v[218:219], 0, s[8:9]
	s_barrier
	ds_read_b128 v[166:169], v148 offset:49152
	ds_read_b128 v[170:173], v148 offset:50176
	ds_read_b128 v[174:177], v148 offset:51200
	ds_read_b128 v[178:181], v148 offset:52224
	ds_read_b128 v[182:185], v148 offset:53248
	ds_read_b128 v[186:189], v148 offset:54272
	ds_read_b128 v[190:193], v148 offset:55296
	ds_read_b128 v[194:197], v148 offset:56320
	global_load_lds_dwordx4 v[214:215], off
	v_lshl_add_u64 v[214:215], v[220:221], 0, s[8:9]
	s_mov_b32 m0, s56
	s_nop 0
	global_load_lds_dwordx4 v[214:215], off
	s_barrier
	s_waitcnt lgkmcnt(0)
	s_waitcnt lgkmcnt(0)
	v_mfma_f32_16x16x32_bf16 v[56:59], v[150:153], v[166:169], v[56:59]
	v_mfma_f32_16x16x32_bf16 v[60:63], v[158:161], v[166:169], v[60:63]
	v_mfma_f32_16x16x32_bf16 v[40:43], v[150:153], v[174:177], v[40:43]
	v_mfma_f32_16x16x32_bf16 v[44:47], v[158:161], v[174:177], v[44:47]
	v_mfma_f32_16x16x32_bf16 v[24:27], v[150:153], v[182:185], v[24:27]
	v_mfma_f32_16x16x32_bf16 v[28:31], v[158:161], v[182:185], v[28:31]
	v_mfma_f32_16x16x32_bf16 v[8:11], v[150:153], v[190:193], v[8:11]
	v_mfma_f32_16x16x32_bf16 v[12:15], v[158:161], v[190:193], v[12:15]
	v_mfma_f32_16x16x32_bf16 v[56:59], v[154:157], v[170:173], v[56:59]
	v_mfma_f32_16x16x32_bf16 v[60:63], v[162:165], v[170:173], v[60:63]
	v_mfma_f32_16x16x32_bf16 v[40:43], v[154:157], v[178:181], v[40:43]
	v_mfma_f32_16x16x32_bf16 v[44:47], v[162:165], v[178:181], v[44:47]
	v_mfma_f32_16x16x32_bf16 v[24:27], v[154:157], v[186:189], v[24:27]
	v_mfma_f32_16x16x32_bf16 v[28:31], v[162:165], v[186:189], v[28:31]
	v_mfma_f32_16x16x32_bf16 v[8:11], v[154:157], v[194:197], v[8:11]
	v_mfma_f32_16x16x32_bf16 v[12:15], v[162:165], v[194:197], v[12:15]
	s_barrier
	s_add_u32 s34, s34, 0x40080
	s_addc_u32 s35, s35, 0
	s_add_i32 s36, s36, s42
	v_lshl_add_u64 v[150:151], s[34:35], 0, v[130:131]
	s_mov_b32 m0, s36
	s_nop 0
	global_load_lds_dwordx4 v[150:151], off
	v_lshl_add_u64 v[150:151], s[34:35], 0, v[132:133]
	s_add_i32 m0, s36, 0x2000
	s_nop 0
	global_load_lds_dwordx4 v[150:151], off
	s_waitcnt vmcnt(6)
	s_barrier
	v_mfma_f32_16x16x32_bf16 v[48:51], v[198:201], v[166:169], v[48:51]
	v_mfma_f32_16x16x32_bf16 v[52:55], v[206:209], v[166:169], v[52:55]
	v_mfma_f32_16x16x32_bf16 v[32:35], v[198:201], v[174:177], v[32:35]
	v_mfma_f32_16x16x32_bf16 v[36:39], v[206:209], v[174:177], v[36:39]
	v_mfma_f32_16x16x32_bf16 v[16:19], v[198:201], v[182:185], v[16:19]
	v_mfma_f32_16x16x32_bf16 v[20:23], v[206:209], v[182:185], v[20:23]
	v_mfma_f32_16x16x32_bf16 v[0:3], v[198:201], v[190:193], v[0:3]
	v_mfma_f32_16x16x32_bf16 v[4:7], v[206:209], v[190:193], v[4:7]
	v_mfma_f32_16x16x32_bf16 v[48:51], v[202:205], v[170:173], v[48:51]
	v_mfma_f32_16x16x32_bf16 v[52:55], v[210:213], v[170:173], v[52:55]
	v_mfma_f32_16x16x32_bf16 v[32:35], v[202:205], v[178:181], v[32:35]
	v_mfma_f32_16x16x32_bf16 v[36:39], v[210:213], v[178:181], v[36:39]
	v_mfma_f32_16x16x32_bf16 v[16:19], v[202:205], v[186:189], v[16:19]
	v_mfma_f32_16x16x32_bf16 v[20:23], v[210:213], v[186:189], v[20:23]
	v_mfma_f32_16x16x32_bf16 v[0:3], v[202:205], v[194:197], v[0:3]
	v_mfma_f32_16x16x32_bf16 v[4:7], v[210:213], v[194:197], v[4:7]
	s_add_i32 s77, s77, 2
	s_add_u32 s30, s30, 0x100
	s_addc_u32 s31, s31, 0
	s_add_u32 s75, s75, 0x100
	s_addc_u32 s76, s76, 0
	s_cmp_gt_u32 s77, 13
	s_barrier
	s_cbranch_scc0 .LBB0_1141
	v_mul_f32_e32 v124, 0xbfb8aa3b, v124
	v_exp_f32_e32 v150, v124
	v_mul_f32_e32 v124, 0xbfb8aa3b, v125
	v_exp_f32_e32 v151, v124
	v_lshl_add_u32 v124, s28, 8, v142
	v_ashrrev_i32_e32 v125, 31, v124
	v_lshlrev_b64 v[154:155], 11, v[124:125]
	v_pk_add_f32 v[150:151], v[150:151], 1.0 op_sel_hi:[1,0]
	v_mul_f32_e32 v126, 0xbfb8aa3b, v126
	v_div_scale_f32 v153, s[30:31], v151, v151, v121
	v_rcp_f32_e32 v156, v153
	v_mul_f32_e32 v127, 0xbfb8aa3b, v127
	v_exp_f32_e32 v126, v126
	v_exp_f32_e32 v127, v127
	v_fma_f32 v125, -v153, v156, 1.0
	v_fmac_f32_e32 v156, v125, v156
	v_div_scale_f32 v125, vcc, v121, v151, v121
	v_mul_f32_e32 v157, v125, v156
	v_fma_f32 v158, -v153, v157, v125
	v_fmac_f32_e32 v157, v158, v156
	v_fma_f32 v125, -v153, v157, v125
	v_div_scale_f32 v153, s[30:31], v150, v150, v120
	v_rcp_f32_e32 v158, v153
	v_div_fmas_f32 v125, v125, v156, v157
	v_div_fixup_f32 v121, v125, v151, v121
	v_pk_add_f32 v[126:127], v[126:127], 1.0 op_sel_hi:[1,0]
	v_fma_f32 v125, -v153, v158, 1.0
	v_fmac_f32_e32 v158, v125, v158
	v_div_scale_f32 v125, vcc, v120, v150, v120
	v_mul_f32_e32 v151, v125, v158
	v_fma_f32 v156, -v153, v151, v125
	v_fmac_f32_e32 v151, v156, v158
	v_fma_f32 v125, -v153, v151, v125
	v_div_scale_f32 v153, s[30:31], v127, v127, v123
	v_rcp_f32_e32 v156, v153
	v_div_fmas_f32 v125, v125, v158, v151
	v_div_fixup_f32 v120, v125, v150, v120
	v_mul_f32_e32 v116, 0xbfb8aa3b, v116
	v_fma_f32 v125, -v153, v156, 1.0
	v_fmac_f32_e32 v156, v125, v156
	v_div_scale_f32 v125, vcc, v123, v127, v123
	v_mul_f32_e32 v150, v125, v156
	v_fma_f32 v151, -v153, v150, v125
	v_fmac_f32_e32 v150, v151, v156
	v_div_scale_f32 v151, s[30:31], v126, v126, v122
	v_fma_f32 v125, -v153, v150, v125
	v_rcp_f32_e32 v153, v151
	v_div_fmas_f32 v125, v125, v156, v150
	v_div_fixup_f32 v123, v125, v127, v123
	v_mul_f32_e32 v117, 0xbfb8aa3b, v117
	v_fma_f32 v125, -v151, v153, 1.0
	v_fmac_f32_e32 v153, v125, v153
	v_div_scale_f32 v125, vcc, v122, v126, v122
	v_mul_f32_e32 v127, v125, v153
	v_fma_f32 v150, -v151, v127, v125
	v_exp_f32_e32 v116, v116
	v_exp_f32_e32 v117, v117
	v_fmac_f32_e32 v127, v150, v153
	v_fma_f32 v125, -v151, v127, v125
	v_div_fmas_f32 v125, v125, v153, v127
	v_div_fixup_f32 v125, v125, v126, v122
	v_pk_add_f32 v[126:127], v[116:117], 1.0 op_sel_hi:[1,0]
	v_cvt_pk_bf16_f32 v123, v125, v123
	v_div_scale_f32 v125, s[30:31], v127, v127, v113
	v_lshl_or_b32 v152, s72, 7, v144
	v_rcp_f32_e32 v150, v125
	v_ashrrev_i32_e32 v153, 31, v152
	v_lshl_add_u64 v[154:155], s[46:47], 0, v[154:155]
	v_cvt_pk_bf16_f32 v122, v120, v121
	v_lshlrev_b64 v[120:121], 1, v[152:153]
	v_lshl_add_u64 v[116:117], v[154:155], 0, v[120:121]
	global_store_dwordx2 v[116:117], v[122:123], off
	v_fma_f32 v122, -v125, v150, 1.0
	v_fmac_f32_e32 v150, v122, v150
	v_div_scale_f32 v122, vcc, v113, v127, v113
	v_mul_f32_e32 v123, v122, v150
	v_fma_f32 v151, -v125, v123, v122
	v_fmac_f32_e32 v123, v151, v150
	v_fma_f32 v122, -v125, v123, v122
	v_div_scale_f32 v125, s[30:31], v126, v126, v112
	v_rcp_f32_e32 v151, v125
	v_div_fmas_f32 v122, v122, v150, v123
	v_mul_f32_e32 v118, 0xbfb8aa3b, v118
	v_mul_f32_e32 v119, 0xbfb8aa3b, v119
	v_div_fixup_f32 v113, v122, v127, v113
	v_fma_f32 v122, -v125, v151, 1.0
	v_exp_f32_e32 v118, v118
	v_exp_f32_e32 v119, v119
	v_fmac_f32_e32 v151, v122, v151
	v_div_scale_f32 v122, vcc, v112, v126, v112
	v_mul_f32_e32 v123, v122, v151
	v_fma_f32 v127, -v125, v123, v122
	v_fmac_f32_e32 v123, v127, v151
	v_pk_add_f32 v[118:119], v[118:119], 1.0 op_sel_hi:[1,0]
	v_fma_f32 v122, -v125, v123, v122
	v_div_scale_f32 v125, s[30:31], v119, v119, v115
	v_rcp_f32_e32 v127, v125
	v_div_fmas_f32 v122, v122, v151, v123
	v_div_fixup_f32 v112, v122, v126, v112
	v_mul_f32_e32 v108, 0xbfb8aa3b, v108
	v_fma_f32 v122, -v125, v127, 1.0
	v_fmac_f32_e32 v127, v122, v127
	v_div_scale_f32 v122, vcc, v115, v119, v115
	v_mul_f32_e32 v123, v122, v127
	v_fma_f32 v126, -v125, v123, v122
	v_fmac_f32_e32 v123, v126, v127
	v_fma_f32 v122, -v125, v123, v122
	v_div_scale_f32 v125, s[30:31], v118, v118, v114
	v_rcp_f32_e32 v126, v125
	v_div_fmas_f32 v122, v122, v127, v123
	v_div_fixup_f32 v115, v122, v119, v115
	v_mul_f32_e32 v109, 0xbfb8aa3b, v109
	v_fma_f32 v119, -v125, v126, 1.0
	v_fmac_f32_e32 v126, v119, v126
	v_div_scale_f32 v119, vcc, v114, v118, v114
	v_mul_f32_e32 v122, v119, v126
	v_fma_f32 v123, -v125, v122, v119
	v_exp_f32_e32 v108, v108
	v_exp_f32_e32 v109, v109
	v_fmac_f32_e32 v122, v123, v126
	v_fma_f32 v119, -v125, v122, v119
	v_div_fmas_f32 v119, v119, v126, v122
	v_div_fixup_f32 v114, v119, v118, v114
	v_pk_add_f32 v[108:109], v[108:109], 1.0 op_sel_hi:[1,0]
	v_cvt_pk_bf16_f32 v112, v112, v113
	v_cvt_pk_bf16_f32 v113, v114, v115
	v_div_scale_f32 v114, s[30:31], v109, v109, v105
	v_rcp_f32_e32 v115, v114
	v_mul_f32_e32 v110, 0xbfb8aa3b, v110
	v_mul_f32_e32 v111, 0xbfb8aa3b, v111
	v_exp_f32_e32 v110, v110
	v_fma_f32 v118, -v114, v115, 1.0
	v_fmac_f32_e32 v115, v118, v115
	v_div_scale_f32 v118, vcc, v105, v109, v105
	v_mul_f32_e32 v119, v118, v115
	v_fma_f32 v122, -v114, v119, v118
	v_fmac_f32_e32 v119, v122, v115
	v_fma_f32 v114, -v114, v119, v118
	v_div_scale_f32 v118, s[30:31], v108, v108, v104
	v_rcp_f32_e32 v122, v118
	v_div_fmas_f32 v114, v114, v115, v119
	v_exp_f32_e32 v111, v111
	v_div_fixup_f32 v105, v114, v109, v105
	v_fma_f32 v109, -v118, v122, 1.0
	v_fmac_f32_e32 v122, v109, v122
	v_div_scale_f32 v109, vcc, v104, v108, v104
	v_mul_f32_e32 v114, v109, v122
	v_fma_f32 v115, -v118, v114, v109
	v_pk_add_f32 v[110:111], v[110:111], 1.0 op_sel_hi:[1,0]
	v_fmac_f32_e32 v114, v115, v122
	v_div_scale_f32 v115, s[30:31], v111, v111, v107
	v_fma_f32 v109, -v118, v114, v109
	v_rcp_f32_e32 v118, v115
	v_div_fmas_f32 v109, v109, v122, v114
	v_div_fixup_f32 v104, v109, v108, v104
	v_mul_f32_e32 v100, 0xbfb8aa3b, v100
	v_fma_f32 v108, -v115, v118, 1.0
	v_fmac_f32_e32 v118, v108, v118
	v_div_scale_f32 v108, vcc, v107, v111, v107
	v_mul_f32_e32 v109, v108, v118
	v_fma_f32 v114, -v115, v109, v108
	v_fmac_f32_e32 v109, v114, v118
	v_div_scale_f32 v114, s[30:31], v110, v110, v106
	v_fma_f32 v108, -v115, v109, v108
	v_rcp_f32_e32 v115, v114
	v_div_fmas_f32 v108, v108, v118, v109
	v_div_fixup_f32 v107, v108, v111, v107
	v_mul_f32_e32 v101, 0xbfb8aa3b, v101
	v_fma_f32 v108, -v114, v115, 1.0
	v_fmac_f32_e32 v115, v108, v115
	v_div_scale_f32 v108, vcc, v106, v110, v106
	v_mul_f32_e32 v109, v108, v115
	v_exp_f32_e32 v100, v100
	v_exp_f32_e32 v101, v101
	v_fma_f32 v111, -v114, v109, v108
	v_fmac_f32_e32 v109, v111, v115
	v_fma_f32 v108, -v114, v109, v108
	v_div_fmas_f32 v108, v108, v115, v109
	v_pk_add_f32 v[100:101], v[100:101], 1.0 op_sel_hi:[1,0]
	global_store_dwordx2 v[116:117], v[112:113], off offset:128
	v_or_b32_e32 v112, 16, v124
	v_div_fixup_f32 v106, v108, v110, v106
	v_div_scale_f32 v108, s[30:31], v101, v101, v97
	v_ashrrev_i32_e32 v113, 31, v112
	v_rcp_f32_e32 v109, v108
	v_lshlrev_b64 v[112:113], 11, v[112:113]
	v_lshl_add_u64 v[112:113], s[46:47], 0, v[112:113]
	v_cvt_pk_bf16_f32 v104, v104, v105
	v_cvt_pk_bf16_f32 v105, v106, v107
	v_lshl_add_u64 v[106:107], v[112:113], 0, v[120:121]
	global_store_dwordx2 v[106:107], v[104:105], off
	v_fma_f32 v104, -v108, v109, 1.0
	v_fmac_f32_e32 v109, v104, v109
	v_div_scale_f32 v104, vcc, v97, v101, v97
	v_mul_f32_e32 v105, v104, v109
	v_fma_f32 v110, -v108, v105, v104
	v_fmac_f32_e32 v105, v110, v109
	v_fma_f32 v104, -v108, v105, v104
	v_div_scale_f32 v108, s[30:31], v100, v100, v96
	v_rcp_f32_e32 v110, v108
	v_mul_f32_e32 v102, 0xbfb8aa3b, v102
	v_mul_f32_e32 v103, 0xbfb8aa3b, v103
	v_div_fmas_f32 v104, v104, v109, v105
	v_exp_f32_e32 v102, v102
	v_exp_f32_e32 v103, v103
	v_div_fixup_f32 v97, v104, v101, v97
	v_fma_f32 v101, -v108, v110, 1.0
	v_fmac_f32_e32 v110, v101, v110
	v_div_scale_f32 v101, vcc, v96, v100, v96
	v_mul_f32_e32 v104, v101, v110
	v_fma_f32 v105, -v108, v104, v101
	v_pk_add_f32 v[102:103], v[102:103], 1.0 op_sel_hi:[1,0]
	v_fmac_f32_e32 v104, v105, v110
	v_div_scale_f32 v105, s[30:31], v103, v103, v99
	v_fma_f32 v101, -v108, v104, v101
	v_rcp_f32_e32 v108, v105
	v_div_fmas_f32 v101, v101, v110, v104
	v_div_fixup_f32 v96, v101, v100, v96
	v_mul_f32_e32 v92, 0xbfb8aa3b, v92
	v_fma_f32 v100, -v105, v108, 1.0
	v_fmac_f32_e32 v108, v100, v108
	v_div_scale_f32 v100, vcc, v99, v103, v99
	v_mul_f32_e32 v101, v100, v108
	v_fma_f32 v104, -v105, v101, v100
	v_fmac_f32_e32 v101, v104, v108
	v_div_scale_f32 v104, s[30:31], v102, v102, v98
	v_fma_f32 v100, -v105, v101, v100
	v_rcp_f32_e32 v105, v104
	v_div_fmas_f32 v100, v100, v108, v101
	v_div_fixup_f32 v99, v100, v103, v99
	v_mul_f32_e32 v93, 0xbfb8aa3b, v93
	v_fma_f32 v100, -v104, v105, 1.0
	v_fmac_f32_e32 v105, v100, v105
	v_div_scale_f32 v100, vcc, v98, v102, v98
	v_mul_f32_e32 v101, v100, v105
	v_fma_f32 v103, -v104, v101, v100
	v_exp_f32_e32 v92, v92
	v_exp_f32_e32 v93, v93
	v_fmac_f32_e32 v101, v103, v105
	v_fma_f32 v100, -v104, v101, v100
	v_div_fmas_f32 v100, v100, v105, v101
	v_div_fixup_f32 v98, v100, v102, v98
	v_pk_add_f32 v[92:93], v[92:93], 1.0 op_sel_hi:[1,0]
	v_cvt_pk_bf16_f32 v96, v96, v97
	v_cvt_pk_bf16_f32 v97, v98, v99
	v_div_scale_f32 v98, s[30:31], v93, v93, v89
	v_rcp_f32_e32 v99, v98
	v_mul_f32_e32 v94, 0xbfb8aa3b, v94
	v_mul_f32_e32 v95, 0xbfb8aa3b, v95
	v_exp_f32_e32 v94, v94
	v_fma_f32 v100, -v98, v99, 1.0
	v_fmac_f32_e32 v99, v100, v99
	v_div_scale_f32 v100, vcc, v89, v93, v89
	v_mul_f32_e32 v101, v100, v99
	v_fma_f32 v102, -v98, v101, v100
	v_fmac_f32_e32 v101, v102, v99
	v_fma_f32 v98, -v98, v101, v100
	v_div_scale_f32 v100, s[30:31], v92, v92, v88
	v_rcp_f32_e32 v102, v100
	v_div_fmas_f32 v98, v98, v99, v101
	v_exp_f32_e32 v95, v95
	v_div_fixup_f32 v89, v98, v93, v89
	v_fma_f32 v93, -v100, v102, 1.0
	v_fmac_f32_e32 v102, v93, v102
	v_div_scale_f32 v93, vcc, v88, v92, v88
	v_mul_f32_e32 v98, v93, v102
	v_fma_f32 v99, -v100, v98, v93
	v_pk_add_f32 v[94:95], v[94:95], 1.0 op_sel_hi:[1,0]
	v_fmac_f32_e32 v98, v99, v102
	v_div_scale_f32 v99, s[30:31], v95, v95, v91
	v_fma_f32 v93, -v100, v98, v93
	v_rcp_f32_e32 v100, v99
	v_div_fmas_f32 v93, v93, v102, v98
	v_div_fixup_f32 v88, v93, v92, v88
	v_mul_f32_e32 v84, 0xbfb8aa3b, v84
	v_fma_f32 v92, -v99, v100, 1.0
	v_fmac_f32_e32 v100, v92, v100
	v_div_scale_f32 v92, vcc, v91, v95, v91
	v_mul_f32_e32 v93, v92, v100
	v_fma_f32 v98, -v99, v93, v92
	v_fmac_f32_e32 v93, v98, v100
	v_div_scale_f32 v98, s[30:31], v94, v94, v90
	v_fma_f32 v92, -v99, v93, v92
	v_rcp_f32_e32 v99, v98
	v_div_fmas_f32 v92, v92, v100, v93
	v_div_fixup_f32 v91, v92, v95, v91
	v_mul_f32_e32 v85, 0xbfb8aa3b, v85
	v_fma_f32 v92, -v98, v99, 1.0
	v_fmac_f32_e32 v99, v92, v99
	v_div_scale_f32 v92, vcc, v90, v94, v90
	v_mul_f32_e32 v93, v92, v99
	v_exp_f32_e32 v84, v84
	v_exp_f32_e32 v85, v85
	v_fma_f32 v95, -v98, v93, v92
	v_fmac_f32_e32 v93, v95, v99
	v_fma_f32 v92, -v98, v93, v92
	v_div_fmas_f32 v92, v92, v99, v93
	v_pk_add_f32 v[84:85], v[84:85], 1.0 op_sel_hi:[1,0]
	global_store_dwordx2 v[106:107], v[96:97], off offset:128
	v_or_b32_e32 v96, 32, v124
	v_div_fixup_f32 v90, v92, v94, v90
	v_div_scale_f32 v92, s[30:31], v85, v85, v81
	v_ashrrev_i32_e32 v97, 31, v96
	v_rcp_f32_e32 v93, v92
	v_lshlrev_b64 v[96:97], 11, v[96:97]
	v_lshl_add_u64 v[96:97], s[46:47], 0, v[96:97]
	v_cvt_pk_bf16_f32 v88, v88, v89
	v_cvt_pk_bf16_f32 v89, v90, v91
	v_lshl_add_u64 v[90:91], v[96:97], 0, v[120:121]
	global_store_dwordx2 v[90:91], v[88:89], off
	v_fma_f32 v88, -v92, v93, 1.0
	v_fmac_f32_e32 v93, v88, v93
	v_div_scale_f32 v88, vcc, v81, v85, v81
	v_mul_f32_e32 v89, v88, v93
	v_fma_f32 v94, -v92, v89, v88
	v_fmac_f32_e32 v89, v94, v93
	v_fma_f32 v88, -v92, v89, v88
	v_div_scale_f32 v92, s[30:31], v84, v84, v80
	v_rcp_f32_e32 v94, v92
	v_mul_f32_e32 v86, 0xbfb8aa3b, v86
	v_mul_f32_e32 v87, 0xbfb8aa3b, v87
	v_div_fmas_f32 v88, v88, v93, v89
	v_exp_f32_e32 v86, v86
	v_exp_f32_e32 v87, v87
	v_div_fixup_f32 v81, v88, v85, v81
	v_fma_f32 v85, -v92, v94, 1.0
	v_fmac_f32_e32 v94, v85, v94
	v_div_scale_f32 v85, vcc, v80, v84, v80
	v_mul_f32_e32 v88, v85, v94
	v_fma_f32 v89, -v92, v88, v85
	v_pk_add_f32 v[86:87], v[86:87], 1.0 op_sel_hi:[1,0]
	v_fmac_f32_e32 v88, v89, v94
	v_div_scale_f32 v89, s[30:31], v87, v87, v83
	v_fma_f32 v85, -v92, v88, v85
	v_rcp_f32_e32 v92, v89
	v_div_fmas_f32 v85, v85, v94, v88
	v_div_fixup_f32 v80, v85, v84, v80
	v_mul_f32_e32 v76, 0xbfb8aa3b, v76
	v_fma_f32 v84, -v89, v92, 1.0
	v_fmac_f32_e32 v92, v84, v92
	v_div_scale_f32 v84, vcc, v83, v87, v83
	v_mul_f32_e32 v85, v84, v92
	v_fma_f32 v88, -v89, v85, v84
	v_fmac_f32_e32 v85, v88, v92
	v_div_scale_f32 v88, s[30:31], v86, v86, v82
	v_fma_f32 v84, -v89, v85, v84
	v_rcp_f32_e32 v89, v88
	v_div_fmas_f32 v84, v84, v92, v85
	v_div_fixup_f32 v83, v84, v87, v83
	v_mul_f32_e32 v77, 0xbfb8aa3b, v77
	v_fma_f32 v84, -v88, v89, 1.0
	v_fmac_f32_e32 v89, v84, v89
	v_div_scale_f32 v84, vcc, v82, v86, v82
	v_mul_f32_e32 v85, v84, v89
	v_fma_f32 v87, -v88, v85, v84
	v_exp_f32_e32 v76, v76
	v_exp_f32_e32 v77, v77
	v_fmac_f32_e32 v85, v87, v89
	v_fma_f32 v84, -v88, v85, v84
	v_div_fmas_f32 v84, v84, v89, v85
	v_div_fixup_f32 v82, v84, v86, v82
	v_pk_add_f32 v[76:77], v[76:77], 1.0 op_sel_hi:[1,0]
	v_cvt_pk_bf16_f32 v80, v80, v81
	v_cvt_pk_bf16_f32 v81, v82, v83
	v_div_scale_f32 v82, s[30:31], v77, v77, v73
	v_rcp_f32_e32 v83, v82
	v_mul_f32_e32 v78, 0xbfb8aa3b, v78
	v_mul_f32_e32 v79, 0xbfb8aa3b, v79
	v_exp_f32_e32 v78, v78
	v_fma_f32 v84, -v82, v83, 1.0
	v_fmac_f32_e32 v83, v84, v83
	v_div_scale_f32 v84, vcc, v73, v77, v73
	v_mul_f32_e32 v85, v84, v83
	v_fma_f32 v86, -v82, v85, v84
	v_fmac_f32_e32 v85, v86, v83
	v_fma_f32 v82, -v82, v85, v84
	v_div_scale_f32 v84, s[30:31], v76, v76, v72
	v_rcp_f32_e32 v86, v84
	v_div_fmas_f32 v82, v82, v83, v85
	v_exp_f32_e32 v79, v79
	v_div_fixup_f32 v73, v82, v77, v73
	v_fma_f32 v77, -v84, v86, 1.0
	v_fmac_f32_e32 v86, v77, v86
	v_div_scale_f32 v77, vcc, v72, v76, v72
	v_mul_f32_e32 v82, v77, v86
	v_fma_f32 v83, -v84, v82, v77
	v_pk_add_f32 v[78:79], v[78:79], 1.0 op_sel_hi:[1,0]
	v_fmac_f32_e32 v82, v83, v86
	v_div_scale_f32 v83, s[30:31], v79, v79, v75
	v_fma_f32 v77, -v84, v82, v77
	v_rcp_f32_e32 v84, v83
	v_div_fmas_f32 v77, v77, v86, v82
	v_div_fixup_f32 v72, v77, v76, v72
	v_mul_f32_e32 v68, 0xbfb8aa3b, v68
	v_fma_f32 v76, -v83, v84, 1.0
	v_fmac_f32_e32 v84, v76, v84
	v_div_scale_f32 v76, vcc, v75, v79, v75
	v_mul_f32_e32 v77, v76, v84
	v_fma_f32 v82, -v83, v77, v76
	v_fmac_f32_e32 v77, v82, v84
	v_div_scale_f32 v82, s[30:31], v78, v78, v74
	v_fma_f32 v76, -v83, v77, v76
	v_rcp_f32_e32 v83, v82
	v_div_fmas_f32 v76, v76, v84, v77
	v_div_fixup_f32 v75, v76, v79, v75
	v_mul_f32_e32 v69, 0xbfb8aa3b, v69
	v_fma_f32 v76, -v82, v83, 1.0
	v_fmac_f32_e32 v83, v76, v83
	v_div_scale_f32 v76, vcc, v74, v78, v74
	v_mul_f32_e32 v77, v76, v83
	v_exp_f32_e32 v68, v68
	v_exp_f32_e32 v69, v69
	v_fma_f32 v79, -v82, v77, v76
	v_fmac_f32_e32 v77, v79, v83
	v_fma_f32 v76, -v82, v77, v76
	v_div_fmas_f32 v76, v76, v83, v77
	v_pk_add_f32 v[68:69], v[68:69], 1.0 op_sel_hi:[1,0]
	global_store_dwordx2 v[90:91], v[80:81], off offset:128
	v_or_b32_e32 v80, 48, v124
	v_div_fixup_f32 v74, v76, v78, v74
	v_div_scale_f32 v76, s[30:31], v69, v69, v65
	v_ashrrev_i32_e32 v81, 31, v80
	v_rcp_f32_e32 v77, v76
	v_lshlrev_b64 v[80:81], 11, v[80:81]
	v_lshl_add_u64 v[80:81], s[46:47], 0, v[80:81]
	v_cvt_pk_bf16_f32 v72, v72, v73
	v_cvt_pk_bf16_f32 v73, v74, v75
	v_lshl_add_u64 v[74:75], v[80:81], 0, v[120:121]
	global_store_dwordx2 v[74:75], v[72:73], off
	v_fma_f32 v72, -v76, v77, 1.0
	v_fmac_f32_e32 v77, v72, v77
	v_div_scale_f32 v72, vcc, v65, v69, v65
	v_mul_f32_e32 v73, v72, v77
	v_fma_f32 v78, -v76, v73, v72
	v_fmac_f32_e32 v73, v78, v77
	v_fma_f32 v72, -v76, v73, v72
	v_div_scale_f32 v76, s[30:31], v68, v68, v64
	v_rcp_f32_e32 v78, v76
	v_mul_f32_e32 v70, 0xbfb8aa3b, v70
	v_mul_f32_e32 v71, 0xbfb8aa3b, v71
	v_div_fmas_f32 v72, v72, v77, v73
	v_exp_f32_e32 v70, v70
	v_exp_f32_e32 v71, v71
	v_div_fixup_f32 v65, v72, v69, v65
	v_fma_f32 v69, -v76, v78, 1.0
	v_fmac_f32_e32 v78, v69, v78
	v_div_scale_f32 v69, vcc, v64, v68, v64
	v_mul_f32_e32 v72, v69, v78
	v_fma_f32 v73, -v76, v72, v69
	v_pk_add_f32 v[70:71], v[70:71], 1.0 op_sel_hi:[1,0]
	v_fmac_f32_e32 v72, v73, v78
	v_div_scale_f32 v73, s[30:31], v71, v71, v67
	v_fma_f32 v69, -v76, v72, v69
	v_rcp_f32_e32 v76, v73
	v_div_fmas_f32 v69, v69, v78, v72
	v_div_fixup_f32 v64, v69, v68, v64
	v_mul_f32_e32 v60, 0xbfb8aa3b, v60
	v_fma_f32 v68, -v73, v76, 1.0
	v_fmac_f32_e32 v76, v68, v76
	v_div_scale_f32 v68, vcc, v67, v71, v67
	v_mul_f32_e32 v69, v68, v76
	v_fma_f32 v72, -v73, v69, v68
	v_fmac_f32_e32 v69, v72, v76
	v_div_scale_f32 v72, s[30:31], v70, v70, v66
	v_fma_f32 v68, -v73, v69, v68
	v_rcp_f32_e32 v73, v72
	v_div_fmas_f32 v68, v68, v76, v69
	v_div_fixup_f32 v67, v68, v71, v67
	v_mul_f32_e32 v61, 0xbfb8aa3b, v61
	v_fma_f32 v68, -v72, v73, 1.0
	v_fmac_f32_e32 v73, v68, v73
	v_div_scale_f32 v68, vcc, v66, v70, v66
	v_mul_f32_e32 v69, v68, v73
	v_exp_f32_e32 v60, v60
	v_exp_f32_e32 v61, v61
	v_fma_f32 v71, -v72, v69, v68
	v_fmac_f32_e32 v69, v71, v73
	v_fma_f32 v68, -v72, v69, v68
	v_div_fmas_f32 v68, v68, v73, v69
	v_pk_add_f32 v[60:61], v[60:61], 1.0 op_sel_hi:[1,0]
	v_div_fixup_f32 v66, v68, v70, v66
	v_div_scale_f32 v68, s[30:31], v61, v61, v57
	v_rcp_f32_e32 v69, v68
	v_cvt_pk_bf16_f32 v64, v64, v65
	v_cvt_pk_bf16_f32 v65, v66, v67
	global_store_dwordx2 v[74:75], v[64:65], off offset:128
	v_fma_f32 v64, -v68, v69, 1.0
	v_fmac_f32_e32 v69, v64, v69
	v_div_scale_f32 v64, vcc, v57, v61, v57
	v_mul_f32_e32 v65, v64, v69
	v_fma_f32 v66, -v68, v65, v64
	v_fmac_f32_e32 v65, v66, v69
	v_div_scale_f32 v66, s[30:31], v60, v60, v56
	v_rcp_f32_e32 v67, v66
	v_fma_f32 v64, -v68, v65, v64
	v_mul_f32_e32 v62, 0xbfb8aa3b, v62
	v_mul_f32_e32 v63, 0xbfb8aa3b, v63
	v_div_fmas_f32 v64, v64, v69, v65
	v_exp_f32_e32 v62, v62
	v_exp_f32_e32 v63, v63
	v_div_fixup_f32 v57, v64, v61, v57
	v_fma_f32 v61, -v66, v67, 1.0
	v_fmac_f32_e32 v67, v61, v67
	v_div_scale_f32 v61, vcc, v56, v60, v56
	v_mul_f32_e32 v64, v61, v67
	v_fma_f32 v65, -v66, v64, v61
	v_pk_add_f32 v[62:63], v[62:63], 1.0 op_sel_hi:[1,0]
	v_fmac_f32_e32 v64, v65, v67
	v_div_scale_f32 v65, s[30:31], v63, v63, v59
	v_fma_f32 v61, -v66, v64, v61
	v_rcp_f32_e32 v66, v65
	v_div_fmas_f32 v61, v61, v67, v64
	v_div_fixup_f32 v56, v61, v60, v56
	v_mul_f32_e32 v52, 0xbfb8aa3b, v52
	v_fma_f32 v60, -v65, v66, 1.0
	v_fmac_f32_e32 v66, v60, v66
	v_div_scale_f32 v60, vcc, v59, v63, v59
	v_mul_f32_e32 v61, v60, v66
	v_fma_f32 v64, -v65, v61, v60
	v_fmac_f32_e32 v61, v64, v66
	v_div_scale_f32 v64, s[30:31], v62, v62, v58
	v_fma_f32 v60, -v65, v61, v60
	v_rcp_f32_e32 v65, v64
	v_div_fmas_f32 v60, v60, v66, v61
	v_div_fixup_f32 v59, v60, v63, v59
	v_mul_f32_e32 v53, 0xbfb8aa3b, v53
	v_fma_f32 v60, -v64, v65, 1.0
	v_fmac_f32_e32 v65, v60, v65
	v_div_scale_f32 v60, vcc, v58, v62, v58
	v_mul_f32_e32 v61, v60, v65
	v_exp_f32_e32 v52, v52
	v_exp_f32_e32 v53, v53
	v_fma_f32 v63, -v64, v61, v60
	v_fmac_f32_e32 v61, v63, v65
	v_fma_f32 v60, -v64, v61, v60
	v_div_fmas_f32 v60, v60, v65, v61
	v_pk_add_f32 v[52:53], v[52:53], 1.0 op_sel_hi:[1,0]
	v_div_fixup_f32 v58, v60, v62, v58
	v_div_scale_f32 v62, s[30:31], v53, v53, v49
	v_rcp_f32_e32 v63, v62
	v_add_co_u32_e32 v60, vcc, s62, v116
	v_cvt_pk_bf16_f32 v56, v56, v57
	v_cvt_pk_bf16_f32 v57, v58, v59
	v_addc_co_u32_e32 v61, vcc, 0, v117, vcc
	global_store_dwordx2 v[60:61], v[56:57], off
	v_fma_f32 v56, -v62, v63, 1.0
	v_fmac_f32_e32 v63, v56, v63
	v_div_scale_f32 v56, vcc, v49, v53, v49
	v_mul_f32_e32 v57, v56, v63
	v_fma_f32 v60, -v62, v57, v56
	v_fmac_f32_e32 v57, v60, v63
	v_div_scale_f32 v60, s[30:31], v52, v52, v48
	v_rcp_f32_e32 v61, v60
	v_fma_f32 v56, -v62, v57, v56
	v_mul_f32_e32 v54, 0xbfb8aa3b, v54
	v_mul_f32_e32 v55, 0xbfb8aa3b, v55
	v_div_fmas_f32 v56, v56, v63, v57
	v_exp_f32_e32 v54, v54
	v_exp_f32_e32 v55, v55
	v_div_fixup_f32 v49, v56, v53, v49
	v_fma_f32 v53, -v60, v61, 1.0
	v_fmac_f32_e32 v61, v53, v61
	v_div_scale_f32 v53, vcc, v48, v52, v48
	v_mul_f32_e32 v56, v53, v61
	v_fma_f32 v57, -v60, v56, v53
	v_pk_add_f32 v[54:55], v[54:55], 1.0 op_sel_hi:[1,0]
	v_fmac_f32_e32 v56, v57, v61
	v_div_scale_f32 v57, s[30:31], v55, v55, v51
	v_fma_f32 v53, -v60, v56, v53
	v_rcp_f32_e32 v60, v57
	v_div_fmas_f32 v53, v53, v61, v56
	v_div_fixup_f32 v48, v53, v52, v48
	v_mul_f32_e32 v44, 0xbfb8aa3b, v44
	v_fma_f32 v52, -v57, v60, 1.0
	v_fmac_f32_e32 v60, v52, v60
	v_div_scale_f32 v52, vcc, v51, v55, v51
	v_mul_f32_e32 v53, v52, v60
	v_fma_f32 v56, -v57, v53, v52
	v_fmac_f32_e32 v53, v56, v60
	v_div_scale_f32 v56, s[30:31], v54, v54, v50
	v_fma_f32 v52, -v57, v53, v52
	v_rcp_f32_e32 v57, v56
	v_div_fmas_f32 v52, v52, v60, v53
	v_div_fixup_f32 v51, v52, v55, v51
	v_mul_f32_e32 v45, 0xbfb8aa3b, v45
	v_fma_f32 v52, -v56, v57, 1.0
	v_fmac_f32_e32 v57, v52, v57
	v_div_scale_f32 v52, vcc, v50, v54, v50
	v_mul_f32_e32 v53, v52, v57
	v_exp_f32_e32 v44, v44
	v_exp_f32_e32 v45, v45
	v_fma_f32 v55, -v56, v53, v52
	v_fmac_f32_e32 v53, v55, v57
	v_fma_f32 v52, -v56, v53, v52
	v_div_fmas_f32 v52, v52, v57, v53
	v_pk_add_f32 v[44:45], v[44:45], 1.0 op_sel_hi:[1,0]
	v_div_fixup_f32 v50, v52, v54, v50
	v_div_scale_f32 v52, s[30:31], v45, v45, v41
	v_rcp_f32_e32 v53, v52
	v_lshl_add_u64 v[58:59], v[116:117], 0, s[6:7]
	v_cvt_pk_bf16_f32 v48, v48, v49
	v_cvt_pk_bf16_f32 v49, v50, v51
	global_store_dwordx2 v[58:59], v[48:49], off offset:128
	v_fma_f32 v48, -v52, v53, 1.0
	v_fmac_f32_e32 v53, v48, v53
	v_div_scale_f32 v48, vcc, v41, v45, v41
	v_mul_f32_e32 v49, v48, v53
	v_fma_f32 v50, -v52, v49, v48
	v_fmac_f32_e32 v49, v50, v53
	v_div_scale_f32 v50, s[30:31], v44, v44, v40
	v_rcp_f32_e32 v51, v50
	v_fma_f32 v48, -v52, v49, v48
	v_mul_f32_e32 v46, 0xbfb8aa3b, v46
	v_mul_f32_e32 v47, 0xbfb8aa3b, v47
	v_div_fmas_f32 v48, v48, v53, v49
	v_exp_f32_e32 v46, v46
	v_exp_f32_e32 v47, v47
	v_div_fixup_f32 v41, v48, v45, v41
	v_fma_f32 v45, -v50, v51, 1.0
	v_fmac_f32_e32 v51, v45, v51
	v_div_scale_f32 v45, vcc, v40, v44, v40
	v_mul_f32_e32 v48, v45, v51
	v_fma_f32 v49, -v50, v48, v45
	v_pk_add_f32 v[46:47], v[46:47], 1.0 op_sel_hi:[1,0]
	v_fmac_f32_e32 v48, v49, v51
	v_div_scale_f32 v49, s[30:31], v47, v47, v43
	v_fma_f32 v45, -v50, v48, v45
	v_rcp_f32_e32 v50, v49
	v_div_fmas_f32 v45, v45, v51, v48
	v_div_fixup_f32 v40, v45, v44, v40
	v_mul_f32_e32 v36, 0xbfb8aa3b, v36
	v_fma_f32 v44, -v49, v50, 1.0
	v_fmac_f32_e32 v50, v44, v50
	v_div_scale_f32 v44, vcc, v43, v47, v43
	v_mul_f32_e32 v45, v44, v50
	v_fma_f32 v48, -v49, v45, v44
	v_fmac_f32_e32 v45, v48, v50
	v_div_scale_f32 v48, s[30:31], v46, v46, v42
	v_fma_f32 v44, -v49, v45, v44
	v_rcp_f32_e32 v49, v48
	v_div_fmas_f32 v44, v44, v50, v45
	v_div_fixup_f32 v43, v44, v47, v43
	v_mul_f32_e32 v37, 0xbfb8aa3b, v37
	v_fma_f32 v44, -v48, v49, 1.0
	v_fmac_f32_e32 v49, v44, v49
	v_div_scale_f32 v44, vcc, v42, v46, v42
	v_mul_f32_e32 v45, v44, v49
	v_exp_f32_e32 v36, v36
	v_exp_f32_e32 v37, v37
	v_fma_f32 v47, -v48, v45, v44
	v_fmac_f32_e32 v45, v47, v49
	v_fma_f32 v44, -v48, v45, v44
	v_div_fmas_f32 v44, v44, v49, v45
	v_pk_add_f32 v[36:37], v[36:37], 1.0 op_sel_hi:[1,0]
	v_div_fixup_f32 v42, v44, v46, v42
	v_div_scale_f32 v46, s[30:31], v37, v37, v33
	v_rcp_f32_e32 v47, v46
	v_add_co_u32_e32 v44, vcc, s63, v116
	v_cvt_pk_bf16_f32 v40, v40, v41
	v_cvt_pk_bf16_f32 v41, v42, v43
	v_addc_co_u32_e32 v45, vcc, 0, v117, vcc
	global_store_dwordx2 v[44:45], v[40:41], off
	v_fma_f32 v40, -v46, v47, 1.0
	v_fmac_f32_e32 v47, v40, v47
	v_div_scale_f32 v40, vcc, v33, v37, v33
	v_mul_f32_e32 v41, v40, v47
	v_fma_f32 v44, -v46, v41, v40
	v_fmac_f32_e32 v41, v44, v47
	v_div_scale_f32 v44, s[30:31], v36, v36, v32
	v_rcp_f32_e32 v45, v44
	v_fma_f32 v40, -v46, v41, v40
	v_mul_f32_e32 v38, 0xbfb8aa3b, v38
	v_mul_f32_e32 v39, 0xbfb8aa3b, v39
	v_div_fmas_f32 v40, v40, v47, v41
	v_exp_f32_e32 v38, v38
	v_exp_f32_e32 v39, v39
	v_div_fixup_f32 v33, v40, v37, v33
	v_fma_f32 v37, -v44, v45, 1.0
	v_fmac_f32_e32 v45, v37, v45
	v_div_scale_f32 v37, vcc, v32, v36, v32
	v_mul_f32_e32 v40, v37, v45
	v_fma_f32 v41, -v44, v40, v37
	v_pk_add_f32 v[38:39], v[38:39], 1.0 op_sel_hi:[1,0]
	v_fmac_f32_e32 v40, v41, v45
	v_div_scale_f32 v41, s[30:31], v39, v39, v35
	v_fma_f32 v37, -v44, v40, v37
	v_rcp_f32_e32 v44, v41
	v_div_fmas_f32 v37, v37, v45, v40
	v_div_fixup_f32 v32, v37, v36, v32
	v_mul_f32_e32 v28, 0xbfb8aa3b, v28
	v_fma_f32 v36, -v41, v44, 1.0
	v_fmac_f32_e32 v44, v36, v44
	v_div_scale_f32 v36, vcc, v35, v39, v35
	v_mul_f32_e32 v37, v36, v44
	v_fma_f32 v40, -v41, v37, v36
	v_fmac_f32_e32 v37, v40, v44
	v_div_scale_f32 v40, s[30:31], v38, v38, v34
	v_fma_f32 v36, -v41, v37, v36
	v_rcp_f32_e32 v41, v40
	v_div_fmas_f32 v36, v36, v44, v37
	v_div_fixup_f32 v35, v36, v39, v35
	v_mul_f32_e32 v29, 0xbfb8aa3b, v29
	v_fma_f32 v36, -v40, v41, 1.0
	v_fmac_f32_e32 v41, v36, v41
	v_div_scale_f32 v36, vcc, v34, v38, v34
	v_mul_f32_e32 v37, v36, v41
	v_exp_f32_e32 v28, v28
	v_exp_f32_e32 v29, v29
	v_fma_f32 v39, -v40, v37, v36
	v_fmac_f32_e32 v37, v39, v41
	v_fma_f32 v36, -v40, v37, v36
	v_div_fmas_f32 v36, v36, v41, v37
	v_pk_add_f32 v[28:29], v[28:29], 1.0 op_sel_hi:[1,0]
	v_div_fixup_f32 v34, v36, v38, v34
	v_div_scale_f32 v36, s[30:31], v29, v29, v25
	v_rcp_f32_e32 v37, v36
	v_lshl_add_u64 v[42:43], v[116:117], 0, s[10:11]
	v_cvt_pk_bf16_f32 v32, v32, v33
	v_cvt_pk_bf16_f32 v33, v34, v35
	global_store_dwordx2 v[42:43], v[32:33], off offset:128
	v_fma_f32 v32, -v36, v37, 1.0
	v_fmac_f32_e32 v37, v32, v37
	v_div_scale_f32 v32, vcc, v25, v29, v25
	v_mul_f32_e32 v33, v32, v37
	v_fma_f32 v34, -v36, v33, v32
	v_fmac_f32_e32 v33, v34, v37
	v_div_scale_f32 v34, s[30:31], v28, v28, v24
	v_rcp_f32_e32 v35, v34
	v_fma_f32 v32, -v36, v33, v32
	v_mul_f32_e32 v30, 0xbfb8aa3b, v30
	v_mul_f32_e32 v31, 0xbfb8aa3b, v31
	v_div_fmas_f32 v32, v32, v37, v33
	v_exp_f32_e32 v30, v30
	v_exp_f32_e32 v31, v31
	v_div_fixup_f32 v25, v32, v29, v25
	v_fma_f32 v29, -v34, v35, 1.0
	v_fmac_f32_e32 v35, v29, v35
	v_div_scale_f32 v29, vcc, v24, v28, v24
	v_mul_f32_e32 v32, v29, v35
	v_fma_f32 v33, -v34, v32, v29
	v_pk_add_f32 v[30:31], v[30:31], 1.0 op_sel_hi:[1,0]
	v_fmac_f32_e32 v32, v33, v35
	v_div_scale_f32 v33, s[30:31], v31, v31, v27
	v_fma_f32 v29, -v34, v32, v29
	v_rcp_f32_e32 v34, v33
	v_div_fmas_f32 v29, v29, v35, v32
	v_div_fixup_f32 v24, v29, v28, v24
	v_mul_f32_e32 v20, 0xbfb8aa3b, v20
	v_fma_f32 v28, -v33, v34, 1.0
	v_fmac_f32_e32 v34, v28, v34
	v_div_scale_f32 v28, vcc, v27, v31, v27
	v_mul_f32_e32 v29, v28, v34
	v_fma_f32 v32, -v33, v29, v28
	v_fmac_f32_e32 v29, v32, v34
	v_div_scale_f32 v32, s[30:31], v30, v30, v26
	v_fma_f32 v28, -v33, v29, v28
	v_rcp_f32_e32 v33, v32
	v_div_fmas_f32 v28, v28, v34, v29
	v_div_fixup_f32 v27, v28, v31, v27
	v_mul_f32_e32 v21, 0xbfb8aa3b, v21
	v_fma_f32 v28, -v32, v33, 1.0
	v_fmac_f32_e32 v33, v28, v33
	v_div_scale_f32 v28, vcc, v26, v30, v26
	v_mul_f32_e32 v29, v28, v33
	v_exp_f32_e32 v20, v20
	v_exp_f32_e32 v21, v21
	v_fma_f32 v31, -v32, v29, v28
	v_fmac_f32_e32 v29, v31, v33
	v_fma_f32 v28, -v32, v29, v28
	v_div_fmas_f32 v28, v28, v33, v29
	v_pk_add_f32 v[20:21], v[20:21], 1.0 op_sel_hi:[1,0]
	v_div_fixup_f32 v26, v28, v30, v26
	v_div_scale_f32 v30, s[30:31], v21, v21, v17
	v_rcp_f32_e32 v31, v30
	v_add_co_u32_e32 v28, vcc, s70, v116
	v_cvt_pk_bf16_f32 v24, v24, v25
	v_cvt_pk_bf16_f32 v25, v26, v27
	v_addc_co_u32_e32 v29, vcc, 0, v117, vcc
	global_store_dwordx2 v[28:29], v[24:25], off
	v_fma_f32 v24, -v30, v31, 1.0
	v_fmac_f32_e32 v31, v24, v31
	v_div_scale_f32 v24, vcc, v17, v21, v17
	v_mul_f32_e32 v25, v24, v31
	v_fma_f32 v28, -v30, v25, v24
	v_fmac_f32_e32 v25, v28, v31
	v_div_scale_f32 v28, s[30:31], v20, v20, v16
	v_rcp_f32_e32 v29, v28
	v_fma_f32 v24, -v30, v25, v24
	v_mul_f32_e32 v22, 0xbfb8aa3b, v22
	v_mul_f32_e32 v23, 0xbfb8aa3b, v23
	v_div_fmas_f32 v24, v24, v31, v25
	v_exp_f32_e32 v22, v22
	v_exp_f32_e32 v23, v23
	v_div_fixup_f32 v17, v24, v21, v17
	v_fma_f32 v21, -v28, v29, 1.0
	v_fmac_f32_e32 v29, v21, v29
	v_div_scale_f32 v21, vcc, v16, v20, v16
	v_mul_f32_e32 v24, v21, v29
	v_fma_f32 v25, -v28, v24, v21
	v_pk_add_f32 v[22:23], v[22:23], 1.0 op_sel_hi:[1,0]
	v_fmac_f32_e32 v24, v25, v29
	v_div_scale_f32 v25, s[30:31], v23, v23, v19
	v_fma_f32 v21, -v28, v24, v21
	v_rcp_f32_e32 v28, v25
	v_div_fmas_f32 v21, v21, v29, v24
	v_div_fixup_f32 v16, v21, v20, v16
	v_mul_f32_e32 v12, 0xbfb8aa3b, v12
	v_fma_f32 v20, -v25, v28, 1.0
	v_fmac_f32_e32 v28, v20, v28
	v_div_scale_f32 v20, vcc, v19, v23, v19
	v_mul_f32_e32 v21, v20, v28
	v_fma_f32 v24, -v25, v21, v20
	v_fmac_f32_e32 v21, v24, v28
	v_div_scale_f32 v24, s[30:31], v22, v22, v18
	v_fma_f32 v20, -v25, v21, v20
	v_rcp_f32_e32 v25, v24
	v_div_fmas_f32 v20, v20, v28, v21
	v_div_fixup_f32 v19, v20, v23, v19
	v_mul_f32_e32 v13, 0xbfb8aa3b, v13
	v_fma_f32 v20, -v24, v25, 1.0
	v_fmac_f32_e32 v25, v20, v25
	v_div_scale_f32 v20, vcc, v18, v22, v18
	v_mul_f32_e32 v21, v20, v25
	v_exp_f32_e32 v12, v12
	v_exp_f32_e32 v13, v13
	v_fma_f32 v23, -v24, v21, v20
	v_fmac_f32_e32 v21, v23, v25
	v_fma_f32 v20, -v24, v21, v20
	v_div_fmas_f32 v20, v20, v25, v21
	v_pk_add_f32 v[12:13], v[12:13], 1.0 op_sel_hi:[1,0]
	v_div_fixup_f32 v18, v20, v22, v18
	v_div_scale_f32 v20, s[30:31], v13, v13, v9
	v_rcp_f32_e32 v21, v20
	v_lshl_add_u64 v[26:27], v[116:117], 0, s[12:13]
	v_cvt_pk_bf16_f32 v16, v16, v17
	v_cvt_pk_bf16_f32 v17, v18, v19
	global_store_dwordx2 v[26:27], v[16:17], off offset:128
	v_fma_f32 v16, -v20, v21, 1.0
	v_fmac_f32_e32 v21, v16, v21
	v_div_scale_f32 v16, vcc, v9, v13, v9
	v_mul_f32_e32 v17, v16, v21
	v_fma_f32 v18, -v20, v17, v16
	v_fmac_f32_e32 v17, v18, v21
	v_div_scale_f32 v18, s[30:31], v12, v12, v8
	v_rcp_f32_e32 v19, v18
	v_fma_f32 v16, -v20, v17, v16
	v_mul_f32_e32 v14, 0xbfb8aa3b, v14
	v_mul_f32_e32 v15, 0xbfb8aa3b, v15
	v_div_fmas_f32 v16, v16, v21, v17
	v_exp_f32_e32 v14, v14
	v_exp_f32_e32 v15, v15
	v_div_fixup_f32 v9, v16, v13, v9
	v_fma_f32 v13, -v18, v19, 1.0
	v_fmac_f32_e32 v19, v13, v19
	v_div_scale_f32 v13, vcc, v8, v12, v8
	v_mul_f32_e32 v16, v13, v19
	v_fma_f32 v17, -v18, v16, v13
	v_pk_add_f32 v[14:15], v[14:15], 1.0 op_sel_hi:[1,0]
	v_fmac_f32_e32 v16, v17, v19
	v_div_scale_f32 v17, s[30:31], v15, v15, v11
	v_fma_f32 v13, -v18, v16, v13
	v_rcp_f32_e32 v18, v17
	v_div_fmas_f32 v13, v13, v19, v16
	v_div_fixup_f32 v8, v13, v12, v8
	v_mul_f32_e32 v4, 0xbfb8aa3b, v4
	v_fma_f32 v12, -v17, v18, 1.0
	v_fmac_f32_e32 v18, v12, v18
	v_div_scale_f32 v12, vcc, v11, v15, v11
	v_mul_f32_e32 v13, v12, v18
	v_fma_f32 v16, -v17, v13, v12
	v_fmac_f32_e32 v13, v16, v18
	v_div_scale_f32 v16, s[30:31], v14, v14, v10
	v_fma_f32 v12, -v17, v13, v12
	v_rcp_f32_e32 v17, v16
	v_div_fmas_f32 v12, v12, v18, v13
	v_div_fixup_f32 v11, v12, v15, v11
	v_mul_f32_e32 v5, 0xbfb8aa3b, v5
	v_fma_f32 v12, -v16, v17, 1.0
	v_fmac_f32_e32 v17, v12, v17
	v_div_scale_f32 v12, vcc, v10, v14, v10
	v_mul_f32_e32 v13, v12, v17
	v_exp_f32_e32 v4, v4
	v_exp_f32_e32 v5, v5
	v_fma_f32 v15, -v16, v13, v12
	v_fmac_f32_e32 v13, v15, v17
	v_fma_f32 v12, -v16, v13, v12
	v_div_fmas_f32 v12, v12, v17, v13
	v_pk_add_f32 v[4:5], v[4:5], 1.0 op_sel_hi:[1,0]
	v_div_fixup_f32 v10, v12, v14, v10
	v_div_scale_f32 v14, s[30:31], v5, v5, v1
	v_rcp_f32_e32 v15, v14
	v_add_co_u32_e32 v12, vcc, s71, v116
	v_cvt_pk_bf16_f32 v8, v8, v9
	v_cvt_pk_bf16_f32 v9, v10, v11
	v_addc_co_u32_e32 v13, vcc, 0, v117, vcc
	global_store_dwordx2 v[12:13], v[8:9], off
	v_fma_f32 v8, -v14, v15, 1.0
	v_fmac_f32_e32 v15, v8, v15
	v_div_scale_f32 v8, vcc, v1, v5, v1
	v_mul_f32_e32 v9, v8, v15
	v_fma_f32 v12, -v14, v9, v8
	v_fmac_f32_e32 v9, v12, v15
	v_div_scale_f32 v12, s[30:31], v4, v4, v0
	v_rcp_f32_e32 v13, v12
	v_fma_f32 v8, -v14, v9, v8
	v_mul_f32_e32 v6, 0xbfb8aa3b, v6
	v_mul_f32_e32 v7, 0xbfb8aa3b, v7
	v_div_fmas_f32 v8, v8, v15, v9
	v_exp_f32_e32 v6, v6
	v_exp_f32_e32 v7, v7
	v_div_fixup_f32 v1, v8, v5, v1
	v_fma_f32 v5, -v12, v13, 1.0
	v_fmac_f32_e32 v13, v5, v13
	v_div_scale_f32 v5, vcc, v0, v4, v0
	v_mul_f32_e32 v8, v5, v13
	v_fma_f32 v9, -v12, v8, v5
	v_pk_add_f32 v[6:7], v[6:7], 1.0 op_sel_hi:[1,0]
	v_fmac_f32_e32 v8, v9, v13
	v_div_scale_f32 v9, s[30:31], v7, v7, v3
	v_fma_f32 v5, -v12, v8, v5
	v_rcp_f32_e32 v12, v9
	v_div_fmas_f32 v5, v5, v13, v8
	v_div_fixup_f32 v0, v5, v4, v0
	v_lshl_add_u64 v[10:11], v[116:117], 0, s[14:15]
	v_fma_f32 v4, -v9, v12, 1.0
	v_fmac_f32_e32 v12, v4, v12
	v_div_scale_f32 v4, vcc, v3, v7, v3
	v_mul_f32_e32 v5, v4, v12
	v_fma_f32 v8, -v9, v5, v4
	v_fmac_f32_e32 v5, v8, v12
	v_div_scale_f32 v8, s[30:31], v6, v6, v2
	v_fma_f32 v4, -v9, v5, v4
	v_rcp_f32_e32 v9, v8
	v_div_fmas_f32 v4, v4, v12, v5
	v_div_fixup_f32 v3, v4, v7, v3
	v_cvt_pk_bf16_f32 v0, v0, v1
	v_fma_f32 v4, -v8, v9, 1.0
	v_fmac_f32_e32 v9, v4, v9
	v_div_scale_f32 v4, vcc, v2, v6, v2
	v_mul_f32_e32 v5, v4, v9
	v_fma_f32 v7, -v8, v5, v4
	v_fmac_f32_e32 v5, v7, v9
	v_fma_f32 v4, -v8, v5, v4
	v_div_fmas_f32 v4, v4, v9, v5
	v_div_fixup_f32 v2, v4, v6, v2
	v_cvt_pk_bf16_f32 v1, v2, v3
	s_and_b64 vcc, exec, s[4:5]
	s_mov_b32 s72, s16
	s_mov_b32 s28, s18
	s_mov_b64 s[34:35], s[26:27]
	s_mov_b64 s[30:31], s[20:21]
	global_store_dwordx2 v[10:11], v[0:1], off offset:128
	s_cbranch_vccz .LBB0_1134
	s_waitcnt vmcnt(16)
	s_cmpk_gt_u32 s40, 0xff
	s_cbranch_scc1 .LBB0_1145
	s_barrier

.LBB0_1291:
	ds_read_b128 v[154:157], v151
	ds_read_b128 v[158:161], v151 offset:1024
	ds_read_b128 v[162:165], v151 offset:2048
	ds_read_b128 v[166:169], v151 offset:3072
	s_add_u32 s36, s34, 0xfffc0080
	s_addc_u32 s37, s35, -1
	s_cmp_eq_u32 s79, 12
	s_cselect_b32 s39, s21, s37
	s_cselect_b32 s38, s75, s36
	s_cselect_b32 s37, s19, s78
	s_cselect_b32 s36, s76, s77
	v_lshl_add_u64 v[202:203], s[34:35], 0, v[138:139]
	s_add_i32 m0, s31, 0xc000
	ds_read_b128 v[170:173], v152
	ds_read_b128 v[174:177], v152 offset:1024
	ds_read_b128 v[178:181], v152 offset:2048
	ds_read_b128 v[182:185], v152 offset:3072
	ds_read_b128 v[186:189], v152 offset:4096
	ds_read_b128 v[190:193], v152 offset:5120
	ds_read_b128 v[194:197], v152 offset:6144
	ds_read_b128 v[198:201], v152 offset:7168
	global_load_lds_dwordx4 v[202:203], off
	v_lshl_add_u64 v[202:203], s[34:35], 0, v[140:141]
	s_add_i32 m0, s31, 0xe000
	s_nop 0
	global_load_lds_dwordx4 v[202:203], off
	s_waitcnt lgkmcnt(8)
	s_barrier
	s_waitcnt lgkmcnt(0)
	s_waitcnt lgkmcnt(0)
	v_mfma_f32_16x16x32_bf16 v[124:127], v[154:157], v[170:173], v[124:127]
	v_mfma_f32_16x16x32_bf16 v[120:123], v[162:165], v[170:173], v[120:123]
	v_mfma_f32_16x16x32_bf16 v[108:111], v[154:157], v[178:181], v[108:111]
	v_mfma_f32_16x16x32_bf16 v[104:107], v[162:165], v[178:181], v[104:107]
	v_mfma_f32_16x16x32_bf16 v[92:95], v[154:157], v[186:189], v[92:95]
	v_mfma_f32_16x16x32_bf16 v[88:91], v[162:165], v[186:189], v[88:91]
	v_mfma_f32_16x16x32_bf16 v[76:79], v[154:157], v[194:197], v[76:79]
	v_mfma_f32_16x16x32_bf16 v[72:75], v[162:165], v[194:197], v[72:75]
	v_mfma_f32_16x16x32_bf16 v[124:127], v[158:161], v[174:177], v[124:127]
	v_mfma_f32_16x16x32_bf16 v[120:123], v[166:169], v[174:177], v[120:123]
	v_mfma_f32_16x16x32_bf16 v[108:111], v[158:161], v[182:185], v[108:111]
	v_mfma_f32_16x16x32_bf16 v[104:107], v[166:169], v[182:185], v[104:107]
	v_mfma_f32_16x16x32_bf16 v[92:95], v[158:161], v[190:193], v[92:95]
	v_mfma_f32_16x16x32_bf16 v[88:91], v[166:169], v[190:193], v[88:91]
	v_mfma_f32_16x16x32_bf16 v[76:79], v[158:161], v[198:201], v[76:79]
	v_mfma_f32_16x16x32_bf16 v[72:75], v[166:169], v[198:201], v[72:75]
	s_barrier
	s_add_i32 s80, s62, s52
	v_lshl_add_u64 v[218:219], s[36:37], 0, v[132:133]
	s_mov_b32 m0, s80
	ds_read_b128 v[202:205], v153
	ds_read_b128 v[206:209], v153 offset:1024
	ds_read_b128 v[210:213], v153 offset:2048
	ds_read_b128 v[214:217], v153 offset:3072
	global_load_lds_dwordx4 v[218:219], off
	v_lshl_add_u64 v[220:221], s[36:37], 0, v[136:137]
	s_add_i32 m0, s80, 0x2000
	s_nop 0
	global_load_lds_dwordx4 v[220:221], off
	s_barrier
	s_waitcnt lgkmcnt(0)
	s_waitcnt lgkmcnt(0)
	v_mfma_f32_16x16x32_bf16 v[116:119], v[202:205], v[170:173], v[116:119]
	v_mfma_f32_16x16x32_bf16 v[112:115], v[210:213], v[170:173], v[112:115]
	v_mfma_f32_16x16x32_bf16 v[100:103], v[202:205], v[178:181], v[100:103]
	v_mfma_f32_16x16x32_bf16 v[96:99], v[210:213], v[178:181], v[96:99]
	v_mfma_f32_16x16x32_bf16 v[84:87], v[202:205], v[186:189], v[84:87]
	v_mfma_f32_16x16x32_bf16 v[80:83], v[210:213], v[186:189], v[80:83]
	v_mfma_f32_16x16x32_bf16 v[68:71], v[202:205], v[194:197], v[68:71]
	v_mfma_f32_16x16x32_bf16 v[64:67], v[210:213], v[194:197], v[64:67]
	v_mfma_f32_16x16x32_bf16 v[116:119], v[206:209], v[174:177], v[116:119]
	v_mfma_f32_16x16x32_bf16 v[112:115], v[214:217], v[174:177], v[112:115]
	v_mfma_f32_16x16x32_bf16 v[100:103], v[206:209], v[182:185], v[100:103]
	v_mfma_f32_16x16x32_bf16 v[96:99], v[214:217], v[182:185], v[96:99]
	v_mfma_f32_16x16x32_bf16 v[84:87], v[206:209], v[190:193], v[84:87]
	v_mfma_f32_16x16x32_bf16 v[80:83], v[214:217], v[190:193], v[80:83]
	v_mfma_f32_16x16x32_bf16 v[68:71], v[206:209], v[198:201], v[68:71]
	v_mfma_f32_16x16x32_bf16 v[64:67], v[214:217], v[198:201], v[64:67]
	s_mov_b32 m0, s31
	v_lshl_add_u64 v[222:223], s[38:39], 0, v[130:131]
	s_barrier
	ds_read_b128 v[170:173], v152 offset:16384
	ds_read_b128 v[174:177], v152 offset:17408
	ds_read_b128 v[178:181], v152 offset:18432
	ds_read_b128 v[182:185], v152 offset:19456
	ds_read_b128 v[186:189], v152 offset:20480
	ds_read_b128 v[190:193], v152 offset:21504
	ds_read_b128 v[194:197], v152 offset:22528
	ds_read_b128 v[198:201], v152 offset:23552
	global_load_lds_dwordx4 v[222:223], off
	v_lshl_add_u64 v[224:225], s[38:39], 0, v[134:135]
	s_mov_b32 m0, s53
	s_nop 0
	global_load_lds_dwordx4 v[224:225], off
	s_barrier
	s_waitcnt lgkmcnt(0)
	s_waitcnt lgkmcnt(0)
	v_mfma_f32_16x16x32_bf16 v[60:63], v[154:157], v[170:173], v[60:63]
	v_mfma_f32_16x16x32_bf16 v[56:59], v[162:165], v[170:173], v[56:59]
	v_mfma_f32_16x16x32_bf16 v[44:47], v[154:157], v[178:181], v[44:47]
	v_mfma_f32_16x16x32_bf16 v[40:43], v[162:165], v[178:181], v[40:43]
	v_mfma_f32_16x16x32_bf16 v[28:31], v[154:157], v[186:189], v[28:31]
	v_mfma_f32_16x16x32_bf16 v[24:27], v[162:165], v[186:189], v[24:27]
	v_mfma_f32_16x16x32_bf16 v[12:15], v[154:157], v[194:197], v[12:15]
	v_mfma_f32_16x16x32_bf16 v[8:11], v[162:165], v[194:197], v[8:11]
	v_mfma_f32_16x16x32_bf16 v[60:63], v[158:161], v[174:177], v[60:63]
	v_mfma_f32_16x16x32_bf16 v[56:59], v[166:169], v[174:177], v[56:59]
	v_mfma_f32_16x16x32_bf16 v[44:47], v[158:161], v[182:185], v[44:47]
	v_mfma_f32_16x16x32_bf16 v[40:43], v[166:169], v[182:185], v[40:43]
	v_mfma_f32_16x16x32_bf16 v[28:31], v[158:161], v[190:193], v[28:31]
	v_mfma_f32_16x16x32_bf16 v[24:27], v[166:169], v[190:193], v[24:27]
	v_mfma_f32_16x16x32_bf16 v[12:15], v[158:161], v[198:201], v[12:15]
	v_mfma_f32_16x16x32_bf16 v[8:11], v[166:169], v[198:201], v[8:11]
	s_barrier
	s_add_u32 s80, s36, 0x40000
	s_addc_u32 s81, s37, 0
	s_add_i32 s82, s63, s52
	v_lshl_add_u64 v[154:155], s[80:81], 0, v[132:133]
	s_mov_b32 m0, s82
	s_nop 0
	global_load_lds_dwordx4 v[154:155], off
	v_lshl_add_u64 v[154:155], s[80:81], 0, v[136:137]
	s_add_i32 m0, s82, 0x2000
	s_nop 0
	global_load_lds_dwordx4 v[154:155], off
	s_waitcnt vmcnt(6)
	s_barrier
	v_mfma_f32_16x16x32_bf16 v[52:55], v[202:205], v[170:173], v[52:55]
	v_mfma_f32_16x16x32_bf16 v[48:51], v[210:213], v[170:173], v[48:51]
	v_mfma_f32_16x16x32_bf16 v[36:39], v[202:205], v[178:181], v[36:39]
	v_mfma_f32_16x16x32_bf16 v[32:35], v[210:213], v[178:181], v[32:35]
	v_mfma_f32_16x16x32_bf16 v[20:23], v[202:205], v[186:189], v[20:23]
	v_mfma_f32_16x16x32_bf16 v[16:19], v[210:213], v[186:189], v[16:19]
	v_mfma_f32_16x16x32_bf16 v[4:7], v[202:205], v[194:197], v[4:7]
	v_mfma_f32_16x16x32_bf16 v[0:3], v[210:213], v[194:197], v[0:3]
	v_mfma_f32_16x16x32_bf16 v[52:55], v[206:209], v[174:177], v[52:55]
	v_mfma_f32_16x16x32_bf16 v[48:51], v[214:217], v[174:177], v[48:51]
	v_mfma_f32_16x16x32_bf16 v[36:39], v[206:209], v[182:185], v[36:39]
	v_mfma_f32_16x16x32_bf16 v[32:35], v[214:217], v[182:185], v[32:35]
	v_mfma_f32_16x16x32_bf16 v[20:23], v[206:209], v[190:193], v[20:23]
	v_mfma_f32_16x16x32_bf16 v[16:19], v[214:217], v[190:193], v[16:19]
	v_mfma_f32_16x16x32_bf16 v[4:7], v[206:209], v[198:201], v[4:7]
	v_mfma_f32_16x16x32_bf16 v[0:3], v[214:217], v[198:201], v[0:3]
	s_add_i32 s80, 0, 0x18000
	v_add_u32_e32 v166, s80, v149
	s_barrier
	ds_read_b128 v[154:157], v166
	ds_read_b128 v[158:161], v166 offset:1024
	ds_read_b128 v[162:165], v166 offset:2048
	ds_read_b128 v[166:169], v166 offset:3072
	s_add_u32 s38, s38, 0x40000
	s_addc_u32 s39, s39, 0
	s_mov_b32 m0, s54
	v_lshl_add_u64 v[202:203], s[38:39], 0, v[130:131]
	ds_read_b128 v[170:173], v152 offset:32768
	ds_read_b128 v[174:177], v152 offset:33792
	ds_read_b128 v[178:181], v152 offset:34816
	ds_read_b128 v[182:185], v152 offset:35840
	ds_read_b128 v[186:189], v152 offset:36864
	ds_read_b128 v[190:193], v152 offset:37888
	ds_read_b128 v[194:197], v152 offset:38912
	ds_read_b128 v[198:201], v152 offset:39936
	global_load_lds_dwordx4 v[202:203], off
	v_lshl_add_u64 v[202:203], s[38:39], 0, v[134:135]
	s_mov_b32 m0, s55
	s_nop 0
	global_load_lds_dwordx4 v[202:203], off
	s_waitcnt lgkmcnt(8)
	s_barrier
	s_waitcnt lgkmcnt(0)
	s_waitcnt lgkmcnt(0)
	v_mfma_f32_16x16x32_bf16 v[124:127], v[154:157], v[170:173], v[124:127]
	v_mfma_f32_16x16x32_bf16 v[120:123], v[162:165], v[170:173], v[120:123]
	v_mfma_f32_16x16x32_bf16 v[108:111], v[154:157], v[178:181], v[108:111]
	v_mfma_f32_16x16x32_bf16 v[104:107], v[162:165], v[178:181], v[104:107]
	v_mfma_f32_16x16x32_bf16 v[92:95], v[154:157], v[186:189], v[92:95]
	v_mfma_f32_16x16x32_bf16 v[88:91], v[162:165], v[186:189], v[88:91]
	v_mfma_f32_16x16x32_bf16 v[76:79], v[154:157], v[194:197], v[76:79]
	v_mfma_f32_16x16x32_bf16 v[72:75], v[162:165], v[194:197], v[72:75]
	v_mfma_f32_16x16x32_bf16 v[124:127], v[158:161], v[174:177], v[124:127]
	v_mfma_f32_16x16x32_bf16 v[120:123], v[166:169], v[174:177], v[120:123]
	v_mfma_f32_16x16x32_bf16 v[108:111], v[158:161], v[182:185], v[108:111]
	v_mfma_f32_16x16x32_bf16 v[104:107], v[166:169], v[182:185], v[104:107]
	v_mfma_f32_16x16x32_bf16 v[92:95], v[158:161], v[190:193], v[92:95]
	v_mfma_f32_16x16x32_bf16 v[88:91], v[166:169], v[190:193], v[88:91]
	v_mfma_f32_16x16x32_bf16 v[76:79], v[158:161], v[198:201], v[76:79]
	v_mfma_f32_16x16x32_bf16 v[72:75], v[166:169], v[198:201], v[72:75]
	s_barrier
	s_add_i32 s38, 0, 0x1c000
	s_add_i32 s39, s80, s52
	v_add_u32_e32 v214, s38, v149
	v_lshl_add_u64 v[218:219], v[218:219], 0, s[8:9]
	s_mov_b32 m0, s39
	ds_read_b128 v[202:205], v214
	ds_read_b128 v[206:209], v214 offset:1024
	ds_read_b128 v[210:213], v214 offset:2048
	ds_read_b128 v[214:217], v214 offset:3072
	global_load_lds_dwordx4 v[218:219], off
	v_lshl_add_u64 v[218:219], v[220:221], 0, s[8:9]
	s_add_i32 m0, s39, 0x2000
	s_nop 0
	global_load_lds_dwordx4 v[218:219], off
	s_barrier
	s_waitcnt lgkmcnt(0)
	s_waitcnt lgkmcnt(0)
	v_mfma_f32_16x16x32_bf16 v[116:119], v[202:205], v[170:173], v[116:119]
	v_mfma_f32_16x16x32_bf16 v[112:115], v[210:213], v[170:173], v[112:115]
	v_mfma_f32_16x16x32_bf16 v[100:103], v[202:205], v[178:181], v[100:103]
	v_mfma_f32_16x16x32_bf16 v[96:99], v[210:213], v[178:181], v[96:99]
	v_mfma_f32_16x16x32_bf16 v[84:87], v[202:205], v[186:189], v[84:87]
	v_mfma_f32_16x16x32_bf16 v[80:83], v[210:213], v[186:189], v[80:83]
	v_mfma_f32_16x16x32_bf16 v[68:71], v[202:205], v[194:197], v[68:71]
	v_mfma_f32_16x16x32_bf16 v[64:67], v[210:213], v[194:197], v[64:67]
	v_mfma_f32_16x16x32_bf16 v[116:119], v[206:209], v[174:177], v[116:119]
	v_mfma_f32_16x16x32_bf16 v[112:115], v[214:217], v[174:177], v[112:115]
	v_mfma_f32_16x16x32_bf16 v[100:103], v[206:209], v[182:185], v[100:103]
	v_mfma_f32_16x16x32_bf16 v[96:99], v[214:217], v[182:185], v[96:99]
	v_mfma_f32_16x16x32_bf16 v[84:87], v[206:209], v[190:193], v[84:87]
	v_mfma_f32_16x16x32_bf16 v[80:83], v[214:217], v[190:193], v[80:83]
	v_mfma_f32_16x16x32_bf16 v[68:71], v[206:209], v[198:201], v[68:71]
	v_mfma_f32_16x16x32_bf16 v[64:67], v[214:217], v[198:201], v[64:67]
	s_mov_b32 m0, s57
	v_lshl_add_u64 v[218:219], v[222:223], 0, s[8:9]
	s_barrier
	ds_read_b128 v[170:173], v152 offset:49152
	ds_read_b128 v[174:177], v152 offset:50176
	ds_read_b128 v[178:181], v152 offset:51200
	ds_read_b128 v[182:185], v152 offset:52224
	ds_read_b128 v[186:189], v152 offset:53248
	ds_read_b128 v[190:193], v152 offset:54272
	ds_read_b128 v[194:197], v152 offset:55296
	ds_read_b128 v[198:201], v152 offset:56320
	global_load_lds_dwordx4 v[218:219], off
	v_lshl_add_u64 v[218:219], v[224:225], 0, s[8:9]
	s_mov_b32 m0, s60
	s_nop 0
	global_load_lds_dwordx4 v[218:219], off
	s_barrier
	s_waitcnt lgkmcnt(0)
	s_waitcnt lgkmcnt(0)
	v_mfma_f32_16x16x32_bf16 v[60:63], v[154:157], v[170:173], v[60:63]
	v_mfma_f32_16x16x32_bf16 v[56:59], v[162:165], v[170:173], v[56:59]
	v_mfma_f32_16x16x32_bf16 v[44:47], v[154:157], v[178:181], v[44:47]
	v_mfma_f32_16x16x32_bf16 v[40:43], v[162:165], v[178:181], v[40:43]
	v_mfma_f32_16x16x32_bf16 v[28:31], v[154:157], v[186:189], v[28:31]
	v_mfma_f32_16x16x32_bf16 v[24:27], v[162:165], v[186:189], v[24:27]
	v_mfma_f32_16x16x32_bf16 v[12:15], v[154:157], v[194:197], v[12:15]
	v_mfma_f32_16x16x32_bf16 v[8:11], v[162:165], v[194:197], v[8:11]
	v_mfma_f32_16x16x32_bf16 v[60:63], v[158:161], v[174:177], v[60:63]
	v_mfma_f32_16x16x32_bf16 v[56:59], v[166:169], v[174:177], v[56:59]
	v_mfma_f32_16x16x32_bf16 v[44:47], v[158:161], v[182:185], v[44:47]
	v_mfma_f32_16x16x32_bf16 v[40:43], v[166:169], v[182:185], v[40:43]
	v_mfma_f32_16x16x32_bf16 v[28:31], v[158:161], v[190:193], v[28:31]
	v_mfma_f32_16x16x32_bf16 v[24:27], v[166:169], v[190:193], v[24:27]
	v_mfma_f32_16x16x32_bf16 v[12:15], v[158:161], v[198:201], v[12:15]
	v_mfma_f32_16x16x32_bf16 v[8:11], v[166:169], v[198:201], v[8:11]
	s_barrier
	s_add_u32 s36, s36, 0x40080
	s_addc_u32 s37, s37, 0
	s_add_i32 s38, s38, s52
	v_lshl_add_u64 v[154:155], s[36:37], 0, v[132:133]
	s_mov_b32 m0, s38
	s_nop 0
	global_load_lds_dwordx4 v[154:155], off
	v_lshl_add_u64 v[154:155], s[36:37], 0, v[136:137]
	s_add_i32 m0, s38, 0x2000
	s_nop 0
	global_load_lds_dwordx4 v[154:155], off
	s_waitcnt vmcnt(6)
	s_barrier
	v_mfma_f32_16x16x32_bf16 v[52:55], v[202:205], v[170:173], v[52:55]
	v_mfma_f32_16x16x32_bf16 v[48:51], v[210:213], v[170:173], v[48:51]
	v_mfma_f32_16x16x32_bf16 v[36:39], v[202:205], v[178:181], v[36:39]
	v_mfma_f32_16x16x32_bf16 v[32:35], v[210:213], v[178:181], v[32:35]
	v_mfma_f32_16x16x32_bf16 v[20:23], v[202:205], v[186:189], v[20:23]
	v_mfma_f32_16x16x32_bf16 v[16:19], v[210:213], v[186:189], v[16:19]
	v_mfma_f32_16x16x32_bf16 v[4:7], v[202:205], v[194:197], v[4:7]
	v_mfma_f32_16x16x32_bf16 v[0:3], v[210:213], v[194:197], v[0:3]
	v_mfma_f32_16x16x32_bf16 v[52:55], v[206:209], v[174:177], v[52:55]
	v_mfma_f32_16x16x32_bf16 v[48:51], v[214:217], v[174:177], v[48:51]
	v_mfma_f32_16x16x32_bf16 v[36:39], v[206:209], v[182:185], v[36:39]
	v_mfma_f32_16x16x32_bf16 v[32:35], v[214:217], v[182:185], v[32:35]
	v_mfma_f32_16x16x32_bf16 v[20:23], v[206:209], v[190:193], v[20:23]
	v_mfma_f32_16x16x32_bf16 v[16:19], v[214:217], v[190:193], v[16:19]
	v_mfma_f32_16x16x32_bf16 v[4:7], v[206:209], v[198:201], v[4:7]
	v_mfma_f32_16x16x32_bf16 v[0:3], v[214:217], v[198:201], v[0:3]
	s_add_i32 s79, s79, 2
	s_add_u32 s34, s34, 0x100
	s_addc_u32 s35, s35, 0
	s_add_u32 s77, s77, 0x100
	s_addc_u32 s78, s78, 0
	s_cmp_gt_u32 s79, 13
	s_barrier
	s_cbranch_scc0 .LBB0_1291
	v_lshl_add_u32 v154, s30, 8, v148
	v_max_f32_e32 v126, v126, v126
	v_max_f32_e32 v127, v127, v127
	v_lshl_or_b32 v156, s74, 8, v150
	v_ashrrev_i32_e32 v155, 31, v154
	v_max_f32_e32 v124, v124, v124
	v_max_f32_e32 v120, v120, v120
	v_max_f32_e32 v125, v125, v125
	v_max_f32_e32 v121, v121, v121
	v_max_f32_e32 v126, 0, v126
	v_max_f32_e32 v122, v122, v122
	v_max_f32_e32 v127, 0, v127
	v_max_f32_e32 v123, v123, v123
	v_lshlrev_b64 v[158:159], 13, v[154:155]
	v_max_f32_e32 v124, 0, v124
	v_max_f32_e32 v120, 0, v120
	v_max_f32_e32 v125, 0, v125
	v_max_f32_e32 v121, 0, v121
	v_max_f32_e32 v122, 0, v122
	v_max_f32_e32 v123, 0, v123
	v_pk_mul_f32 v[126:127], v[126:127], v[126:127]
	v_ashrrev_i32_e32 v157, 31, v156
	v_lshl_add_u64 v[158:159], s[46:47], 0, v[158:159]
	v_pk_mul_f32 v[124:125], v[124:125], v[124:125]
	v_pk_mul_f32 v[120:121], v[120:121], v[120:121]
	v_pk_mul_f32 v[160:161], v[122:123], v[122:123]
	v_cvt_pk_bf16_f32 v123, v126, v127
	v_lshlrev_b64 v[126:127], 1, v[156:157]
	v_max_f32_e32 v112, v112, v112
	v_max_f32_e32 v113, v113, v113
	v_cvt_pk_bf16_f32 v122, v124, v125
	v_cvt_pk_bf16_f32 v124, v120, v121
	v_cvt_pk_bf16_f32 v125, v160, v161
	v_lshl_add_u64 v[120:121], v[158:159], 0, v[126:127]
	v_max_f32_e32 v112, 0, v112
	v_max_f32_e32 v113, 0, v113
	global_store_dwordx4 v[120:121], v[122:125], off
	v_max_f32_e32 v116, v116, v116
	v_max_f32_e32 v117, v117, v117
	v_pk_mul_f32 v[122:123], v[112:113], v[112:113]
	v_max_f32_e32 v113, v114, v114
	v_max_f32_e32 v112, v118, v118
	v_max_f32_e32 v114, 0, v113
	v_max_f32_e32 v113, v119, v119
	v_max_f32_e32 v115, v115, v115
	v_max_f32_e32 v116, 0, v116
	v_max_f32_e32 v117, 0, v117
	v_max_f32_e32 v112, 0, v112
	v_max_f32_e32 v113, 0, v113
	v_max_f32_e32 v115, 0, v115
	v_pk_mul_f32 v[116:117], v[116:117], v[116:117]
	v_pk_mul_f32 v[118:119], v[112:113], v[112:113]
	v_pk_mul_f32 v[124:125], v[114:115], v[114:115]
	v_max_f32_e32 v104, v104, v104
	v_max_f32_e32 v105, v105, v105
	v_cvt_pk_bf16_f32 v112, v116, v117
	v_cvt_pk_bf16_f32 v113, v118, v119
	v_cvt_pk_bf16_f32 v114, v122, v123
	v_cvt_pk_bf16_f32 v115, v124, v125
	v_max_f32_e32 v104, 0, v104
	v_max_f32_e32 v105, 0, v105
	global_store_dwordx4 v[120:121], v[112:115], off offset:256
	v_max_f32_e32 v108, v108, v108
	v_max_f32_e32 v109, v109, v109
	v_or_b32_e32 v112, 16, v154
	v_pk_mul_f32 v[114:115], v[104:105], v[104:105]
	v_max_f32_e32 v105, v106, v106
	v_ashrrev_i32_e32 v113, 31, v112
	v_max_f32_e32 v104, v110, v110
	v_max_f32_e32 v106, 0, v105
	v_max_f32_e32 v105, v111, v111
	v_max_f32_e32 v107, v107, v107
	v_lshlrev_b64 v[112:113], 13, v[112:113]
	v_max_f32_e32 v108, 0, v108
	v_max_f32_e32 v109, 0, v109
	v_max_f32_e32 v104, 0, v104
	v_max_f32_e32 v105, 0, v105
	v_max_f32_e32 v107, 0, v107
	v_lshl_add_u64 v[112:113], s[46:47], 0, v[112:113]
	v_pk_mul_f32 v[108:109], v[108:109], v[108:109]
	v_pk_mul_f32 v[110:111], v[104:105], v[104:105]
	v_pk_mul_f32 v[116:117], v[106:107], v[106:107]
	v_max_f32_e32 v96, v96, v96
	v_max_f32_e32 v97, v97, v97
	v_cvt_pk_bf16_f32 v104, v108, v109
	v_cvt_pk_bf16_f32 v105, v110, v111
	v_cvt_pk_bf16_f32 v106, v114, v115
	v_cvt_pk_bf16_f32 v107, v116, v117
	v_lshl_add_u64 v[108:109], v[112:113], 0, v[126:127]
	v_max_f32_e32 v96, 0, v96
	v_max_f32_e32 v97, 0, v97
	global_store_dwordx4 v[108:109], v[104:107], off
	v_max_f32_e32 v100, v100, v100
	v_max_f32_e32 v101, v101, v101
	v_pk_mul_f32 v[104:105], v[96:97], v[96:97]
	v_max_f32_e32 v97, v98, v98
	v_max_f32_e32 v96, v102, v102
	v_max_f32_e32 v98, 0, v97
	v_max_f32_e32 v97, v103, v103
	v_max_f32_e32 v99, v99, v99
	v_max_f32_e32 v100, 0, v100
	v_max_f32_e32 v101, 0, v101
	v_max_f32_e32 v96, 0, v96
	v_max_f32_e32 v97, 0, v97
	v_max_f32_e32 v99, 0, v99
	v_pk_mul_f32 v[100:101], v[100:101], v[100:101]
	v_pk_mul_f32 v[102:103], v[96:97], v[96:97]
	v_pk_mul_f32 v[106:107], v[98:99], v[98:99]
	v_max_f32_e32 v88, v88, v88
	v_max_f32_e32 v89, v89, v89
	v_cvt_pk_bf16_f32 v96, v100, v101
	v_cvt_pk_bf16_f32 v97, v102, v103
	v_cvt_pk_bf16_f32 v98, v104, v105
	v_cvt_pk_bf16_f32 v99, v106, v107
	v_max_f32_e32 v88, 0, v88
	v_max_f32_e32 v89, 0, v89
	global_store_dwordx4 v[108:109], v[96:99], off offset:256
	v_max_f32_e32 v92, v92, v92
	v_max_f32_e32 v93, v93, v93
	v_or_b32_e32 v96, 32, v154
	v_pk_mul_f32 v[98:99], v[88:89], v[88:89]
	v_max_f32_e32 v89, v90, v90
	v_ashrrev_i32_e32 v97, 31, v96
	v_max_f32_e32 v88, v94, v94
	v_max_f32_e32 v90, 0, v89
	v_max_f32_e32 v89, v95, v95
	v_max_f32_e32 v91, v91, v91
	v_lshlrev_b64 v[96:97], 13, v[96:97]
	v_max_f32_e32 v92, 0, v92
	v_max_f32_e32 v93, 0, v93
	v_max_f32_e32 v88, 0, v88
	v_max_f32_e32 v89, 0, v89
	v_max_f32_e32 v91, 0, v91
	v_lshl_add_u64 v[96:97], s[46:47], 0, v[96:97]
	v_pk_mul_f32 v[92:93], v[92:93], v[92:93]
	v_pk_mul_f32 v[94:95], v[88:89], v[88:89]
	v_pk_mul_f32 v[100:101], v[90:91], v[90:91]
	v_max_f32_e32 v80, v80, v80
	v_max_f32_e32 v81, v81, v81
	v_cvt_pk_bf16_f32 v88, v92, v93
	v_cvt_pk_bf16_f32 v89, v94, v95
	v_cvt_pk_bf16_f32 v90, v98, v99
	v_cvt_pk_bf16_f32 v91, v100, v101
	v_lshl_add_u64 v[92:93], v[96:97], 0, v[126:127]
	v_max_f32_e32 v80, 0, v80
	v_max_f32_e32 v81, 0, v81
	global_store_dwordx4 v[92:93], v[88:91], off
	v_max_f32_e32 v84, v84, v84
	v_max_f32_e32 v85, v85, v85
	v_pk_mul_f32 v[88:89], v[80:81], v[80:81]
	v_max_f32_e32 v81, v82, v82
	v_max_f32_e32 v80, v86, v86
	v_max_f32_e32 v82, 0, v81
	v_max_f32_e32 v81, v87, v87
	v_max_f32_e32 v83, v83, v83
	v_max_f32_e32 v84, 0, v84
	v_max_f32_e32 v85, 0, v85
	v_max_f32_e32 v80, 0, v80
	v_max_f32_e32 v81, 0, v81
	v_max_f32_e32 v83, 0, v83
	v_pk_mul_f32 v[84:85], v[84:85], v[84:85]
	v_pk_mul_f32 v[86:87], v[80:81], v[80:81]
	v_pk_mul_f32 v[90:91], v[82:83], v[82:83]
	v_max_f32_e32 v72, v72, v72
	v_max_f32_e32 v73, v73, v73
	v_cvt_pk_bf16_f32 v80, v84, v85
	v_cvt_pk_bf16_f32 v81, v86, v87
	v_cvt_pk_bf16_f32 v82, v88, v89
	v_cvt_pk_bf16_f32 v83, v90, v91
	v_max_f32_e32 v72, 0, v72
	v_max_f32_e32 v73, 0, v73
	global_store_dwordx4 v[92:93], v[80:83], off offset:256
	v_max_f32_e32 v76, v76, v76
	v_max_f32_e32 v77, v77, v77
	v_or_b32_e32 v80, 48, v154
	v_pk_mul_f32 v[82:83], v[72:73], v[72:73]
	v_max_f32_e32 v73, v74, v74
	v_ashrrev_i32_e32 v81, 31, v80
	v_max_f32_e32 v72, v78, v78
	v_max_f32_e32 v74, 0, v73
	v_max_f32_e32 v73, v79, v79
	v_max_f32_e32 v75, v75, v75
	v_lshlrev_b64 v[80:81], 13, v[80:81]
	v_max_f32_e32 v76, 0, v76
	v_max_f32_e32 v77, 0, v77
	v_max_f32_e32 v72, 0, v72
	v_max_f32_e32 v73, 0, v73
	v_max_f32_e32 v75, 0, v75
	v_lshl_add_u64 v[80:81], s[46:47], 0, v[80:81]
	v_pk_mul_f32 v[76:77], v[76:77], v[76:77]
	v_pk_mul_f32 v[78:79], v[72:73], v[72:73]
	v_pk_mul_f32 v[84:85], v[74:75], v[74:75]
	v_max_f32_e32 v64, v64, v64
	v_max_f32_e32 v65, v65, v65
	v_cvt_pk_bf16_f32 v72, v76, v77
	v_cvt_pk_bf16_f32 v73, v78, v79
	v_cvt_pk_bf16_f32 v74, v82, v83
	v_cvt_pk_bf16_f32 v75, v84, v85
	v_lshl_add_u64 v[76:77], v[80:81], 0, v[126:127]
	v_max_f32_e32 v64, 0, v64
	v_max_f32_e32 v65, 0, v65
	global_store_dwordx4 v[76:77], v[72:75], off
	v_max_f32_e32 v68, v68, v68
	v_max_f32_e32 v69, v69, v69
	v_pk_mul_f32 v[72:73], v[64:65], v[64:65]
	v_max_f32_e32 v65, v66, v66
	v_max_f32_e32 v64, v70, v70
	v_max_f32_e32 v66, 0, v65
	v_max_f32_e32 v65, v71, v71
	v_max_f32_e32 v67, v67, v67
	v_max_f32_e32 v68, 0, v68
	v_max_f32_e32 v69, 0, v69
	v_max_f32_e32 v64, 0, v64
	v_max_f32_e32 v65, 0, v65
	v_max_f32_e32 v67, 0, v67
	v_pk_mul_f32 v[68:69], v[68:69], v[68:69]
	v_pk_mul_f32 v[70:71], v[64:65], v[64:65]
	v_pk_mul_f32 v[74:75], v[66:67], v[66:67]
	v_max_f32_e32 v56, v56, v56
	v_max_f32_e32 v57, v57, v57
	v_cvt_pk_bf16_f32 v64, v68, v69
	v_cvt_pk_bf16_f32 v65, v70, v71
	v_cvt_pk_bf16_f32 v66, v72, v73
	v_cvt_pk_bf16_f32 v67, v74, v75
	v_max_f32_e32 v56, 0, v56
	v_max_f32_e32 v57, 0, v57
	global_store_dwordx4 v[76:77], v[64:67], off offset:256
	v_max_f32_e32 v60, v60, v60
	v_max_f32_e32 v61, v61, v61
	v_pk_mul_f32 v[64:65], v[56:57], v[56:57]
	v_max_f32_e32 v57, v58, v58
	v_max_f32_e32 v56, v62, v62
	v_max_f32_e32 v58, 0, v57
	v_max_f32_e32 v57, v63, v63
	v_max_f32_e32 v56, 0, v56
	v_max_f32_e32 v57, 0, v57
	v_max_f32_e32 v59, v59, v59
	v_max_f32_e32 v60, 0, v60
	v_max_f32_e32 v61, 0, v61
	v_max_f32_e32 v59, 0, v59
	v_pk_mul_f32 v[62:63], v[56:57], v[56:57]
	v_pk_mul_f32 v[60:61], v[60:61], v[60:61]
	v_pk_mul_f32 v[66:67], v[58:59], v[58:59]
	v_cvt_pk_bf16_f32 v57, v62, v63
	v_add_co_u32_e32 v62, vcc, s70, v120
	v_max_f32_e32 v48, v48, v48
	v_max_f32_e32 v49, v49, v49
	v_cvt_pk_bf16_f32 v56, v60, v61
	v_cvt_pk_bf16_f32 v58, v64, v65
	v_cvt_pk_bf16_f32 v59, v66, v67
	v_addc_co_u32_e32 v63, vcc, 0, v121, vcc
	v_max_f32_e32 v48, 0, v48
	v_max_f32_e32 v49, 0, v49
	global_store_dwordx4 v[62:63], v[56:59], off
	v_max_f32_e32 v52, v52, v52
	v_max_f32_e32 v53, v53, v53
	v_pk_mul_f32 v[56:57], v[48:49], v[48:49]
	v_max_f32_e32 v49, v50, v50
	v_max_f32_e32 v48, v54, v54
	v_max_f32_e32 v50, 0, v49
	v_max_f32_e32 v49, v55, v55
	v_max_f32_e32 v51, v51, v51
	v_max_f32_e32 v52, 0, v52
	v_max_f32_e32 v53, 0, v53
	v_max_f32_e32 v48, 0, v48
	v_max_f32_e32 v49, 0, v49
	v_max_f32_e32 v51, 0, v51
	v_pk_mul_f32 v[52:53], v[52:53], v[52:53]
	v_pk_mul_f32 v[54:55], v[48:49], v[48:49]
	v_pk_mul_f32 v[58:59], v[50:51], v[50:51]
	v_max_f32_e32 v40, v40, v40
	v_max_f32_e32 v41, v41, v41
	v_lshl_add_u64 v[60:61], v[120:121], 0, s[10:11]
	v_cvt_pk_bf16_f32 v48, v52, v53
	v_cvt_pk_bf16_f32 v49, v54, v55
	v_cvt_pk_bf16_f32 v50, v56, v57
	v_cvt_pk_bf16_f32 v51, v58, v59
	v_max_f32_e32 v40, 0, v40
	v_max_f32_e32 v41, 0, v41
	global_store_dwordx4 v[60:61], v[48:51], off offset:256
	v_max_f32_e32 v44, v44, v44
	v_max_f32_e32 v45, v45, v45
	v_pk_mul_f32 v[48:49], v[40:41], v[40:41]
	v_max_f32_e32 v41, v42, v42
	v_max_f32_e32 v40, v46, v46
	v_max_f32_e32 v42, 0, v41
	v_max_f32_e32 v41, v47, v47
	v_max_f32_e32 v40, 0, v40
	v_max_f32_e32 v41, 0, v41
	v_max_f32_e32 v43, v43, v43
	v_max_f32_e32 v44, 0, v44
	v_max_f32_e32 v45, 0, v45
	v_max_f32_e32 v43, 0, v43
	v_pk_mul_f32 v[46:47], v[40:41], v[40:41]
	v_pk_mul_f32 v[44:45], v[44:45], v[44:45]
	v_pk_mul_f32 v[50:51], v[42:43], v[42:43]
	v_cvt_pk_bf16_f32 v41, v46, v47
	v_add_co_u32_e32 v46, vcc, s71, v120
	v_max_f32_e32 v32, v32, v32
	v_max_f32_e32 v33, v33, v33
	v_cvt_pk_bf16_f32 v40, v44, v45
	v_cvt_pk_bf16_f32 v42, v48, v49
	v_cvt_pk_bf16_f32 v43, v50, v51
	v_addc_co_u32_e32 v47, vcc, 0, v121, vcc
	v_max_f32_e32 v32, 0, v32
	v_max_f32_e32 v33, 0, v33
	global_store_dwordx4 v[46:47], v[40:43], off
	v_max_f32_e32 v36, v36, v36
	v_max_f32_e32 v37, v37, v37
	v_pk_mul_f32 v[40:41], v[32:33], v[32:33]
	v_max_f32_e32 v33, v34, v34
	v_max_f32_e32 v32, v38, v38
	v_max_f32_e32 v34, 0, v33
	v_max_f32_e32 v33, v39, v39
	v_max_f32_e32 v35, v35, v35
	v_max_f32_e32 v36, 0, v36
	v_max_f32_e32 v37, 0, v37
	v_max_f32_e32 v32, 0, v32
	v_max_f32_e32 v33, 0, v33
	v_max_f32_e32 v35, 0, v35
	v_pk_mul_f32 v[36:37], v[36:37], v[36:37]
	v_pk_mul_f32 v[38:39], v[32:33], v[32:33]
	v_pk_mul_f32 v[42:43], v[34:35], v[34:35]
	v_max_f32_e32 v24, v24, v24
	v_max_f32_e32 v25, v25, v25
	v_lshl_add_u64 v[44:45], v[120:121], 0, s[12:13]
	v_cvt_pk_bf16_f32 v32, v36, v37
	v_cvt_pk_bf16_f32 v33, v38, v39
	v_cvt_pk_bf16_f32 v34, v40, v41
	v_cvt_pk_bf16_f32 v35, v42, v43
	v_max_f32_e32 v24, 0, v24
	v_max_f32_e32 v25, 0, v25
	global_store_dwordx4 v[44:45], v[32:35], off offset:256
	v_max_f32_e32 v28, v28, v28
	v_max_f32_e32 v29, v29, v29
	v_pk_mul_f32 v[32:33], v[24:25], v[24:25]
	v_max_f32_e32 v25, v26, v26
	v_max_f32_e32 v24, v30, v30
	v_max_f32_e32 v26, 0, v25
	v_max_f32_e32 v25, v31, v31
	v_max_f32_e32 v24, 0, v24
	v_max_f32_e32 v25, 0, v25
	v_max_f32_e32 v27, v27, v27
	v_max_f32_e32 v28, 0, v28
	v_max_f32_e32 v29, 0, v29
	v_max_f32_e32 v27, 0, v27
	v_pk_mul_f32 v[30:31], v[24:25], v[24:25]
	v_pk_mul_f32 v[28:29], v[28:29], v[28:29]
	v_pk_mul_f32 v[34:35], v[26:27], v[26:27]
	v_cvt_pk_bf16_f32 v25, v30, v31
	v_add_co_u32_e32 v30, vcc, s72, v120
	v_max_f32_e32 v16, v16, v16
	v_max_f32_e32 v17, v17, v17
	v_cvt_pk_bf16_f32 v24, v28, v29
	v_cvt_pk_bf16_f32 v26, v32, v33
	v_cvt_pk_bf16_f32 v27, v34, v35
	v_addc_co_u32_e32 v31, vcc, 0, v121, vcc
	v_max_f32_e32 v16, 0, v16
	v_max_f32_e32 v17, 0, v17
	global_store_dwordx4 v[30:31], v[24:27], off
	v_max_f32_e32 v20, v20, v20
	v_max_f32_e32 v21, v21, v21
	v_pk_mul_f32 v[24:25], v[16:17], v[16:17]
	v_max_f32_e32 v17, v18, v18
	v_max_f32_e32 v16, v22, v22
	v_max_f32_e32 v18, 0, v17
	v_max_f32_e32 v17, v23, v23
	v_max_f32_e32 v19, v19, v19
	v_max_f32_e32 v20, 0, v20
	v_max_f32_e32 v21, 0, v21
	v_max_f32_e32 v16, 0, v16
	v_max_f32_e32 v17, 0, v17
	v_max_f32_e32 v19, 0, v19
	v_pk_mul_f32 v[20:21], v[20:21], v[20:21]
	v_pk_mul_f32 v[22:23], v[16:17], v[16:17]
	v_pk_mul_f32 v[26:27], v[18:19], v[18:19]
	v_max_f32_e32 v8, v8, v8
	v_max_f32_e32 v9, v9, v9
	v_lshl_add_u64 v[28:29], v[120:121], 0, s[14:15]
	v_cvt_pk_bf16_f32 v16, v20, v21
	v_cvt_pk_bf16_f32 v17, v22, v23
	v_cvt_pk_bf16_f32 v18, v24, v25
	v_cvt_pk_bf16_f32 v19, v26, v27
	v_max_f32_e32 v8, 0, v8
	v_max_f32_e32 v9, 0, v9
	global_store_dwordx4 v[28:29], v[16:19], off offset:256
	v_max_f32_e32 v12, v12, v12
	v_max_f32_e32 v13, v13, v13
	v_pk_mul_f32 v[16:17], v[8:9], v[8:9]
	v_max_f32_e32 v9, v10, v10
	v_max_f32_e32 v8, v14, v14
	v_max_f32_e32 v10, 0, v9
	v_max_f32_e32 v9, v15, v15
	v_max_f32_e32 v8, 0, v8
	v_max_f32_e32 v9, 0, v9
	v_max_f32_e32 v11, v11, v11
	v_max_f32_e32 v12, 0, v12
	v_max_f32_e32 v13, 0, v13
	v_max_f32_e32 v11, 0, v11
	v_pk_mul_f32 v[14:15], v[8:9], v[8:9]
	v_pk_mul_f32 v[12:13], v[12:13], v[12:13]
	v_pk_mul_f32 v[18:19], v[10:11], v[10:11]
	v_cvt_pk_bf16_f32 v9, v14, v15
	v_add_co_u32_e32 v14, vcc, s73, v120
	v_max_f32_e32 v0, v0, v0
	v_max_f32_e32 v1, v1, v1
	v_cvt_pk_bf16_f32 v8, v12, v13
	v_cvt_pk_bf16_f32 v10, v16, v17
	v_cvt_pk_bf16_f32 v11, v18, v19
	v_addc_co_u32_e32 v15, vcc, 0, v121, vcc
	v_max_f32_e32 v0, 0, v0
	v_max_f32_e32 v1, 0, v1
	global_store_dwordx4 v[14:15], v[8:11], off
	v_max_f32_e32 v4, v4, v4
	v_max_f32_e32 v5, v5, v5
	v_pk_mul_f32 v[8:9], v[0:1], v[0:1]
	v_max_f32_e32 v1, v2, v2
	v_max_f32_e32 v0, v6, v6
	v_max_f32_e32 v2, 0, v1
	v_max_f32_e32 v1, v7, v7
	v_max_f32_e32 v3, v3, v3
	v_max_f32_e32 v4, 0, v4
	v_max_f32_e32 v5, 0, v5
	v_max_f32_e32 v0, 0, v0
	v_max_f32_e32 v1, 0, v1
	v_max_f32_e32 v3, 0, v3
	v_pk_mul_f32 v[4:5], v[4:5], v[4:5]
	v_pk_mul_f32 v[6:7], v[0:1], v[0:1]
	v_pk_mul_f32 v[10:11], v[2:3], v[2:3]
	v_lshl_add_u64 v[12:13], v[120:121], 0, s[16:17]
	v_cvt_pk_bf16_f32 v0, v4, v5
	v_cvt_pk_bf16_f32 v1, v6, v7
	v_cvt_pk_bf16_f32 v2, v8, v9
	v_cvt_pk_bf16_f32 v3, v10, v11
	s_and_b64 vcc, exec, s[4:5]
	s_mov_b32 s74, s18
	s_mov_b32 s30, s20
	s_mov_b64 s[36:37], s[28:29]
	s_mov_b64 s[34:35], s[26:27]
	global_store_dwordx4 v[12:13], v[0:3], off offset:256
	s_cbranch_vccz .LBB0_1284
	s_waitcnt vmcnt(16)
	s_cmpk_gt_u32 s40, 0xff
	s_cbranch_scc1 .LBB0_1295
	s_barrier

.LBB0_1310:
	ds_read_b128 v[154:157], v151
	ds_read_b128 v[158:161], v151 offset:1024
	ds_read_b128 v[162:165], v151 offset:2048
	ds_read_b128 v[166:169], v151 offset:3072
	s_add_u32 s38, s36, 0xfffc0080
	s_addc_u32 s39, s37, -1
	s_cmp_eq_u32 s77, 12
	s_cselect_b32 s41, s27, s39
	s_cselect_b32 s40, s73, s38
	s_cselect_b32 s39, s21, s76
	s_cselect_b32 s38, s74, s75
	v_lshl_add_u64 v[202:203], s[36:37], 0, v[138:139]
	s_add_i32 m0, s35, 0xc000
	ds_read_b128 v[170:173], v152
	ds_read_b128 v[174:177], v152 offset:1024
	ds_read_b128 v[178:181], v152 offset:2048
	ds_read_b128 v[182:185], v152 offset:3072
	ds_read_b128 v[186:189], v152 offset:4096
	ds_read_b128 v[190:193], v152 offset:5120
	ds_read_b128 v[194:197], v152 offset:6144
	ds_read_b128 v[198:201], v152 offset:7168
	global_load_lds_dwordx4 v[202:203], off
	v_lshl_add_u64 v[202:203], s[36:37], 0, v[140:141]
	s_add_i32 m0, s35, 0xe000
	s_nop 0
	global_load_lds_dwordx4 v[202:203], off
	s_waitcnt lgkmcnt(8)
	s_barrier
	s_waitcnt lgkmcnt(0)
	s_waitcnt lgkmcnt(0)
	v_mfma_f32_16x16x32_bf16 v[124:127], v[154:157], v[170:173], v[124:127]
	v_mfma_f32_16x16x32_bf16 v[120:123], v[162:165], v[170:173], v[120:123]
	v_mfma_f32_16x16x32_bf16 v[108:111], v[154:157], v[178:181], v[108:111]
	v_mfma_f32_16x16x32_bf16 v[104:107], v[162:165], v[178:181], v[104:107]
	v_mfma_f32_16x16x32_bf16 v[92:95], v[154:157], v[186:189], v[92:95]
	v_mfma_f32_16x16x32_bf16 v[88:91], v[162:165], v[186:189], v[88:91]
	v_mfma_f32_16x16x32_bf16 v[76:79], v[154:157], v[194:197], v[76:79]
	v_mfma_f32_16x16x32_bf16 v[72:75], v[162:165], v[194:197], v[72:75]
	v_mfma_f32_16x16x32_bf16 v[124:127], v[158:161], v[174:177], v[124:127]
	v_mfma_f32_16x16x32_bf16 v[120:123], v[166:169], v[174:177], v[120:123]
	v_mfma_f32_16x16x32_bf16 v[108:111], v[158:161], v[182:185], v[108:111]
	v_mfma_f32_16x16x32_bf16 v[104:107], v[166:169], v[182:185], v[104:107]
	v_mfma_f32_16x16x32_bf16 v[92:95], v[158:161], v[190:193], v[92:95]
	v_mfma_f32_16x16x32_bf16 v[88:91], v[166:169], v[190:193], v[88:91]
	v_mfma_f32_16x16x32_bf16 v[76:79], v[158:161], v[198:201], v[76:79]
	v_mfma_f32_16x16x32_bf16 v[72:75], v[166:169], v[198:201], v[72:75]
	s_barrier
	s_add_i32 s78, s62, s52
	v_lshl_add_u64 v[218:219], s[38:39], 0, v[132:133]
	s_mov_b32 m0, s78
	ds_read_b128 v[202:205], v153
	ds_read_b128 v[206:209], v153 offset:1024
	ds_read_b128 v[210:213], v153 offset:2048
	ds_read_b128 v[214:217], v153 offset:3072
	global_load_lds_dwordx4 v[218:219], off
	v_lshl_add_u64 v[220:221], s[38:39], 0, v[136:137]
	s_add_i32 m0, s78, 0x2000
	s_nop 0
	global_load_lds_dwordx4 v[220:221], off
	s_barrier
	s_waitcnt lgkmcnt(0)
	s_waitcnt lgkmcnt(0)
	v_mfma_f32_16x16x32_bf16 v[116:119], v[202:205], v[170:173], v[116:119]
	v_mfma_f32_16x16x32_bf16 v[112:115], v[210:213], v[170:173], v[112:115]
	v_mfma_f32_16x16x32_bf16 v[100:103], v[202:205], v[178:181], v[100:103]
	v_mfma_f32_16x16x32_bf16 v[96:99], v[210:213], v[178:181], v[96:99]
	v_mfma_f32_16x16x32_bf16 v[84:87], v[202:205], v[186:189], v[84:87]
	v_mfma_f32_16x16x32_bf16 v[80:83], v[210:213], v[186:189], v[80:83]
	v_mfma_f32_16x16x32_bf16 v[68:71], v[202:205], v[194:197], v[68:71]
	v_mfma_f32_16x16x32_bf16 v[64:67], v[210:213], v[194:197], v[64:67]
	v_mfma_f32_16x16x32_bf16 v[116:119], v[206:209], v[174:177], v[116:119]
	v_mfma_f32_16x16x32_bf16 v[112:115], v[214:217], v[174:177], v[112:115]
	v_mfma_f32_16x16x32_bf16 v[100:103], v[206:209], v[182:185], v[100:103]
	v_mfma_f32_16x16x32_bf16 v[96:99], v[214:217], v[182:185], v[96:99]
	v_mfma_f32_16x16x32_bf16 v[84:87], v[206:209], v[190:193], v[84:87]
	v_mfma_f32_16x16x32_bf16 v[80:83], v[214:217], v[190:193], v[80:83]
	v_mfma_f32_16x16x32_bf16 v[68:71], v[206:209], v[198:201], v[68:71]
	v_mfma_f32_16x16x32_bf16 v[64:67], v[214:217], v[198:201], v[64:67]
	s_mov_b32 m0, s35
	v_lshl_add_u64 v[222:223], s[40:41], 0, v[130:131]
	s_barrier
	ds_read_b128 v[170:173], v152 offset:16384
	ds_read_b128 v[174:177], v152 offset:17408
	ds_read_b128 v[178:181], v152 offset:18432
	ds_read_b128 v[182:185], v152 offset:19456
	ds_read_b128 v[186:189], v152 offset:20480
	ds_read_b128 v[190:193], v152 offset:21504
	ds_read_b128 v[194:197], v152 offset:22528
	ds_read_b128 v[198:201], v152 offset:23552
	global_load_lds_dwordx4 v[222:223], off
	v_lshl_add_u64 v[224:225], s[40:41], 0, v[134:135]
	s_mov_b32 m0, s53
	s_nop 0
	global_load_lds_dwordx4 v[224:225], off
	s_barrier
	s_waitcnt lgkmcnt(0)
	s_waitcnt lgkmcnt(0)
	v_mfma_f32_16x16x32_bf16 v[60:63], v[154:157], v[170:173], v[60:63]
	v_mfma_f32_16x16x32_bf16 v[56:59], v[162:165], v[170:173], v[56:59]
	v_mfma_f32_16x16x32_bf16 v[44:47], v[154:157], v[178:181], v[44:47]
	v_mfma_f32_16x16x32_bf16 v[40:43], v[162:165], v[178:181], v[40:43]
	v_mfma_f32_16x16x32_bf16 v[28:31], v[154:157], v[186:189], v[28:31]
	v_mfma_f32_16x16x32_bf16 v[24:27], v[162:165], v[186:189], v[24:27]
	v_mfma_f32_16x16x32_bf16 v[12:15], v[154:157], v[194:197], v[12:15]
	v_mfma_f32_16x16x32_bf16 v[8:11], v[162:165], v[194:197], v[8:11]
	v_mfma_f32_16x16x32_bf16 v[60:63], v[158:161], v[174:177], v[60:63]
	v_mfma_f32_16x16x32_bf16 v[56:59], v[166:169], v[174:177], v[56:59]
	v_mfma_f32_16x16x32_bf16 v[44:47], v[158:161], v[182:185], v[44:47]
	v_mfma_f32_16x16x32_bf16 v[40:43], v[166:169], v[182:185], v[40:43]
	v_mfma_f32_16x16x32_bf16 v[28:31], v[158:161], v[190:193], v[28:31]
	v_mfma_f32_16x16x32_bf16 v[24:27], v[166:169], v[190:193], v[24:27]
	v_mfma_f32_16x16x32_bf16 v[12:15], v[158:161], v[198:201], v[12:15]
	v_mfma_f32_16x16x32_bf16 v[8:11], v[166:169], v[198:201], v[8:11]
	s_barrier
	s_add_u32 s78, s38, 0x40000
	s_addc_u32 s79, s39, 0
	s_add_i32 s80, s63, s52
	v_lshl_add_u64 v[154:155], s[78:79], 0, v[132:133]
	s_mov_b32 m0, s80
	s_nop 0
	global_load_lds_dwordx4 v[154:155], off
	v_lshl_add_u64 v[154:155], s[78:79], 0, v[136:137]
	s_add_i32 m0, s80, 0x2000
	s_nop 0
	global_load_lds_dwordx4 v[154:155], off
	s_waitcnt vmcnt(6)
	s_barrier
	v_mfma_f32_16x16x32_bf16 v[52:55], v[202:205], v[170:173], v[52:55]
	v_mfma_f32_16x16x32_bf16 v[48:51], v[210:213], v[170:173], v[48:51]
	v_mfma_f32_16x16x32_bf16 v[36:39], v[202:205], v[178:181], v[36:39]
	v_mfma_f32_16x16x32_bf16 v[32:35], v[210:213], v[178:181], v[32:35]
	v_mfma_f32_16x16x32_bf16 v[20:23], v[202:205], v[186:189], v[20:23]
	v_mfma_f32_16x16x32_bf16 v[16:19], v[210:213], v[186:189], v[16:19]
	v_mfma_f32_16x16x32_bf16 v[4:7], v[202:205], v[194:197], v[4:7]
	v_mfma_f32_16x16x32_bf16 v[0:3], v[210:213], v[194:197], v[0:3]
	v_mfma_f32_16x16x32_bf16 v[52:55], v[206:209], v[174:177], v[52:55]
	v_mfma_f32_16x16x32_bf16 v[48:51], v[214:217], v[174:177], v[48:51]
	v_mfma_f32_16x16x32_bf16 v[36:39], v[206:209], v[182:185], v[36:39]
	v_mfma_f32_16x16x32_bf16 v[32:35], v[214:217], v[182:185], v[32:35]
	v_mfma_f32_16x16x32_bf16 v[20:23], v[206:209], v[190:193], v[20:23]
	v_mfma_f32_16x16x32_bf16 v[16:19], v[214:217], v[190:193], v[16:19]
	v_mfma_f32_16x16x32_bf16 v[4:7], v[206:209], v[198:201], v[4:7]
	v_mfma_f32_16x16x32_bf16 v[0:3], v[214:217], v[198:201], v[0:3]
	s_add_i32 s78, 0, 0x18000
	v_add_u32_e32 v166, s78, v149
	s_barrier
	ds_read_b128 v[154:157], v166
	ds_read_b128 v[158:161], v166 offset:1024
	ds_read_b128 v[162:165], v166 offset:2048
	ds_read_b128 v[166:169], v166 offset:3072
	s_add_u32 s40, s40, 0x40000
	s_addc_u32 s41, s41, 0
	s_mov_b32 m0, s54
	v_lshl_add_u64 v[202:203], s[40:41], 0, v[130:131]
	ds_read_b128 v[170:173], v152 offset:32768
	ds_read_b128 v[174:177], v152 offset:33792
	ds_read_b128 v[178:181], v152 offset:34816
	ds_read_b128 v[182:185], v152 offset:35840
	ds_read_b128 v[186:189], v152 offset:36864
	ds_read_b128 v[190:193], v152 offset:37888
	ds_read_b128 v[194:197], v152 offset:38912
	ds_read_b128 v[198:201], v152 offset:39936
	global_load_lds_dwordx4 v[202:203], off
	v_lshl_add_u64 v[202:203], s[40:41], 0, v[134:135]
	s_mov_b32 m0, s55
	s_nop 0
	global_load_lds_dwordx4 v[202:203], off
	s_waitcnt lgkmcnt(8)
	s_barrier
	s_waitcnt lgkmcnt(0)
	s_waitcnt lgkmcnt(0)
	v_mfma_f32_16x16x32_bf16 v[124:127], v[154:157], v[170:173], v[124:127]
	v_mfma_f32_16x16x32_bf16 v[120:123], v[162:165], v[170:173], v[120:123]
	v_mfma_f32_16x16x32_bf16 v[108:111], v[154:157], v[178:181], v[108:111]
	v_mfma_f32_16x16x32_bf16 v[104:107], v[162:165], v[178:181], v[104:107]
	v_mfma_f32_16x16x32_bf16 v[92:95], v[154:157], v[186:189], v[92:95]
	v_mfma_f32_16x16x32_bf16 v[88:91], v[162:165], v[186:189], v[88:91]
	v_mfma_f32_16x16x32_bf16 v[76:79], v[154:157], v[194:197], v[76:79]
	v_mfma_f32_16x16x32_bf16 v[72:75], v[162:165], v[194:197], v[72:75]
	v_mfma_f32_16x16x32_bf16 v[124:127], v[158:161], v[174:177], v[124:127]
	v_mfma_f32_16x16x32_bf16 v[120:123], v[166:169], v[174:177], v[120:123]
	v_mfma_f32_16x16x32_bf16 v[108:111], v[158:161], v[182:185], v[108:111]
	v_mfma_f32_16x16x32_bf16 v[104:107], v[166:169], v[182:185], v[104:107]
	v_mfma_f32_16x16x32_bf16 v[92:95], v[158:161], v[190:193], v[92:95]
	v_mfma_f32_16x16x32_bf16 v[88:91], v[166:169], v[190:193], v[88:91]
	v_mfma_f32_16x16x32_bf16 v[76:79], v[158:161], v[198:201], v[76:79]
	v_mfma_f32_16x16x32_bf16 v[72:75], v[166:169], v[198:201], v[72:75]
	s_barrier
	s_add_i32 s40, 0, 0x1c000
	s_add_i32 s41, s78, s52
	v_add_u32_e32 v214, s40, v149
	v_lshl_add_u64 v[218:219], v[218:219], 0, s[10:11]
	s_mov_b32 m0, s41
	ds_read_b128 v[202:205], v214
	ds_read_b128 v[206:209], v214 offset:1024
	ds_read_b128 v[210:213], v214 offset:2048
	ds_read_b128 v[214:217], v214 offset:3072
	global_load_lds_dwordx4 v[218:219], off
	v_lshl_add_u64 v[218:219], v[220:221], 0, s[10:11]
	s_add_i32 m0, s41, 0x2000
	s_nop 0
	global_load_lds_dwordx4 v[218:219], off
	s_barrier
	s_waitcnt lgkmcnt(0)
	s_waitcnt lgkmcnt(0)
	v_mfma_f32_16x16x32_bf16 v[116:119], v[202:205], v[170:173], v[116:119]
	v_mfma_f32_16x16x32_bf16 v[112:115], v[210:213], v[170:173], v[112:115]
	v_mfma_f32_16x16x32_bf16 v[100:103], v[202:205], v[178:181], v[100:103]
	v_mfma_f32_16x16x32_bf16 v[96:99], v[210:213], v[178:181], v[96:99]
	v_mfma_f32_16x16x32_bf16 v[84:87], v[202:205], v[186:189], v[84:87]
	v_mfma_f32_16x16x32_bf16 v[80:83], v[210:213], v[186:189], v[80:83]
	v_mfma_f32_16x16x32_bf16 v[68:71], v[202:205], v[194:197], v[68:71]
	v_mfma_f32_16x16x32_bf16 v[64:67], v[210:213], v[194:197], v[64:67]
	v_mfma_f32_16x16x32_bf16 v[116:119], v[206:209], v[174:177], v[116:119]
	v_mfma_f32_16x16x32_bf16 v[112:115], v[214:217], v[174:177], v[112:115]
	v_mfma_f32_16x16x32_bf16 v[100:103], v[206:209], v[182:185], v[100:103]
	v_mfma_f32_16x16x32_bf16 v[96:99], v[214:217], v[182:185], v[96:99]
	v_mfma_f32_16x16x32_bf16 v[84:87], v[206:209], v[190:193], v[84:87]
	v_mfma_f32_16x16x32_bf16 v[80:83], v[214:217], v[190:193], v[80:83]
	v_mfma_f32_16x16x32_bf16 v[68:71], v[206:209], v[198:201], v[68:71]
	v_mfma_f32_16x16x32_bf16 v[64:67], v[214:217], v[198:201], v[64:67]
	s_mov_b32 m0, s57
	v_lshl_add_u64 v[218:219], v[222:223], 0, s[10:11]
	s_barrier
	ds_read_b128 v[170:173], v152 offset:49152
	ds_read_b128 v[174:177], v152 offset:50176
	ds_read_b128 v[178:181], v152 offset:51200
	ds_read_b128 v[182:185], v152 offset:52224
	ds_read_b128 v[186:189], v152 offset:53248
	ds_read_b128 v[190:193], v152 offset:54272
	ds_read_b128 v[194:197], v152 offset:55296
	ds_read_b128 v[198:201], v152 offset:56320
	global_load_lds_dwordx4 v[218:219], off
	v_lshl_add_u64 v[218:219], v[224:225], 0, s[10:11]
	s_mov_b32 m0, s60
	s_nop 0
	global_load_lds_dwordx4 v[218:219], off
	s_barrier
	s_waitcnt lgkmcnt(0)
	s_waitcnt lgkmcnt(0)
	v_mfma_f32_16x16x32_bf16 v[60:63], v[154:157], v[170:173], v[60:63]
	v_mfma_f32_16x16x32_bf16 v[56:59], v[162:165], v[170:173], v[56:59]
	v_mfma_f32_16x16x32_bf16 v[44:47], v[154:157], v[178:181], v[44:47]
	v_mfma_f32_16x16x32_bf16 v[40:43], v[162:165], v[178:181], v[40:43]
	v_mfma_f32_16x16x32_bf16 v[28:31], v[154:157], v[186:189], v[28:31]
	v_mfma_f32_16x16x32_bf16 v[24:27], v[162:165], v[186:189], v[24:27]
	v_mfma_f32_16x16x32_bf16 v[12:15], v[154:157], v[194:197], v[12:15]
	v_mfma_f32_16x16x32_bf16 v[8:11], v[162:165], v[194:197], v[8:11]
	v_mfma_f32_16x16x32_bf16 v[60:63], v[158:161], v[174:177], v[60:63]
	v_mfma_f32_16x16x32_bf16 v[56:59], v[166:169], v[174:177], v[56:59]
	v_mfma_f32_16x16x32_bf16 v[44:47], v[158:161], v[182:185], v[44:47]
	v_mfma_f32_16x16x32_bf16 v[40:43], v[166:169], v[182:185], v[40:43]
	v_mfma_f32_16x16x32_bf16 v[28:31], v[158:161], v[190:193], v[28:31]
	v_mfma_f32_16x16x32_bf16 v[24:27], v[166:169], v[190:193], v[24:27]
	v_mfma_f32_16x16x32_bf16 v[12:15], v[158:161], v[198:201], v[12:15]
	v_mfma_f32_16x16x32_bf16 v[8:11], v[166:169], v[198:201], v[8:11]
	s_barrier
	s_add_u32 s38, s38, 0x40080
	s_addc_u32 s39, s39, 0
	s_add_i32 s40, s40, s52
	v_lshl_add_u64 v[154:155], s[38:39], 0, v[132:133]
	s_mov_b32 m0, s40
	s_nop 0
	global_load_lds_dwordx4 v[154:155], off
	v_lshl_add_u64 v[154:155], s[38:39], 0, v[136:137]
	s_add_i32 m0, s40, 0x2000
	s_nop 0
	global_load_lds_dwordx4 v[154:155], off
	s_waitcnt vmcnt(6)
	s_barrier
	v_mfma_f32_16x16x32_bf16 v[52:55], v[202:205], v[170:173], v[52:55]
	v_mfma_f32_16x16x32_bf16 v[48:51], v[210:213], v[170:173], v[48:51]
	v_mfma_f32_16x16x32_bf16 v[36:39], v[202:205], v[178:181], v[36:39]
	v_mfma_f32_16x16x32_bf16 v[32:35], v[210:213], v[178:181], v[32:35]
	v_mfma_f32_16x16x32_bf16 v[20:23], v[202:205], v[186:189], v[20:23]
	v_mfma_f32_16x16x32_bf16 v[16:19], v[210:213], v[186:189], v[16:19]
	v_mfma_f32_16x16x32_bf16 v[4:7], v[202:205], v[194:197], v[4:7]
	v_mfma_f32_16x16x32_bf16 v[0:3], v[210:213], v[194:197], v[0:3]
	v_mfma_f32_16x16x32_bf16 v[52:55], v[206:209], v[174:177], v[52:55]
	v_mfma_f32_16x16x32_bf16 v[48:51], v[214:217], v[174:177], v[48:51]
	v_mfma_f32_16x16x32_bf16 v[36:39], v[206:209], v[182:185], v[36:39]
	v_mfma_f32_16x16x32_bf16 v[32:35], v[214:217], v[182:185], v[32:35]
	v_mfma_f32_16x16x32_bf16 v[20:23], v[206:209], v[190:193], v[20:23]
	v_mfma_f32_16x16x32_bf16 v[16:19], v[214:217], v[190:193], v[16:19]
	v_mfma_f32_16x16x32_bf16 v[4:7], v[206:209], v[198:201], v[4:7]
	v_mfma_f32_16x16x32_bf16 v[0:3], v[214:217], v[198:201], v[0:3]
	s_add_i32 s77, s77, 2
	s_add_u32 s36, s36, 0x100
	s_addc_u32 s37, s37, 0
	s_add_u32 s75, s75, 0x100
	s_addc_u32 s76, s76, 0
	s_cmp_gt_u32 s77, 13
	s_barrier
	s_cbranch_scc0 .LBB0_1310
	v_lshl_add_u32 v154, s34, 8, v148
	v_max_f32_e32 v126, v126, v126
	v_max_f32_e32 v127, v127, v127
	v_lshl_or_b32 v156, s72, 8, v150
	v_ashrrev_i32_e32 v155, 31, v154
	v_max_f32_e32 v124, v124, v124
	v_max_f32_e32 v120, v120, v120
	v_max_f32_e32 v125, v125, v125
	v_max_f32_e32 v121, v121, v121
	v_max_f32_e32 v126, 0, v126
	v_max_f32_e32 v122, v122, v122
	v_max_f32_e32 v127, 0, v127
	v_max_f32_e32 v123, v123, v123
	v_lshlrev_b64 v[158:159], 13, v[154:155]
	v_max_f32_e32 v124, 0, v124
	v_max_f32_e32 v120, 0, v120
	v_max_f32_e32 v125, 0, v125
	v_max_f32_e32 v121, 0, v121
	v_max_f32_e32 v122, 0, v122
	v_max_f32_e32 v123, 0, v123
	v_pk_mul_f32 v[126:127], v[126:127], v[126:127]
	v_ashrrev_i32_e32 v157, 31, v156
	v_lshl_add_u64 v[158:159], s[46:47], 0, v[158:159]
	v_pk_mul_f32 v[124:125], v[124:125], v[124:125]
	v_pk_mul_f32 v[120:121], v[120:121], v[120:121]
	v_pk_mul_f32 v[160:161], v[122:123], v[122:123]
	v_cvt_pk_bf16_f32 v123, v126, v127
	v_lshlrev_b64 v[126:127], 1, v[156:157]
	v_max_f32_e32 v112, v112, v112
	v_max_f32_e32 v113, v113, v113
	v_cvt_pk_bf16_f32 v122, v124, v125
	v_cvt_pk_bf16_f32 v124, v120, v121
	v_cvt_pk_bf16_f32 v125, v160, v161
	v_lshl_add_u64 v[120:121], v[158:159], 0, v[126:127]
	v_max_f32_e32 v112, 0, v112
	v_max_f32_e32 v113, 0, v113
	global_store_dwordx4 v[120:121], v[122:125], off
	v_max_f32_e32 v116, v116, v116
	v_max_f32_e32 v117, v117, v117
	v_pk_mul_f32 v[122:123], v[112:113], v[112:113]
	v_max_f32_e32 v113, v114, v114
	v_max_f32_e32 v112, v118, v118
	v_max_f32_e32 v114, 0, v113
	v_max_f32_e32 v113, v119, v119
	v_max_f32_e32 v115, v115, v115
	v_max_f32_e32 v116, 0, v116
	v_max_f32_e32 v117, 0, v117
	v_max_f32_e32 v112, 0, v112
	v_max_f32_e32 v113, 0, v113
	v_max_f32_e32 v115, 0, v115
	v_pk_mul_f32 v[116:117], v[116:117], v[116:117]
	v_pk_mul_f32 v[118:119], v[112:113], v[112:113]
	v_pk_mul_f32 v[124:125], v[114:115], v[114:115]
	v_max_f32_e32 v104, v104, v104
	v_max_f32_e32 v105, v105, v105
	v_cvt_pk_bf16_f32 v112, v116, v117
	v_cvt_pk_bf16_f32 v113, v118, v119
	v_cvt_pk_bf16_f32 v114, v122, v123
	v_cvt_pk_bf16_f32 v115, v124, v125
	v_max_f32_e32 v104, 0, v104
	v_max_f32_e32 v105, 0, v105
	global_store_dwordx4 v[120:121], v[112:115], off offset:256
	v_max_f32_e32 v108, v108, v108
	v_max_f32_e32 v109, v109, v109
	v_or_b32_e32 v112, 16, v154
	v_pk_mul_f32 v[114:115], v[104:105], v[104:105]
	v_max_f32_e32 v105, v106, v106
	v_ashrrev_i32_e32 v113, 31, v112
	v_max_f32_e32 v104, v110, v110
	v_max_f32_e32 v106, 0, v105
	v_max_f32_e32 v105, v111, v111
	v_max_f32_e32 v107, v107, v107
	v_lshlrev_b64 v[112:113], 13, v[112:113]
	v_max_f32_e32 v108, 0, v108
	v_max_f32_e32 v109, 0, v109
	v_max_f32_e32 v104, 0, v104
	v_max_f32_e32 v105, 0, v105
	v_max_f32_e32 v107, 0, v107
	v_lshl_add_u64 v[112:113], s[46:47], 0, v[112:113]
	v_pk_mul_f32 v[108:109], v[108:109], v[108:109]
	v_pk_mul_f32 v[110:111], v[104:105], v[104:105]
	v_pk_mul_f32 v[116:117], v[106:107], v[106:107]
	v_max_f32_e32 v96, v96, v96
	v_max_f32_e32 v97, v97, v97
	v_cvt_pk_bf16_f32 v104, v108, v109
	v_cvt_pk_bf16_f32 v105, v110, v111
	v_cvt_pk_bf16_f32 v106, v114, v115
	v_cvt_pk_bf16_f32 v107, v116, v117
	v_lshl_add_u64 v[108:109], v[112:113], 0, v[126:127]
	v_max_f32_e32 v96, 0, v96
	v_max_f32_e32 v97, 0, v97
	global_store_dwordx4 v[108:109], v[104:107], off
	v_max_f32_e32 v100, v100, v100
	v_max_f32_e32 v101, v101, v101
	v_pk_mul_f32 v[104:105], v[96:97], v[96:97]
	v_max_f32_e32 v97, v98, v98
	v_max_f32_e32 v96, v102, v102
	v_max_f32_e32 v98, 0, v97
	v_max_f32_e32 v97, v103, v103
	v_max_f32_e32 v99, v99, v99
	v_max_f32_e32 v100, 0, v100
	v_max_f32_e32 v101, 0, v101
	v_max_f32_e32 v96, 0, v96
	v_max_f32_e32 v97, 0, v97
	v_max_f32_e32 v99, 0, v99
	v_pk_mul_f32 v[100:101], v[100:101], v[100:101]
	v_pk_mul_f32 v[102:103], v[96:97], v[96:97]
	v_pk_mul_f32 v[106:107], v[98:99], v[98:99]
	v_max_f32_e32 v88, v88, v88
	v_max_f32_e32 v89, v89, v89
	v_cvt_pk_bf16_f32 v96, v100, v101
	v_cvt_pk_bf16_f32 v97, v102, v103
	v_cvt_pk_bf16_f32 v98, v104, v105
	v_cvt_pk_bf16_f32 v99, v106, v107
	v_max_f32_e32 v88, 0, v88
	v_max_f32_e32 v89, 0, v89
	global_store_dwordx4 v[108:109], v[96:99], off offset:256
	v_max_f32_e32 v92, v92, v92
	v_max_f32_e32 v93, v93, v93
	v_or_b32_e32 v96, 32, v154
	v_pk_mul_f32 v[98:99], v[88:89], v[88:89]
	v_max_f32_e32 v89, v90, v90
	v_ashrrev_i32_e32 v97, 31, v96
	v_max_f32_e32 v88, v94, v94
	v_max_f32_e32 v90, 0, v89
	v_max_f32_e32 v89, v95, v95
	v_max_f32_e32 v91, v91, v91
	v_lshlrev_b64 v[96:97], 13, v[96:97]
	v_max_f32_e32 v92, 0, v92
	v_max_f32_e32 v93, 0, v93
	v_max_f32_e32 v88, 0, v88
	v_max_f32_e32 v89, 0, v89
	v_max_f32_e32 v91, 0, v91
	v_lshl_add_u64 v[96:97], s[46:47], 0, v[96:97]
	v_pk_mul_f32 v[92:93], v[92:93], v[92:93]
	v_pk_mul_f32 v[94:95], v[88:89], v[88:89]
	v_pk_mul_f32 v[100:101], v[90:91], v[90:91]
	v_max_f32_e32 v80, v80, v80
	v_max_f32_e32 v81, v81, v81
	v_cvt_pk_bf16_f32 v88, v92, v93
	v_cvt_pk_bf16_f32 v89, v94, v95
	v_cvt_pk_bf16_f32 v90, v98, v99
	v_cvt_pk_bf16_f32 v91, v100, v101
	v_lshl_add_u64 v[92:93], v[96:97], 0, v[126:127]
	v_max_f32_e32 v80, 0, v80
	v_max_f32_e32 v81, 0, v81
	global_store_dwordx4 v[92:93], v[88:91], off
	v_max_f32_e32 v84, v84, v84
	v_max_f32_e32 v85, v85, v85
	v_pk_mul_f32 v[88:89], v[80:81], v[80:81]
	v_max_f32_e32 v81, v82, v82
	v_max_f32_e32 v80, v86, v86
	v_max_f32_e32 v82, 0, v81
	v_max_f32_e32 v81, v87, v87
	v_max_f32_e32 v83, v83, v83
	v_max_f32_e32 v84, 0, v84
	v_max_f32_e32 v85, 0, v85
	v_max_f32_e32 v80, 0, v80
	v_max_f32_e32 v81, 0, v81
	v_max_f32_e32 v83, 0, v83
	v_pk_mul_f32 v[84:85], v[84:85], v[84:85]
	v_pk_mul_f32 v[86:87], v[80:81], v[80:81]
	v_pk_mul_f32 v[90:91], v[82:83], v[82:83]
	v_max_f32_e32 v72, v72, v72
	v_max_f32_e32 v73, v73, v73
	v_cvt_pk_bf16_f32 v80, v84, v85
	v_cvt_pk_bf16_f32 v81, v86, v87
	v_cvt_pk_bf16_f32 v82, v88, v89
	v_cvt_pk_bf16_f32 v83, v90, v91
	v_max_f32_e32 v72, 0, v72
	v_max_f32_e32 v73, 0, v73
	global_store_dwordx4 v[92:93], v[80:83], off offset:256
	v_max_f32_e32 v76, v76, v76
	v_max_f32_e32 v77, v77, v77
	v_or_b32_e32 v80, 48, v154
	v_pk_mul_f32 v[82:83], v[72:73], v[72:73]
	v_max_f32_e32 v73, v74, v74
	v_ashrrev_i32_e32 v81, 31, v80
	v_max_f32_e32 v72, v78, v78
	v_max_f32_e32 v74, 0, v73
	v_max_f32_e32 v73, v79, v79
	v_max_f32_e32 v75, v75, v75
	v_lshlrev_b64 v[80:81], 13, v[80:81]
	v_max_f32_e32 v76, 0, v76
	v_max_f32_e32 v77, 0, v77
	v_max_f32_e32 v72, 0, v72
	v_max_f32_e32 v73, 0, v73
	v_max_f32_e32 v75, 0, v75
	v_lshl_add_u64 v[80:81], s[46:47], 0, v[80:81]
	v_pk_mul_f32 v[76:77], v[76:77], v[76:77]
	v_pk_mul_f32 v[78:79], v[72:73], v[72:73]
	v_pk_mul_f32 v[84:85], v[74:75], v[74:75]
	v_max_f32_e32 v64, v64, v64
	v_max_f32_e32 v65, v65, v65
	v_cvt_pk_bf16_f32 v72, v76, v77
	v_cvt_pk_bf16_f32 v73, v78, v79
	v_cvt_pk_bf16_f32 v74, v82, v83
	v_cvt_pk_bf16_f32 v75, v84, v85
	v_lshl_add_u64 v[76:77], v[80:81], 0, v[126:127]
	v_max_f32_e32 v64, 0, v64
	v_max_f32_e32 v65, 0, v65
	global_store_dwordx4 v[76:77], v[72:75], off
	v_max_f32_e32 v68, v68, v68
	v_max_f32_e32 v69, v69, v69
	v_pk_mul_f32 v[72:73], v[64:65], v[64:65]
	v_max_f32_e32 v65, v66, v66
	v_max_f32_e32 v64, v70, v70
	v_max_f32_e32 v66, 0, v65
	v_max_f32_e32 v65, v71, v71
	v_max_f32_e32 v67, v67, v67
	v_max_f32_e32 v68, 0, v68
	v_max_f32_e32 v69, 0, v69
	v_max_f32_e32 v64, 0, v64
	v_max_f32_e32 v65, 0, v65
	v_max_f32_e32 v67, 0, v67
	v_pk_mul_f32 v[68:69], v[68:69], v[68:69]
	v_pk_mul_f32 v[70:71], v[64:65], v[64:65]
	v_pk_mul_f32 v[74:75], v[66:67], v[66:67]
	v_max_f32_e32 v56, v56, v56
	v_max_f32_e32 v57, v57, v57
	v_cvt_pk_bf16_f32 v64, v68, v69
	v_cvt_pk_bf16_f32 v65, v70, v71
	v_cvt_pk_bf16_f32 v66, v72, v73
	v_cvt_pk_bf16_f32 v67, v74, v75
	v_max_f32_e32 v56, 0, v56
	v_max_f32_e32 v57, 0, v57
	global_store_dwordx4 v[76:77], v[64:67], off offset:256
	v_max_f32_e32 v60, v60, v60
	v_max_f32_e32 v61, v61, v61
	v_pk_mul_f32 v[64:65], v[56:57], v[56:57]
	v_max_f32_e32 v57, v58, v58
	v_max_f32_e32 v56, v62, v62
	v_max_f32_e32 v58, 0, v57
	v_max_f32_e32 v57, v63, v63
	v_max_f32_e32 v56, 0, v56
	v_max_f32_e32 v57, 0, v57
	v_max_f32_e32 v59, v59, v59
	v_max_f32_e32 v60, 0, v60
	v_max_f32_e32 v61, 0, v61
	v_max_f32_e32 v59, 0, v59
	v_pk_mul_f32 v[62:63], v[56:57], v[56:57]
	v_pk_mul_f32 v[60:61], v[60:61], v[60:61]
	v_pk_mul_f32 v[66:67], v[58:59], v[58:59]
	v_cvt_pk_bf16_f32 v57, v62, v63
	v_add_co_u32_e32 v62, vcc, s64, v120
	v_max_f32_e32 v48, v48, v48
	v_max_f32_e32 v49, v49, v49
	v_cvt_pk_bf16_f32 v56, v60, v61
	v_cvt_pk_bf16_f32 v58, v64, v65
	v_cvt_pk_bf16_f32 v59, v66, v67
	v_addc_co_u32_e32 v63, vcc, 0, v121, vcc
	v_max_f32_e32 v48, 0, v48
	v_max_f32_e32 v49, 0, v49
	global_store_dwordx4 v[62:63], v[56:59], off
	v_max_f32_e32 v52, v52, v52
	v_max_f32_e32 v53, v53, v53
	v_pk_mul_f32 v[56:57], v[48:49], v[48:49]
	v_max_f32_e32 v49, v50, v50
	v_max_f32_e32 v48, v54, v54
	v_max_f32_e32 v50, 0, v49
	v_max_f32_e32 v49, v55, v55
	v_max_f32_e32 v51, v51, v51
	v_max_f32_e32 v52, 0, v52
	v_max_f32_e32 v53, 0, v53
	v_max_f32_e32 v48, 0, v48
	v_max_f32_e32 v49, 0, v49
	v_max_f32_e32 v51, 0, v51
	v_pk_mul_f32 v[52:53], v[52:53], v[52:53]
	v_pk_mul_f32 v[54:55], v[48:49], v[48:49]
	v_pk_mul_f32 v[58:59], v[50:51], v[50:51]
	v_max_f32_e32 v40, v40, v40
	v_max_f32_e32 v41, v41, v41
	v_lshl_add_u64 v[60:61], v[120:121], 0, s[12:13]
	v_cvt_pk_bf16_f32 v48, v52, v53
	v_cvt_pk_bf16_f32 v49, v54, v55
	v_cvt_pk_bf16_f32 v50, v56, v57
	v_cvt_pk_bf16_f32 v51, v58, v59
	v_max_f32_e32 v40, 0, v40
	v_max_f32_e32 v41, 0, v41
	global_store_dwordx4 v[60:61], v[48:51], off offset:256
	v_max_f32_e32 v44, v44, v44
	v_max_f32_e32 v45, v45, v45
	v_pk_mul_f32 v[48:49], v[40:41], v[40:41]
	v_max_f32_e32 v41, v42, v42
	v_max_f32_e32 v40, v46, v46
	v_max_f32_e32 v42, 0, v41
	v_max_f32_e32 v41, v47, v47
	v_max_f32_e32 v40, 0, v40
	v_max_f32_e32 v41, 0, v41
	v_max_f32_e32 v43, v43, v43
	v_max_f32_e32 v44, 0, v44
	v_max_f32_e32 v45, 0, v45
	v_max_f32_e32 v43, 0, v43
	v_pk_mul_f32 v[46:47], v[40:41], v[40:41]
	v_pk_mul_f32 v[44:45], v[44:45], v[44:45]
	v_pk_mul_f32 v[50:51], v[42:43], v[42:43]
	v_cvt_pk_bf16_f32 v41, v46, v47
	v_add_co_u32_e32 v46, vcc, s65, v120
	v_max_f32_e32 v32, v32, v32
	v_max_f32_e32 v33, v33, v33
	v_cvt_pk_bf16_f32 v40, v44, v45
	v_cvt_pk_bf16_f32 v42, v48, v49
	v_cvt_pk_bf16_f32 v43, v50, v51
	v_addc_co_u32_e32 v47, vcc, 0, v121, vcc
	v_max_f32_e32 v32, 0, v32
	v_max_f32_e32 v33, 0, v33
	global_store_dwordx4 v[46:47], v[40:43], off
	v_max_f32_e32 v36, v36, v36
	v_max_f32_e32 v37, v37, v37
	v_pk_mul_f32 v[40:41], v[32:33], v[32:33]
	v_max_f32_e32 v33, v34, v34
	v_max_f32_e32 v32, v38, v38
	v_max_f32_e32 v34, 0, v33
	v_max_f32_e32 v33, v39, v39
	v_max_f32_e32 v35, v35, v35
	v_max_f32_e32 v36, 0, v36
	v_max_f32_e32 v37, 0, v37
	v_max_f32_e32 v32, 0, v32
	v_max_f32_e32 v33, 0, v33
	v_max_f32_e32 v35, 0, v35
	v_pk_mul_f32 v[36:37], v[36:37], v[36:37]
	v_pk_mul_f32 v[38:39], v[32:33], v[32:33]
	v_pk_mul_f32 v[42:43], v[34:35], v[34:35]
	v_max_f32_e32 v24, v24, v24
	v_max_f32_e32 v25, v25, v25
	v_lshl_add_u64 v[44:45], v[120:121], 0, s[14:15]
	v_cvt_pk_bf16_f32 v32, v36, v37
	v_cvt_pk_bf16_f32 v33, v38, v39
	v_cvt_pk_bf16_f32 v34, v40, v41
	v_cvt_pk_bf16_f32 v35, v42, v43
	v_max_f32_e32 v24, 0, v24
	v_max_f32_e32 v25, 0, v25
	global_store_dwordx4 v[44:45], v[32:35], off offset:256
	v_max_f32_e32 v28, v28, v28
	v_max_f32_e32 v29, v29, v29
	v_pk_mul_f32 v[32:33], v[24:25], v[24:25]
	v_max_f32_e32 v25, v26, v26
	v_max_f32_e32 v24, v30, v30
	v_max_f32_e32 v26, 0, v25
	v_max_f32_e32 v25, v31, v31
	v_max_f32_e32 v24, 0, v24
	v_max_f32_e32 v25, 0, v25
	v_max_f32_e32 v27, v27, v27
	v_max_f32_e32 v28, 0, v28
	v_max_f32_e32 v29, 0, v29
	v_max_f32_e32 v27, 0, v27
	v_pk_mul_f32 v[30:31], v[24:25], v[24:25]
	v_pk_mul_f32 v[28:29], v[28:29], v[28:29]
	v_pk_mul_f32 v[34:35], v[26:27], v[26:27]
	v_cvt_pk_bf16_f32 v25, v30, v31
	v_add_co_u32_e32 v30, vcc, s70, v120
	v_max_f32_e32 v16, v16, v16
	v_max_f32_e32 v17, v17, v17
	v_cvt_pk_bf16_f32 v24, v28, v29
	v_cvt_pk_bf16_f32 v26, v32, v33
	v_cvt_pk_bf16_f32 v27, v34, v35
	v_addc_co_u32_e32 v31, vcc, 0, v121, vcc
	v_max_f32_e32 v16, 0, v16
	v_max_f32_e32 v17, 0, v17
	global_store_dwordx4 v[30:31], v[24:27], off
	v_max_f32_e32 v20, v20, v20
	v_max_f32_e32 v21, v21, v21
	v_pk_mul_f32 v[24:25], v[16:17], v[16:17]
	v_max_f32_e32 v17, v18, v18
	v_max_f32_e32 v16, v22, v22
	v_max_f32_e32 v18, 0, v17
	v_max_f32_e32 v17, v23, v23
	v_max_f32_e32 v19, v19, v19
	v_max_f32_e32 v20, 0, v20
	v_max_f32_e32 v21, 0, v21
	v_max_f32_e32 v16, 0, v16
	v_max_f32_e32 v17, 0, v17
	v_max_f32_e32 v19, 0, v19
	v_pk_mul_f32 v[20:21], v[20:21], v[20:21]
	v_pk_mul_f32 v[22:23], v[16:17], v[16:17]
	v_pk_mul_f32 v[26:27], v[18:19], v[18:19]
	v_max_f32_e32 v8, v8, v8
	v_max_f32_e32 v9, v9, v9
	v_lshl_add_u64 v[28:29], v[120:121], 0, s[16:17]
	v_cvt_pk_bf16_f32 v16, v20, v21
	v_cvt_pk_bf16_f32 v17, v22, v23
	v_cvt_pk_bf16_f32 v18, v24, v25
	v_cvt_pk_bf16_f32 v19, v26, v27
	v_max_f32_e32 v8, 0, v8
	v_max_f32_e32 v9, 0, v9
	global_store_dwordx4 v[28:29], v[16:19], off offset:256
	v_max_f32_e32 v12, v12, v12
	v_max_f32_e32 v13, v13, v13
	v_pk_mul_f32 v[16:17], v[8:9], v[8:9]
	v_max_f32_e32 v9, v10, v10
	v_max_f32_e32 v8, v14, v14
	v_max_f32_e32 v10, 0, v9
	v_max_f32_e32 v9, v15, v15
	v_max_f32_e32 v8, 0, v8
	v_max_f32_e32 v9, 0, v9
	v_max_f32_e32 v11, v11, v11
	v_max_f32_e32 v12, 0, v12
	v_max_f32_e32 v13, 0, v13
	v_max_f32_e32 v11, 0, v11
	v_pk_mul_f32 v[14:15], v[8:9], v[8:9]
	v_pk_mul_f32 v[12:13], v[12:13], v[12:13]
	v_pk_mul_f32 v[18:19], v[10:11], v[10:11]
	v_cvt_pk_bf16_f32 v9, v14, v15
	v_add_co_u32_e32 v14, vcc, s71, v120
	v_max_f32_e32 v0, v0, v0
	v_max_f32_e32 v1, v1, v1
	v_cvt_pk_bf16_f32 v8, v12, v13
	v_cvt_pk_bf16_f32 v10, v16, v17
	v_cvt_pk_bf16_f32 v11, v18, v19
	v_addc_co_u32_e32 v15, vcc, 0, v121, vcc
	v_max_f32_e32 v0, 0, v0
	v_max_f32_e32 v1, 0, v1
	global_store_dwordx4 v[14:15], v[8:11], off
	v_max_f32_e32 v4, v4, v4
	v_max_f32_e32 v5, v5, v5
	v_pk_mul_f32 v[8:9], v[0:1], v[0:1]
	v_max_f32_e32 v1, v2, v2
	v_max_f32_e32 v0, v6, v6
	v_max_f32_e32 v2, 0, v1
	v_max_f32_e32 v1, v7, v7
	v_max_f32_e32 v3, v3, v3
	v_max_f32_e32 v4, 0, v4
	v_max_f32_e32 v5, 0, v5
	v_max_f32_e32 v0, 0, v0
	v_max_f32_e32 v1, 0, v1
	v_max_f32_e32 v3, 0, v3
	v_pk_mul_f32 v[4:5], v[4:5], v[4:5]
	v_pk_mul_f32 v[6:7], v[0:1], v[0:1]
	v_pk_mul_f32 v[10:11], v[2:3], v[2:3]
	v_lshl_add_u64 v[12:13], v[120:121], 0, s[18:19]
	v_cvt_pk_bf16_f32 v0, v4, v5
	v_cvt_pk_bf16_f32 v1, v6, v7
	v_cvt_pk_bf16_f32 v2, v8, v9
	v_cvt_pk_bf16_f32 v3, v10, v11
	s_and_b64 vcc, exec, s[4:5]
	s_mov_b32 s72, s20
	s_mov_b32 s34, s26
	s_mov_b64 s[38:39], s[30:31]
	s_mov_b64 s[36:37], s[28:29]
	global_store_dwordx4 v[12:13], v[0:3], off offset:256
	s_cbranch_vccz .LBB0_1303
	s_waitcnt vmcnt(16)
	s_cmpk_gt_u32 s42, 0xff
	s_cbranch_scc1 .LBB0_1314
	s_barrier

.LBB0_1384:
	ds_read_b128 v[156:159], v153
	ds_read_b128 v[160:163], v153 offset:1024
	ds_read_b128 v[164:167], v153 offset:2048
	ds_read_b128 v[168:171], v153 offset:3072
	s_add_u32 s36, s34, 0xfff00080
	s_addc_u32 s37, s35, -1
	s_cmp_eq_u32 s77, 60
	s_cselect_b32 s39, s27, s37
	s_cselect_b32 s38, s73, s36
	s_cselect_b32 s37, s21, s76
	s_cselect_b32 s36, s74, s75
	v_lshl_add_u64 v[204:205], s[34:35], 0, v[138:139]
	s_add_i32 m0, s19, 0xc000
	ds_read_b128 v[172:175], v154
	ds_read_b128 v[176:179], v154 offset:1024
	ds_read_b128 v[180:183], v154 offset:2048
	ds_read_b128 v[184:187], v154 offset:3072
	ds_read_b128 v[188:191], v154 offset:4096
	ds_read_b128 v[192:195], v154 offset:5120
	ds_read_b128 v[196:199], v154 offset:6144
	ds_read_b128 v[200:203], v154 offset:7168
	global_load_lds_dwordx4 v[204:205], off
	v_lshl_add_u64 v[204:205], s[34:35], 0, v[140:141]
	s_add_i32 m0, s19, 0xe000
	s_nop 0
	global_load_lds_dwordx4 v[204:205], off
	s_waitcnt lgkmcnt(8)
	s_barrier
	s_waitcnt lgkmcnt(0)
	s_waitcnt lgkmcnt(0)
	v_mfma_f32_16x16x32_bf16 v[124:127], v[156:159], v[172:175], v[124:127]
	v_mfma_f32_16x16x32_bf16 v[120:123], v[164:167], v[172:175], v[120:123]
	v_mfma_f32_16x16x32_bf16 v[116:119], v[156:159], v[180:183], v[116:119]
	v_mfma_f32_16x16x32_bf16 v[112:115], v[164:167], v[180:183], v[112:115]
	v_mfma_f32_16x16x32_bf16 v[100:103], v[156:159], v[188:191], v[100:103]
	v_mfma_f32_16x16x32_bf16 v[96:99], v[164:167], v[188:191], v[96:99]
	v_mfma_f32_16x16x32_bf16 v[84:87], v[156:159], v[196:199], v[84:87]
	v_mfma_f32_16x16x32_bf16 v[80:83], v[164:167], v[196:199], v[80:83]
	v_mfma_f32_16x16x32_bf16 v[124:127], v[160:163], v[176:179], v[124:127]
	v_mfma_f32_16x16x32_bf16 v[120:123], v[168:171], v[176:179], v[120:123]
	v_mfma_f32_16x16x32_bf16 v[116:119], v[160:163], v[184:187], v[116:119]
	v_mfma_f32_16x16x32_bf16 v[112:115], v[168:171], v[184:187], v[112:115]
	v_mfma_f32_16x16x32_bf16 v[100:103], v[160:163], v[192:195], v[100:103]
	v_mfma_f32_16x16x32_bf16 v[96:99], v[168:171], v[192:195], v[96:99]
	v_mfma_f32_16x16x32_bf16 v[84:87], v[160:163], v[200:203], v[84:87]
	v_mfma_f32_16x16x32_bf16 v[80:83], v[168:171], v[200:203], v[80:83]
	s_barrier
	s_add_i32 s78, s62, s43
	v_lshl_add_u64 v[220:221], s[36:37], 0, v[134:135]
	s_mov_b32 m0, s78
	ds_read_b128 v[204:207], v155
	ds_read_b128 v[208:211], v155 offset:1024
	ds_read_b128 v[212:215], v155 offset:2048
	ds_read_b128 v[216:219], v155 offset:3072
	global_load_lds_dwordx4 v[220:221], off
	v_lshl_add_u64 v[222:223], s[36:37], 0, v[130:131]
	s_add_i32 m0, s78, 0x2000
	s_nop 0
	global_load_lds_dwordx4 v[222:223], off
	s_barrier
	s_waitcnt lgkmcnt(0)
	s_waitcnt lgkmcnt(0)
	v_mfma_f32_16x16x32_bf16 v[108:111], v[204:207], v[172:175], v[108:111]
	v_mfma_f32_16x16x32_bf16 v[104:107], v[212:215], v[172:175], v[104:107]
	v_mfma_f32_16x16x32_bf16 v[92:95], v[204:207], v[180:183], v[92:95]
	v_mfma_f32_16x16x32_bf16 v[88:91], v[212:215], v[180:183], v[88:91]
	v_mfma_f32_16x16x32_bf16 v[76:79], v[204:207], v[188:191], v[76:79]
	v_mfma_f32_16x16x32_bf16 v[72:75], v[212:215], v[188:191], v[72:75]
	v_mfma_f32_16x16x32_bf16 v[68:71], v[204:207], v[196:199], v[68:71]
	v_mfma_f32_16x16x32_bf16 v[64:67], v[212:215], v[196:199], v[64:67]
	v_mfma_f32_16x16x32_bf16 v[108:111], v[208:211], v[176:179], v[108:111]
	v_mfma_f32_16x16x32_bf16 v[104:107], v[216:219], v[176:179], v[104:107]
	v_mfma_f32_16x16x32_bf16 v[92:95], v[208:211], v[184:187], v[92:95]
	v_mfma_f32_16x16x32_bf16 v[88:91], v[216:219], v[184:187], v[88:91]
	v_mfma_f32_16x16x32_bf16 v[76:79], v[208:211], v[192:195], v[76:79]
	v_mfma_f32_16x16x32_bf16 v[72:75], v[216:219], v[192:195], v[72:75]
	v_mfma_f32_16x16x32_bf16 v[68:71], v[208:211], v[200:203], v[68:71]
	v_mfma_f32_16x16x32_bf16 v[64:67], v[216:219], v[200:203], v[64:67]
	s_mov_b32 m0, s19
	v_lshl_add_u64 v[224:225], s[38:39], 0, v[136:137]
	s_barrier
	ds_read_b128 v[172:175], v154 offset:16384
	ds_read_b128 v[176:179], v154 offset:17408
	ds_read_b128 v[180:183], v154 offset:18432
	ds_read_b128 v[184:187], v154 offset:19456
	ds_read_b128 v[188:191], v154 offset:20480
	ds_read_b128 v[192:195], v154 offset:21504
	ds_read_b128 v[196:199], v154 offset:22528
	ds_read_b128 v[200:203], v154 offset:23552
	global_load_lds_dwordx4 v[224:225], off
	v_lshl_add_u64 v[226:227], s[38:39], 0, v[132:133]
	s_mov_b32 m0, s53
	s_nop 0
	global_load_lds_dwordx4 v[226:227], off
	s_barrier
	s_waitcnt lgkmcnt(0)
	s_waitcnt lgkmcnt(0)
	v_mfma_f32_16x16x32_bf16 v[60:63], v[156:159], v[172:175], v[60:63]
	v_mfma_f32_16x16x32_bf16 v[56:59], v[164:167], v[172:175], v[56:59]
	v_mfma_f32_16x16x32_bf16 v[52:55], v[156:159], v[180:183], v[52:55]
	v_mfma_f32_16x16x32_bf16 v[48:51], v[164:167], v[180:183], v[48:51]
	v_mfma_f32_16x16x32_bf16 v[36:39], v[156:159], v[188:191], v[36:39]
	v_mfma_f32_16x16x32_bf16 v[32:35], v[164:167], v[188:191], v[32:35]
	v_mfma_f32_16x16x32_bf16 v[20:23], v[156:159], v[196:199], v[20:23]
	v_mfma_f32_16x16x32_bf16 v[16:19], v[164:167], v[196:199], v[16:19]
	v_mfma_f32_16x16x32_bf16 v[60:63], v[160:163], v[176:179], v[60:63]
	v_mfma_f32_16x16x32_bf16 v[56:59], v[168:171], v[176:179], v[56:59]
	v_mfma_f32_16x16x32_bf16 v[52:55], v[160:163], v[184:187], v[52:55]
	v_mfma_f32_16x16x32_bf16 v[48:51], v[168:171], v[184:187], v[48:51]
	v_mfma_f32_16x16x32_bf16 v[36:39], v[160:163], v[192:195], v[36:39]
	v_mfma_f32_16x16x32_bf16 v[32:35], v[168:171], v[192:195], v[32:35]
	v_mfma_f32_16x16x32_bf16 v[20:23], v[160:163], v[200:203], v[20:23]
	v_mfma_f32_16x16x32_bf16 v[16:19], v[168:171], v[200:203], v[16:19]
	s_barrier
	s_add_u32 s78, s36, 0x100000
	s_addc_u32 s79, s37, 0
	s_add_i32 s80, s63, s43
	v_lshl_add_u64 v[156:157], s[78:79], 0, v[134:135]
	s_mov_b32 m0, s80
	s_nop 0
	global_load_lds_dwordx4 v[156:157], off
	v_lshl_add_u64 v[156:157], s[78:79], 0, v[130:131]
	s_add_i32 m0, s80, 0x2000
	s_nop 0
	global_load_lds_dwordx4 v[156:157], off
	s_waitcnt vmcnt(6)
	s_barrier
	v_mfma_f32_16x16x32_bf16 v[44:47], v[204:207], v[172:175], v[44:47]
	v_mfma_f32_16x16x32_bf16 v[40:43], v[212:215], v[172:175], v[40:43]
	v_mfma_f32_16x16x32_bf16 v[28:31], v[204:207], v[180:183], v[28:31]
	v_mfma_f32_16x16x32_bf16 v[24:27], v[212:215], v[180:183], v[24:27]
	v_mfma_f32_16x16x32_bf16 v[12:15], v[204:207], v[188:191], v[12:15]
	v_mfma_f32_16x16x32_bf16 v[8:11], v[212:215], v[188:191], v[8:11]
	v_mfma_f32_16x16x32_bf16 v[4:7], v[204:207], v[196:199], v[4:7]
	v_mfma_f32_16x16x32_bf16 v[0:3], v[212:215], v[196:199], v[0:3]
	v_mfma_f32_16x16x32_bf16 v[44:47], v[208:211], v[176:179], v[44:47]
	v_mfma_f32_16x16x32_bf16 v[40:43], v[216:219], v[176:179], v[40:43]
	v_mfma_f32_16x16x32_bf16 v[28:31], v[208:211], v[184:187], v[28:31]
	v_mfma_f32_16x16x32_bf16 v[24:27], v[216:219], v[184:187], v[24:27]
	v_mfma_f32_16x16x32_bf16 v[12:15], v[208:211], v[192:195], v[12:15]
	v_mfma_f32_16x16x32_bf16 v[8:11], v[216:219], v[192:195], v[8:11]
	v_mfma_f32_16x16x32_bf16 v[4:7], v[208:211], v[200:203], v[4:7]
	v_mfma_f32_16x16x32_bf16 v[0:3], v[216:219], v[200:203], v[0:3]
	s_add_i32 s78, 0, 0x18000
	v_add_u32_e32 v168, s78, v151
	s_barrier
	ds_read_b128 v[156:159], v168
	ds_read_b128 v[160:163], v168 offset:1024
	ds_read_b128 v[164:167], v168 offset:2048
	ds_read_b128 v[168:171], v168 offset:3072
	s_add_u32 s38, s38, 0x100000
	s_addc_u32 s39, s39, 0
	s_mov_b32 m0, s54
	v_lshl_add_u64 v[204:205], s[38:39], 0, v[136:137]
	ds_read_b128 v[172:175], v154 offset:32768
	ds_read_b128 v[176:179], v154 offset:33792
	ds_read_b128 v[180:183], v154 offset:34816
	ds_read_b128 v[184:187], v154 offset:35840
	ds_read_b128 v[188:191], v154 offset:36864
	ds_read_b128 v[192:195], v154 offset:37888
	ds_read_b128 v[196:199], v154 offset:38912
	ds_read_b128 v[200:203], v154 offset:39936
	global_load_lds_dwordx4 v[204:205], off
	v_lshl_add_u64 v[204:205], s[38:39], 0, v[132:133]
	s_mov_b32 m0, s55
	s_nop 0
	global_load_lds_dwordx4 v[204:205], off
	s_waitcnt lgkmcnt(8)
	s_barrier
	s_waitcnt lgkmcnt(0)
	s_waitcnt lgkmcnt(0)
	v_mfma_f32_16x16x32_bf16 v[124:127], v[156:159], v[172:175], v[124:127]
	v_mfma_f32_16x16x32_bf16 v[120:123], v[164:167], v[172:175], v[120:123]
	v_mfma_f32_16x16x32_bf16 v[116:119], v[156:159], v[180:183], v[116:119]
	v_mfma_f32_16x16x32_bf16 v[112:115], v[164:167], v[180:183], v[112:115]
	v_mfma_f32_16x16x32_bf16 v[100:103], v[156:159], v[188:191], v[100:103]
	v_mfma_f32_16x16x32_bf16 v[96:99], v[164:167], v[188:191], v[96:99]
	v_mfma_f32_16x16x32_bf16 v[84:87], v[156:159], v[196:199], v[84:87]
	v_mfma_f32_16x16x32_bf16 v[80:83], v[164:167], v[196:199], v[80:83]
	v_mfma_f32_16x16x32_bf16 v[124:127], v[160:163], v[176:179], v[124:127]
	v_mfma_f32_16x16x32_bf16 v[120:123], v[168:171], v[176:179], v[120:123]
	v_mfma_f32_16x16x32_bf16 v[116:119], v[160:163], v[184:187], v[116:119]
	v_mfma_f32_16x16x32_bf16 v[112:115], v[168:171], v[184:187], v[112:115]
	v_mfma_f32_16x16x32_bf16 v[100:103], v[160:163], v[192:195], v[100:103]
	v_mfma_f32_16x16x32_bf16 v[96:99], v[168:171], v[192:195], v[96:99]
	v_mfma_f32_16x16x32_bf16 v[84:87], v[160:163], v[200:203], v[84:87]
	v_mfma_f32_16x16x32_bf16 v[80:83], v[168:171], v[200:203], v[80:83]
	s_barrier
	s_add_i32 s38, 0, 0x1c000
	s_add_i32 s39, s78, s43
	v_add_u32_e32 v216, s38, v151
	v_lshl_add_u64 v[220:221], v[220:221], 0, s[8:9]
	s_mov_b32 m0, s39
	ds_read_b128 v[204:207], v216
	ds_read_b128 v[208:211], v216 offset:1024
	ds_read_b128 v[212:215], v216 offset:2048
	ds_read_b128 v[216:219], v216 offset:3072
	global_load_lds_dwordx4 v[220:221], off
	v_lshl_add_u64 v[220:221], v[222:223], 0, s[8:9]
	s_add_i32 m0, s39, 0x2000
	s_nop 0
	global_load_lds_dwordx4 v[220:221], off
	s_barrier
	s_waitcnt lgkmcnt(0)
	s_waitcnt lgkmcnt(0)
	v_mfma_f32_16x16x32_bf16 v[108:111], v[204:207], v[172:175], v[108:111]
	v_mfma_f32_16x16x32_bf16 v[104:107], v[212:215], v[172:175], v[104:107]
	v_mfma_f32_16x16x32_bf16 v[92:95], v[204:207], v[180:183], v[92:95]
	v_mfma_f32_16x16x32_bf16 v[88:91], v[212:215], v[180:183], v[88:91]
	v_mfma_f32_16x16x32_bf16 v[76:79], v[204:207], v[188:191], v[76:79]
	v_mfma_f32_16x16x32_bf16 v[72:75], v[212:215], v[188:191], v[72:75]
	v_mfma_f32_16x16x32_bf16 v[68:71], v[204:207], v[196:199], v[68:71]
	v_mfma_f32_16x16x32_bf16 v[64:67], v[212:215], v[196:199], v[64:67]
	v_mfma_f32_16x16x32_bf16 v[108:111], v[208:211], v[176:179], v[108:111]
	v_mfma_f32_16x16x32_bf16 v[104:107], v[216:219], v[176:179], v[104:107]
	v_mfma_f32_16x16x32_bf16 v[92:95], v[208:211], v[184:187], v[92:95]
	v_mfma_f32_16x16x32_bf16 v[88:91], v[216:219], v[184:187], v[88:91]
	v_mfma_f32_16x16x32_bf16 v[76:79], v[208:211], v[192:195], v[76:79]
	v_mfma_f32_16x16x32_bf16 v[72:75], v[216:219], v[192:195], v[72:75]
	v_mfma_f32_16x16x32_bf16 v[68:71], v[208:211], v[200:203], v[68:71]
	v_mfma_f32_16x16x32_bf16 v[64:67], v[216:219], v[200:203], v[64:67]
	s_mov_b32 m0, s57
	v_lshl_add_u64 v[220:221], v[224:225], 0, s[8:9]
	s_barrier
	ds_read_b128 v[172:175], v154 offset:49152
	ds_read_b128 v[176:179], v154 offset:50176
	ds_read_b128 v[180:183], v154 offset:51200
	ds_read_b128 v[184:187], v154 offset:52224
	ds_read_b128 v[188:191], v154 offset:53248
	ds_read_b128 v[192:195], v154 offset:54272
	ds_read_b128 v[196:199], v154 offset:55296
	ds_read_b128 v[200:203], v154 offset:56320
	global_load_lds_dwordx4 v[220:221], off
	v_lshl_add_u64 v[220:221], v[226:227], 0, s[8:9]
	s_mov_b32 m0, s60
	s_nop 0
	global_load_lds_dwordx4 v[220:221], off
	s_barrier
	s_waitcnt lgkmcnt(0)
	s_waitcnt lgkmcnt(0)
	v_mfma_f32_16x16x32_bf16 v[60:63], v[156:159], v[172:175], v[60:63]
	v_mfma_f32_16x16x32_bf16 v[56:59], v[164:167], v[172:175], v[56:59]
	v_mfma_f32_16x16x32_bf16 v[52:55], v[156:159], v[180:183], v[52:55]
	v_mfma_f32_16x16x32_bf16 v[48:51], v[164:167], v[180:183], v[48:51]
	v_mfma_f32_16x16x32_bf16 v[36:39], v[156:159], v[188:191], v[36:39]
	v_mfma_f32_16x16x32_bf16 v[32:35], v[164:167], v[188:191], v[32:35]
	v_mfma_f32_16x16x32_bf16 v[20:23], v[156:159], v[196:199], v[20:23]
	v_mfma_f32_16x16x32_bf16 v[16:19], v[164:167], v[196:199], v[16:19]
	v_mfma_f32_16x16x32_bf16 v[60:63], v[160:163], v[176:179], v[60:63]
	v_mfma_f32_16x16x32_bf16 v[56:59], v[168:171], v[176:179], v[56:59]
	v_mfma_f32_16x16x32_bf16 v[52:55], v[160:163], v[184:187], v[52:55]
	v_mfma_f32_16x16x32_bf16 v[48:51], v[168:171], v[184:187], v[48:51]
	v_mfma_f32_16x16x32_bf16 v[36:39], v[160:163], v[192:195], v[36:39]
	v_mfma_f32_16x16x32_bf16 v[32:35], v[168:171], v[192:195], v[32:35]
	v_mfma_f32_16x16x32_bf16 v[20:23], v[160:163], v[200:203], v[20:23]
	v_mfma_f32_16x16x32_bf16 v[16:19], v[168:171], v[200:203], v[16:19]
	s_barrier
	s_add_u32 s36, s36, 0x100080
	s_addc_u32 s37, s37, 0
	s_add_i32 s38, s38, s43
	v_lshl_add_u64 v[156:157], s[36:37], 0, v[134:135]
	s_mov_b32 m0, s38
	s_nop 0
	global_load_lds_dwordx4 v[156:157], off
	v_lshl_add_u64 v[156:157], s[36:37], 0, v[130:131]
	s_add_i32 m0, s38, 0x2000
	s_nop 0
	global_load_lds_dwordx4 v[156:157], off
	s_waitcnt vmcnt(6)
	s_barrier
	v_mfma_f32_16x16x32_bf16 v[44:47], v[204:207], v[172:175], v[44:47]
	v_mfma_f32_16x16x32_bf16 v[40:43], v[212:215], v[172:175], v[40:43]
	v_mfma_f32_16x16x32_bf16 v[28:31], v[204:207], v[180:183], v[28:31]
	v_mfma_f32_16x16x32_bf16 v[24:27], v[212:215], v[180:183], v[24:27]
	v_mfma_f32_16x16x32_bf16 v[12:15], v[204:207], v[188:191], v[12:15]
	v_mfma_f32_16x16x32_bf16 v[8:11], v[212:215], v[188:191], v[8:11]
	v_mfma_f32_16x16x32_bf16 v[4:7], v[204:207], v[196:199], v[4:7]
	v_mfma_f32_16x16x32_bf16 v[0:3], v[212:215], v[196:199], v[0:3]
	v_mfma_f32_16x16x32_bf16 v[44:47], v[208:211], v[176:179], v[44:47]
	v_mfma_f32_16x16x32_bf16 v[40:43], v[216:219], v[176:179], v[40:43]
	v_mfma_f32_16x16x32_bf16 v[28:31], v[208:211], v[184:187], v[28:31]
	v_mfma_f32_16x16x32_bf16 v[24:27], v[216:219], v[184:187], v[24:27]
	v_mfma_f32_16x16x32_bf16 v[12:15], v[208:211], v[192:195], v[12:15]
	v_mfma_f32_16x16x32_bf16 v[8:11], v[216:219], v[192:195], v[8:11]
	v_mfma_f32_16x16x32_bf16 v[4:7], v[208:211], v[200:203], v[4:7]
	v_mfma_f32_16x16x32_bf16 v[0:3], v[216:219], v[200:203], v[0:3]
	s_add_i32 s77, s77, 2
	s_add_u32 s34, s34, 0x100
	s_addc_u32 s35, s35, 0
	s_add_u32 s75, s75, 0x100
	s_addc_u32 s76, s76, 0
	s_cmp_gt_u32 s77, 61
	s_barrier
	s_cbranch_scc0 .LBB0_1384
	v_lshl_add_u32 v156, s18, 8, v150
	v_lshl_or_b32 v158, s72, 8, v152
	v_ashrrev_i32_e32 v157, 31, v156
	v_lshlrev_b64 v[160:161], 11, v[156:157]
	v_ashrrev_i32_e32 v159, 31, v158
	v_lshl_add_u64 v[160:161], s[44:45], 0, v[160:161]
	v_cvt_pk_bf16_f32 v124, v124, v125
	v_cvt_pk_bf16_f32 v125, v126, v127
	v_cvt_pk_bf16_f32 v126, v120, v121
	v_lshlrev_b64 v[120:121], 1, v[158:159]
	v_cvt_pk_bf16_f32 v127, v122, v123
	v_lshl_add_u64 v[122:123], v[160:161], 0, v[120:121]
	v_cvt_pk_bf16_f32 v108, v108, v109
	v_cvt_pk_bf16_f32 v109, v110, v111
	v_cvt_pk_bf16_f32 v110, v104, v105
	v_or_b32_e32 v104, 16, v156
	v_cvt_pk_bf16_f32 v60, v60, v61
	v_cvt_pk_bf16_f32 v61, v62, v63
	v_cvt_pk_bf16_f32 v63, v58, v59
	v_add_co_u32_e32 v58, vcc, s64, v122
	v_ashrrev_i32_e32 v105, 31, v104
	v_cvt_pk_bf16_f32 v62, v56, v57
	v_lshl_add_u64 v[56:57], v[122:123], 0, s[10:11]
	v_addc_co_u32_e32 v59, vcc, 0, v123, vcc
	v_cvt_pk_bf16_f32 v44, v44, v45
	v_cvt_pk_bf16_f32 v45, v46, v47
	v_cvt_pk_bf16_f32 v46, v40, v41
	v_cvt_pk_bf16_f32 v47, v42, v43
	v_cvt_pk_bf16_f32 v111, v106, v107
	v_lshlrev_b64 v[104:105], 11, v[104:105]
	v_cvt_pk_bf16_f32 v92, v92, v93
	v_cvt_pk_bf16_f32 v93, v94, v95
	v_cvt_pk_bf16_f32 v94, v88, v89
	v_or_b32_e32 v88, 32, v156
	global_store_dwordx4 v[56:57], v[44:47], off offset:256
	global_store_dwordx4 v[122:123], v[108:111], off offset:256
	v_ashrrev_i32_e32 v89, 31, v88
	v_add_co_u32_e32 v46, vcc, s65, v122
	v_lshl_add_u64 v[108:109], s[44:45], 0, v[104:105]
	v_lshl_add_u64 v[44:45], v[122:123], 0, s[12:13]
	v_addc_co_u32_e32 v47, vcc, 0, v123, vcc
	v_cvt_pk_bf16_f32 v28, v28, v29
	v_cvt_pk_bf16_f32 v29, v30, v31
	v_cvt_pk_bf16_f32 v30, v24, v25
	v_cvt_pk_bf16_f32 v31, v26, v27
	v_lshl_add_u64 v[108:109], v[108:109], 0, v[120:121]
	v_cvt_pk_bf16_f32 v95, v90, v91
	v_lshlrev_b64 v[88:89], 11, v[88:89]
	v_cvt_pk_bf16_f32 v76, v76, v77
	v_cvt_pk_bf16_f32 v77, v78, v79
	v_cvt_pk_bf16_f32 v78, v72, v73
	v_or_b32_e32 v72, 48, v156
	global_store_dwordx4 v[44:45], v[28:31], off offset:256
	global_store_dwordx4 v[108:109], v[92:95], off offset:256
	v_ashrrev_i32_e32 v73, 31, v72
	v_add_co_u32_e32 v30, vcc, s70, v122
	v_lshl_add_u64 v[92:93], s[44:45], 0, v[88:89]
	v_lshl_add_u64 v[28:29], v[122:123], 0, s[14:15]
	v_addc_co_u32_e32 v31, vcc, 0, v123, vcc
	v_cvt_pk_bf16_f32 v12, v12, v13
	v_cvt_pk_bf16_f32 v13, v14, v15
	v_cvt_pk_bf16_f32 v14, v8, v9
	v_cvt_pk_bf16_f32 v15, v10, v11
	v_lshl_add_u64 v[92:93], v[92:93], 0, v[120:121]
	v_cvt_pk_bf16_f32 v79, v74, v75
	v_lshlrev_b64 v[72:73], 11, v[72:73]
	global_store_dwordx4 v[28:29], v[12:15], off offset:256
	global_store_dwordx4 v[92:93], v[76:79], off offset:256
	v_cvt_pk_bf16_f32 v104, v116, v117
	v_add_co_u32_e32 v14, vcc, s71, v122
	v_lshl_add_u64 v[76:77], s[44:45], 0, v[72:73]
	s_nop 0
	v_addc_co_u32_e32 v15, vcc, 0, v123, vcc
	v_cvt_pk_bf16_f32 v105, v118, v119
	v_cvt_pk_bf16_f32 v106, v112, v113
	v_cvt_pk_bf16_f32 v107, v114, v115
	v_cvt_pk_bf16_f32 v88, v100, v101
	v_cvt_pk_bf16_f32 v89, v102, v103
	v_cvt_pk_bf16_f32 v90, v96, v97
	v_cvt_pk_bf16_f32 v91, v98, v99
	v_cvt_pk_bf16_f32 v72, v84, v85
	v_cvt_pk_bf16_f32 v73, v86, v87
	v_cvt_pk_bf16_f32 v74, v80, v81
	v_cvt_pk_bf16_f32 v75, v82, v83
	v_lshl_add_u64 v[76:77], v[76:77], 0, v[120:121]
	v_cvt_pk_bf16_f32 v68, v68, v69
	v_cvt_pk_bf16_f32 v69, v70, v71
	v_cvt_pk_bf16_f32 v70, v64, v65
	v_cvt_pk_bf16_f32 v71, v66, v67
	v_cvt_pk_bf16_f32 v40, v52, v53
	v_cvt_pk_bf16_f32 v41, v54, v55
	v_cvt_pk_bf16_f32 v42, v48, v49
	v_cvt_pk_bf16_f32 v43, v50, v51
	v_cvt_pk_bf16_f32 v24, v36, v37
	v_cvt_pk_bf16_f32 v25, v38, v39
	v_cvt_pk_bf16_f32 v26, v32, v33
	v_cvt_pk_bf16_f32 v27, v34, v35
	v_cvt_pk_bf16_f32 v8, v20, v21
	v_cvt_pk_bf16_f32 v9, v22, v23
	v_cvt_pk_bf16_f32 v10, v16, v17
	v_cvt_pk_bf16_f32 v11, v18, v19
	v_lshl_add_u64 v[12:13], v[122:123], 0, s[16:17]
	v_cvt_pk_bf16_f32 v4, v4, v5
	v_cvt_pk_bf16_f32 v5, v6, v7
	v_cvt_pk_bf16_f32 v6, v0, v1
	v_cvt_pk_bf16_f32 v7, v2, v3
	s_and_b64 vcc, exec, s[4:5]
	s_mov_b32 s72, s20
	s_mov_b32 s18, s26
	s_mov_b64 s[36:37], s[30:31]
	s_mov_b64 s[34:35], s[28:29]
	global_store_dwordx4 v[122:123], v[124:127], off
	global_store_dwordx4 v[108:109], v[104:107], off
	global_store_dwordx4 v[92:93], v[88:91], off
	global_store_dwordx4 v[76:77], v[72:75], off
	global_store_dwordx4 v[76:77], v[68:71], off offset:256
	global_store_dwordx4 v[58:59], v[60:63], off
	global_store_dwordx4 v[46:47], v[40:43], off
	global_store_dwordx4 v[30:31], v[24:27], off
	global_store_dwordx4 v[14:15], v[8:11], off
	global_store_dwordx4 v[12:13], v[4:7], off offset:256
	s_cbranch_vccz .LBB0_1381
	s_waitcnt vmcnt(16)
	s_cmpk_gt_u32 s40, 0xff
	s_cbranch_scc1 .LBB0_1388
	s_barrier
